# scan phase rewritten by hand (single pass over LU, 128 loads in flight) + GEMM loop LDS-DMA loads use scalar base + 32-bit VGPR offset (no 64-bit VALU adds)
# speedup vs baseline: 1.0094x; 1.0094x over previous
; #define PG8_STAGE(bufoff, gbase, voff) do { _Pragma("unroll") for (int _i = 0; _i < 2; ++_i) \
;         __builtin_amdgcn_global_load_lds((const unsigned*)((const char*)(gbase) + (voff)[_i]), (LAS unsigned*)(lds + (bufoff) + ldsw + _i * 8192), 16, 0, 0); } while (0)
; #define PG8_LDA(dst, b, h) do { _Pragma("unroll") for (int m = 0; m < 4; ++m) _Pragma("unroll") for (int k = 0; k < 2; ++k) dst[m][k] = *(const LAS bf16x8*)(lds + PG8_SA(b, h) + aoff + m * 2048 + k * 1024); } while (0)
; #define PG8_LDB(dst, b, h) do { _Pragma("unroll") for (int n = 0; n < 2; ++n) _Pragma("unroll") for (int k = 0; k < 2; ++k) dst[n][k] = *(const LAS bf16x8*)(lds + PG8_SB(b, h) + boff + n * 2048 + k * 1024); } while (0)
; #define PG8_MMA(ai, bj, At, Bt) do { __builtin_amdgcn_s_setprio(1); _Pragma("unroll") for (int m = 0; m < 4; ++m) _Pragma("unroll") for (int n = 0; n < 2; ++n) _Pragma("unroll") for (int k = 0; k < 2; ++k) \
;         acc[ai][bj][m][n] = __builtin_amdgcn_mfma_f32_16x16x32_bf16(Bt[n][k], At[m][k], acc[ai][bj][m][n], 0, 0, 0); __builtin_amdgcn_s_setprio(0); } while (0)
; #define PG8_WAIT_V(n) asm volatile("s_waitcnt vmcnt(" #n ")" ::: "memory")
; #define PG8_WAIT_L(n) asm volatile("s_waitcnt lgkmcnt(" #n ")" ::: "memory")
; #define PG8_BAR __builtin_amdgcn_s_barrier()
; #define PG8_SCHED __builtin_amdgcn_sched_barrier(0)
; template <class Epi, class S_t>
; __device__ __forceinline__ void gemm_phase(LAS unsigned char* lds, int lda, int ldb, const S_t& S, const Epi& E) {
;     ...
;             const char* a1 = cA + (size_t)(t + 1) * kstep;
;             const char* a2 = last ? nA : cA + (size_t)(t + 2) * kstep; const char* b2 = last ? nB : cB + (size_t)(t + 2) * kstep;
;             const char* a3 = a2 + kstep; const char* b3 = b2 + kstep;
;             PG8_LDB(B0, 0, 0); PG8_SCHED; PG8_LDA(At, 0, 0); PG8_STAGE(PG8_SA(1, 1), a1 + hstepA, voffA);
;             PG8_WAIT_L(8); PG8_BAR; PG8_WAIT_L(0); PG8_MMA(0, 0, At, B0); PG8_BAR; PG8_SCHED;
;             PG8_LDB(B1, 0, 1); PG8_STAGE(PG8_SB(0, 0), b2, voffB);
;             PG8_BAR; PG8_WAIT_L(0); PG8_MMA(0, 1, At, B1); PG8_BAR;
;             PG8_LDA(At, 0, 1); PG8_STAGE(PG8_SA(0, 0), a2, voffA);
;             PG8_BAR; PG8_WAIT_L(0); PG8_MMA(1, 0, At, B0); PG8_BAR; PG8_SCHED;
;             PG8_STAGE(PG8_SB(0, 1), b2 + hstepB, voffB);
;             PG8_WAIT_V(6); PG8_BAR; PG8_MMA(1, 1, At, B1); PG8_BAR;
.LBB0_133:
	ds_read_b128 v[152:155], v175
	ds_read_b128 v[156:159], v175 offset:1024
	ds_read_b128 v[160:163], v175 offset:2048
	ds_read_b128 v[164:167], v175 offset:3072
	s_add_u32 s18, s16, 0xfff80080
	s_addc_u32 s19, s17, -1
	s_cmp_eq_u32 s9, 28
	s_cselect_b32 s21, s11, s19
	s_cselect_b32 s20, s10, s18
	s_cselect_b32 s19, s13, s1
	s_cselect_b32 s18, s12, s0
	s_add_i32 m0, s53, 0xc000
	ds_read_b128 v[186:189], v178
	ds_read_b128 v[190:193], v178 offset:1024
	ds_read_b128 v[194:197], v178 offset:2048
	ds_read_b128 v[198:201], v178 offset:3072
	ds_read_b128 v[202:205], v178 offset:4096
	ds_read_b128 v[206:209], v178 offset:5120
	ds_read_b128 v[214:217], v178 offset:6144
	ds_read_b128 v[218:221], v178 offset:7168
	global_load_lds_dwordx4 v148, s[16:17]
	s_add_i32 m0, s53, 0xe000
	s_nop 0
	global_load_lds_dwordx4 v150, s[16:17]
	s_waitcnt lgkmcnt(8)
	s_barrier
	s_waitcnt lgkmcnt(0)
	s_setprio 1
	s_waitcnt lgkmcnt(0)
	v_mfma_f32_16x16x32_bf16 v[124:127], v[152:155], v[186:189], v[124:127]
	v_mfma_f32_16x16x32_bf16 v[92:95], v[160:163], v[186:189], v[92:95]
	v_mfma_f32_16x16x32_bf16 v[120:123], v[152:155], v[194:197], v[120:123]
	v_mfma_f32_16x16x32_bf16 v[88:91], v[160:163], v[194:197], v[88:91]
	v_mfma_f32_16x16x32_bf16 v[116:119], v[152:155], v[202:205], v[116:119]
	v_mfma_f32_16x16x32_bf16 v[84:87], v[160:163], v[202:205], v[84:87]
	v_mfma_f32_16x16x32_bf16 v[112:115], v[152:155], v[214:217], v[112:115]
	v_mfma_f32_16x16x32_bf16 v[80:83], v[160:163], v[214:217], v[80:83]
	v_mfma_f32_16x16x32_bf16 v[124:127], v[156:159], v[190:193], v[124:127]
	v_mfma_f32_16x16x32_bf16 v[92:95], v[164:167], v[190:193], v[92:95]
	v_mfma_f32_16x16x32_bf16 v[120:123], v[156:159], v[198:201], v[120:123]
	v_mfma_f32_16x16x32_bf16 v[88:91], v[164:167], v[198:201], v[88:91]
	v_mfma_f32_16x16x32_bf16 v[116:119], v[156:159], v[206:209], v[116:119]
	v_mfma_f32_16x16x32_bf16 v[84:87], v[164:167], v[206:209], v[84:87]
	v_mfma_f32_16x16x32_bf16 v[112:115], v[156:159], v[218:221], v[112:115]
	v_mfma_f32_16x16x32_bf16 v[80:83], v[164:167], v[218:221], v[80:83]
	s_setprio 0
	s_barrier
	s_add_i32 s33, s62, s43
	s_add_u32 s98, s18, s6
	s_addc_u32 s99, s19, s7
	s_mov_b32 m0, s33
	ds_read_b128 v[222:225], v179
	ds_read_b128 v[226:229], v179 offset:1024
	ds_read_b128 v[230:233], v179 offset:2048
	ds_read_b128 v[234:237], v179 offset:3072
	global_load_lds_dwordx4 v128, s[18:19]
	s_add_i32 m0, s33, 0x2000
	s_nop 0
	global_load_lds_dwordx4 v130, s[18:19]
	s_barrier
	s_waitcnt lgkmcnt(0)
	s_setprio 1
	s_waitcnt lgkmcnt(0)
	v_mfma_f32_16x16x32_bf16 v[60:63], v[222:225], v[186:189], v[60:63]
	v_mfma_f32_16x16x32_bf16 v[28:31], v[230:233], v[186:189], v[28:31]
	v_mfma_f32_16x16x32_bf16 v[56:59], v[222:225], v[194:197], v[56:59]
	v_mfma_f32_16x16x32_bf16 v[24:27], v[230:233], v[194:197], v[24:27]
	v_mfma_f32_16x16x32_bf16 v[52:55], v[222:225], v[202:205], v[52:55]
	v_mfma_f32_16x16x32_bf16 v[20:23], v[230:233], v[202:205], v[20:23]
	v_mfma_f32_16x16x32_bf16 v[48:51], v[222:225], v[214:217], v[48:51]
	v_mfma_f32_16x16x32_bf16 v[16:19], v[230:233], v[214:217], v[16:19]
	v_mfma_f32_16x16x32_bf16 v[60:63], v[226:229], v[190:193], v[60:63]
	v_mfma_f32_16x16x32_bf16 v[28:31], v[234:237], v[190:193], v[28:31]
	v_mfma_f32_16x16x32_bf16 v[56:59], v[226:229], v[198:201], v[56:59]
	v_mfma_f32_16x16x32_bf16 v[24:27], v[234:237], v[198:201], v[24:27]
	v_mfma_f32_16x16x32_bf16 v[52:55], v[226:229], v[206:209], v[52:55]
	v_mfma_f32_16x16x32_bf16 v[20:23], v[234:237], v[206:209], v[20:23]
	v_mfma_f32_16x16x32_bf16 v[48:51], v[226:229], v[218:221], v[48:51]
	v_mfma_f32_16x16x32_bf16 v[16:19], v[234:237], v[218:221], v[16:19]
	s_setprio 0
	s_mov_b32 m0, s53
	s_add_u32 s100, s20, s6
	s_addc_u32 s101, s21, s7
	s_barrier
	ds_read_b128 v[186:189], v178 offset:16384
	ds_read_b128 v[190:193], v178 offset:17408
	ds_read_b128 v[194:197], v178 offset:18432
	ds_read_b128 v[198:201], v178 offset:19456
	ds_read_b128 v[202:205], v178 offset:20480
	ds_read_b128 v[206:209], v178 offset:21504
	ds_read_b128 v[214:217], v178 offset:22528
	ds_read_b128 v[218:221], v178 offset:23552
	global_load_lds_dwordx4 v128, s[20:21]
	s_mov_b32 m0, s54
	s_nop 0
	global_load_lds_dwordx4 v130, s[20:21]
	s_barrier
	s_waitcnt lgkmcnt(0)
	s_setprio 1
	s_waitcnt lgkmcnt(0)
	v_mfma_f32_16x16x32_bf16 v[108:111], v[152:155], v[186:189], v[108:111]
	v_mfma_f32_16x16x32_bf16 v[76:79], v[160:163], v[186:189], v[76:79]
	v_mfma_f32_16x16x32_bf16 v[104:107], v[152:155], v[194:197], v[104:107]
	v_mfma_f32_16x16x32_bf16 v[72:75], v[160:163], v[194:197], v[72:75]
	v_mfma_f32_16x16x32_bf16 v[100:103], v[152:155], v[202:205], v[100:103]
	v_mfma_f32_16x16x32_bf16 v[68:71], v[160:163], v[202:205], v[68:71]
	v_mfma_f32_16x16x32_bf16 v[96:99], v[152:155], v[214:217], v[96:99]
	v_mfma_f32_16x16x32_bf16 v[64:67], v[160:163], v[214:217], v[64:67]
	v_mfma_f32_16x16x32_bf16 v[108:111], v[156:159], v[190:193], v[108:111]
	v_mfma_f32_16x16x32_bf16 v[76:79], v[164:167], v[190:193], v[76:79]
	v_mfma_f32_16x16x32_bf16 v[104:107], v[156:159], v[198:201], v[104:107]
	v_mfma_f32_16x16x32_bf16 v[72:75], v[164:167], v[198:201], v[72:75]
	v_mfma_f32_16x16x32_bf16 v[100:103], v[156:159], v[206:209], v[100:103]
	v_mfma_f32_16x16x32_bf16 v[68:71], v[164:167], v[206:209], v[68:71]
	v_mfma_f32_16x16x32_bf16 v[96:99], v[156:159], v[218:221], v[96:99]
	v_mfma_f32_16x16x32_bf16 v[64:67], v[164:167], v[218:221], v[64:67]
	s_setprio 0
	s_barrier
	s_add_u32 s66, s18, 0x80000
	s_addc_u32 s67, s19, 0
	s_add_i32 s33, s63, s43
	s_mov_b32 m0, s33
	s_nop 0
	global_load_lds_dwordx4 v128, s[66:67]
	s_add_i32 m0, s33, 0x2000
	s_nop 0
	global_load_lds_dwordx4 v130, s[66:67]
	s_waitcnt vmcnt(6)
	s_barrier
; #define PG8_STAGE(bufoff, gbase, voff) do { _Pragma("unroll") for (int _i = 0; _i < 2; ++_i) \
;         __builtin_amdgcn_global_load_lds((const unsigned*)((const char*)(gbase) + (voff)[_i]), (LAS unsigned*)(lds + (bufoff) + ldsw + _i * 8192), 16, 0, 0); } while (0)
; #define PG8_LDA(dst, b, h) do { _Pragma("unroll") for (int m = 0; m < 4; ++m) _Pragma("unroll") for (int k = 0; k < 2; ++k) dst[m][k] = *(const LAS bf16x8*)(lds + PG8_SA(b, h) + aoff + m * 2048 + k * 1024); } while (0)
; #define PG8_LDB(dst, b, h) do { _Pragma("unroll") for (int n = 0; n < 2; ++n) _Pragma("unroll") for (int k = 0; k < 2; ++k) dst[n][k] = *(const LAS bf16x8*)(lds + PG8_SB(b, h) + boff + n * 2048 + k * 1024); } while (0)
; #define PG8_MMA(ai, bj, At, Bt) do { __builtin_amdgcn_s_setprio(1); _Pragma("unroll") for (int m = 0; m < 4; ++m) _Pragma("unroll") for (int n = 0; n < 2; ++n) _Pragma("unroll") for (int k = 0; k < 2; ++k) \
;         acc[ai][bj][m][n] = __builtin_amdgcn_mfma_f32_16x16x32_bf16(Bt[n][k], At[m][k], acc[ai][bj][m][n], 0, 0, 0); __builtin_amdgcn_s_setprio(0); } while (0)
; #define PG8_WAIT_V(n) asm volatile("s_waitcnt vmcnt(" #n ")" ::: "memory")
; #define PG8_WAIT_L(n) asm volatile("s_waitcnt lgkmcnt(" #n ")" ::: "memory")
; #define PG8_BAR __builtin_amdgcn_s_barrier()
; #define PG8_SCHED __builtin_amdgcn_sched_barrier(0)
; template <class Epi, class S_t>
; __device__ __forceinline__ void gemm_phase(LAS unsigned char* lds, int lda, int ldb, const S_t& S, const Epi& E) {
;     ...
;             PG8_WAIT_V(6); PG8_BAR; PG8_MMA(1, 1, At, B1); PG8_BAR;
;             PG8_LDB(B0, 1, 0); PG8_SCHED; PG8_LDA(At, 1, 0); PG8_STAGE(PG8_SA(0, 1), a2 + hstepA, voffA);
;             PG8_WAIT_L(8); PG8_BAR; PG8_WAIT_L(0); PG8_MMA(0, 0, At, B0); PG8_BAR; PG8_SCHED;
;             PG8_LDB(B1, 1, 1); PG8_STAGE(PG8_SB(1, 0), b3, voffB);
;             PG8_BAR; PG8_WAIT_L(0); PG8_MMA(0, 1, At, B1); PG8_BAR;
;             PG8_LDA(At, 1, 1); PG8_STAGE(PG8_SA(1, 0), a3, voffA);
;             PG8_BAR; PG8_WAIT_L(0); PG8_MMA(1, 0, At, B0); PG8_BAR; PG8_SCHED;
	s_setprio 1
	v_mfma_f32_16x16x32_bf16 v[44:47], v[222:225], v[186:189], v[44:47]
	v_mfma_f32_16x16x32_bf16 v[12:15], v[230:233], v[186:189], v[12:15]
	v_mfma_f32_16x16x32_bf16 v[40:43], v[222:225], v[194:197], v[40:43]
	v_mfma_f32_16x16x32_bf16 v[8:11], v[230:233], v[194:197], v[8:11]
	v_mfma_f32_16x16x32_bf16 v[36:39], v[222:225], v[202:205], v[36:39]
	v_mfma_f32_16x16x32_bf16 v[4:7], v[230:233], v[202:205], v[4:7]
	v_mfma_f32_16x16x32_bf16 v[32:35], v[222:225], v[214:217], v[32:35]
	v_mfma_f32_16x16x32_bf16 v[0:3], v[230:233], v[214:217], v[0:3]
	v_mfma_f32_16x16x32_bf16 v[44:47], v[226:229], v[190:193], v[44:47]
	v_mfma_f32_16x16x32_bf16 v[12:15], v[234:237], v[190:193], v[12:15]
	v_mfma_f32_16x16x32_bf16 v[40:43], v[226:229], v[198:201], v[40:43]
	v_mfma_f32_16x16x32_bf16 v[8:11], v[234:237], v[198:201], v[8:11]
	v_mfma_f32_16x16x32_bf16 v[36:39], v[226:229], v[206:209], v[36:39]
	v_mfma_f32_16x16x32_bf16 v[4:7], v[234:237], v[206:209], v[4:7]
	v_mfma_f32_16x16x32_bf16 v[32:35], v[226:229], v[218:221], v[32:35]
	v_mfma_f32_16x16x32_bf16 v[0:3], v[234:237], v[218:221], v[0:3]
	s_setprio 0
	s_add_i32 s33, 0, 0x18000
	v_add_u32_e32 v164, s33, v171
	s_barrier
	ds_read_b128 v[152:155], v164
	ds_read_b128 v[156:159], v164 offset:1024
	ds_read_b128 v[160:163], v164 offset:2048
	ds_read_b128 v[164:167], v164 offset:3072
	s_add_u32 s20, s20, 0x80000
	s_addc_u32 s21, s21, 0
	s_mov_b32 m0, s55
	ds_read_b128 v[186:189], v178 offset:32768
	ds_read_b128 v[190:193], v178 offset:33792
	ds_read_b128 v[194:197], v178 offset:34816
	ds_read_b128 v[198:201], v178 offset:35840
	ds_read_b128 v[202:205], v178 offset:36864
	ds_read_b128 v[206:209], v178 offset:37888
	ds_read_b128 v[214:217], v178 offset:38912
	ds_read_b128 v[218:221], v178 offset:39936
	global_load_lds_dwordx4 v128, s[20:21]
	s_mov_b32 m0, s56
	s_nop 0
	global_load_lds_dwordx4 v130, s[20:21]
	s_waitcnt lgkmcnt(8)
	s_barrier
	s_waitcnt lgkmcnt(0)
	s_setprio 1
	s_waitcnt lgkmcnt(0)
	v_mfma_f32_16x16x32_bf16 v[124:127], v[152:155], v[186:189], v[124:127]
	v_mfma_f32_16x16x32_bf16 v[92:95], v[160:163], v[186:189], v[92:95]
	v_mfma_f32_16x16x32_bf16 v[120:123], v[152:155], v[194:197], v[120:123]
	v_mfma_f32_16x16x32_bf16 v[88:91], v[160:163], v[194:197], v[88:91]
	v_mfma_f32_16x16x32_bf16 v[116:119], v[152:155], v[202:205], v[116:119]
	v_mfma_f32_16x16x32_bf16 v[84:87], v[160:163], v[202:205], v[84:87]
	v_mfma_f32_16x16x32_bf16 v[112:115], v[152:155], v[214:217], v[112:115]
	v_mfma_f32_16x16x32_bf16 v[80:83], v[160:163], v[214:217], v[80:83]
	v_mfma_f32_16x16x32_bf16 v[124:127], v[156:159], v[190:193], v[124:127]
	v_mfma_f32_16x16x32_bf16 v[92:95], v[164:167], v[190:193], v[92:95]
	v_mfma_f32_16x16x32_bf16 v[120:123], v[156:159], v[198:201], v[120:123]
	v_mfma_f32_16x16x32_bf16 v[88:91], v[164:167], v[198:201], v[88:91]
	v_mfma_f32_16x16x32_bf16 v[116:119], v[156:159], v[206:209], v[116:119]
	v_mfma_f32_16x16x32_bf16 v[84:87], v[164:167], v[206:209], v[84:87]
	v_mfma_f32_16x16x32_bf16 v[112:115], v[156:159], v[218:221], v[112:115]
	v_mfma_f32_16x16x32_bf16 v[80:83], v[164:167], v[218:221], v[80:83]
	s_setprio 0
	s_barrier
	s_add_i32 s20, 0, 0x1c000
	s_add_i32 s21, s33, s43
	v_add_u32_e32 v170, s20, v171
	s_mov_b32 m0, s21
	ds_read_b128 v[222:225], v170
	ds_read_b128 v[226:229], v170 offset:1024
	ds_read_b128 v[230:233], v170 offset:2048
	ds_read_b128 v[234:237], v170 offset:3072
	global_load_lds_dwordx4 v128, s[98:99]
	s_add_i32 m0, s21, 0x2000
	s_nop 0
	global_load_lds_dwordx4 v130, s[98:99]
	s_barrier
	s_waitcnt lgkmcnt(0)
	s_setprio 1
	s_waitcnt lgkmcnt(0)
	v_mfma_f32_16x16x32_bf16 v[60:63], v[222:225], v[186:189], v[60:63]
	v_mfma_f32_16x16x32_bf16 v[28:31], v[230:233], v[186:189], v[28:31]
	v_mfma_f32_16x16x32_bf16 v[56:59], v[222:225], v[194:197], v[56:59]
	v_mfma_f32_16x16x32_bf16 v[24:27], v[230:233], v[194:197], v[24:27]
	v_mfma_f32_16x16x32_bf16 v[52:55], v[222:225], v[202:205], v[52:55]
	v_mfma_f32_16x16x32_bf16 v[20:23], v[230:233], v[202:205], v[20:23]
	v_mfma_f32_16x16x32_bf16 v[48:51], v[222:225], v[214:217], v[48:51]
	v_mfma_f32_16x16x32_bf16 v[16:19], v[230:233], v[214:217], v[16:19]
	v_mfma_f32_16x16x32_bf16 v[60:63], v[226:229], v[190:193], v[60:63]
	v_mfma_f32_16x16x32_bf16 v[28:31], v[234:237], v[190:193], v[28:31]
	v_mfma_f32_16x16x32_bf16 v[56:59], v[226:229], v[198:201], v[56:59]
	v_mfma_f32_16x16x32_bf16 v[24:27], v[234:237], v[198:201], v[24:27]
	v_mfma_f32_16x16x32_bf16 v[52:55], v[226:229], v[206:209], v[52:55]
	v_mfma_f32_16x16x32_bf16 v[20:23], v[234:237], v[206:209], v[20:23]
	v_mfma_f32_16x16x32_bf16 v[48:51], v[226:229], v[218:221], v[48:51]
	v_mfma_f32_16x16x32_bf16 v[16:19], v[234:237], v[218:221], v[16:19]
	s_setprio 0
	s_mov_b32 m0, s58
	s_barrier
; #define PG8_STAGE(bufoff, gbase, voff) do { _Pragma("unroll") for (int _i = 0; _i < 2; ++_i) \
;         __builtin_amdgcn_global_load_lds((const unsigned*)((const char*)(gbase) + (voff)[_i]), (LAS unsigned*)(lds + (bufoff) + ldsw + _i * 8192), 16, 0, 0); } while (0)
; #define PG8_LDA(dst, b, h) do { _Pragma("unroll") for (int m = 0; m < 4; ++m) _Pragma("unroll") for (int k = 0; k < 2; ++k) dst[m][k] = *(const LAS bf16x8*)(lds + PG8_SA(b, h) + aoff + m * 2048 + k * 1024); } while (0)
; #define PG8_LDB(dst, b, h) do { _Pragma("unroll") for (int n = 0; n < 2; ++n) _Pragma("unroll") for (int k = 0; k < 2; ++k) dst[n][k] = *(const LAS bf16x8*)(lds + PG8_SB(b, h) + boff + n * 2048 + k * 1024); } while (0)
; #define PG8_MMA(ai, bj, At, Bt) do { __builtin_amdgcn_s_setprio(1); _Pragma("unroll") for (int m = 0; m < 4; ++m) _Pragma("unroll") for (int n = 0; n < 2; ++n) _Pragma("unroll") for (int k = 0; k < 2; ++k) \
;         acc[ai][bj][m][n] = __builtin_amdgcn_mfma_f32_16x16x32_bf16(Bt[n][k], At[m][k], acc[ai][bj][m][n], 0, 0, 0); __builtin_amdgcn_s_setprio(0); } while (0)
; template <class Epi, class S_t>
; __device__ __forceinline__ void gemm_phase(LAS unsigned char* lds, int lda, int ldb, const S_t& S, const Epi& E) {
;     ...
;             PG8_WAIT_V(6); PG8_BAR; PG8_MMA(1, 1, At, B1); PG8_BAR;
;             PG8_LDB(B0, 1, 0); PG8_SCHED; PG8_LDA(At, 1, 0); PG8_STAGE(PG8_SA(0, 1), a2 + hstepA, voffA);
;             PG8_WAIT_L(8); PG8_BAR; PG8_WAIT_L(0); PG8_MMA(0, 0, At, B0); PG8_BAR; PG8_SCHED;
;             PG8_LDB(B1, 1, 1); PG8_STAGE(PG8_SB(1, 0), b3, voffB);
;             PG8_BAR; PG8_WAIT_L(0); PG8_MMA(0, 1, At, B1); PG8_BAR;
;             PG8_LDA(At, 1, 1); PG8_STAGE(PG8_SA(1, 0), a3, voffA);
;             PG8_BAR; PG8_WAIT_L(0); PG8_MMA(1, 0, At, B0); PG8_BAR; PG8_SCHED;
;             PG8_STAGE(PG8_SB(1, 1), b3 + hstepB, voffB);
;             PG8_WAIT_V(6); PG8_BAR; PG8_MMA(1, 1, At, B1); PG8_BAR;
;     __device__ __forceinline__ void operator()(const f32x4 (&acc)[2][2][4][2], const Unit& u, int wr, int wc, int fr, int fq) const {
;         const int row0 = wr * 64 + fr, col0 = u.pn * BM + wc * 32 + 4 * fq, kind = u.pn >> 3;
;         const float* gm = kind == 2 ? g2 : kind == 4 ? g4 : kind == 5 ? g5 : g1;
;         const float one = (kind == 1 || kind == 4) ? 1.0f : 0.0f, gs = (kind == 0 || kind == 3) ? 0.0f : 1.0f;
	ds_read_b128 v[186:189], v178 offset:49152
	ds_read_b128 v[190:193], v178 offset:50176
	ds_read_b128 v[194:197], v178 offset:51200
	ds_read_b128 v[198:201], v178 offset:52224
	ds_read_b128 v[202:205], v178 offset:53248
	ds_read_b128 v[206:209], v178 offset:54272
	ds_read_b128 v[214:217], v178 offset:55296
	ds_read_b128 v[218:221], v178 offset:56320
	global_load_lds_dwordx4 v128, s[100:101]
	s_mov_b32 m0, s59
	s_nop 0
	global_load_lds_dwordx4 v130, s[100:101]
	s_barrier
	s_waitcnt lgkmcnt(0)
	s_setprio 1
	s_waitcnt lgkmcnt(0)
	v_mfma_f32_16x16x32_bf16 v[108:111], v[152:155], v[186:189], v[108:111]
	v_mfma_f32_16x16x32_bf16 v[76:79], v[160:163], v[186:189], v[76:79]
	v_mfma_f32_16x16x32_bf16 v[104:107], v[152:155], v[194:197], v[104:107]
	v_mfma_f32_16x16x32_bf16 v[72:75], v[160:163], v[194:197], v[72:75]
	v_mfma_f32_16x16x32_bf16 v[100:103], v[152:155], v[202:205], v[100:103]
	v_mfma_f32_16x16x32_bf16 v[68:71], v[160:163], v[202:205], v[68:71]
	v_mfma_f32_16x16x32_bf16 v[96:99], v[152:155], v[214:217], v[96:99]
	v_mfma_f32_16x16x32_bf16 v[64:67], v[160:163], v[214:217], v[64:67]
	v_mfma_f32_16x16x32_bf16 v[108:111], v[156:159], v[190:193], v[108:111]
	v_mfma_f32_16x16x32_bf16 v[76:79], v[164:167], v[190:193], v[76:79]
	v_mfma_f32_16x16x32_bf16 v[104:107], v[156:159], v[198:201], v[104:107]
	v_mfma_f32_16x16x32_bf16 v[72:75], v[164:167], v[198:201], v[72:75]
	v_mfma_f32_16x16x32_bf16 v[100:103], v[156:159], v[206:209], v[100:103]
	v_mfma_f32_16x16x32_bf16 v[68:71], v[164:167], v[206:209], v[68:71]
	v_mfma_f32_16x16x32_bf16 v[96:99], v[156:159], v[218:221], v[96:99]
	v_mfma_f32_16x16x32_bf16 v[64:67], v[164:167], v[218:221], v[64:67]
	s_setprio 0
	s_barrier
	s_add_u32 s18, s18, 0x80080
	s_addc_u32 s19, s19, 0
	s_add_i32 s20, s20, s43
	s_mov_b32 m0, s20
	s_nop 0
	global_load_lds_dwordx4 v128, s[18:19]
	s_add_i32 m0, s20, 0x2000
	s_nop 0
	global_load_lds_dwordx4 v130, s[18:19]
	s_waitcnt vmcnt(6)
	s_barrier
	s_setprio 1
	v_mfma_f32_16x16x32_bf16 v[44:47], v[222:225], v[186:189], v[44:47]
	v_mfma_f32_16x16x32_bf16 v[12:15], v[230:233], v[186:189], v[12:15]
	v_mfma_f32_16x16x32_bf16 v[40:43], v[222:225], v[194:197], v[40:43]
	v_mfma_f32_16x16x32_bf16 v[8:11], v[230:233], v[194:197], v[8:11]
	v_mfma_f32_16x16x32_bf16 v[36:39], v[222:225], v[202:205], v[36:39]
	v_mfma_f32_16x16x32_bf16 v[4:7], v[230:233], v[202:205], v[4:7]
	v_mfma_f32_16x16x32_bf16 v[32:35], v[222:225], v[214:217], v[32:35]
	v_mfma_f32_16x16x32_bf16 v[0:3], v[230:233], v[214:217], v[0:3]
	v_mfma_f32_16x16x32_bf16 v[44:47], v[226:229], v[190:193], v[44:47]
	v_mfma_f32_16x16x32_bf16 v[12:15], v[234:237], v[190:193], v[12:15]
	v_mfma_f32_16x16x32_bf16 v[40:43], v[226:229], v[198:201], v[40:43]
	v_mfma_f32_16x16x32_bf16 v[8:11], v[234:237], v[198:201], v[8:11]
	v_mfma_f32_16x16x32_bf16 v[36:39], v[226:229], v[206:209], v[36:39]
	v_mfma_f32_16x16x32_bf16 v[4:7], v[234:237], v[206:209], v[4:7]
	v_mfma_f32_16x16x32_bf16 v[32:35], v[226:229], v[218:221], v[32:35]
	v_mfma_f32_16x16x32_bf16 v[0:3], v[234:237], v[218:221], v[0:3]
	s_setprio 0
	s_add_i32 s9, s9, 2
	s_add_u32 s16, s16, 0x100
	s_addc_u32 s17, s17, 0
	s_add_u32 s0, s0, 0x100
	s_addc_u32 s1, s1, 0
	s_cmp_gt_u32 s9, 29
	s_barrier
	s_cbranch_scc0 .LBB0_133
	s_ashr_i32 s9, s64, 3
	s_cmp_lt_i32 s9, 4
	s_cbranch_scc1 .LBB0_138
	v_readlane_b32 s68, v254, 17
	v_readlane_b32 s76, v254, 25
	v_readlane_b32 s77, v254, 26
	s_cmp_gt_i32 s9, 4
	s_mov_b64 s[18:19], 0
	s_mov_b64 s[16:17], s[76:77]
	s_mov_b64 s[0:1], 0
	v_readlane_b32 s69, v254, 18
	v_readlane_b32 s70, v254, 19
	v_readlane_b32 s71, v254, 20
	v_readlane_b32 s72, v254, 21
	v_readlane_b32 s73, v254, 22
	v_readlane_b32 s74, v254, 23
	v_readlane_b32 s75, v254, 24
	v_readlane_b32 s78, v254, 27
	v_readlane_b32 s79, v254, 28
	v_readlane_b32 s80, v254, 29
	v_readlane_b32 s81, v254, 30
	v_readlane_b32 s82, v254, 31
	v_readlane_b32 s83, v254, 32
	s_cbranch_scc0 .LBB0_139
	s_cmp_eq_u32 s9, 5
	s_mov_b64 s[0:1], -1
	s_cbranch_scc0 .LBB0_139
	v_readlane_b32 s68, v254, 17
	v_readlane_b32 s78, v254, 27
	v_readlane_b32 s79, v254, 28
	s_mov_b64 s[0:1], 0
	v_readlane_b32 s69, v254, 18
	v_readlane_b32 s70, v254, 19
	v_readlane_b32 s71, v254, 20
	v_readlane_b32 s72, v254, 21
	v_readlane_b32 s73, v254, 22
	v_readlane_b32 s74, v254, 23
	v_readlane_b32 s75, v254, 24
	v_readlane_b32 s76, v254, 25
	v_readlane_b32 s77, v254, 26
	v_readlane_b32 s80, v254, 29
	v_readlane_b32 s81, v254, 30
	v_readlane_b32 s82, v254, 31
	v_readlane_b32 s83, v254, 32
	s_mov_b64 s[16:17], s[78:79]
	s_branch .LBB0_139

; #define PG8_STAGE(bufoff, gbase, voff) do { _Pragma("unroll") for (int _i = 0; _i < 2; ++_i) \
;         __builtin_amdgcn_global_load_lds((const unsigned*)((const char*)(gbase) + (voff)[_i]), (LAS unsigned*)(lds + (bufoff) + ldsw + _i * 8192), 16, 0, 0); } while (0)
; #define PG8_LDA(dst, b, h) do { _Pragma("unroll") for (int m = 0; m < 4; ++m) _Pragma("unroll") for (int k = 0; k < 2; ++k) dst[m][k] = *(const LAS bf16x8*)(lds + PG8_SA(b, h) + aoff + m * 2048 + k * 1024); } while (0)
; #define PG8_LDB(dst, b, h) do { _Pragma("unroll") for (int n = 0; n < 2; ++n) _Pragma("unroll") for (int k = 0; k < 2; ++k) dst[n][k] = *(const LAS bf16x8*)(lds + PG8_SB(b, h) + boff + n * 2048 + k * 1024); } while (0)
; #define PG8_MMA(ai, bj, At, Bt) do { __builtin_amdgcn_s_setprio(1); _Pragma("unroll") for (int m = 0; m < 4; ++m) _Pragma("unroll") for (int n = 0; n < 2; ++n) _Pragma("unroll") for (int k = 0; k < 2; ++k) \
;         acc[ai][bj][m][n] = __builtin_amdgcn_mfma_f32_16x16x32_bf16(Bt[n][k], At[m][k], acc[ai][bj][m][n], 0, 0, 0); __builtin_amdgcn_s_setprio(0); } while (0)
; #define PG8_WAIT_V(n) asm volatile("s_waitcnt vmcnt(" #n ")" ::: "memory")
; #define PG8_WAIT_L(n) asm volatile("s_waitcnt lgkmcnt(" #n ")" ::: "memory")
; #define PG8_BAR __builtin_amdgcn_s_barrier()
; #define PG8_SCHED __builtin_amdgcn_sched_barrier(0)
; template <class Epi, class S_t>
; __device__ __forceinline__ void gemm_phase(LAS unsigned char* lds, int lda, int ldb, const S_t& S, const Epi& E) {
;     ...
;             const char* a1 = cA + (size_t)(t + 1) * kstep;
;             const char* a2 = last ? nA : cA + (size_t)(t + 2) * kstep; const char* b2 = last ? nB : cB + (size_t)(t + 2) * kstep;
;             const char* a3 = a2 + kstep; const char* b3 = b2 + kstep;
;             PG8_LDB(B0, 0, 0); PG8_SCHED; PG8_LDA(At, 0, 0); PG8_STAGE(PG8_SA(1, 1), a1 + hstepA, voffA);
;             PG8_WAIT_L(8); PG8_BAR; PG8_WAIT_L(0); PG8_MMA(0, 0, At, B0); PG8_BAR; PG8_SCHED;
;             PG8_LDB(B1, 0, 1); PG8_STAGE(PG8_SB(0, 0), b2, voffB);
;             PG8_BAR; PG8_WAIT_L(0); PG8_MMA(0, 1, At, B1); PG8_BAR;
;             PG8_LDA(At, 0, 1); PG8_STAGE(PG8_SA(0, 0), a2, voffA);
;             PG8_BAR; PG8_WAIT_L(0); PG8_MMA(1, 0, At, B0); PG8_BAR; PG8_SCHED;
;             PG8_STAGE(PG8_SB(0, 1), b2 + hstepB, voffB);
;             PG8_WAIT_V(6); PG8_BAR; PG8_MMA(1, 1, At, B1); PG8_BAR;
.LBB0_236:
	ds_read_b128 v[142:145], v149
	ds_read_b128 v[152:155], v149 offset:1024
	ds_read_b128 v[156:159], v149 offset:2048
	ds_read_b128 v[160:163], v149 offset:3072
	s_add_u32 s11, s54, 0xfff80080
	s_addc_u32 s13, s55, -1
	s_cmp_eq_u32 s7, 28
	s_cselect_b32 s59, s15, s13
	s_cselect_b32 s58, s14, s11
	s_cselect_b32 s57, s19, s1
	s_cselect_b32 s56, s18, s0
	s_add_i32 m0, s21, 0xc000
	ds_read_b128 v[164:167], v150
	ds_read_b128 v[168:171], v150 offset:1024
	ds_read_b128 v[172:175], v150 offset:2048
	ds_read_b128 v[176:179], v150 offset:3072
	ds_read_b128 v[180:183], v150 offset:4096
	ds_read_b128 v[186:189], v150 offset:5120
	ds_read_b128 v[190:193], v150 offset:6144
	ds_read_b128 v[194:197], v150 offset:7168
	global_load_lds_dwordx4 v136, s[54:55]
	s_add_i32 m0, s21, 0xe000
	s_nop 0
	global_load_lds_dwordx4 v138, s[54:55]
	s_waitcnt lgkmcnt(8)
	s_barrier
	s_waitcnt lgkmcnt(0)
	s_setprio 1
	s_waitcnt lgkmcnt(0)
	v_mfma_f32_16x16x32_bf16 v[124:127], v[142:145], v[164:167], v[124:127]
	v_mfma_f32_16x16x32_bf16 v[120:123], v[156:159], v[164:167], v[120:123]
	v_mfma_f32_16x16x32_bf16 v[108:111], v[142:145], v[172:175], v[108:111]
	v_mfma_f32_16x16x32_bf16 v[104:107], v[156:159], v[172:175], v[104:107]
	v_mfma_f32_16x16x32_bf16 v[92:95], v[142:145], v[180:183], v[92:95]
	v_mfma_f32_16x16x32_bf16 v[88:91], v[156:159], v[180:183], v[88:91]
	v_mfma_f32_16x16x32_bf16 v[76:79], v[142:145], v[190:193], v[76:79]
	v_mfma_f32_16x16x32_bf16 v[72:75], v[156:159], v[190:193], v[72:75]
	v_mfma_f32_16x16x32_bf16 v[124:127], v[152:155], v[168:171], v[124:127]
	v_mfma_f32_16x16x32_bf16 v[120:123], v[160:163], v[168:171], v[120:123]
	v_mfma_f32_16x16x32_bf16 v[108:111], v[152:155], v[176:179], v[108:111]
	v_mfma_f32_16x16x32_bf16 v[104:107], v[160:163], v[176:179], v[104:107]
	v_mfma_f32_16x16x32_bf16 v[92:95], v[152:155], v[186:189], v[92:95]
	v_mfma_f32_16x16x32_bf16 v[88:91], v[160:163], v[186:189], v[88:91]
	v_mfma_f32_16x16x32_bf16 v[76:79], v[152:155], v[194:197], v[76:79]
	v_mfma_f32_16x16x32_bf16 v[72:75], v[160:163], v[194:197], v[72:75]
	s_setprio 0
	s_barrier
	s_add_i32 s11, s67, s20
	s_add_u32 s98, s56, s8
	s_addc_u32 s99, s57, s9
	s_mov_b32 m0, s11
	ds_read_b128 v[198:201], v151
	ds_read_b128 v[202:205], v151 offset:1024
	ds_read_b128 v[206:209], v151 offset:2048
	ds_read_b128 v[220:223], v151 offset:3072
	global_load_lds_dwordx4 v130, s[56:57]
	s_add_i32 m0, s11, 0x2000
	s_nop 0
	global_load_lds_dwordx4 v134, s[56:57]
	s_barrier
	s_waitcnt lgkmcnt(0)
	s_setprio 1
	s_waitcnt lgkmcnt(0)
	v_mfma_f32_16x16x32_bf16 v[116:119], v[198:201], v[164:167], v[116:119]
	v_mfma_f32_16x16x32_bf16 v[112:115], v[206:209], v[164:167], v[112:115]
	v_mfma_f32_16x16x32_bf16 v[100:103], v[198:201], v[172:175], v[100:103]
	v_mfma_f32_16x16x32_bf16 v[96:99], v[206:209], v[172:175], v[96:99]
	v_mfma_f32_16x16x32_bf16 v[84:87], v[198:201], v[180:183], v[84:87]
	v_mfma_f32_16x16x32_bf16 v[80:83], v[206:209], v[180:183], v[80:83]
	v_mfma_f32_16x16x32_bf16 v[68:71], v[198:201], v[190:193], v[68:71]
	v_mfma_f32_16x16x32_bf16 v[64:67], v[206:209], v[190:193], v[64:67]
	v_mfma_f32_16x16x32_bf16 v[116:119], v[202:205], v[168:171], v[116:119]
	v_mfma_f32_16x16x32_bf16 v[112:115], v[220:223], v[168:171], v[112:115]
	v_mfma_f32_16x16x32_bf16 v[100:103], v[202:205], v[176:179], v[100:103]
	v_mfma_f32_16x16x32_bf16 v[96:99], v[220:223], v[176:179], v[96:99]
	v_mfma_f32_16x16x32_bf16 v[84:87], v[202:205], v[186:189], v[84:87]
	v_mfma_f32_16x16x32_bf16 v[80:83], v[220:223], v[186:189], v[80:83]
	v_mfma_f32_16x16x32_bf16 v[68:71], v[202:205], v[194:197], v[68:71]
	v_mfma_f32_16x16x32_bf16 v[64:67], v[220:223], v[194:197], v[64:67]
	s_setprio 0
	s_mov_b32 m0, s21
	s_add_u32 s100, s58, s8
	s_addc_u32 s101, s59, s9
	s_barrier
	ds_read_b128 v[164:167], v150 offset:16384
	ds_read_b128 v[168:171], v150 offset:17408
	ds_read_b128 v[172:175], v150 offset:18432
	ds_read_b128 v[176:179], v150 offset:19456
	ds_read_b128 v[180:183], v150 offset:20480
	ds_read_b128 v[186:189], v150 offset:21504
	ds_read_b128 v[190:193], v150 offset:22528
	ds_read_b128 v[194:197], v150 offset:23552
	global_load_lds_dwordx4 v128, s[58:59]
	s_mov_b32 m0, s35
	s_nop 0
	global_load_lds_dwordx4 v132, s[58:59]
	s_barrier
	s_waitcnt lgkmcnt(0)
	s_setprio 1
	s_waitcnt lgkmcnt(0)
	v_mfma_f32_16x16x32_bf16 v[60:63], v[142:145], v[164:167], v[60:63]
	v_mfma_f32_16x16x32_bf16 v[56:59], v[156:159], v[164:167], v[56:59]
	v_mfma_f32_16x16x32_bf16 v[44:47], v[142:145], v[172:175], v[44:47]
	v_mfma_f32_16x16x32_bf16 v[40:43], v[156:159], v[172:175], v[40:43]
	v_mfma_f32_16x16x32_bf16 v[28:31], v[142:145], v[180:183], v[28:31]
	v_mfma_f32_16x16x32_bf16 v[24:27], v[156:159], v[180:183], v[24:27]
	v_mfma_f32_16x16x32_bf16 v[12:15], v[142:145], v[190:193], v[12:15]
	v_mfma_f32_16x16x32_bf16 v[8:11], v[156:159], v[190:193], v[8:11]
	v_mfma_f32_16x16x32_bf16 v[60:63], v[152:155], v[168:171], v[60:63]
	v_mfma_f32_16x16x32_bf16 v[56:59], v[160:163], v[168:171], v[56:59]
	v_mfma_f32_16x16x32_bf16 v[44:47], v[152:155], v[176:179], v[44:47]
	v_mfma_f32_16x16x32_bf16 v[40:43], v[160:163], v[176:179], v[40:43]
	v_mfma_f32_16x16x32_bf16 v[28:31], v[152:155], v[186:189], v[28:31]
	v_mfma_f32_16x16x32_bf16 v[24:27], v[160:163], v[186:189], v[24:27]
	v_mfma_f32_16x16x32_bf16 v[12:15], v[152:155], v[194:197], v[12:15]
	v_mfma_f32_16x16x32_bf16 v[8:11], v[160:163], v[194:197], v[8:11]
	s_setprio 0
	s_barrier
	s_add_u32 s42, s56, 0x80000
	s_addc_u32 s43, s57, 0
	s_add_i32 s11, s74, s20
	s_mov_b32 m0, s11
	s_nop 0
	global_load_lds_dwordx4 v130, s[42:43]
	s_add_i32 m0, s11, 0x2000
	s_nop 0
	global_load_lds_dwordx4 v134, s[42:43]
	s_waitcnt vmcnt(6)
	s_barrier
; #define PG8_STAGE(bufoff, gbase, voff) do { _Pragma("unroll") for (int _i = 0; _i < 2; ++_i) \
;         __builtin_amdgcn_global_load_lds((const unsigned*)((const char*)(gbase) + (voff)[_i]), (LAS unsigned*)(lds + (bufoff) + ldsw + _i * 8192), 16, 0, 0); } while (0)
; #define PG8_LDA(dst, b, h) do { _Pragma("unroll") for (int m = 0; m < 4; ++m) _Pragma("unroll") for (int k = 0; k < 2; ++k) dst[m][k] = *(const LAS bf16x8*)(lds + PG8_SA(b, h) + aoff + m * 2048 + k * 1024); } while (0)
; #define PG8_LDB(dst, b, h) do { _Pragma("unroll") for (int n = 0; n < 2; ++n) _Pragma("unroll") for (int k = 0; k < 2; ++k) dst[n][k] = *(const LAS bf16x8*)(lds + PG8_SB(b, h) + boff + n * 2048 + k * 1024); } while (0)
; #define PG8_MMA(ai, bj, At, Bt) do { __builtin_amdgcn_s_setprio(1); _Pragma("unroll") for (int m = 0; m < 4; ++m) _Pragma("unroll") for (int n = 0; n < 2; ++n) _Pragma("unroll") for (int k = 0; k < 2; ++k) \
;         acc[ai][bj][m][n] = __builtin_amdgcn_mfma_f32_16x16x32_bf16(Bt[n][k], At[m][k], acc[ai][bj][m][n], 0, 0, 0); __builtin_amdgcn_s_setprio(0); } while (0)
; #define PG8_WAIT_V(n) asm volatile("s_waitcnt vmcnt(" #n ")" ::: "memory")
; #define PG8_WAIT_L(n) asm volatile("s_waitcnt lgkmcnt(" #n ")" ::: "memory")
; #define PG8_BAR __builtin_amdgcn_s_barrier()
; #define PG8_SCHED __builtin_amdgcn_sched_barrier(0)
; template <class Epi, class S_t>
; __device__ __forceinline__ void gemm_phase(LAS unsigned char* lds, int lda, int ldb, const S_t& S, const Epi& E) {
;     ...
;             PG8_WAIT_V(6); PG8_BAR; PG8_MMA(1, 1, At, B1); PG8_BAR;
;             PG8_LDB(B0, 1, 0); PG8_SCHED; PG8_LDA(At, 1, 0); PG8_STAGE(PG8_SA(0, 1), a2 + hstepA, voffA);
;             PG8_WAIT_L(8); PG8_BAR; PG8_WAIT_L(0); PG8_MMA(0, 0, At, B0); PG8_BAR; PG8_SCHED;
;             PG8_LDB(B1, 1, 1); PG8_STAGE(PG8_SB(1, 0), b3, voffB);
;             PG8_BAR; PG8_WAIT_L(0); PG8_MMA(0, 1, At, B1); PG8_BAR;
;             PG8_LDA(At, 1, 1); PG8_STAGE(PG8_SA(1, 0), a3, voffA);
;             PG8_BAR; PG8_WAIT_L(0); PG8_MMA(1, 0, At, B0); PG8_BAR; PG8_SCHED;
	s_setprio 1
	v_mfma_f32_16x16x32_bf16 v[52:55], v[198:201], v[164:167], v[52:55]
	v_mfma_f32_16x16x32_bf16 v[48:51], v[206:209], v[164:167], v[48:51]
	v_mfma_f32_16x16x32_bf16 v[36:39], v[198:201], v[172:175], v[36:39]
	v_mfma_f32_16x16x32_bf16 v[32:35], v[206:209], v[172:175], v[32:35]
	v_mfma_f32_16x16x32_bf16 v[20:23], v[198:201], v[180:183], v[20:23]
	v_mfma_f32_16x16x32_bf16 v[16:19], v[206:209], v[180:183], v[16:19]
	v_mfma_f32_16x16x32_bf16 v[4:7], v[198:201], v[190:193], v[4:7]
	v_mfma_f32_16x16x32_bf16 v[0:3], v[206:209], v[190:193], v[0:3]
	v_mfma_f32_16x16x32_bf16 v[52:55], v[202:205], v[168:171], v[52:55]
	v_mfma_f32_16x16x32_bf16 v[48:51], v[220:223], v[168:171], v[48:51]
	v_mfma_f32_16x16x32_bf16 v[36:39], v[202:205], v[176:179], v[36:39]
	v_mfma_f32_16x16x32_bf16 v[32:35], v[220:223], v[176:179], v[32:35]
	v_mfma_f32_16x16x32_bf16 v[20:23], v[202:205], v[186:189], v[20:23]
	v_mfma_f32_16x16x32_bf16 v[16:19], v[220:223], v[186:189], v[16:19]
	v_mfma_f32_16x16x32_bf16 v[4:7], v[202:205], v[194:197], v[4:7]
	v_mfma_f32_16x16x32_bf16 v[0:3], v[220:223], v[194:197], v[0:3]
	s_setprio 0
	s_add_i32 s11, 0, 0x18000
	v_add_u32_e32 v160, s11, v147
	s_barrier
	ds_read_b128 v[142:145], v160
	ds_read_b128 v[152:155], v160 offset:1024
	ds_read_b128 v[156:159], v160 offset:2048
	ds_read_b128 v[160:163], v160 offset:3072
	s_add_u32 s42, s58, 0x80000
	s_addc_u32 s43, s59, 0
	s_mov_b32 m0, s52
	ds_read_b128 v[164:167], v150 offset:32768
	ds_read_b128 v[168:171], v150 offset:33792
	ds_read_b128 v[172:175], v150 offset:34816
	ds_read_b128 v[176:179], v150 offset:35840
	ds_read_b128 v[180:183], v150 offset:36864
	ds_read_b128 v[186:189], v150 offset:37888
	ds_read_b128 v[190:193], v150 offset:38912
	ds_read_b128 v[194:197], v150 offset:39936
	global_load_lds_dwordx4 v128, s[42:43]
	s_mov_b32 m0, s53
	s_nop 0
	global_load_lds_dwordx4 v132, s[42:43]
	s_waitcnt lgkmcnt(8)
	s_barrier
	s_waitcnt lgkmcnt(0)
	s_setprio 1
	s_waitcnt lgkmcnt(0)
	v_mfma_f32_16x16x32_bf16 v[124:127], v[142:145], v[164:167], v[124:127]
	v_mfma_f32_16x16x32_bf16 v[120:123], v[156:159], v[164:167], v[120:123]
	v_mfma_f32_16x16x32_bf16 v[108:111], v[142:145], v[172:175], v[108:111]
	v_mfma_f32_16x16x32_bf16 v[104:107], v[156:159], v[172:175], v[104:107]
	v_mfma_f32_16x16x32_bf16 v[92:95], v[142:145], v[180:183], v[92:95]
	v_mfma_f32_16x16x32_bf16 v[88:91], v[156:159], v[180:183], v[88:91]
	v_mfma_f32_16x16x32_bf16 v[76:79], v[142:145], v[190:193], v[76:79]
	v_mfma_f32_16x16x32_bf16 v[72:75], v[156:159], v[190:193], v[72:75]
	v_mfma_f32_16x16x32_bf16 v[124:127], v[152:155], v[168:171], v[124:127]
	v_mfma_f32_16x16x32_bf16 v[120:123], v[160:163], v[168:171], v[120:123]
	v_mfma_f32_16x16x32_bf16 v[108:111], v[152:155], v[176:179], v[108:111]
	v_mfma_f32_16x16x32_bf16 v[104:107], v[160:163], v[176:179], v[104:107]
	v_mfma_f32_16x16x32_bf16 v[92:95], v[152:155], v[186:189], v[92:95]
	v_mfma_f32_16x16x32_bf16 v[88:91], v[160:163], v[186:189], v[88:91]
	v_mfma_f32_16x16x32_bf16 v[76:79], v[152:155], v[194:197], v[76:79]
	v_mfma_f32_16x16x32_bf16 v[72:75], v[160:163], v[194:197], v[72:75]
	s_setprio 0
	s_barrier
	s_add_i32 s13, 0, 0x1c000
	s_add_i32 s11, s11, s20
	v_add_u32_e32 v215, s13, v147
	s_mov_b32 m0, s11
	ds_read_b128 v[198:201], v215
	ds_read_b128 v[202:205], v215 offset:1024
	ds_read_b128 v[206:209], v215 offset:2048
	ds_read_b128 v[220:223], v215 offset:3072
	global_load_lds_dwordx4 v130, s[98:99]
	s_add_i32 m0, s11, 0x2000
	s_nop 0
	global_load_lds_dwordx4 v134, s[98:99]
	s_barrier
	s_waitcnt lgkmcnt(0)
	s_setprio 1
	s_waitcnt lgkmcnt(0)
	v_mfma_f32_16x16x32_bf16 v[116:119], v[198:201], v[164:167], v[116:119]
	v_mfma_f32_16x16x32_bf16 v[112:115], v[206:209], v[164:167], v[112:115]
	v_mfma_f32_16x16x32_bf16 v[100:103], v[198:201], v[172:175], v[100:103]
	v_mfma_f32_16x16x32_bf16 v[96:99], v[206:209], v[172:175], v[96:99]
	v_mfma_f32_16x16x32_bf16 v[84:87], v[198:201], v[180:183], v[84:87]
	v_mfma_f32_16x16x32_bf16 v[80:83], v[206:209], v[180:183], v[80:83]
	v_mfma_f32_16x16x32_bf16 v[68:71], v[198:201], v[190:193], v[68:71]
	v_mfma_f32_16x16x32_bf16 v[64:67], v[206:209], v[190:193], v[64:67]
	v_mfma_f32_16x16x32_bf16 v[116:119], v[202:205], v[168:171], v[116:119]
	v_mfma_f32_16x16x32_bf16 v[112:115], v[220:223], v[168:171], v[112:115]
	v_mfma_f32_16x16x32_bf16 v[100:103], v[202:205], v[176:179], v[100:103]
	v_mfma_f32_16x16x32_bf16 v[96:99], v[220:223], v[176:179], v[96:99]
	v_mfma_f32_16x16x32_bf16 v[84:87], v[202:205], v[186:189], v[84:87]
	v_mfma_f32_16x16x32_bf16 v[80:83], v[220:223], v[186:189], v[80:83]
	v_mfma_f32_16x16x32_bf16 v[68:71], v[202:205], v[194:197], v[68:71]
	v_mfma_f32_16x16x32_bf16 v[64:67], v[220:223], v[194:197], v[64:67]
	s_setprio 0
	s_mov_b32 m0, s61
	s_barrier
; __device__ __forceinline__ float sigmoidf_(float x) { return __builtin_amdgcn_rcpf(1.0f + __expf(-x)); }
; #define PG8_STAGE(bufoff, gbase, voff) do { _Pragma("unroll") for (int _i = 0; _i < 2; ++_i) \
;         __builtin_amdgcn_global_load_lds((const unsigned*)((const char*)(gbase) + (voff)[_i]), (LAS unsigned*)(lds + (bufoff) + ldsw + _i * 8192), 16, 0, 0); } while (0)
; #define PG8_MMA(ai, bj, At, Bt) do { __builtin_amdgcn_s_setprio(1); _Pragma("unroll") for (int m = 0; m < 4; ++m) _Pragma("unroll") for (int n = 0; n < 2; ++n) _Pragma("unroll") for (int k = 0; k < 2; ++k) \
;         acc[ai][bj][m][n] = __builtin_amdgcn_mfma_f32_16x16x32_bf16(Bt[n][k], At[m][k], acc[ai][bj][m][n], 0, 0, 0); __builtin_amdgcn_s_setprio(0); } while (0)
; #define PG8_WAIT_V(n) asm volatile("s_waitcnt vmcnt(" #n ")" ::: "memory")
; #define PG8_WAIT_L(n) asm volatile("s_waitcnt lgkmcnt(" #n ")" ::: "memory")
; #define PG8_BAR __builtin_amdgcn_s_barrier()
; #define PG8_SCHED __builtin_amdgcn_sched_barrier(0)
; template <class Epi, class S_t>
; __device__ __forceinline__ void gemm_phase(LAS unsigned char* lds, int lda, int ldb, const S_t& S, const Epi& E) {
;     ...
;             PG8_BAR; PG8_WAIT_L(0); PG8_MMA(1, 0, At, B0); PG8_BAR; PG8_SCHED;
;             PG8_STAGE(PG8_SB(1, 1), b3 + hstepB, voffB);
;             PG8_WAIT_V(6); PG8_BAR; PG8_MMA(1, 1, At, B1); PG8_BAR;
;     __device__ __forceinline__ void operator()(const f32x4 (&acc)[2][2][4][2], const Unit& u, int wr, int wc, int fr, int fq) const {
;     ...
;         const bool sg = u.pn >= sig_pn;
; #pragma unroll
;         for (int ai = 0; ai < 2; ++ai)
; #pragma unroll
;             for (int m = 0; m < 4; ++m) { bf16_t* rowp = O + (size_t)(row0 + ai * HALF + m * 16) * ldc + col0;
; #pragma unroll
;                 for (int bj = 0; bj < 2; ++bj) { f32x4 v0 = acc[ai][bj][m][0], v1 = acc[ai][bj][m][1];
;                     if (sg) {
; #pragma unroll
;                         for (int j = 0; j < 4; ++j) { v0[j] = sigmoidf_(v0[j]); v1[j] = sigmoidf_(v1[j]); } }
	ds_read_b128 v[164:167], v150 offset:49152
	ds_read_b128 v[168:171], v150 offset:50176
	ds_read_b128 v[172:175], v150 offset:51200
	ds_read_b128 v[176:179], v150 offset:52224
	ds_read_b128 v[180:183], v150 offset:53248
	ds_read_b128 v[186:189], v150 offset:54272
	ds_read_b128 v[190:193], v150 offset:55296
	ds_read_b128 v[194:197], v150 offset:56320
	global_load_lds_dwordx4 v128, s[100:101]
	s_mov_b32 m0, s62
	s_nop 0
	global_load_lds_dwordx4 v132, s[100:101]
	s_barrier
	s_waitcnt lgkmcnt(0)
	s_setprio 1
	s_waitcnt lgkmcnt(0)
	v_mfma_f32_16x16x32_bf16 v[60:63], v[142:145], v[164:167], v[60:63]
	v_mfma_f32_16x16x32_bf16 v[56:59], v[156:159], v[164:167], v[56:59]
	v_mfma_f32_16x16x32_bf16 v[44:47], v[142:145], v[172:175], v[44:47]
	v_mfma_f32_16x16x32_bf16 v[40:43], v[156:159], v[172:175], v[40:43]
	v_mfma_f32_16x16x32_bf16 v[28:31], v[142:145], v[180:183], v[28:31]
	v_mfma_f32_16x16x32_bf16 v[24:27], v[156:159], v[180:183], v[24:27]
	v_mfma_f32_16x16x32_bf16 v[12:15], v[142:145], v[190:193], v[12:15]
	v_mfma_f32_16x16x32_bf16 v[8:11], v[156:159], v[190:193], v[8:11]
	v_mfma_f32_16x16x32_bf16 v[60:63], v[152:155], v[168:171], v[60:63]
	v_mfma_f32_16x16x32_bf16 v[56:59], v[160:163], v[168:171], v[56:59]
	v_mfma_f32_16x16x32_bf16 v[44:47], v[152:155], v[176:179], v[44:47]
	v_mfma_f32_16x16x32_bf16 v[40:43], v[160:163], v[176:179], v[40:43]
	v_mfma_f32_16x16x32_bf16 v[28:31], v[152:155], v[186:189], v[28:31]
	v_mfma_f32_16x16x32_bf16 v[24:27], v[160:163], v[186:189], v[24:27]
	v_mfma_f32_16x16x32_bf16 v[12:15], v[152:155], v[194:197], v[12:15]
	v_mfma_f32_16x16x32_bf16 v[8:11], v[160:163], v[194:197], v[8:11]
	s_setprio 0
	s_barrier
	s_add_u32 s42, s56, 0x80080
	s_addc_u32 s43, s57, 0
	s_add_i32 s11, s13, s20
	s_mov_b32 m0, s11
	s_nop 0
	global_load_lds_dwordx4 v130, s[42:43]
	s_add_i32 m0, s11, 0x2000
	s_nop 0
	global_load_lds_dwordx4 v134, s[42:43]
	s_waitcnt vmcnt(6)
	s_barrier
	s_setprio 1
	v_mfma_f32_16x16x32_bf16 v[52:55], v[198:201], v[164:167], v[52:55]
	v_mfma_f32_16x16x32_bf16 v[48:51], v[206:209], v[164:167], v[48:51]
	v_mfma_f32_16x16x32_bf16 v[36:39], v[198:201], v[172:175], v[36:39]
	v_mfma_f32_16x16x32_bf16 v[32:35], v[206:209], v[172:175], v[32:35]
	v_mfma_f32_16x16x32_bf16 v[20:23], v[198:201], v[180:183], v[20:23]
	v_mfma_f32_16x16x32_bf16 v[16:19], v[206:209], v[180:183], v[16:19]
	v_mfma_f32_16x16x32_bf16 v[4:7], v[198:201], v[190:193], v[4:7]
	v_mfma_f32_16x16x32_bf16 v[0:3], v[206:209], v[190:193], v[0:3]
	v_mfma_f32_16x16x32_bf16 v[52:55], v[202:205], v[168:171], v[52:55]
	v_mfma_f32_16x16x32_bf16 v[48:51], v[220:223], v[168:171], v[48:51]
	v_mfma_f32_16x16x32_bf16 v[36:39], v[202:205], v[176:179], v[36:39]
	v_mfma_f32_16x16x32_bf16 v[32:35], v[220:223], v[176:179], v[32:35]
	v_mfma_f32_16x16x32_bf16 v[20:23], v[202:205], v[186:189], v[20:23]
	v_mfma_f32_16x16x32_bf16 v[16:19], v[220:223], v[186:189], v[16:19]
	v_mfma_f32_16x16x32_bf16 v[4:7], v[202:205], v[194:197], v[4:7]
	v_mfma_f32_16x16x32_bf16 v[0:3], v[220:223], v[194:197], v[0:3]
	s_setprio 0
	s_add_i32 s7, s7, 2
	s_add_u32 s54, s54, 0x100
	s_addc_u32 s55, s55, 0
	s_add_u32 s0, s0, 0x100
	s_addc_u32 s1, s1, 0
	s_cmp_gt_u32 s7, 29
	s_barrier
	s_cbranch_scc0 .LBB0_236
	s_cmp_gt_i32 s78, 11
	s_cselect_b64 s[0:1], -1, 0
	s_cmp_lt_i32 s78, 12
	s_cbranch_scc1 .LBB0_239
	v_mul_f32_e32 v124, 0xbfb8aa3b, v124
	v_mul_f32_e32 v120, 0xbfb8aa3b, v120
	v_mul_f32_e32 v125, 0xbfb8aa3b, v125
	v_mul_f32_e32 v121, 0xbfb8aa3b, v121
	v_mul_f32_e32 v126, 0xbfb8aa3b, v126
	v_mul_f32_e32 v122, 0xbfb8aa3b, v122
	v_mul_f32_e32 v127, 0xbfb8aa3b, v127
	v_mul_f32_e32 v123, 0xbfb8aa3b, v123
	v_exp_f32_e32 v124, v124
	v_exp_f32_e32 v120, v120
	v_exp_f32_e32 v125, v125
	v_exp_f32_e32 v121, v121
	v_exp_f32_e32 v126, v126
	v_exp_f32_e32 v122, v122
	v_exp_f32_e32 v127, v127
	v_exp_f32_e32 v123, v123
	v_add_f32_e32 v124, 1.0, v124
	v_add_f32_e32 v120, 1.0, v120
	v_add_f32_e32 v125, 1.0, v125
	v_add_f32_e32 v121, 1.0, v121
	v_add_f32_e32 v126, 1.0, v126
	v_add_f32_e32 v122, 1.0, v122
	v_add_f32_e32 v127, 1.0, v127
	v_add_f32_e32 v123, 1.0, v123
	v_rcp_f32_e32 v124, v124
	v_rcp_f32_e32 v120, v120
	v_rcp_f32_e32 v125, v125
	v_rcp_f32_e32 v121, v121
	v_rcp_f32_e32 v126, v126
	v_rcp_f32_e32 v122, v122
	v_rcp_f32_e32 v127, v127
	v_rcp_f32_e32 v123, v123

; #define PG8_STAGE(bufoff, gbase, voff) do { _Pragma("unroll") for (int _i = 0; _i < 2; ++_i) \
;         __builtin_amdgcn_global_load_lds((const unsigned*)((const char*)(gbase) + (voff)[_i]), (LAS unsigned*)(lds + (bufoff) + ldsw + _i * 8192), 16, 0, 0); } while (0)
; #define PG8_LDA(dst, b, h) do { _Pragma("unroll") for (int m = 0; m < 4; ++m) _Pragma("unroll") for (int k = 0; k < 2; ++k) dst[m][k] = *(const LAS bf16x8*)(lds + PG8_SA(b, h) + aoff + m * 2048 + k * 1024); } while (0)
; #define PG8_LDB(dst, b, h) do { _Pragma("unroll") for (int n = 0; n < 2; ++n) _Pragma("unroll") for (int k = 0; k < 2; ++k) dst[n][k] = *(const LAS bf16x8*)(lds + PG8_SB(b, h) + boff + n * 2048 + k * 1024); } while (0)
; #define PG8_MMA(ai, bj, At, Bt) do { __builtin_amdgcn_s_setprio(1); _Pragma("unroll") for (int m = 0; m < 4; ++m) _Pragma("unroll") for (int n = 0; n < 2; ++n) _Pragma("unroll") for (int k = 0; k < 2; ++k) \
;         acc[ai][bj][m][n] = __builtin_amdgcn_mfma_f32_16x16x32_bf16(Bt[n][k], At[m][k], acc[ai][bj][m][n], 0, 0, 0); __builtin_amdgcn_s_setprio(0); } while (0)
; template <class Epi, class S_t>
; __device__ __forceinline__ void gemm_phase(LAS unsigned char* lds, int lda, int ldb, const S_t& S, const Epi& E) {
;     ...
;         const bool has_next = S.next(ui + 1, nxt);
;         const char* nA = has_next ? nxt.A : cA; const char* nB = has_next ? nxt.B : cB;
;         const int nt = cur.nt;
;         for (int t = 0; t < nt; t += 2) {
;             const bool last = (t == nt - 2);
;             const char* a1 = cA + (size_t)(t + 1) * kstep;
;             const char* a2 = last ? nA : cA + (size_t)(t + 2) * kstep; const char* b2 = last ? nB : cB + (size_t)(t + 2) * kstep;
;             const char* a3 = a2 + kstep; const char* b3 = b2 + kstep;
;             PG8_LDB(B0, 0, 0); PG8_SCHED; PG8_LDA(At, 0, 0); PG8_STAGE(PG8_SA(1, 1), a1 + hstepA, voffA);
;             PG8_WAIT_L(8); PG8_BAR; PG8_WAIT_L(0); PG8_MMA(0, 0, At, B0); PG8_BAR; PG8_SCHED;
;             PG8_LDB(B1, 0, 1); PG8_STAGE(PG8_SB(0, 0), b2, voffB);
;             PG8_BAR; PG8_WAIT_L(0); PG8_MMA(0, 1, At, B1); PG8_BAR;
;             PG8_LDA(At, 0, 1); PG8_STAGE(PG8_SA(0, 0), a2, voffA);
;             PG8_BAR; PG8_WAIT_L(0); PG8_MMA(1, 0, At, B0); PG8_BAR; PG8_SCHED;
;             PG8_STAGE(PG8_SB(0, 1), b2 + hstepB, voffB);
;             PG8_WAIT_V(6); PG8_BAR; PG8_MMA(1, 1, At, B1); PG8_BAR;
.LBB0_535:
	s_add_u32 s13, s58, s0
	s_addc_u32 s15, s59, 0
	s_add_u32 s1, s13, 0x100
	s_addc_u32 s33, s15, 0
	s_and_b64 s[42:43], s[66:67], exec
	s_cselect_b32 s75, s19, s33
	s_cselect_b32 s74, s18, s1
	s_add_u32 s0, s60, s0
	s_addc_u32 s1, s61, 0
	s_add_u32 s33, s0, 0x100
	s_addc_u32 s42, s1, 0
	s_and_b64 s[0:1], s[66:67], exec
	s_cselect_b32 s79, s45, s42
	s_cselect_b32 s78, s44, s33
	s_add_u32 s82, s13, 0x40080
	s_addc_u32 s83, s15, 0
	s_add_i32 s96, s90, s17
	s_add_i32 m0, s21, 0xc000
	s_add_i32 s33, s21, 0xe000
	s_add_i32 s95, s96, 0x2000
	s_add_u32 s72, s78, 0x10000
	s_addc_u32 s73, s79, 0
	s_add_i32 s94, s91, s17
	s_add_i32 s93, s94, 0x2000
	s_add_i32 s43, 0, 0x18000
	ds_read_b128 v[128:131], v163
	ds_read_b128 v[132:135], v163 offset:1024
	ds_read_b128 v[136:139], v163 offset:2048
	ds_read_b128 v[140:143], v163 offset:3072
	s_add_u32 s70, s74, 0x40000
	s_addc_u32 s71, s75, 0
	s_add_i32 s42, s43, s17
	s_add_i32 s15, 0, 0x1c000
	s_add_i32 s13, s42, 0x2000
	s_add_u32 s66, s78, 0x10080
	s_addc_u32 s67, s79, 0
	s_add_i32 s1, s15, s17
	s_add_i32 s0, s1, 0x2000
	ds_read_b128 v[154:157], v164
	ds_read_b128 v[166:169], v164 offset:1024
	ds_read_b128 v[170:173], v164 offset:2048
	ds_read_b128 v[174:177], v164 offset:3072
	ds_read_b128 v[178:181], v164 offset:4096
	ds_read_b128 v[186:189], v164 offset:5120
	ds_read_b128 v[190:193], v164 offset:6144
	ds_read_b128 v[194:197], v164 offset:7168
	global_load_lds_dwordx4 v150, s[82:83]
	s_mov_b32 m0, s33
	s_nop 0
	global_load_lds_dwordx4 v146, s[82:83]
	s_waitcnt lgkmcnt(8)
	s_barrier
	s_waitcnt lgkmcnt(0)
	s_setprio 1
	s_waitcnt lgkmcnt(0)
	v_mfma_f32_16x16x32_bf16 v[124:127], v[128:131], v[154:157], v[124:127]
	v_mfma_f32_16x16x32_bf16 v[120:123], v[136:139], v[154:157], v[120:123]
	v_mfma_f32_16x16x32_bf16 v[116:119], v[128:131], v[170:173], v[116:119]
	v_mfma_f32_16x16x32_bf16 v[112:115], v[136:139], v[170:173], v[112:115]
	v_mfma_f32_16x16x32_bf16 v[108:111], v[128:131], v[178:181], v[108:111]
	v_mfma_f32_16x16x32_bf16 v[100:103], v[136:139], v[178:181], v[100:103]
	v_mfma_f32_16x16x32_bf16 v[76:79], v[128:131], v[190:193], v[76:79]
	v_mfma_f32_16x16x32_bf16 v[72:75], v[136:139], v[190:193], v[72:75]
	v_mfma_f32_16x16x32_bf16 v[124:127], v[132:135], v[166:169], v[124:127]
	v_mfma_f32_16x16x32_bf16 v[120:123], v[140:143], v[166:169], v[120:123]
	v_mfma_f32_16x16x32_bf16 v[116:119], v[132:135], v[174:177], v[116:119]
	v_mfma_f32_16x16x32_bf16 v[112:115], v[140:143], v[174:177], v[112:115]
	v_mfma_f32_16x16x32_bf16 v[108:111], v[132:135], v[186:189], v[108:111]
	v_mfma_f32_16x16x32_bf16 v[100:103], v[140:143], v[186:189], v[100:103]
	v_mfma_f32_16x16x32_bf16 v[76:79], v[132:135], v[194:197], v[76:79]
	v_mfma_f32_16x16x32_bf16 v[72:75], v[140:143], v[194:197], v[72:75]
	s_setprio 0
	s_barrier
	s_mov_b32 m0, s96
	s_add_u32 s100, s78, s10
	s_addc_u32 s101, s79, s11
	ds_read_b128 v[198:201], v165
	ds_read_b128 v[202:205], v165 offset:1024
	ds_read_b128 v[206:209], v165 offset:2048
	ds_read_b128 v[222:225], v165 offset:3072
	global_load_lds_dwordx4 v148, s[78:79]
	s_mov_b32 m0, s95
	s_nop 0
	global_load_lds_dwordx4 v144, s[78:79]
	s_barrier
	s_waitcnt lgkmcnt(0)
	s_setprio 1
	s_waitcnt lgkmcnt(0)
	v_mfma_f32_16x16x32_bf16 v[104:107], v[198:201], v[154:157], v[104:107]
	v_mfma_f32_16x16x32_bf16 v[96:99], v[206:209], v[154:157], v[96:99]
	v_mfma_f32_16x16x32_bf16 v[92:95], v[198:201], v[170:173], v[92:95]
	v_mfma_f32_16x16x32_bf16 v[88:91], v[206:209], v[170:173], v[88:91]
	v_mfma_f32_16x16x32_bf16 v[84:87], v[198:201], v[178:181], v[84:87]
	v_mfma_f32_16x16x32_bf16 v[80:83], v[206:209], v[178:181], v[80:83]
	v_mfma_f32_16x16x32_bf16 v[68:71], v[198:201], v[190:193], v[68:71]
	v_mfma_f32_16x16x32_bf16 v[64:67], v[206:209], v[190:193], v[64:67]
	v_mfma_f32_16x16x32_bf16 v[104:107], v[202:205], v[166:169], v[104:107]
	v_mfma_f32_16x16x32_bf16 v[96:99], v[222:225], v[166:169], v[96:99]
	v_mfma_f32_16x16x32_bf16 v[92:95], v[202:205], v[174:177], v[92:95]
	v_mfma_f32_16x16x32_bf16 v[88:91], v[222:225], v[174:177], v[88:91]
	v_mfma_f32_16x16x32_bf16 v[84:87], v[202:205], v[186:189], v[84:87]
	v_mfma_f32_16x16x32_bf16 v[80:83], v[222:225], v[186:189], v[80:83]
	v_mfma_f32_16x16x32_bf16 v[68:71], v[202:205], v[194:197], v[68:71]
	v_mfma_f32_16x16x32_bf16 v[64:67], v[222:225], v[194:197], v[64:67]
	s_setprio 0
	s_mov_b32 m0, s21
	s_add_u32 s98, s74, s10
	s_addc_u32 s99, s75, s11
	s_barrier
	ds_read_b128 v[154:157], v164 offset:16384
	ds_read_b128 v[166:169], v164 offset:17408
	ds_read_b128 v[170:173], v164 offset:18432
	ds_read_b128 v[174:177], v164 offset:19456
	ds_read_b128 v[178:181], v164 offset:20480
	ds_read_b128 v[186:189], v164 offset:21504
	ds_read_b128 v[190:193], v164 offset:22528
	ds_read_b128 v[194:197], v164 offset:23552
	global_load_lds_dwordx4 v150, s[74:75]
	s_mov_b32 m0, s35
	s_nop 0
	global_load_lds_dwordx4 v146, s[74:75]
	s_barrier
	s_waitcnt lgkmcnt(0)
	s_setprio 1
	s_waitcnt lgkmcnt(0)
	v_mfma_f32_16x16x32_bf16 v[60:63], v[128:131], v[154:157], v[60:63]
	v_mfma_f32_16x16x32_bf16 v[56:59], v[136:139], v[154:157], v[56:59]
	v_mfma_f32_16x16x32_bf16 v[48:51], v[128:131], v[170:173], v[48:51]
	v_mfma_f32_16x16x32_bf16 v[40:43], v[136:139], v[170:173], v[40:43]
	v_mfma_f32_16x16x32_bf16 v[32:35], v[128:131], v[178:181], v[32:35]
	v_mfma_f32_16x16x32_bf16 v[24:27], v[136:139], v[178:181], v[24:27]
	v_mfma_f32_16x16x32_bf16 v[16:19], v[128:131], v[190:193], v[16:19]
	v_mfma_f32_16x16x32_bf16 v[8:11], v[136:139], v[190:193], v[8:11]
	v_mfma_f32_16x16x32_bf16 v[60:63], v[132:135], v[166:169], v[60:63]
	v_mfma_f32_16x16x32_bf16 v[56:59], v[140:143], v[166:169], v[56:59]
	v_mfma_f32_16x16x32_bf16 v[48:51], v[132:135], v[174:177], v[48:51]
	v_mfma_f32_16x16x32_bf16 v[40:43], v[140:143], v[174:177], v[40:43]
	v_mfma_f32_16x16x32_bf16 v[32:35], v[132:135], v[186:189], v[32:35]
	v_mfma_f32_16x16x32_bf16 v[24:27], v[140:143], v[186:189], v[24:27]
	v_mfma_f32_16x16x32_bf16 v[16:19], v[132:135], v[194:197], v[16:19]
	v_mfma_f32_16x16x32_bf16 v[8:11], v[140:143], v[194:197], v[8:11]
	s_setprio 0
	s_barrier
; #define PG8_STAGE(bufoff, gbase, voff) do { _Pragma("unroll") for (int _i = 0; _i < 2; ++_i) \
;         __builtin_amdgcn_global_load_lds((const unsigned*)((const char*)(gbase) + (voff)[_i]), (LAS unsigned*)(lds + (bufoff) + ldsw + _i * 8192), 16, 0, 0); } while (0)
; #define PG8_LDA(dst, b, h) do { _Pragma("unroll") for (int m = 0; m < 4; ++m) _Pragma("unroll") for (int k = 0; k < 2; ++k) dst[m][k] = *(const LAS bf16x8*)(lds + PG8_SA(b, h) + aoff + m * 2048 + k * 1024); } while (0)
; #define PG8_LDB(dst, b, h) do { _Pragma("unroll") for (int n = 0; n < 2; ++n) _Pragma("unroll") for (int k = 0; k < 2; ++k) dst[n][k] = *(const LAS bf16x8*)(lds + PG8_SB(b, h) + boff + n * 2048 + k * 1024); } while (0)
; #define PG8_MMA(ai, bj, At, Bt) do { __builtin_amdgcn_s_setprio(1); _Pragma("unroll") for (int m = 0; m < 4; ++m) _Pragma("unroll") for (int n = 0; n < 2; ++n) _Pragma("unroll") for (int k = 0; k < 2; ++k) \
;         acc[ai][bj][m][n] = __builtin_amdgcn_mfma_f32_16x16x32_bf16(Bt[n][k], At[m][k], acc[ai][bj][m][n], 0, 0, 0); __builtin_amdgcn_s_setprio(0); } while (0)
; #define PG8_WAIT_V(n) asm volatile("s_waitcnt vmcnt(" #n ")" ::: "memory")
; #define PG8_WAIT_L(n) asm volatile("s_waitcnt lgkmcnt(" #n ")" ::: "memory")
; #define PG8_BAR __builtin_amdgcn_s_barrier()
; #define PG8_SCHED __builtin_amdgcn_sched_barrier(0)
; template <class Epi, class S_t>
; __device__ __forceinline__ void gemm_phase(LAS unsigned char* lds, int lda, int ldb, const S_t& S, const Epi& E) {
;     ...
;             PG8_WAIT_V(6); PG8_BAR; PG8_MMA(1, 1, At, B1); PG8_BAR;
;             PG8_LDB(B0, 1, 0); PG8_SCHED; PG8_LDA(At, 1, 0); PG8_STAGE(PG8_SA(0, 1), a2 + hstepA, voffA);
;             PG8_WAIT_L(8); PG8_BAR; PG8_WAIT_L(0); PG8_MMA(0, 0, At, B0); PG8_BAR; PG8_SCHED;
;             PG8_LDB(B1, 1, 1); PG8_STAGE(PG8_SB(1, 0), b3, voffB);
;             PG8_BAR; PG8_WAIT_L(0); PG8_MMA(0, 1, At, B1); PG8_BAR;
;             PG8_LDA(At, 1, 1); PG8_STAGE(PG8_SA(1, 0), a3, voffA);
;             PG8_BAR; PG8_WAIT_L(0); PG8_MMA(1, 0, At, B0); PG8_BAR; PG8_SCHED;
	s_mov_b32 m0, s94
	global_load_lds_dwordx4 v148, s[72:73]
	s_mov_b32 m0, s93
	s_nop 0
	global_load_lds_dwordx4 v144, s[72:73]
	s_waitcnt vmcnt(6)
	s_barrier
	s_setprio 1
	v_mfma_f32_16x16x32_bf16 v[52:55], v[198:201], v[154:157], v[52:55]
	v_mfma_f32_16x16x32_bf16 v[44:47], v[206:209], v[154:157], v[44:47]
	v_mfma_f32_16x16x32_bf16 v[36:39], v[198:201], v[170:173], v[36:39]
	v_mfma_f32_16x16x32_bf16 v[28:31], v[206:209], v[170:173], v[28:31]
	v_mfma_f32_16x16x32_bf16 v[20:23], v[198:201], v[178:181], v[20:23]
	v_mfma_f32_16x16x32_bf16 v[12:15], v[206:209], v[178:181], v[12:15]
	v_mfma_f32_16x16x32_bf16 v[4:7], v[198:201], v[190:193], v[4:7]
	v_mfma_f32_16x16x32_bf16 v[0:3], v[206:209], v[190:193], v[0:3]
	v_mfma_f32_16x16x32_bf16 v[52:55], v[202:205], v[166:169], v[52:55]
	v_mfma_f32_16x16x32_bf16 v[44:47], v[222:225], v[166:169], v[44:47]
	v_mfma_f32_16x16x32_bf16 v[36:39], v[202:205], v[174:177], v[36:39]
	v_mfma_f32_16x16x32_bf16 v[28:31], v[222:225], v[174:177], v[28:31]
	v_mfma_f32_16x16x32_bf16 v[20:23], v[202:205], v[186:189], v[20:23]
	v_mfma_f32_16x16x32_bf16 v[12:15], v[222:225], v[186:189], v[12:15]
	v_mfma_f32_16x16x32_bf16 v[4:7], v[202:205], v[194:197], v[4:7]
	v_mfma_f32_16x16x32_bf16 v[0:3], v[222:225], v[194:197], v[0:3]
	s_setprio 0
	v_add_u32_e32 v140, s43, v161
	s_barrier
	ds_read_b128 v[128:131], v140
	ds_read_b128 v[132:135], v140 offset:1024
	ds_read_b128 v[136:139], v140 offset:2048
	ds_read_b128 v[140:143], v140 offset:3072
	s_mov_b32 m0, s52
	ds_read_b128 v[154:157], v164 offset:32768
	ds_read_b128 v[166:169], v164 offset:33792
	ds_read_b128 v[170:173], v164 offset:34816
	ds_read_b128 v[174:177], v164 offset:35840
	ds_read_b128 v[178:181], v164 offset:36864
	ds_read_b128 v[186:189], v164 offset:37888
	ds_read_b128 v[190:193], v164 offset:38912
	ds_read_b128 v[194:197], v164 offset:39936
	global_load_lds_dwordx4 v150, s[70:71]
	s_mov_b32 m0, s53
	s_nop 0
	global_load_lds_dwordx4 v146, s[70:71]
	s_waitcnt lgkmcnt(8)
	s_barrier
	s_waitcnt lgkmcnt(0)
	s_setprio 1
	s_waitcnt lgkmcnt(0)
	v_mfma_f32_16x16x32_bf16 v[124:127], v[128:131], v[154:157], v[124:127]
	v_mfma_f32_16x16x32_bf16 v[120:123], v[136:139], v[154:157], v[120:123]
	v_mfma_f32_16x16x32_bf16 v[116:119], v[128:131], v[170:173], v[116:119]
	v_mfma_f32_16x16x32_bf16 v[112:115], v[136:139], v[170:173], v[112:115]
	v_mfma_f32_16x16x32_bf16 v[108:111], v[128:131], v[178:181], v[108:111]
	v_mfma_f32_16x16x32_bf16 v[100:103], v[136:139], v[178:181], v[100:103]
	v_mfma_f32_16x16x32_bf16 v[76:79], v[128:131], v[190:193], v[76:79]
	v_mfma_f32_16x16x32_bf16 v[72:75], v[136:139], v[190:193], v[72:75]
	v_mfma_f32_16x16x32_bf16 v[124:127], v[132:135], v[166:169], v[124:127]
	v_mfma_f32_16x16x32_bf16 v[120:123], v[140:143], v[166:169], v[120:123]
	v_mfma_f32_16x16x32_bf16 v[116:119], v[132:135], v[174:177], v[116:119]
	v_mfma_f32_16x16x32_bf16 v[112:115], v[140:143], v[174:177], v[112:115]
	v_mfma_f32_16x16x32_bf16 v[108:111], v[132:135], v[186:189], v[108:111]
	v_mfma_f32_16x16x32_bf16 v[100:103], v[140:143], v[186:189], v[100:103]
	v_mfma_f32_16x16x32_bf16 v[76:79], v[132:135], v[194:197], v[76:79]
	v_mfma_f32_16x16x32_bf16 v[72:75], v[140:143], v[194:197], v[72:75]
	s_setprio 0
	s_barrier
	s_mov_b32 m0, s42
	v_add_u32_e32 v215, s15, v161
	ds_read_b128 v[198:201], v215
	ds_read_b128 v[202:205], v215 offset:1024
	ds_read_b128 v[206:209], v215 offset:2048
	ds_read_b128 v[222:225], v215 offset:3072
	global_load_lds_dwordx4 v148, s[100:101]
	s_mov_b32 m0, s13
	s_nop 0
	global_load_lds_dwordx4 v144, s[100:101]
	s_barrier
	s_waitcnt lgkmcnt(0)
	s_setprio 1
	s_waitcnt lgkmcnt(0)
	v_mfma_f32_16x16x32_bf16 v[104:107], v[198:201], v[154:157], v[104:107]
	v_mfma_f32_16x16x32_bf16 v[96:99], v[206:209], v[154:157], v[96:99]
	v_mfma_f32_16x16x32_bf16 v[92:95], v[198:201], v[170:173], v[92:95]
	v_mfma_f32_16x16x32_bf16 v[88:91], v[206:209], v[170:173], v[88:91]
	v_mfma_f32_16x16x32_bf16 v[84:87], v[198:201], v[178:181], v[84:87]
	v_mfma_f32_16x16x32_bf16 v[80:83], v[206:209], v[178:181], v[80:83]
	v_mfma_f32_16x16x32_bf16 v[68:71], v[198:201], v[190:193], v[68:71]
	v_mfma_f32_16x16x32_bf16 v[64:67], v[206:209], v[190:193], v[64:67]
	v_mfma_f32_16x16x32_bf16 v[104:107], v[202:205], v[166:169], v[104:107]
	v_mfma_f32_16x16x32_bf16 v[96:99], v[222:225], v[166:169], v[96:99]
	v_mfma_f32_16x16x32_bf16 v[92:95], v[202:205], v[174:177], v[92:95]
	v_mfma_f32_16x16x32_bf16 v[88:91], v[222:225], v[174:177], v[88:91]
	v_mfma_f32_16x16x32_bf16 v[84:87], v[202:205], v[186:189], v[84:87]
	v_mfma_f32_16x16x32_bf16 v[80:83], v[222:225], v[186:189], v[80:83]
	v_mfma_f32_16x16x32_bf16 v[68:71], v[202:205], v[194:197], v[68:71]
	v_mfma_f32_16x16x32_bf16 v[64:67], v[222:225], v[194:197], v[64:67]
	s_setprio 0
	s_mov_b32 m0, s64
	s_barrier
	ds_read_b128 v[154:157], v164 offset:49152
	ds_read_b128 v[166:169], v164 offset:50176
	ds_read_b128 v[170:173], v164 offset:51200
	ds_read_b128 v[174:177], v164 offset:52224
	ds_read_b128 v[178:181], v164 offset:53248
	ds_read_b128 v[186:189], v164 offset:54272
	ds_read_b128 v[190:193], v164 offset:55296
	ds_read_b128 v[194:197], v164 offset:56320
	global_load_lds_dwordx4 v150, s[98:99]
	s_mov_b32 m0, s65
	s_nop 0
	global_load_lds_dwordx4 v146, s[98:99]
	s_barrier
; #define PG8_STAGE(bufoff, gbase, voff) do { _Pragma("unroll") for (int _i = 0; _i < 2; ++_i) \
;         __builtin_amdgcn_global_load_lds((const unsigned*)((const char*)(gbase) + (voff)[_i]), (LAS unsigned*)(lds + (bufoff) + ldsw + _i * 8192), 16, 0, 0); } while (0)
; #define PG8_MMA(ai, bj, At, Bt) do { __builtin_amdgcn_s_setprio(1); _Pragma("unroll") for (int m = 0; m < 4; ++m) _Pragma("unroll") for (int n = 0; n < 2; ++n) _Pragma("unroll") for (int k = 0; k < 2; ++k) \
;         acc[ai][bj][m][n] = __builtin_amdgcn_mfma_f32_16x16x32_bf16(Bt[n][k], At[m][k], acc[ai][bj][m][n], 0, 0, 0); __builtin_amdgcn_s_setprio(0); } while (0)
; #define PG8_WAIT_V(n) asm volatile("s_waitcnt vmcnt(" #n ")" ::: "memory")
; #define PG8_WAIT_L(n) asm volatile("s_waitcnt lgkmcnt(" #n ")" ::: "memory")
; #define PG8_BAR __builtin_amdgcn_s_barrier()
; #define PG8_SCHED __builtin_amdgcn_sched_barrier(0)
; template <class Epi, class S_t>
; __device__ __forceinline__ void gemm_phase(LAS unsigned char* lds, int lda, int ldb, const S_t& S, const Epi& E) {
;     ...
;             PG8_BAR; PG8_WAIT_L(0); PG8_MMA(1, 0, At, B0); PG8_BAR; PG8_SCHED;
;             PG8_STAGE(PG8_SB(1, 1), b3 + hstepB, voffB);
;             PG8_WAIT_V(6); PG8_BAR; PG8_MMA(1, 1, At, B1); PG8_BAR;
;     __device__ __forceinline__ void operator()(const f32x4 (&acc)[2][2][4][2], const Unit& u, int wr, int wc, int fr, int fq) const {
;         const int row0 = u.pm * BM + wr * 64 + fr, col0 = u.pn * BM + wc * 32 + 8 * fq;
;         f32x4 sv[2][2];
; #pragma unroll
;         for (int bj = 0; bj < 2; ++bj)
; #pragma unroll
;             for (int n = 0; n < 2; ++n) sv[bj][n] = *(const f32x4*)(scale + col0 + bj * HALF + 4 * n);
	s_waitcnt lgkmcnt(0)
	s_setprio 1
	s_waitcnt lgkmcnt(0)
	v_mfma_f32_16x16x32_bf16 v[60:63], v[128:131], v[154:157], v[60:63]
	v_mfma_f32_16x16x32_bf16 v[56:59], v[136:139], v[154:157], v[56:59]
	v_mfma_f32_16x16x32_bf16 v[48:51], v[128:131], v[170:173], v[48:51]
	v_mfma_f32_16x16x32_bf16 v[40:43], v[136:139], v[170:173], v[40:43]
	v_mfma_f32_16x16x32_bf16 v[32:35], v[128:131], v[178:181], v[32:35]
	v_mfma_f32_16x16x32_bf16 v[24:27], v[136:139], v[178:181], v[24:27]
	v_mfma_f32_16x16x32_bf16 v[16:19], v[128:131], v[190:193], v[16:19]
	v_mfma_f32_16x16x32_bf16 v[8:11], v[136:139], v[190:193], v[8:11]
	v_mfma_f32_16x16x32_bf16 v[60:63], v[132:135], v[166:169], v[60:63]
	v_mfma_f32_16x16x32_bf16 v[56:59], v[140:143], v[166:169], v[56:59]
	v_mfma_f32_16x16x32_bf16 v[48:51], v[132:135], v[174:177], v[48:51]
	v_mfma_f32_16x16x32_bf16 v[40:43], v[140:143], v[174:177], v[40:43]
	v_mfma_f32_16x16x32_bf16 v[32:35], v[132:135], v[186:189], v[32:35]
	v_mfma_f32_16x16x32_bf16 v[24:27], v[140:143], v[186:189], v[24:27]
	v_mfma_f32_16x16x32_bf16 v[16:19], v[132:135], v[194:197], v[16:19]
	v_mfma_f32_16x16x32_bf16 v[8:11], v[140:143], v[194:197], v[8:11]
	s_setprio 0
	s_barrier
	s_mov_b32 m0, s1
	global_load_lds_dwordx4 v148, s[66:67]
	s_mov_b32 m0, s0
	s_nop 0
	global_load_lds_dwordx4 v144, s[66:67]
	s_waitcnt vmcnt(6)
	s_barrier
	s_setprio 1
	v_mfma_f32_16x16x32_bf16 v[52:55], v[198:201], v[154:157], v[52:55]
	v_mfma_f32_16x16x32_bf16 v[44:47], v[206:209], v[154:157], v[44:47]
	v_mfma_f32_16x16x32_bf16 v[36:39], v[198:201], v[170:173], v[36:39]
	v_mfma_f32_16x16x32_bf16 v[28:31], v[206:209], v[170:173], v[28:31]
	v_mfma_f32_16x16x32_bf16 v[20:23], v[198:201], v[178:181], v[20:23]
	v_mfma_f32_16x16x32_bf16 v[12:15], v[206:209], v[178:181], v[12:15]
	v_mfma_f32_16x16x32_bf16 v[4:7], v[198:201], v[190:193], v[4:7]
	v_mfma_f32_16x16x32_bf16 v[0:3], v[206:209], v[190:193], v[0:3]
	v_mfma_f32_16x16x32_bf16 v[52:55], v[202:205], v[166:169], v[52:55]
	v_mfma_f32_16x16x32_bf16 v[44:47], v[222:225], v[166:169], v[44:47]
	v_mfma_f32_16x16x32_bf16 v[36:39], v[202:205], v[174:177], v[36:39]
	v_mfma_f32_16x16x32_bf16 v[28:31], v[222:225], v[174:177], v[28:31]
	v_mfma_f32_16x16x32_bf16 v[20:23], v[202:205], v[186:189], v[20:23]
	v_mfma_f32_16x16x32_bf16 v[12:15], v[222:225], v[186:189], v[12:15]
	v_mfma_f32_16x16x32_bf16 v[4:7], v[202:205], v[194:197], v[4:7]
	v_mfma_f32_16x16x32_bf16 v[0:3], v[222:225], v[194:197], v[0:3]
	s_setprio 0
	s_movk_i32 s0, 0x100
	s_andn2_b64 vcc, exec, s[62:63]
	s_mov_b64 s[66:67], -1
	s_mov_b64 s[62:63], 0
	s_barrier
	s_cbranch_vccz .LBB0_535
	v_lshl_or_b32 v154, s92, 8, v162
	v_readlane_b32 s68, v254, 49
	v_ashrrev_i32_e32 v155, 31, v154
	v_readlane_b32 s69, v254, 50
	v_lshl_add_u32 v156, s56, 8, v160
	v_ashrrev_i32_e32 v157, 31, v156
	v_lshl_add_u64 v[128:129], v[154:155], 2, s[68:69]
	global_load_dwordx4 v[140:143], v[128:129], off
	global_load_dwordx4 v[136:139], v[128:129], off offset:16
	global_load_dwordx4 v[132:135], v[128:129], off offset:512
	s_nop 0
	global_load_dwordx4 v[128:131], v[128:129], off offset:528
	v_or_b32_e32 v158, 16, v156
	v_or_b32_e32 v166, 32, v156
	v_or_b32_e32 v168, 48, v156
	v_lshlrev_b64 v[156:157], 11, v[156:157]
	v_ashrrev_i32_e32 v159, 31, v158
	v_ashrrev_i32_e32 v167, 31, v166
	v_ashrrev_i32_e32 v169, 31, v168
	v_lshlrev_b64 v[170:171], 1, v[154:155]
	v_lshl_add_u64 v[154:155], s[46:47], 0, v[156:157]
	v_lshlrev_b64 v[156:157], 11, v[158:159]
	v_lshlrev_b64 v[158:159], 11, v[166:167]
	v_lshlrev_b64 v[166:167], 11, v[168:169]
	v_lshl_add_u64 v[154:155], v[154:155], 0, v[170:171]
	v_lshl_add_u64 v[156:157], s[46:47], 0, v[156:157]
	v_lshl_add_u64 v[158:159], s[46:47], 0, v[158:159]
	v_lshl_add_u64 v[166:167], s[46:47], 0, v[166:167]
	v_lshl_add_u64 v[168:169], v[156:157], 0, v[170:171]
	v_lshl_add_u64 v[158:159], v[158:159], 0, v[170:171]
	v_lshl_add_u64 v[156:157], v[166:167], 0, v[170:171]
	s_mov_b64 s[0:1], 0x40000
	s_mov_b32 s92, s12
	s_mov_b32 s56, s14
	s_mov_b64 s[60:61], s[44:45]
	s_mov_b64 s[58:59], s[18:19]
	v_readlane_b32 s70, v254, 51
	v_readlane_b32 s71, v254, 52
	v_readlane_b32 s72, v254, 53
	v_readlane_b32 s73, v254, 54
	v_readlane_b32 s74, v254, 55
	v_readlane_b32 s75, v254, 56
	v_readlane_b32 s76, v254, 57
	v_readlane_b32 s77, v254, 58
	v_readlane_b32 s78, v254, 59
	v_readlane_b32 s79, v254, 60
	v_readlane_b32 s80, v254, 61
	v_readlane_b32 s81, v254, 62
	v_readlane_b32 s82, v254, 63
	v_readlane_b32 s83, v255, 0
	s_waitcnt vmcnt(0)
; __device__ __forceinline__ unsigned pk2(float lo, float hi) { unsigned r; asm("v_cvt_pk_bf16_f32 %0, %1, %2" : "=v"(r) : "v"(lo), "v"(hi)); return r; }
; #define PG8_WAIT_V(n) asm volatile("s_waitcnt vmcnt(" #n ")" ::: "memory")
; #define PG8_BAR __builtin_amdgcn_s_barrier()
; template <class Epi, class S_t>
; __device__ __forceinline__ void gemm_phase(LAS unsigned char* lds, int lda, int ldb, const S_t& S, const Epi& E) {
;     ...
;         if (!has_next) break;
; #pragma unroll
;         for (int a = 0; a < 2; ++a)
; #pragma unroll
;             for (int b = 0; b < 2; ++b)
; #pragma unroll
;                 for (int m = 0; m < 4; ++m)
; #pragma unroll
;                     for (int n = 0; n < 2; ++n) acc[a][b][m][n] = (f32x4){0.f, 0.f, 0.f, 0.f};
;         cur = nxt; cA = nA; cB = nB; ++ui;
;     }
;     PG8_WAIT_V(0);
;     if (wr == 0) PG8_BAR;
;     __device__ __forceinline__ void operator()(const f32x4 (&acc)[2][2][4][2], const Unit& u, int wr, int wc, int fr, int fq) const {
;     ...
; #pragma unroll
;         for (int ai = 0; ai < 2; ++ai)
; #pragma unroll
;             for (int m = 0; m < 4; ++m) { bf16_t* rowp = O + (size_t)(row0 + ai * HALF + m * 16) * PW + col0;
; #pragma unroll
;                 for (int bj = 0; bj < 2; ++bj) { const f32x4 v0 = acc[ai][bj][m][0] * sv[bj][0], v1 = acc[ai][bj][m][1] * sv[bj][1];
;                     u32x4 w; w.x = pk2(v0[0], v0[1]); w.y = pk2(v0[2], v0[3]); w.z = pk2(v1[0], v1[1]); w.w = pk2(v1[2], v1[3]);
;                     *(u32x4*)(rowp + bj * HALF) = w; } }
	v_pk_mul_f32 v[126:127], v[126:127], v[142:143]
	v_pk_mul_f32 v[124:125], v[124:125], v[140:141]
	v_pk_mul_f32 v[122:123], v[122:123], v[138:139]
	v_pk_mul_f32 v[120:121], v[120:121], v[136:137]
	v_pk_mul_f32 v[94:95], v[94:95], v[134:135]
	v_pk_mul_f32 v[92:93], v[92:93], v[132:133]
	v_pk_mul_f32 v[90:91], v[90:91], v[130:131]
	v_pk_mul_f32 v[88:89], v[88:89], v[128:129]
	v_pk_mul_f32 v[180:181], v[74:75], v[138:139]
	v_pk_mul_f32 v[182:183], v[72:73], v[136:137]
	v_cvt_pk_bf16_f32 v72, v124, v125
	v_cvt_pk_bf16_f32 v73, v126, v127
	v_cvt_pk_bf16_f32 v74, v120, v121
	v_cvt_pk_bf16_f32 v75, v122, v123
	v_pk_mul_f32 v[106:107], v[106:107], v[134:135]
	v_pk_mul_f32 v[104:105], v[104:105], v[132:133]
	v_pk_mul_f32 v[98:99], v[98:99], v[130:131]
	v_pk_mul_f32 v[96:97], v[96:97], v[128:129]
	v_pk_mul_f32 v[118:119], v[118:119], v[142:143]
	v_pk_mul_f32 v[116:117], v[116:117], v[140:141]
	v_pk_mul_f32 v[114:115], v[114:115], v[138:139]
	v_pk_mul_f32 v[112:113], v[112:113], v[136:137]
	v_pk_mul_f32 v[110:111], v[110:111], v[142:143]
	v_pk_mul_f32 v[108:109], v[108:109], v[140:141]
	v_pk_mul_f32 v[102:103], v[102:103], v[138:139]
	v_pk_mul_f32 v[100:101], v[100:101], v[136:137]
	v_pk_mul_f32 v[166:167], v[86:87], v[134:135]
	v_pk_mul_f32 v[170:171], v[84:85], v[132:133]
	v_pk_mul_f32 v[172:173], v[82:83], v[130:131]
	v_pk_mul_f32 v[174:175], v[80:81], v[128:129]
	v_pk_mul_f32 v[176:177], v[78:79], v[142:143]
	v_pk_mul_f32 v[178:179], v[76:77], v[140:141]
	v_cvt_pk_bf16_f32 v76, v104, v105
	v_cvt_pk_bf16_f32 v77, v106, v107
	v_cvt_pk_bf16_f32 v78, v96, v97
	v_cvt_pk_bf16_f32 v79, v98, v99
	v_cvt_pk_bf16_f32 v80, v116, v117
	v_cvt_pk_bf16_f32 v81, v118, v119
	v_cvt_pk_bf16_f32 v82, v112, v113
	v_cvt_pk_bf16_f32 v83, v114, v115
	v_cvt_pk_bf16_f32 v84, v92, v93
	v_cvt_pk_bf16_f32 v85, v94, v95
	v_cvt_pk_bf16_f32 v86, v88, v89
	v_cvt_pk_bf16_f32 v87, v90, v91
	v_cvt_pk_bf16_f32 v88, v108, v109
	v_cvt_pk_bf16_f32 v89, v110, v111
	v_cvt_pk_bf16_f32 v90, v100, v101
	v_cvt_pk_bf16_f32 v91, v102, v103
	v_cvt_pk_bf16_f32 v92, v170, v171
	v_cvt_pk_bf16_f32 v93, v166, v167
	v_cvt_pk_bf16_f32 v94, v174, v175
	v_cvt_pk_bf16_f32 v95, v172, v173
	global_store_dwordx4 v[154:155], v[72:75], off
	global_store_dwordx4 v[154:155], v[76:79], off offset:256
	global_store_dwordx4 v[168:169], v[80:83], off
	global_store_dwordx4 v[168:169], v[84:87], off offset:256
	global_store_dwordx4 v[158:159], v[88:91], off
	global_store_dwordx4 v[158:159], v[92:95], off offset:256
	v_cvt_pk_bf16_f32 v72, v178, v179
	v_cvt_pk_bf16_f32 v73, v176, v177
	v_cvt_pk_bf16_f32 v74, v182, v183
	v_cvt_pk_bf16_f32 v75, v180, v181
	global_store_dwordx4 v[156:157], v[72:75], off
	v_pk_mul_f32 v[70:71], v[70:71], v[134:135]
	v_pk_mul_f32 v[68:69], v[68:69], v[132:133]
	v_pk_mul_f32 v[72:73], v[66:67], v[130:131]
	v_pk_mul_f32 v[66:67], v[64:65], v[128:129]
	v_cvt_pk_bf16_f32 v64, v68, v69
	v_cvt_pk_bf16_f32 v65, v70, v71
	v_pk_mul_f32 v[60:61], v[60:61], v[140:141]
	v_cvt_pk_bf16_f32 v66, v66, v67
	v_cvt_pk_bf16_f32 v67, v72, v73
	global_store_dwordx4 v[156:157], v[64:67], off offset:256
	v_pk_mul_f32 v[62:63], v[62:63], v[142:143]
	v_pk_mul_f32 v[54:55], v[54:55], v[134:135]
	v_lshl_add_u64 v[64:65], v[154:155], 0, s[0:1]
	s_mov_b32 s0, 0x40000
	v_pk_mul_f32 v[66:67], v[58:59], v[138:139]
	v_pk_mul_f32 v[58:59], v[56:57], v[136:137]
	v_cvt_pk_bf16_f32 v56, v60, v61
	v_add_co_u32_e32 v60, vcc, s0, v154
	v_cvt_pk_bf16_f32 v57, v62, v63
	v_cvt_pk_bf16_f32 v58, v58, v59
	v_cvt_pk_bf16_f32 v59, v66, v67
	v_pk_mul_f32 v[52:53], v[52:53], v[132:133]
	s_nop 0
	v_addc_co_u32_e32 v61, vcc, 0, v155, vcc
	global_store_dwordx4 v[60:61], v[56:59], off
	s_mov_b64 s[0:1], 0x48000
	v_pk_mul_f32 v[48:49], v[48:49], v[140:141]
	v_pk_mul_f32 v[56:57], v[46:47], v[130:131]
	v_pk_mul_f32 v[46:47], v[44:45], v[128:129]
	v_cvt_pk_bf16_f32 v44, v52, v53
	v_cvt_pk_bf16_f32 v45, v54, v55
	v_pk_mul_f32 v[38:39], v[38:39], v[134:135]
	v_cvt_pk_bf16_f32 v46, v46, v47
	v_cvt_pk_bf16_f32 v47, v56, v57
	global_store_dwordx4 v[64:65], v[44:47], off offset:256
	v_pk_mul_f32 v[36:37], v[36:37], v[132:133]
	v_pk_mul_f32 v[32:33], v[32:33], v[140:141]
	v_lshl_add_u64 v[44:45], v[154:155], 0, s[0:1]
	v_pk_mul_f32 v[46:47], v[50:51], v[142:143]
	s_mov_b32 s0, 0x48000
	v_pk_mul_f32 v[50:51], v[42:43], v[138:139]
	v_pk_mul_f32 v[42:43], v[40:41], v[136:137]
	v_cvt_pk_bf16_f32 v41, v46, v47
	v_add_co_u32_e32 v46, vcc, s0, v154
	v_cvt_pk_bf16_f32 v40, v48, v49
	v_cvt_pk_bf16_f32 v42, v42, v43
	v_cvt_pk_bf16_f32 v43, v50, v51
	s_mov_b64 s[0:1], 0x50000
	s_nop 0
	v_addc_co_u32_e32 v47, vcc, 0, v155, vcc
	global_store_dwordx4 v[46:47], v[40:43], off
	v_pk_mul_f32 v[22:23], v[22:23], v[134:135]
	v_pk_mul_f32 v[20:21], v[20:21], v[132:133]
	v_pk_mul_f32 v[40:41], v[30:31], v[130:131]
	v_pk_mul_f32 v[30:31], v[28:29], v[128:129]
	v_cvt_pk_bf16_f32 v28, v36, v37
	v_cvt_pk_bf16_f32 v29, v38, v39
	v_pk_mul_f32 v[16:17], v[16:17], v[140:141]
	v_cvt_pk_bf16_f32 v30, v30, v31
	v_cvt_pk_bf16_f32 v31, v40, v41
	global_store_dwordx4 v[44:45], v[28:31], off offset:256
	v_pk_mul_f32 v[6:7], v[6:7], v[134:135]
	v_pk_mul_f32 v[4:5], v[4:5], v[132:133]
	v_lshl_add_u64 v[28:29], v[154:155], 0, s[0:1]
	v_pk_mul_f32 v[30:31], v[34:35], v[142:143]
	s_mov_b32 s0, 0x50000
	v_pk_mul_f32 v[34:35], v[26:27], v[138:139]
	v_pk_mul_f32 v[26:27], v[24:25], v[136:137]
	v_cvt_pk_bf16_f32 v25, v30, v31
	v_add_co_u32_e32 v30, vcc, s0, v154
	v_cvt_pk_bf16_f32 v24, v32, v33
	v_cvt_pk_bf16_f32 v26, v26, v27
	v_cvt_pk_bf16_f32 v27, v34, v35
	s_mov_b64 s[0:1], 0x58000
	s_nop 0
	v_addc_co_u32_e32 v31, vcc, 0, v155, vcc
	global_store_dwordx4 v[30:31], v[24:27], off
	s_nop 1
	v_pk_mul_f32 v[24:25], v[14:15], v[130:131]
	v_pk_mul_f32 v[14:15], v[12:13], v[128:129]
	v_cvt_pk_bf16_f32 v12, v20, v21
	v_cvt_pk_bf16_f32 v13, v22, v23
	s_nop 0
	v_cvt_pk_bf16_f32 v14, v14, v15
	v_cvt_pk_bf16_f32 v15, v24, v25
	global_store_dwordx4 v[28:29], v[12:15], off offset:256
	s_nop 1
	v_lshl_add_u64 v[12:13], v[154:155], 0, s[0:1]
	v_pk_mul_f32 v[14:15], v[18:19], v[142:143]
	s_mov_b32 s0, 0x58000
	v_pk_mul_f32 v[18:19], v[10:11], v[138:139]
	v_pk_mul_f32 v[10:11], v[8:9], v[136:137]
	v_cvt_pk_bf16_f32 v9, v14, v15
	v_add_co_u32_e32 v14, vcc, s0, v154
	v_cvt_pk_bf16_f32 v8, v16, v17
	v_cvt_pk_bf16_f32 v10, v10, v11
	v_cvt_pk_bf16_f32 v11, v18, v19
	s_nop 1
	v_addc_co_u32_e32 v15, vcc, 0, v155, vcc
	global_store_dwordx4 v[14:15], v[8:11], off
	s_and_b64 vcc, exec, s[6:7]
	s_nop 0
	v_pk_mul_f32 v[8:9], v[2:3], v[130:131]
	v_pk_mul_f32 v[2:3], v[0:1], v[128:129]
	v_cvt_pk_bf16_f32 v0, v4, v5
	v_cvt_pk_bf16_f32 v1, v6, v7
	s_nop 0
	v_cvt_pk_bf16_f32 v2, v2, v3
	v_cvt_pk_bf16_f32 v3, v8, v9
	global_store_dwordx4 v[12:13], v[0:3], off offset:256
	s_cbranch_vccz .LBB0_532
	s_waitcnt vmcnt(0)
	s_cmpk_gt_u32 s4, 0xff
	s_cbranch_scc1 .LBB0_539
	s_barrier

; #define PG8_STAGE(bufoff, gbase, voff) do { _Pragma("unroll") for (int _i = 0; _i < 2; ++_i) \
;         __builtin_amdgcn_global_load_lds((const unsigned*)((const char*)(gbase) + (voff)[_i]), (LAS unsigned*)(lds + (bufoff) + ldsw + _i * 8192), 16, 0, 0); } while (0)
; #define PG8_LDA(dst, b, h) do { _Pragma("unroll") for (int m = 0; m < 4; ++m) _Pragma("unroll") for (int k = 0; k < 2; ++k) dst[m][k] = *(const LAS bf16x8*)(lds + PG8_SA(b, h) + aoff + m * 2048 + k * 1024); } while (0)
; #define PG8_LDB(dst, b, h) do { _Pragma("unroll") for (int n = 0; n < 2; ++n) _Pragma("unroll") for (int k = 0; k < 2; ++k) dst[n][k] = *(const LAS bf16x8*)(lds + PG8_SB(b, h) + boff + n * 2048 + k * 1024); } while (0)
; #define PG8_MMA(ai, bj, At, Bt) do { __builtin_amdgcn_s_setprio(1); _Pragma("unroll") for (int m = 0; m < 4; ++m) _Pragma("unroll") for (int n = 0; n < 2; ++n) _Pragma("unroll") for (int k = 0; k < 2; ++k) \
;         acc[ai][bj][m][n] = __builtin_amdgcn_mfma_f32_16x16x32_bf16(Bt[n][k], At[m][k], acc[ai][bj][m][n], 0, 0, 0); __builtin_amdgcn_s_setprio(0); } while (0)
; #define PG8_WAIT_V(n) asm volatile("s_waitcnt vmcnt(" #n ")" ::: "memory")
; #define PG8_WAIT_L(n) asm volatile("s_waitcnt lgkmcnt(" #n ")" ::: "memory")
; #define PG8_BAR __builtin_amdgcn_s_barrier()
; #define PG8_SCHED __builtin_amdgcn_sched_barrier(0)
; template <class Epi, class S_t>
; __device__ __forceinline__ void gemm_phase(LAS unsigned char* lds, int lda, int ldb, const S_t& S, const Epi& E) {
;     ...
;             const char* a1 = cA + (size_t)(t + 1) * kstep;
;             const char* a2 = last ? nA : cA + (size_t)(t + 2) * kstep; const char* b2 = last ? nB : cB + (size_t)(t + 2) * kstep;
;             const char* a3 = a2 + kstep; const char* b3 = b2 + kstep;
;             PG8_LDB(B0, 0, 0); PG8_SCHED; PG8_LDA(At, 0, 0); PG8_STAGE(PG8_SA(1, 1), a1 + hstepA, voffA);
;             PG8_WAIT_L(8); PG8_BAR; PG8_WAIT_L(0); PG8_MMA(0, 0, At, B0); PG8_BAR; PG8_SCHED;
;             PG8_LDB(B1, 0, 1); PG8_STAGE(PG8_SB(0, 0), b2, voffB);
;             PG8_BAR; PG8_WAIT_L(0); PG8_MMA(0, 1, At, B1); PG8_BAR;
;             PG8_LDA(At, 0, 1); PG8_STAGE(PG8_SA(0, 0), a2, voffA);
;             PG8_BAR; PG8_WAIT_L(0); PG8_MMA(1, 0, At, B0); PG8_BAR; PG8_SCHED;
;             PG8_STAGE(PG8_SB(0, 1), b2 + hstepB, voffB);
;             PG8_WAIT_V(6); PG8_BAR; PG8_MMA(1, 1, At, B1); PG8_BAR;
.LBB0_547:
	s_add_u32 s15, s60, s0
	s_addc_u32 s19, s61, 0
	s_add_u32 s1, s15, 0x100
	s_addc_u32 s33, s19, 0
	s_and_b64 s[70:71], s[68:69], exec
	s_cselect_b32 s75, s57, s33
	s_cselect_b32 s74, s56, s1
	s_add_u32 s0, s62, s0
	s_addc_u32 s1, s63, 0
	s_add_u32 s33, s0, 0x100
	s_addc_u32 s43, s1, 0
	s_and_b64 s[0:1], s[68:69], exec
	s_cselect_b32 s79, s59, s43
	s_cselect_b32 s78, s58, s33
	s_add_u32 s82, s15, 0x80080
	s_addc_u32 s83, s19, 0
	s_add_i32 vcc_hi, s88, s64
	s_add_i32 m0, s53, 0xc000
	s_add_i32 s65, s53, 0xe000
	s_add_i32 s33, vcc_hi, 0x2000
	s_add_u32 s72, s78, 0x10000
	s_addc_u32 s73, s79, 0
	s_add_i32 vcc_lo, s89, s64
	s_add_i32 s43, vcc_lo, 0x2000
	s_add_i32 s90, 0, 0x18000
	ds_read_b128 v[32:35], v226
	ds_read_b128 v[36:39], v226 offset:1024
	ds_read_b128 v[48:51], v226 offset:2048
	ds_read_b128 v[52:55], v226 offset:3072
	s_add_u32 s70, s74, 0x80000
	s_addc_u32 s71, s75, 0
	s_add_i32 s19, s90, s64
	s_add_i32 s91, 0, 0x1c000
	s_add_i32 s15, s19, 0x2000
	s_add_u32 s68, s78, 0x10080
	s_addc_u32 s69, s79, 0
	s_add_i32 s1, s91, s64
	s_add_i32 s0, s1, 0x2000
	ds_read_b128 v[56:59], v227
	ds_read_b128 v[64:67], v227 offset:1024
	ds_read_b128 v[68:71], v227 offset:2048
	ds_read_b128 v[76:79], v227 offset:3072
	ds_read_b128 v[96:99], v227 offset:4096
	ds_read_b128 v[116:119], v227 offset:5120
	ds_read_b128 v[136:139], v227 offset:6144
	ds_read_b128 v[156:159], v227 offset:7168
	global_load_lds_dwordx4 v186, s[82:83]
	s_mov_b32 m0, s65
	s_nop 0
	global_load_lds_dwordx4 v190, s[82:83]
	s_waitcnt lgkmcnt(8)
	s_barrier
	s_waitcnt lgkmcnt(0)
	s_setprio 1
	s_waitcnt lgkmcnt(0)
	v_mfma_f32_16x16x32_bf16 v[172:175], v[32:35], v[56:59], v[172:175]
	v_mfma_f32_16x16x32_bf16 v[168:171], v[48:51], v[56:59], v[168:171]
	v_mfma_f32_16x16x32_bf16 v[152:155], v[32:35], v[68:71], v[152:155]
	v_mfma_f32_16x16x32_bf16 v[148:151], v[48:51], v[68:71], v[148:151]
	v_mfma_f32_16x16x32_bf16 v[132:135], v[32:35], v[96:99], v[132:135]
	v_mfma_f32_16x16x32_bf16 v[128:131], v[48:51], v[96:99], v[128:131]
	v_mfma_f32_16x16x32_bf16 v[112:115], v[32:35], v[136:139], v[112:115]
	v_mfma_f32_16x16x32_bf16 v[108:111], v[48:51], v[136:139], v[108:111]
	v_mfma_f32_16x16x32_bf16 v[172:175], v[36:39], v[64:67], v[172:175]
	v_mfma_f32_16x16x32_bf16 v[168:171], v[52:55], v[64:67], v[168:171]
	v_mfma_f32_16x16x32_bf16 v[152:155], v[36:39], v[76:79], v[152:155]
	v_mfma_f32_16x16x32_bf16 v[148:151], v[52:55], v[76:79], v[148:151]
	v_mfma_f32_16x16x32_bf16 v[132:135], v[36:39], v[116:119], v[132:135]
	v_mfma_f32_16x16x32_bf16 v[128:131], v[52:55], v[116:119], v[128:131]
	v_mfma_f32_16x16x32_bf16 v[112:115], v[36:39], v[156:159], v[112:115]
	v_mfma_f32_16x16x32_bf16 v[108:111], v[52:55], v[156:159], v[108:111]
	s_setprio 0
	s_barrier
	s_mov_b32 m0, vcc_hi
	s_add_u32 s100, s78, s12
	s_addc_u32 s101, s79, s13
	ds_read_b128 v[176:179], v228
	ds_read_b128 v[180:183], v228 offset:1024
	ds_read_b128 v[196:199], v228 offset:2048
	ds_read_b128 v[200:203], v228 offset:3072
	global_load_lds_dwordx4 v188, s[78:79]
	s_mov_b32 m0, s33
	s_nop 0
	global_load_lds_dwordx4 v192, s[78:79]
	s_barrier
	s_waitcnt lgkmcnt(0)
	s_setprio 1
	s_waitcnt lgkmcnt(0)
	v_mfma_f32_16x16x32_bf16 v[160:163], v[176:179], v[56:59], v[160:163]
	v_mfma_f32_16x16x32_bf16 v[56:59], v[196:199], v[56:59], v[164:167]
	v_mfma_f32_16x16x32_bf16 v[160:163], v[180:183], v[64:67], v[160:163]
	v_mfma_f32_16x16x32_bf16 v[56:59], v[200:203], v[64:67], v[56:59]
	v_mfma_f32_16x16x32_bf16 v[64:67], v[176:179], v[68:71], v[140:143]
	v_mfma_f32_16x16x32_bf16 v[68:71], v[196:199], v[68:71], v[144:147]
	v_mfma_f32_16x16x32_bf16 v[100:103], v[176:179], v[136:139], v[100:103]
	v_mfma_f32_16x16x32_bf16 v[104:107], v[196:199], v[136:139], v[104:107]
	v_mfma_f32_16x16x32_bf16 v[64:67], v[180:183], v[76:79], v[64:67]
	v_mfma_f32_16x16x32_bf16 v[68:71], v[200:203], v[76:79], v[68:71]
	v_mfma_f32_16x16x32_bf16 v[76:79], v[176:179], v[96:99], v[120:123]
	v_mfma_f32_16x16x32_bf16 v[96:99], v[196:199], v[96:99], v[124:127]
	v_mfma_f32_16x16x32_bf16 v[100:103], v[180:183], v[156:159], v[100:103]
	v_mfma_f32_16x16x32_bf16 v[104:107], v[200:203], v[156:159], v[104:107]
	v_mfma_f32_16x16x32_bf16 v[76:79], v[180:183], v[116:119], v[76:79]
	v_mfma_f32_16x16x32_bf16 v[96:99], v[200:203], v[116:119], v[96:99]
	s_setprio 0
	s_mov_b32 m0, s53
	s_add_u32 s98, s74, s12
	s_addc_u32 s99, s75, s13
	s_barrier
	ds_read_b128 v[116:119], v227 offset:16384
	ds_read_b128 v[120:123], v227 offset:17408
	ds_read_b128 v[124:127], v227 offset:18432
	ds_read_b128 v[136:139], v227 offset:19456
	ds_read_b128 v[140:143], v227 offset:20480
	ds_read_b128 v[144:147], v227 offset:21504
	ds_read_b128 v[156:159], v227 offset:22528
	ds_read_b128 v[164:167], v227 offset:23552
	global_load_lds_dwordx4 v186, s[74:75]
	s_mov_b32 m0, s95
	s_nop 0
	global_load_lds_dwordx4 v190, s[74:75]
	s_barrier
	s_waitcnt lgkmcnt(0)
	s_setprio 1
	s_waitcnt lgkmcnt(0)
	v_mfma_f32_16x16x32_bf16 v[92:95], v[32:35], v[116:119], v[92:95]
	v_mfma_f32_16x16x32_bf16 v[88:91], v[48:51], v[116:119], v[88:91]
	v_mfma_f32_16x16x32_bf16 v[72:75], v[32:35], v[124:127], v[72:75]
	v_mfma_f32_16x16x32_bf16 v[60:63], v[48:51], v[124:127], v[60:63]
	v_mfma_f32_16x16x32_bf16 v[28:31], v[32:35], v[140:143], v[28:31]
	v_mfma_f32_16x16x32_bf16 v[24:27], v[48:51], v[140:143], v[24:27]
	v_mfma_f32_16x16x32_bf16 v[12:15], v[32:35], v[156:159], v[12:15]
	v_mfma_f32_16x16x32_bf16 v[8:11], v[48:51], v[156:159], v[8:11]
	v_mfma_f32_16x16x32_bf16 v[92:95], v[36:39], v[120:123], v[92:95]
	v_mfma_f32_16x16x32_bf16 v[88:91], v[52:55], v[120:123], v[88:91]
	v_mfma_f32_16x16x32_bf16 v[72:75], v[36:39], v[136:139], v[72:75]
	v_mfma_f32_16x16x32_bf16 v[60:63], v[52:55], v[136:139], v[60:63]
	v_mfma_f32_16x16x32_bf16 v[28:31], v[36:39], v[144:147], v[28:31]
	v_mfma_f32_16x16x32_bf16 v[24:27], v[52:55], v[144:147], v[24:27]
	v_mfma_f32_16x16x32_bf16 v[12:15], v[36:39], v[164:167], v[12:15]
	v_mfma_f32_16x16x32_bf16 v[8:11], v[52:55], v[164:167], v[8:11]
	s_setprio 0
	s_barrier
; #define PG8_STAGE(bufoff, gbase, voff) do { _Pragma("unroll") for (int _i = 0; _i < 2; ++_i) \
;         __builtin_amdgcn_global_load_lds((const unsigned*)((const char*)(gbase) + (voff)[_i]), (LAS unsigned*)(lds + (bufoff) + ldsw + _i * 8192), 16, 0, 0); } while (0)
; #define PG8_LDA(dst, b, h) do { _Pragma("unroll") for (int m = 0; m < 4; ++m) _Pragma("unroll") for (int k = 0; k < 2; ++k) dst[m][k] = *(const LAS bf16x8*)(lds + PG8_SA(b, h) + aoff + m * 2048 + k * 1024); } while (0)
; #define PG8_LDB(dst, b, h) do { _Pragma("unroll") for (int n = 0; n < 2; ++n) _Pragma("unroll") for (int k = 0; k < 2; ++k) dst[n][k] = *(const LAS bf16x8*)(lds + PG8_SB(b, h) + boff + n * 2048 + k * 1024); } while (0)
; #define PG8_MMA(ai, bj, At, Bt) do { __builtin_amdgcn_s_setprio(1); _Pragma("unroll") for (int m = 0; m < 4; ++m) _Pragma("unroll") for (int n = 0; n < 2; ++n) _Pragma("unroll") for (int k = 0; k < 2; ++k) \
;         acc[ai][bj][m][n] = __builtin_amdgcn_mfma_f32_16x16x32_bf16(Bt[n][k], At[m][k], acc[ai][bj][m][n], 0, 0, 0); __builtin_amdgcn_s_setprio(0); } while (0)
; #define PG8_WAIT_V(n) asm volatile("s_waitcnt vmcnt(" #n ")" ::: "memory")
; #define PG8_WAIT_L(n) asm volatile("s_waitcnt lgkmcnt(" #n ")" ::: "memory")
; #define PG8_BAR __builtin_amdgcn_s_barrier()
; #define PG8_SCHED __builtin_amdgcn_sched_barrier(0)
; template <class Epi, class S_t>
; __device__ __forceinline__ void gemm_phase(LAS unsigned char* lds, int lda, int ldb, const S_t& S, const Epi& E) {
;     ...
;             PG8_WAIT_V(6); PG8_BAR; PG8_MMA(1, 1, At, B1); PG8_BAR;
;             PG8_LDB(B0, 1, 0); PG8_SCHED; PG8_LDA(At, 1, 0); PG8_STAGE(PG8_SA(0, 1), a2 + hstepA, voffA);
;             PG8_WAIT_L(8); PG8_BAR; PG8_WAIT_L(0); PG8_MMA(0, 0, At, B0); PG8_BAR; PG8_SCHED;
;             PG8_LDB(B1, 1, 1); PG8_STAGE(PG8_SB(1, 0), b3, voffB);
;             PG8_BAR; PG8_WAIT_L(0); PG8_MMA(0, 1, At, B1); PG8_BAR;
;             PG8_LDA(At, 1, 1); PG8_STAGE(PG8_SA(1, 0), a3, voffA);
;             PG8_BAR; PG8_WAIT_L(0); PG8_MMA(1, 0, At, B0); PG8_BAR; PG8_SCHED;
	s_mov_b32 m0, vcc_lo
	global_load_lds_dwordx4 v188, s[72:73]
	s_mov_b32 m0, s43
	s_nop 0
	global_load_lds_dwordx4 v192, s[72:73]
	s_waitcnt vmcnt(6)
	s_barrier
	s_setprio 1
	v_mfma_f32_16x16x32_bf16 v[40:43], v[176:179], v[124:127], v[40:43]
	v_mfma_f32_16x16x32_bf16 v[44:47], v[196:199], v[124:127], v[44:47]
	v_mfma_f32_16x16x32_bf16 v[16:19], v[176:179], v[140:143], v[16:19]
	v_mfma_f32_16x16x32_bf16 v[20:23], v[196:199], v[140:143], v[20:23]
	v_mfma_f32_16x16x32_bf16 v[0:3], v[176:179], v[156:159], v[0:3]
	v_mfma_f32_16x16x32_bf16 v[4:7], v[196:199], v[156:159], v[4:7]
	v_mfma_f32_16x16x32_bf16 v[32:35], v[176:179], v[116:119], v[80:83]
	v_mfma_f32_16x16x32_bf16 v[36:39], v[196:199], v[116:119], v[84:87]
	v_mfma_f32_16x16x32_bf16 v[40:43], v[180:183], v[136:139], v[40:43]
	v_mfma_f32_16x16x32_bf16 v[44:47], v[200:203], v[136:139], v[44:47]
	v_mfma_f32_16x16x32_bf16 v[16:19], v[180:183], v[144:147], v[16:19]
	v_mfma_f32_16x16x32_bf16 v[20:23], v[200:203], v[144:147], v[20:23]
	v_mfma_f32_16x16x32_bf16 v[0:3], v[180:183], v[164:167], v[0:3]
	v_mfma_f32_16x16x32_bf16 v[4:7], v[200:203], v[164:167], v[4:7]
	v_mfma_f32_16x16x32_bf16 v[32:35], v[180:183], v[120:123], v[32:35]
	v_mfma_f32_16x16x32_bf16 v[36:39], v[200:203], v[120:123], v[36:39]
	s_setprio 0
	v_add_u32_e32 v84, s90, v219
	s_barrier
	ds_read_b128 v[48:51], v84
	ds_read_b128 v[52:55], v84 offset:1024
	ds_read_b128 v[80:83], v84 offset:2048
	ds_read_b128 v[84:87], v84 offset:3072
	s_mov_b32 m0, s96
	ds_read_b128 v[116:119], v227 offset:32768
	ds_read_b128 v[120:123], v227 offset:33792
	ds_read_b128 v[124:127], v227 offset:34816
	ds_read_b128 v[136:139], v227 offset:35840
	ds_read_b128 v[156:159], v227 offset:36864
	ds_read_b128 v[176:179], v227 offset:37888
	ds_read_b128 v[180:183], v227 offset:38912
	ds_read_b128 v[196:199], v227 offset:39936
	global_load_lds_dwordx4 v186, s[70:71]
	s_mov_b32 m0, s97
	s_nop 0
	global_load_lds_dwordx4 v190, s[70:71]
	s_waitcnt lgkmcnt(8)
	s_barrier
	s_waitcnt lgkmcnt(0)
	s_setprio 1
	s_waitcnt lgkmcnt(0)
	v_mfma_f32_16x16x32_bf16 v[140:143], v[48:51], v[116:119], v[172:175]
	v_mfma_f32_16x16x32_bf16 v[172:175], v[52:55], v[120:123], v[140:143]
	v_mfma_f32_16x16x32_bf16 v[140:143], v[80:83], v[116:119], v[168:171]
	v_mfma_f32_16x16x32_bf16 v[168:171], v[84:87], v[120:123], v[140:143]
	v_mfma_f32_16x16x32_bf16 v[140:143], v[48:51], v[124:127], v[152:155]
	v_mfma_f32_16x16x32_bf16 v[152:155], v[52:55], v[136:139], v[140:143]
	v_mfma_f32_16x16x32_bf16 v[140:143], v[80:83], v[124:127], v[148:151]
	v_mfma_f32_16x16x32_bf16 v[132:135], v[48:51], v[156:159], v[132:135]
	v_mfma_f32_16x16x32_bf16 v[128:131], v[80:83], v[156:159], v[128:131]
	v_mfma_f32_16x16x32_bf16 v[112:115], v[48:51], v[180:183], v[112:115]
	v_mfma_f32_16x16x32_bf16 v[108:111], v[80:83], v[180:183], v[108:111]
	v_mfma_f32_16x16x32_bf16 v[148:151], v[84:87], v[136:139], v[140:143]
	v_mfma_f32_16x16x32_bf16 v[132:135], v[52:55], v[176:179], v[132:135]
	v_mfma_f32_16x16x32_bf16 v[128:131], v[84:87], v[176:179], v[128:131]
	v_mfma_f32_16x16x32_bf16 v[112:115], v[52:55], v[196:199], v[112:115]
	v_mfma_f32_16x16x32_bf16 v[108:111], v[84:87], v[196:199], v[108:111]
	s_setprio 0
	s_barrier
	v_add_u32_e32 v140, s91, v219
	s_mov_b32 m0, s19
	ds_read_b128 v[200:203], v140
	ds_read_b128 v[204:207], v140 offset:1024
	ds_read_b128 v[222:225], v140 offset:2048
	ds_read_b128 v[234:237], v140 offset:3072
	global_load_lds_dwordx4 v188, s[100:101]
	s_mov_b32 m0, s15
	s_nop 0
	global_load_lds_dwordx4 v192, s[100:101]
	s_barrier
	s_waitcnt lgkmcnt(0)
	s_setprio 1
	s_waitcnt lgkmcnt(0)
	v_mfma_f32_16x16x32_bf16 v[56:59], v[222:225], v[116:119], v[56:59]
	v_mfma_f32_16x16x32_bf16 v[140:143], v[200:203], v[116:119], v[160:163]
	v_mfma_f32_16x16x32_bf16 v[164:167], v[234:237], v[120:123], v[56:59]
	v_mfma_f32_16x16x32_bf16 v[56:59], v[200:203], v[124:127], v[64:67]
	v_mfma_f32_16x16x32_bf16 v[160:163], v[204:207], v[120:123], v[140:143]
	v_mfma_f32_16x16x32_bf16 v[140:143], v[204:207], v[136:139], v[56:59]
	v_mfma_f32_16x16x32_bf16 v[56:59], v[222:225], v[124:127], v[68:71]
	v_mfma_f32_16x16x32_bf16 v[144:147], v[234:237], v[136:139], v[56:59]
	v_mfma_f32_16x16x32_bf16 v[56:59], v[200:203], v[156:159], v[76:79]
	v_mfma_f32_16x16x32_bf16 v[120:123], v[204:207], v[176:179], v[56:59]
	v_mfma_f32_16x16x32_bf16 v[56:59], v[222:225], v[156:159], v[96:99]
	v_mfma_f32_16x16x32_bf16 v[124:127], v[234:237], v[176:179], v[56:59]
	v_mfma_f32_16x16x32_bf16 v[56:59], v[200:203], v[180:183], v[100:103]
	v_mfma_f32_16x16x32_bf16 v[100:103], v[204:207], v[196:199], v[56:59]
	v_mfma_f32_16x16x32_bf16 v[56:59], v[222:225], v[180:183], v[104:107]
	v_mfma_f32_16x16x32_bf16 v[104:107], v[234:237], v[196:199], v[56:59]
	s_setprio 0
	s_mov_b32 m0, s16
	s_barrier
	s_nop 2
	ds_read_b128 v[56:59], v227 offset:49152
	ds_read_b128 v[64:67], v227 offset:50176
	ds_read_b128 v[68:71], v227 offset:51200
	ds_read_b128 v[76:79], v227 offset:52224
	ds_read_b128 v[96:99], v227 offset:53248
	ds_read_b128 v[116:119], v227 offset:54272
	ds_read_b128 v[136:139], v227 offset:55296
	ds_read_b128 v[156:159], v227 offset:56320
	global_load_lds_dwordx4 v186, s[98:99]
	s_mov_b32 m0, s17
	s_nop 0
	global_load_lds_dwordx4 v190, s[98:99]
	s_barrier
; #define PG8_STAGE(bufoff, gbase, voff) do { _Pragma("unroll") for (int _i = 0; _i < 2; ++_i) \
;         __builtin_amdgcn_global_load_lds((const unsigned*)((const char*)(gbase) + (voff)[_i]), (LAS unsigned*)(lds + (bufoff) + ldsw + _i * 8192), 16, 0, 0); } while (0)
; #define PG8_MMA(ai, bj, At, Bt) do { __builtin_amdgcn_s_setprio(1); _Pragma("unroll") for (int m = 0; m < 4; ++m) _Pragma("unroll") for (int n = 0; n < 2; ++n) _Pragma("unroll") for (int k = 0; k < 2; ++k) \
;         acc[ai][bj][m][n] = __builtin_amdgcn_mfma_f32_16x16x32_bf16(Bt[n][k], At[m][k], acc[ai][bj][m][n], 0, 0, 0); __builtin_amdgcn_s_setprio(0); } while (0)
; #define PG8_WAIT_V(n) asm volatile("s_waitcnt vmcnt(" #n ")" ::: "memory")
; #define PG8_WAIT_L(n) asm volatile("s_waitcnt lgkmcnt(" #n ")" ::: "memory")
; #define PG8_BAR __builtin_amdgcn_s_barrier()
; #define PG8_SCHED __builtin_amdgcn_sched_barrier(0)
; template <class Epi, class S_t>
; __device__ __forceinline__ void gemm_phase(LAS unsigned char* lds, int lda, int ldb, const S_t& S, const Epi& E) {
;     ...
;             PG8_BAR; PG8_WAIT_L(0); PG8_MMA(1, 0, At, B0); PG8_BAR; PG8_SCHED;
;             PG8_STAGE(PG8_SB(1, 1), b3 + hstepB, voffB);
;             PG8_WAIT_V(6); PG8_BAR; PG8_MMA(1, 1, At, B1); PG8_BAR;
;     __device__ __forceinline__ void operator()(const f32x4 (&acc)[2][2][4][2], const Unit& u, int wr, int wc, int fr, int fq) const {
;         const int row0 = u.pm * BM + wr * 64 + fr, ch0 = u.pn * HALF + wc * 32 + 8 * fq;
;         float br[8], bi[8], sp[8];
; #pragma unroll
;         for (int q = 0; q < 2; ++q) { const f32x4 a = *(const f32x4*)(brg + ch0 + 4 * q), b = *(const f32x4*)(big + ch0 + 4 * q), c = *(const f32x4*)(spl + ch0 + 4 * q);
; #pragma unroll
;             for (int j = 0; j < 4; ++j) { br[4 * q + j] = a[j]; bi[4 * q + j] = b[j]; sp[4 * q + j] = c[j]; } }
;         u32x4 xraw[2][4];
; #pragma unroll
;         for (int ai = 0; ai < 2; ++ai)
; #pragma unroll
;             for (int m = 0; m < 4; ++m) xraw[ai][m] = *(const u32x4*)(XC + (size_t)(row0 + ai * HALF + m * 16) * LW + ch0);
	s_waitcnt lgkmcnt(0)
	s_setprio 1
	s_waitcnt lgkmcnt(0)
	v_mfma_f32_16x16x32_bf16 v[92:95], v[48:51], v[56:59], v[92:95]
	v_mfma_f32_16x16x32_bf16 v[88:91], v[80:83], v[56:59], v[88:91]
	v_mfma_f32_16x16x32_bf16 v[72:75], v[48:51], v[68:71], v[72:75]
	v_mfma_f32_16x16x32_bf16 v[60:63], v[80:83], v[68:71], v[60:63]
	v_mfma_f32_16x16x32_bf16 v[28:31], v[48:51], v[96:99], v[28:31]
	v_mfma_f32_16x16x32_bf16 v[24:27], v[80:83], v[96:99], v[24:27]
	v_mfma_f32_16x16x32_bf16 v[12:15], v[48:51], v[136:139], v[12:15]
	v_mfma_f32_16x16x32_bf16 v[8:11], v[80:83], v[136:139], v[8:11]
	v_mfma_f32_16x16x32_bf16 v[92:95], v[52:55], v[64:67], v[92:95]
	v_mfma_f32_16x16x32_bf16 v[88:91], v[84:87], v[64:67], v[88:91]
	v_mfma_f32_16x16x32_bf16 v[72:75], v[52:55], v[76:79], v[72:75]
	v_mfma_f32_16x16x32_bf16 v[60:63], v[84:87], v[76:79], v[60:63]
	v_mfma_f32_16x16x32_bf16 v[28:31], v[52:55], v[116:119], v[28:31]
	v_mfma_f32_16x16x32_bf16 v[24:27], v[84:87], v[116:119], v[24:27]
	v_mfma_f32_16x16x32_bf16 v[12:15], v[52:55], v[156:159], v[12:15]
	v_mfma_f32_16x16x32_bf16 v[8:11], v[84:87], v[156:159], v[8:11]
	s_setprio 0
	s_barrier
	s_mov_b32 m0, s1
	global_load_lds_dwordx4 v188, s[68:69]
	s_mov_b32 m0, s0
	s_nop 0
	global_load_lds_dwordx4 v192, s[68:69]
	s_waitcnt vmcnt(6)
	s_barrier
	s_setprio 1
	v_mfma_f32_16x16x32_bf16 v[32:35], v[200:203], v[56:59], v[32:35]
	v_mfma_f32_16x16x32_bf16 v[80:83], v[204:207], v[64:67], v[32:35]
	v_mfma_f32_16x16x32_bf16 v[32:35], v[222:225], v[56:59], v[36:39]
	v_mfma_f32_16x16x32_bf16 v[84:87], v[234:237], v[64:67], v[32:35]
	v_mfma_f32_16x16x32_bf16 v[32:35], v[200:203], v[68:71], v[40:43]
	v_mfma_f32_16x16x32_bf16 v[40:43], v[204:207], v[76:79], v[32:35]
	v_mfma_f32_16x16x32_bf16 v[32:35], v[222:225], v[68:71], v[44:47]
	v_mfma_f32_16x16x32_bf16 v[16:19], v[200:203], v[96:99], v[16:19]
	v_mfma_f32_16x16x32_bf16 v[20:23], v[222:225], v[96:99], v[20:23]
	v_mfma_f32_16x16x32_bf16 v[0:3], v[200:203], v[136:139], v[0:3]
	v_mfma_f32_16x16x32_bf16 v[4:7], v[222:225], v[136:139], v[4:7]
	v_mfma_f32_16x16x32_bf16 v[44:47], v[234:237], v[76:79], v[32:35]
	v_mfma_f32_16x16x32_bf16 v[16:19], v[204:207], v[116:119], v[16:19]
	v_mfma_f32_16x16x32_bf16 v[20:23], v[234:237], v[116:119], v[20:23]
	v_mfma_f32_16x16x32_bf16 v[0:3], v[204:207], v[156:159], v[0:3]
	v_mfma_f32_16x16x32_bf16 v[4:7], v[234:237], v[156:159], v[4:7]
	s_setprio 0
	s_movk_i32 s0, 0x100
	s_andn2_b64 vcc, exec, s[66:67]
	s_mov_b64 s[68:69], -1
	s_mov_b64 s[66:67], 0
	s_barrier
	s_cbranch_vccz .LBB0_547
	v_lshl_or_b32 v196, s42, 7, v221
	v_readlane_b32 s68, v254, 49
	v_ashrrev_i32_e32 v197, 31, v196
	v_readlane_b32 s76, v254, 57
	v_readlane_b32 s77, v254, 58
	v_lshlrev_b64 v[32:33], 2, v[196:197]
	v_readlane_b32 s80, v254, 61
	v_readlane_b32 s81, v254, 62
	s_mov_b64 s[24:25], s[76:77]
	s_mov_b64 s[28:29], s[80:81]
	v_lshl_add_u64 v[34:35], s[24:25], 0, v[32:33]
	v_lshl_add_u64 v[48:49], s[28:29], 0, v[32:33]
	v_lshl_add_u64 v[50:51], s[10:11], 0, v[32:33]
	global_load_dwordx4 v[56:59], v[34:35], off offset:16
	global_load_dwordx4 v[68:71], v[34:35], off
	global_load_dwordx4 v[36:39], v[48:49], off offset:16
	s_nop 0
	global_load_dwordx4 v[32:35], v[48:49], off
	global_load_dwordx4 v[52:55], v[50:51], off offset:16
	global_load_dwordx4 v[64:67], v[50:51], off
	v_lshl_add_u32 v224, s5, 8, v215
	v_or_b32_e32 v222, 16, v224
	v_ashrrev_i32_e32 v225, 31, v224
	v_ashrrev_i32_e32 v223, 31, v222
	v_lshl_add_u64 v[48:49], v[196:197], 1, s[8:9]
	v_lshlrev_b64 v[50:51], 12, v[224:225]
	v_lshlrev_b64 v[76:77], 12, v[222:223]
	v_or_b32_e32 v208, 32, v224
	v_or_b32_e32 v206, 48, v224
	v_lshl_add_u64 v[50:51], v[48:49], 0, v[50:51]
	v_lshl_add_u64 v[76:77], v[48:49], 0, v[76:77]
	v_ashrrev_i32_e32 v209, 31, v208
	v_ashrrev_i32_e32 v207, 31, v206
	global_load_dwordx4 v[180:183], v[50:51], off
	global_load_dwordx4 v[176:179], v[76:77], off
	v_lshlrev_b64 v[50:51], 12, v[208:209]
	v_lshlrev_b64 v[76:77], 12, v[206:207]
	v_add_u32_e32 v204, 0x80, v224
	v_add_u32_e32 v202, 0x90, v224
	v_lshl_add_u64 v[50:51], v[48:49], 0, v[50:51]
	v_lshl_add_u64 v[76:77], v[48:49], 0, v[76:77]
	v_ashrrev_i32_e32 v205, 31, v204
	v_ashrrev_i32_e32 v203, 31, v202
	global_load_dwordx4 v[156:159], v[50:51], off
	global_load_dwordx4 v[136:139], v[76:77], off
	v_lshlrev_b64 v[50:51], 12, v[204:205]
	v_lshlrev_b64 v[76:77], 12, v[202:203]
	v_add_u32_e32 v200, 0xa0, v224
	v_add_u32_e32 v198, 0xb0, v224
	v_lshl_add_u64 v[50:51], v[48:49], 0, v[50:51]
	v_lshl_add_u64 v[76:77], v[48:49], 0, v[76:77]
	v_ashrrev_i32_e32 v201, 31, v200
	v_ashrrev_i32_e32 v199, 31, v198
	global_load_dwordx4 v[116:119], v[50:51], off
	global_load_dwordx4 v[96:99], v[76:77], off
	v_lshlrev_b64 v[50:51], 12, v[200:201]
	v_lshlrev_b64 v[76:77], 12, v[198:199]
	v_lshl_add_u64 v[50:51], v[48:49], 0, v[50:51]
	v_lshl_add_u64 v[48:49], v[48:49], 0, v[76:77]
	global_load_dwordx4 v[76:79], v[50:51], off
	s_nop 0
	global_load_dwordx4 v[48:51], v[48:49], off
	v_readlane_b32 s69, v254, 50
	v_readlane_b32 s70, v254, 51
	v_readlane_b32 s71, v254, 52
	v_readlane_b32 s72, v254, 53
	v_readlane_b32 s73, v254, 54
	v_readlane_b32 s74, v254, 55
	v_readlane_b32 s75, v254, 56
	v_readlane_b32 s78, v254, 59
	v_readlane_b32 s79, v254, 60
	v_readlane_b32 s82, v254, 63
	v_readlane_b32 s83, v255, 0
	s_waitcnt vmcnt(0)
; __device__ __forceinline__ float sigmoidf_(float x) { return __builtin_amdgcn_rcpf(1.0f + __expf(-x)); }
;     __device__ __forceinline__ void operator()(const f32x4 (&acc)[2][2][4][2], const Unit& u, int wr, int wc, int fr, int fq) const {
;     ...
;                     for (int j = 0; j < 4; ++j) { const int e = 4 * n + j;
;                         const float r = sigmoidf_(acc[ai][0][m][n][j] + br[e]), ig = sigmoidf_(acc[ai][1][m][n][j] + bi[e]);
;                         const float l = -8.0f * r * sp[e]; la[e] = l;
;                         const float x2 = 2.0f * l;
;                         const float om = x2 > -0.03125f ? -x2 * (1.0f + x2 * (0.5f + x2 * (0.16666667f + x2 * 0.041666668f))) : 1.0f - __expf(x2);
;                         uu[e] = __builtin_amdgcn_sqrtf(om) * (ig * xc[e]); }
	v_add_f32_e32 v172, v172, v68
	v_mul_f32_e32 v172, 0xbfb8aa3b, v172
	v_exp_f32_e32 v172, v172
	s_nop 0
	v_add_f32_e32 v172, 1.0, v172
	v_rcp_f32_e32 v172, v172
	s_nop 0
	v_mul_f32_e32 v172, 0xc1000000, v172
	v_mul_f32_e32 v172, v64, v172
	v_add_f32_e32 v231, v172, v172
	v_cmp_nlt_f32_e32 vcc, s4, v231
	s_and_saveexec_b64 s[0:1], vcc
	s_xor_b64 s[0:1], exec, s[0:1]
	v_mul_f32_e32 v230, 0x3fb8aa3b, v231
	v_exp_f32_e32 v230, v230
	s_nop 0
	v_sub_f32_e32 v230, 1.0, v230
	s_andn2_saveexec_b64 s[0:1], s[0:1]
	v_fmamk_f32 v230, v231, 0x3d2aaaab, v229
	v_fma_f32 v230, v231, v230, 0.5
	v_fma_f32 v230, v231, v230, 1.0
	v_mul_f32_e64 v230, v230, -v231
	s_or_b64 exec, exec, s[0:1]
	v_add_f32_e32 v173, v173, v69
	v_mul_f32_e32 v173, 0xbfb8aa3b, v173
	v_exp_f32_e32 v173, v173
	s_nop 0
	v_add_f32_e32 v173, 1.0, v173
	v_rcp_f32_e32 v173, v173
	s_nop 0
	v_mul_f32_e32 v173, 0xc1000000, v173
	v_mul_f32_e32 v173, v65, v173
	v_add_f32_e32 v232, v173, v173
	v_cmp_nlt_f32_e32 vcc, s4, v232
	s_and_saveexec_b64 s[0:1], vcc
	s_xor_b64 s[0:1], exec, s[0:1]
	v_mul_f32_e32 v231, 0x3fb8aa3b, v232
	v_exp_f32_e32 v231, v231
	s_nop 0
	v_sub_f32_e32 v231, 1.0, v231
	s_andn2_saveexec_b64 s[0:1], s[0:1]
	v_fmamk_f32 v231, v232, 0x3d2aaaab, v229
	v_fma_f32 v231, v232, v231, 0.5
	v_fma_f32 v231, v232, v231, 1.0
	v_mul_f32_e64 v231, v231, -v232
	s_or_b64 exec, exec, s[0:1]
	v_add_f32_e32 v174, v174, v70
	v_mul_f32_e32 v174, 0xbfb8aa3b, v174
	v_exp_f32_e32 v174, v174
	s_nop 0
	v_add_f32_e32 v174, 1.0, v174
	v_rcp_f32_e32 v174, v174
	s_nop 0
	v_mul_f32_e32 v174, 0xc1000000, v174
	v_mul_f32_e32 v174, v66, v174
	v_add_f32_e32 v234, v174, v174
	v_cmp_nlt_f32_e32 vcc, s4, v234
	s_and_saveexec_b64 s[0:1], vcc
	s_xor_b64 s[0:1], exec, s[0:1]
	v_mul_f32_e32 v232, 0x3fb8aa3b, v234
	v_exp_f32_e32 v232, v232
	s_nop 0
	v_sub_f32_e32 v232, 1.0, v232
	s_andn2_saveexec_b64 s[0:1], s[0:1]
	v_fmamk_f32 v232, v234, 0x3d2aaaab, v229
	v_fma_f32 v232, v234, v232, 0.5
	v_fma_f32 v232, v234, v232, 1.0
	v_mul_f32_e64 v232, v232, -v234
	s_or_b64 exec, exec, s[0:1]
	v_add_f32_e32 v175, v175, v71
	v_mul_f32_e32 v175, 0xbfb8aa3b, v175
	v_exp_f32_e32 v175, v175
	s_nop 0
	v_add_f32_e32 v175, 1.0, v175
	v_rcp_f32_e32 v175, v175
	s_nop 0
	v_mul_f32_e32 v175, 0xc1000000, v175
	v_mul_f32_e32 v175, v67, v175
	v_add_f32_e32 v235, v175, v175
	v_cmp_nlt_f32_e32 vcc, s4, v235
	s_and_saveexec_b64 s[0:1], vcc
	s_xor_b64 s[0:1], exec, s[0:1]
	v_mul_f32_e32 v234, 0x3fb8aa3b, v235
	v_exp_f32_e32 v234, v234
	s_nop 0
	v_sub_f32_e32 v234, 1.0, v234
	s_andn2_saveexec_b64 s[0:1], s[0:1]
	v_fmamk_f32 v234, v235, 0x3d2aaaab, v229
	v_fma_f32 v234, v235, v234, 0.5
	v_fma_f32 v234, v235, v234, 1.0
	v_mul_f32_e64 v234, v234, -v235
	s_or_b64 exec, exec, s[0:1]
	v_add_f32_e32 v168, v168, v56
	v_mul_f32_e32 v168, 0xbfb8aa3b, v168
	v_exp_f32_e32 v168, v168
	s_nop 0
	v_add_f32_e32 v168, 1.0, v168
	v_rcp_f32_e32 v168, v168
	s_nop 0
	v_mul_f32_e32 v168, 0xc1000000, v168
	v_mul_f32_e32 v168, v52, v168
	v_add_f32_e32 v236, v168, v168
	v_cmp_nlt_f32_e32 vcc, s4, v236
	s_and_saveexec_b64 s[0:1], vcc
	s_xor_b64 s[0:1], exec, s[0:1]
	v_mul_f32_e32 v235, 0x3fb8aa3b, v236
	v_exp_f32_e32 v235, v235
	s_nop 0
	v_sub_f32_e32 v235, 1.0, v235
	s_andn2_saveexec_b64 s[0:1], s[0:1]
	v_fmamk_f32 v235, v236, 0x3d2aaaab, v229
	v_fma_f32 v235, v236, v235, 0.5
	v_fma_f32 v235, v236, v235, 1.0
	v_mul_f32_e64 v235, v235, -v236
	s_or_b64 exec, exec, s[0:1]
	v_add_f32_e32 v169, v169, v57
	v_mul_f32_e32 v169, 0xbfb8aa3b, v169
	v_exp_f32_e32 v169, v169
	s_nop 0
	v_add_f32_e32 v169, 1.0, v169
	v_rcp_f32_e32 v169, v169
	s_nop 0
	v_mul_f32_e32 v169, 0xc1000000, v169
	v_mul_f32_e32 v169, v53, v169
	v_add_f32_e32 v237, v169, v169
	v_cmp_nlt_f32_e32 vcc, s4, v237
	s_and_saveexec_b64 s[0:1], vcc
	s_xor_b64 s[0:1], exec, s[0:1]
	v_mul_f32_e32 v236, 0x3fb8aa3b, v237
	v_exp_f32_e32 v236, v236
	s_nop 0
	v_sub_f32_e32 v236, 1.0, v236
	s_andn2_saveexec_b64 s[0:1], s[0:1]
	v_fmamk_f32 v236, v237, 0x3d2aaaab, v229
	v_fma_f32 v236, v237, v236, 0.5
	v_fma_f32 v236, v237, v236, 1.0
	v_mul_f32_e64 v236, v236, -v237
	s_or_b64 exec, exec, s[0:1]
	v_add_f32_e32 v170, v170, v58
	v_mul_f32_e32 v170, 0xbfb8aa3b, v170
	v_exp_f32_e32 v170, v170
	s_nop 0
	v_add_f32_e32 v170, 1.0, v170
	v_rcp_f32_e32 v170, v170
	s_nop 0
	v_mul_f32_e32 v170, 0xc1000000, v170
	v_mul_f32_e32 v170, v54, v170
	v_add_f32_e32 v237, v170, v170
	v_cmp_nlt_f32_e32 vcc, s4, v237
	s_and_saveexec_b64 s[0:1], vcc
	s_xor_b64 s[0:1], exec, s[0:1]
	v_mul_f32_e32 v237, 0x3fb8aa3b, v237
	v_exp_f32_e32 v237, v237
	s_nop 0
	v_sub_f32_e32 v238, 1.0, v237
	s_andn2_saveexec_b64 s[0:1], s[0:1]
	v_fmamk_f32 v238, v237, 0x3d2aaaab, v229
	v_fma_f32 v238, v237, v238, 0.5
	v_fma_f32 v238, v237, v238, 1.0
	v_mul_f32_e64 v238, v238, -v237
	s_or_b64 exec, exec, s[0:1]
	v_add_f32_e32 v171, v171, v59
	v_mul_f32_e32 v171, 0xbfb8aa3b, v171
	v_exp_f32_e32 v171, v171
	s_nop 0
	v_add_f32_e32 v171, 1.0, v171
	v_rcp_f32_e32 v171, v171
	s_nop 0
	v_mul_f32_e32 v171, 0xc1000000, v171
	v_mul_f32_e32 v171, v55, v171
	v_add_f32_e32 v239, v171, v171
	v_cmp_nlt_f32_e32 vcc, s4, v239
	s_and_saveexec_b64 s[0:1], vcc
	s_xor_b64 s[0:1], exec, s[0:1]
	v_mul_f32_e32 v237, 0x3fb8aa3b, v239
	v_exp_f32_e32 v237, v237
	s_nop 0
	v_sub_f32_e32 v237, 1.0, v237
	s_andn2_saveexec_b64 s[0:1], s[0:1]
	v_fmamk_f32 v237, v239, 0x3d2aaaab, v229
	v_fma_f32 v237, v239, v237, 0.5
	v_fma_f32 v237, v239, v237, 1.0
	v_mul_f32_e64 v237, v237, -v239
	s_or_b64 exec, exec, s[0:1]
	v_add_f32_e32 v166, v166, v38
	v_mul_f32_e32 v166, 0xbfb8aa3b, v166
	v_exp_f32_e32 v166, v166
	v_add_f32_e32 v164, v164, v36
	v_mul_f32_e32 v164, 0xbfb8aa3b, v164
	v_exp_f32_e32 v164, v164
	v_add_f32_e32 v163, v163, v35
; __device__ __forceinline__ unsigned pk2(float lo, float hi) { unsigned r; asm("v_cvt_pk_bf16_f32 %0, %1, %2" : "=v"(r) : "v"(lo), "v"(hi)); return r; }
; __device__ __forceinline__ float sigmoidf_(float x) { return __builtin_amdgcn_rcpf(1.0f + __expf(-x)); }
;     __device__ __forceinline__ void operator()(const f32x4 (&acc)[2][2][4][2], const Unit& u, int wr, int wc, int fr, int fq) const {
;     ...
;                     for (int j = 0; j < 4; ++j) { const int e = 4 * n + j;
;                         const float r = sigmoidf_(acc[ai][0][m][n][j] + br[e]), ig = sigmoidf_(acc[ai][1][m][n][j] + bi[e]);
;                         const float l = -8.0f * r * sp[e]; la[e] = l;
;                         const float x2 = 2.0f * l;
;                         const float om = x2 > -0.03125f ? -x2 * (1.0f + x2 * (0.5f + x2 * (0.16666667f + x2 * 0.041666668f))) : 1.0f - __expf(x2);
;                         uu[e] = __builtin_amdgcn_sqrtf(om) * (ig * xc[e]); }
;                 u32x4 w0, w1; w0.x = pk2(la[0], uu[0]); w0.y = pk2(la[1], uu[1]); w0.z = pk2(la[2], uu[2]); w0.w = pk2(la[3], uu[3]);
;                 w1.x = pk2(la[4], uu[4]); w1.y = pk2(la[5], uu[5]); w1.z = pk2(la[6], uu[6]); w1.w = pk2(la[7], uu[7]);
;                 *(u32x4*)(LU + off) = w0; *(u32x4*)(LU + off + 4) = w1; }
	v_add_f32_e32 v166, 1.0, v166
	v_mul_f32_e32 v163, 0xbfb8aa3b, v163
	v_rcp_f32_e32 v166, v166
	v_exp_f32_e32 v163, v163
	v_sqrt_f32_e32 v238, v238
	v_add_f32_e32 v164, 1.0, v164
	v_add_f32_e32 v162, v162, v34
	v_rcp_f32_e32 v164, v164
	v_mul_f32_e32 v162, 0xbfb8aa3b, v162
	v_add_f32_e32 v161, v161, v33
	v_lshlrev_b32_e32 v239, 16, v183
	v_exp_f32_e32 v162, v162
	v_mul_f32_e32 v161, 0xbfb8aa3b, v161
	v_add_f32_e32 v165, v165, v37
	v_mul_f32_e32 v166, v166, v239
	v_add_f32_e32 v163, 1.0, v163
	v_exp_f32_e32 v161, v161
	v_add_f32_e32 v160, v160, v32
	v_mul_f32_e32 v165, 0xbfb8aa3b, v165
	v_mul_f32_e32 v166, v166, v238
	v_and_b32_e32 v238, 0xffff0000, v182
	v_lshlrev_b32_e32 v182, 16, v182
	v_rcp_f32_e32 v163, v163
	v_mul_f32_e32 v160, 0xbfb8aa3b, v160
	v_exp_f32_e32 v165, v165
	v_mul_f32_e32 v164, v164, v182
	v_sqrt_f32_e32 v182, v234
	v_exp_f32_e32 v160, v160
	v_add_f32_e32 v167, v167, v39
	v_add_f32_e32 v162, 1.0, v162
	v_add_f32_e32 v152, v152, v68
	v_mul_f32_e32 v167, 0xbfb8aa3b, v167
	v_and_b32_e32 v234, 0xffff0000, v181
	v_rcp_f32_e32 v162, v162
	v_add_f32_e32 v161, 1.0, v161
	v_mul_f32_e32 v152, 0xbfb8aa3b, v152
	v_exp_f32_e32 v167, v167
	v_mul_f32_e32 v163, v163, v234
	v_rcp_f32_e32 v161, v161
	v_exp_f32_e32 v152, v152
	v_add_f32_e32 v165, 1.0, v165
	v_mul_f32_e32 v163, v163, v182
	v_sqrt_f32_e32 v182, v232
	v_add_f32_e32 v160, 1.0, v160
	v_rcp_f32_e32 v165, v165
	v_lshlrev_b32_e32 v181, 16, v181
	v_rcp_f32_e32 v160, v160
	v_sqrt_f32_e32 v236, v236
	v_sqrt_f32_e32 v235, v235
	v_mul_f32_e32 v162, v162, v181
	v_and_b32_e32 v181, 0xffff0000, v180
	v_add_f32_e32 v167, 1.0, v167
	v_mul_f32_e32 v161, v161, v181
	v_sqrt_f32_e32 v181, v230
	v_add_f32_e32 v152, 1.0, v152
	v_rcp_f32_e32 v167, v167
	v_mul_f32_e32 v162, v162, v182
	v_sqrt_f32_e32 v182, v231
	v_lshlrev_b32_e32 v180, 16, v180
	v_rcp_f32_e32 v152, v152
	v_mul_f32_e32 v165, v165, v238
	v_mul_f32_e32 v160, v160, v180
	v_sqrt_f32_e32 v180, v237
	v_mul_f32_e32 v165, v165, v236
	v_mul_f32_e32 v164, v164, v235
	v_mul_f32_e32 v160, v160, v181
	v_and_b32_e32 v181, 0xffff0000, v183
	v_cvt_pk_bf16_f32 v164, v168, v164
	v_cvt_pk_bf16_f32 v165, v169, v165
	v_lshlrev_b64 v[168:169], 13, v[224:225]
	v_mul_f32_e32 v161, v161, v182
	v_mul_f32_e32 v167, v167, v181
	v_lshl_add_u64 v[168:169], s[44:45], 0, v[168:169]
	v_mul_f32_e32 v152, 0xc1000000, v152
	v_mul_f32_e32 v167, v167, v180
	v_cvt_pk_bf16_f32 v160, v172, v160
	v_cvt_pk_bf16_f32 v161, v173, v161
	v_cvt_pk_bf16_f32 v162, v174, v162
	v_cvt_pk_bf16_f32 v163, v175, v163
	v_lshl_add_u64 v[168:169], v[196:197], 2, v[168:169]
	v_mul_f32_e32 v152, v64, v152
	v_cvt_pk_bf16_f32 v166, v170, v166
	v_cvt_pk_bf16_f32 v167, v171, v167
	global_store_dwordx4 v[168:169], v[160:163], off
	global_store_dwordx4 v[168:169], v[164:167], off offset:16
	s_nop 0
	v_add_f32_e32 v161, v152, v152
	v_cmp_nlt_f32_e32 vcc, s4, v161
	s_and_saveexec_b64 s[0:1], vcc
	s_xor_b64 s[0:1], exec, s[0:1]
	v_mul_f32_e32 v160, 0x3fb8aa3b, v161
	v_exp_f32_e32 v160, v160
	s_nop 0
	v_sub_f32_e32 v160, 1.0, v160
	s_andn2_saveexec_b64 s[0:1], s[0:1]
	v_fmamk_f32 v160, v161, 0x3d2aaaab, v229
	v_fma_f32 v160, v161, v160, 0.5
	v_fma_f32 v160, v161, v160, 1.0
	v_mul_f32_e64 v160, v160, -v161
	s_or_b64 exec, exec, s[0:1]
	v_add_f32_e32 v153, v153, v69
	v_mul_f32_e32 v153, 0xbfb8aa3b, v153
	v_exp_f32_e32 v153, v153
	s_nop 0
	v_add_f32_e32 v153, 1.0, v153
	v_rcp_f32_e32 v153, v153
	s_nop 0
	v_mul_f32_e32 v153, 0xc1000000, v153
	v_mul_f32_e32 v153, v65, v153
	v_add_f32_e32 v162, v153, v153
	v_cmp_nlt_f32_e32 vcc, s4, v162
	s_and_saveexec_b64 s[0:1], vcc
	s_xor_b64 s[0:1], exec, s[0:1]
	v_mul_f32_e32 v161, 0x3fb8aa3b, v162
	v_exp_f32_e32 v161, v161
	s_nop 0
	v_sub_f32_e32 v161, 1.0, v161
	s_andn2_saveexec_b64 s[0:1], s[0:1]
	v_fmamk_f32 v161, v162, 0x3d2aaaab, v229
	v_fma_f32 v161, v162, v161, 0.5
	v_fma_f32 v161, v162, v161, 1.0
	v_mul_f32_e64 v161, v161, -v162
	s_or_b64 exec, exec, s[0:1]
	v_add_f32_e32 v154, v154, v70
	v_mul_f32_e32 v154, 0xbfb8aa3b, v154
	v_exp_f32_e32 v154, v154
	s_nop 0
	v_add_f32_e32 v154, 1.0, v154
	v_rcp_f32_e32 v154, v154
	s_nop 0
	v_mul_f32_e32 v154, 0xc1000000, v154
	v_mul_f32_e32 v154, v66, v154
	v_add_f32_e32 v163, v154, v154
	v_cmp_nlt_f32_e32 vcc, s4, v163
	s_and_saveexec_b64 s[0:1], vcc
	s_xor_b64 s[0:1], exec, s[0:1]
	v_mul_f32_e32 v162, 0x3fb8aa3b, v163
	v_exp_f32_e32 v162, v162
	s_nop 0
	v_sub_f32_e32 v162, 1.0, v162
	s_andn2_saveexec_b64 s[0:1], s[0:1]
	v_fmamk_f32 v162, v163, 0x3d2aaaab, v229
	v_fma_f32 v162, v163, v162, 0.5
	v_fma_f32 v162, v163, v162, 1.0
	v_mul_f32_e64 v162, v162, -v163
	s_or_b64 exec, exec, s[0:1]
	v_add_f32_e32 v155, v155, v71
	v_mul_f32_e32 v155, 0xbfb8aa3b, v155
	v_exp_f32_e32 v155, v155
	s_nop 0
	v_add_f32_e32 v155, 1.0, v155
	v_rcp_f32_e32 v155, v155
	s_nop 0
	v_mul_f32_e32 v155, 0xc1000000, v155
	v_mul_f32_e32 v155, v67, v155
	v_add_f32_e32 v164, v155, v155
	v_cmp_nlt_f32_e32 vcc, s4, v164
	s_and_saveexec_b64 s[0:1], vcc
	s_xor_b64 s[0:1], exec, s[0:1]
	v_mul_f32_e32 v163, 0x3fb8aa3b, v164
	v_exp_f32_e32 v163, v163
	s_nop 0
	v_sub_f32_e32 v163, 1.0, v163
	s_andn2_saveexec_b64 s[0:1], s[0:1]
	v_fmamk_f32 v163, v164, 0x3d2aaaab, v229
	v_fma_f32 v163, v164, v163, 0.5
	v_fma_f32 v163, v164, v163, 1.0
	v_mul_f32_e64 v163, v163, -v164
	s_or_b64 exec, exec, s[0:1]
	v_add_f32_e32 v148, v148, v56
	v_mul_f32_e32 v148, 0xbfb8aa3b, v148
	v_exp_f32_e32 v148, v148
	s_nop 0
	v_add_f32_e32 v148, 1.0, v148
	v_rcp_f32_e32 v148, v148
	s_nop 0
	v_mul_f32_e32 v148, 0xc1000000, v148
	v_mul_f32_e32 v148, v52, v148
	v_add_f32_e32 v165, v148, v148
	v_cmp_nlt_f32_e32 vcc, s4, v165
	s_and_saveexec_b64 s[0:1], vcc
	s_xor_b64 s[0:1], exec, s[0:1]
; __device__ __forceinline__ unsigned pk2(float lo, float hi) { unsigned r; asm("v_cvt_pk_bf16_f32 %0, %1, %2" : "=v"(r) : "v"(lo), "v"(hi)); return r; }
; __device__ __forceinline__ float sigmoidf_(float x) { return __builtin_amdgcn_rcpf(1.0f + __expf(-x)); }
;     __device__ __forceinline__ void operator()(const f32x4 (&acc)[2][2][4][2], const Unit& u, int wr, int wc, int fr, int fq) const {
;     ...
;                     for (int j = 0; j < 4; ++j) { const int e = 4 * n + j;
;                         const float r = sigmoidf_(acc[ai][0][m][n][j] + br[e]), ig = sigmoidf_(acc[ai][1][m][n][j] + bi[e]);
;                         const float l = -8.0f * r * sp[e]; la[e] = l;
;                         const float x2 = 2.0f * l;
;                         const float om = x2 > -0.03125f ? -x2 * (1.0f + x2 * (0.5f + x2 * (0.16666667f + x2 * 0.041666668f))) : 1.0f - __expf(x2);
;                         uu[e] = __builtin_amdgcn_sqrtf(om) * (ig * xc[e]); }
;                 u32x4 w0, w1; w0.x = pk2(la[0], uu[0]); w0.y = pk2(la[1], uu[1]); w0.z = pk2(la[2], uu[2]); w0.w = pk2(la[3], uu[3]);
;                 w1.x = pk2(la[4], uu[4]); w1.y = pk2(la[5], uu[5]); w1.z = pk2(la[6], uu[6]); w1.w = pk2(la[7], uu[7]);
;                 *(u32x4*)(LU + off) = w0; *(u32x4*)(LU + off + 4) = w1; }
	v_mul_f32_e32 v164, 0x3fb8aa3b, v165
	v_exp_f32_e32 v164, v164
	s_nop 0
	v_sub_f32_e32 v164, 1.0, v164
	s_andn2_saveexec_b64 s[0:1], s[0:1]
	v_fmamk_f32 v164, v165, 0x3d2aaaab, v229
	v_fma_f32 v164, v165, v164, 0.5
	v_fma_f32 v164, v165, v164, 1.0
	v_mul_f32_e64 v164, v164, -v165
	s_or_b64 exec, exec, s[0:1]
	v_add_f32_e32 v149, v149, v57
	v_mul_f32_e32 v149, 0xbfb8aa3b, v149
	v_exp_f32_e32 v149, v149
	s_nop 0
	v_add_f32_e32 v149, 1.0, v149
	v_rcp_f32_e32 v149, v149
	s_nop 0
	v_mul_f32_e32 v149, 0xc1000000, v149
	v_mul_f32_e32 v149, v53, v149
	v_add_f32_e32 v166, v149, v149
	v_cmp_nlt_f32_e32 vcc, s4, v166
	s_and_saveexec_b64 s[0:1], vcc
	s_xor_b64 s[0:1], exec, s[0:1]
	v_mul_f32_e32 v165, 0x3fb8aa3b, v166
	v_exp_f32_e32 v165, v165
	s_nop 0
	v_sub_f32_e32 v165, 1.0, v165
	s_andn2_saveexec_b64 s[0:1], s[0:1]
	v_fmamk_f32 v165, v166, 0x3d2aaaab, v229
	v_fma_f32 v165, v166, v165, 0.5
	v_fma_f32 v165, v166, v165, 1.0
	v_mul_f32_e64 v165, v165, -v166
	s_or_b64 exec, exec, s[0:1]
	v_add_f32_e32 v150, v150, v58
	v_mul_f32_e32 v150, 0xbfb8aa3b, v150
	v_exp_f32_e32 v150, v150
	s_nop 0
	v_add_f32_e32 v150, 1.0, v150
	v_rcp_f32_e32 v150, v150
	s_nop 0
	v_mul_f32_e32 v150, 0xc1000000, v150
	v_mul_f32_e32 v150, v54, v150
	v_add_f32_e32 v166, v150, v150
	v_cmp_nlt_f32_e32 vcc, s4, v166
	s_and_saveexec_b64 s[0:1], vcc
	s_xor_b64 s[0:1], exec, s[0:1]
	v_mul_f32_e32 v166, 0x3fb8aa3b, v166
	v_exp_f32_e32 v166, v166
	s_nop 0
	v_sub_f32_e32 v167, 1.0, v166
	s_andn2_saveexec_b64 s[0:1], s[0:1]
	v_fmamk_f32 v167, v166, 0x3d2aaaab, v229
	v_fma_f32 v167, v166, v167, 0.5
	v_fma_f32 v167, v166, v167, 1.0
	v_mul_f32_e64 v167, v167, -v166
	s_or_b64 exec, exec, s[0:1]
	v_add_f32_e32 v151, v151, v59
	v_mul_f32_e32 v151, 0xbfb8aa3b, v151
	v_exp_f32_e32 v151, v151
	s_nop 0
	v_add_f32_e32 v151, 1.0, v151
	v_rcp_f32_e32 v151, v151
	s_nop 0
	v_mul_f32_e32 v151, 0xc1000000, v151
	v_mul_f32_e32 v151, v55, v151
	v_add_f32_e32 v168, v151, v151
	v_cmp_nlt_f32_e32 vcc, s4, v168
	s_and_saveexec_b64 s[0:1], vcc
	s_xor_b64 s[0:1], exec, s[0:1]
	v_mul_f32_e32 v166, 0x3fb8aa3b, v168
	v_exp_f32_e32 v166, v166
	s_nop 0
	v_sub_f32_e32 v166, 1.0, v166
	s_andn2_saveexec_b64 s[0:1], s[0:1]
	v_fmamk_f32 v166, v168, 0x3d2aaaab, v229
	v_fma_f32 v166, v168, v166, 0.5
	v_fma_f32 v166, v168, v166, 1.0
	v_mul_f32_e64 v166, v166, -v168
	s_or_b64 exec, exec, s[0:1]
	v_add_f32_e32 v146, v146, v38
	v_mul_f32_e32 v146, 0xbfb8aa3b, v146
	v_exp_f32_e32 v146, v146
	v_add_f32_e32 v145, v145, v37
	v_mul_f32_e32 v145, 0xbfb8aa3b, v145
	v_exp_f32_e32 v145, v145
	v_add_f32_e32 v144, v144, v36
	v_mul_f32_e32 v144, 0xbfb8aa3b, v144
	v_add_f32_e32 v146, 1.0, v146
	v_exp_f32_e32 v144, v144
	v_add_f32_e32 v143, v143, v35
	v_rcp_f32_e32 v146, v146
	v_mul_f32_e32 v143, 0xbfb8aa3b, v143
	v_sqrt_f32_e32 v167, v167
	v_add_f32_e32 v145, 1.0, v145
	v_exp_f32_e32 v143, v143
	v_add_f32_e32 v142, v142, v34
	v_rcp_f32_e32 v145, v145
	v_mul_f32_e32 v142, 0xbfb8aa3b, v142
	v_lshlrev_b32_e32 v168, 16, v179
	v_sqrt_f32_e32 v165, v165
	v_add_f32_e32 v144, 1.0, v144
	v_exp_f32_e32 v142, v142
	v_add_f32_e32 v141, v141, v33
	v_mul_f32_e32 v146, v146, v168
	v_rcp_f32_e32 v144, v144
	v_mul_f32_e32 v141, 0xbfb8aa3b, v141
	v_mul_f32_e32 v146, v146, v167
	v_and_b32_e32 v167, 0xffff0000, v178
	v_sqrt_f32_e32 v164, v164
	v_add_f32_e32 v143, 1.0, v143
	v_exp_f32_e32 v141, v141
	v_add_f32_e32 v140, v140, v32
	v_mul_f32_e32 v145, v145, v167
	v_rcp_f32_e32 v143, v143
	v_mul_f32_e32 v140, 0xbfb8aa3b, v140
	v_mul_f32_e32 v145, v145, v165
	v_lshlrev_b32_e32 v165, 16, v178
	v_sqrt_f32_e32 v163, v163
	v_add_f32_e32 v142, 1.0, v142
	v_exp_f32_e32 v140, v140
	v_add_f32_e32 v147, v147, v39
	v_mul_f32_e32 v144, v144, v165
	v_rcp_f32_e32 v142, v142
	v_add_f32_e32 v132, v132, v68
	v_mul_f32_e32 v147, 0xbfb8aa3b, v147
	v_mul_f32_e32 v144, v144, v164
	v_and_b32_e32 v164, 0xffff0000, v177
	v_sqrt_f32_e32 v162, v162
	v_add_f32_e32 v141, 1.0, v141
	v_mul_f32_e32 v132, 0xbfb8aa3b, v132
	v_exp_f32_e32 v147, v147
	v_mul_f32_e32 v143, v143, v164
	v_rcp_f32_e32 v141, v141
	v_exp_f32_e32 v132, v132
	v_mul_f32_e32 v143, v143, v163
	v_lshlrev_b32_e32 v163, 16, v177
	v_sqrt_f32_e32 v161, v161
	v_add_f32_e32 v140, 1.0, v140
	v_mul_f32_e32 v142, v142, v163
	v_rcp_f32_e32 v140, v140
	v_mul_f32_e32 v142, v142, v162
	v_and_b32_e32 v162, 0xffff0000, v176
	v_add_f32_e32 v147, 1.0, v147
	v_mul_f32_e32 v141, v141, v162
	v_sqrt_f32_e32 v160, v160
	v_add_f32_e32 v132, 1.0, v132
	v_rcp_f32_e32 v147, v147
	v_mul_f32_e32 v141, v141, v161
	v_lshlrev_b32_e32 v161, 16, v176
	v_rcp_f32_e32 v132, v132
	v_mul_f32_e32 v140, v140, v161
	v_sqrt_f32_e32 v161, v166
	v_mul_f32_e32 v140, v140, v160
	v_and_b32_e32 v160, 0xffff0000, v179
	v_cvt_pk_bf16_f32 v144, v148, v144
	v_cvt_pk_bf16_f32 v145, v149, v145
	v_lshlrev_b64 v[148:149], 13, v[222:223]
	v_mul_f32_e32 v147, v147, v160
	v_lshl_add_u64 v[148:149], s[44:45], 0, v[148:149]
	v_mul_f32_e32 v132, 0xc1000000, v132
	v_mul_f32_e32 v147, v147, v161
	v_cvt_pk_bf16_f32 v140, v152, v140
	v_cvt_pk_bf16_f32 v141, v153, v141
	v_cvt_pk_bf16_f32 v142, v154, v142
	v_cvt_pk_bf16_f32 v143, v155, v143
	v_lshl_add_u64 v[148:149], v[196:197], 2, v[148:149]
	v_mul_f32_e32 v132, v64, v132
	v_cvt_pk_bf16_f32 v146, v150, v146
	v_cvt_pk_bf16_f32 v147, v151, v147
	global_store_dwordx4 v[148:149], v[140:143], off
	global_store_dwordx4 v[148:149], v[144:147], off offset:16
	s_nop 0
	v_add_f32_e32 v141, v132, v132
	v_cmp_nlt_f32_e32 vcc, s4, v141
	s_and_saveexec_b64 s[0:1], vcc
	s_xor_b64 s[0:1], exec, s[0:1]
	v_mul_f32_e32 v140, 0x3fb8aa3b, v141
	v_exp_f32_e32 v140, v140
	s_nop 0
	v_sub_f32_e32 v140, 1.0, v140
	s_andn2_saveexec_b64 s[0:1], s[0:1]
; __device__ __forceinline__ unsigned pk2(float lo, float hi) { unsigned r; asm("v_cvt_pk_bf16_f32 %0, %1, %2" : "=v"(r) : "v"(lo), "v"(hi)); return r; }
; __device__ __forceinline__ float sigmoidf_(float x) { return __builtin_amdgcn_rcpf(1.0f + __expf(-x)); }
;     __device__ __forceinline__ void operator()(const f32x4 (&acc)[2][2][4][2], const Unit& u, int wr, int wc, int fr, int fq) const {
;     ...
;                     for (int j = 0; j < 4; ++j) { const int e = 4 * n + j;
;                         const float r = sigmoidf_(acc[ai][0][m][n][j] + br[e]), ig = sigmoidf_(acc[ai][1][m][n][j] + bi[e]);
;                         const float l = -8.0f * r * sp[e]; la[e] = l;
;                         const float x2 = 2.0f * l;
;                         const float om = x2 > -0.03125f ? -x2 * (1.0f + x2 * (0.5f + x2 * (0.16666667f + x2 * 0.041666668f))) : 1.0f - __expf(x2);
;                         uu[e] = __builtin_amdgcn_sqrtf(om) * (ig * xc[e]); }
;                 u32x4 w0, w1; w0.x = pk2(la[0], uu[0]); w0.y = pk2(la[1], uu[1]); w0.z = pk2(la[2], uu[2]); w0.w = pk2(la[3], uu[3]);
;                 w1.x = pk2(la[4], uu[4]); w1.y = pk2(la[5], uu[5]); w1.z = pk2(la[6], uu[6]); w1.w = pk2(la[7], uu[7]);
;                 *(u32x4*)(LU + off) = w0; *(u32x4*)(LU + off + 4) = w1; }
	v_fmamk_f32 v140, v141, 0x3d2aaaab, v229
	v_fma_f32 v140, v141, v140, 0.5
	v_fma_f32 v140, v141, v140, 1.0
	v_mul_f32_e64 v140, v140, -v141
	s_or_b64 exec, exec, s[0:1]
	v_add_f32_e32 v133, v133, v69
	v_mul_f32_e32 v133, 0xbfb8aa3b, v133
	v_exp_f32_e32 v133, v133
	s_nop 0
	v_add_f32_e32 v133, 1.0, v133
	v_rcp_f32_e32 v133, v133
	s_nop 0
	v_mul_f32_e32 v133, 0xc1000000, v133
	v_mul_f32_e32 v133, v65, v133
	v_add_f32_e32 v142, v133, v133
	v_cmp_nlt_f32_e32 vcc, s4, v142
	s_and_saveexec_b64 s[0:1], vcc
	s_xor_b64 s[0:1], exec, s[0:1]
	v_mul_f32_e32 v141, 0x3fb8aa3b, v142
	v_exp_f32_e32 v141, v141
	s_nop 0
	v_sub_f32_e32 v141, 1.0, v141
	s_andn2_saveexec_b64 s[0:1], s[0:1]
	v_fmamk_f32 v141, v142, 0x3d2aaaab, v229
	v_fma_f32 v141, v142, v141, 0.5
	v_fma_f32 v141, v142, v141, 1.0
	v_mul_f32_e64 v141, v141, -v142
	s_or_b64 exec, exec, s[0:1]
	v_add_f32_e32 v134, v134, v70
	v_mul_f32_e32 v134, 0xbfb8aa3b, v134
	v_exp_f32_e32 v134, v134
	s_nop 0
	v_add_f32_e32 v134, 1.0, v134
	v_rcp_f32_e32 v134, v134
	s_nop 0
	v_mul_f32_e32 v134, 0xc1000000, v134
	v_mul_f32_e32 v134, v66, v134
	v_add_f32_e32 v143, v134, v134
	v_cmp_nlt_f32_e32 vcc, s4, v143
	s_and_saveexec_b64 s[0:1], vcc
	s_xor_b64 s[0:1], exec, s[0:1]
	v_mul_f32_e32 v142, 0x3fb8aa3b, v143
	v_exp_f32_e32 v142, v142
	s_nop 0
	v_sub_f32_e32 v142, 1.0, v142
	s_andn2_saveexec_b64 s[0:1], s[0:1]
	v_fmamk_f32 v142, v143, 0x3d2aaaab, v229
	v_fma_f32 v142, v143, v142, 0.5
	v_fma_f32 v142, v143, v142, 1.0
	v_mul_f32_e64 v142, v142, -v143
	s_or_b64 exec, exec, s[0:1]
	v_add_f32_e32 v135, v135, v71
	v_mul_f32_e32 v135, 0xbfb8aa3b, v135
	v_exp_f32_e32 v135, v135
	s_nop 0
	v_add_f32_e32 v135, 1.0, v135
	v_rcp_f32_e32 v135, v135
	s_nop 0
	v_mul_f32_e32 v135, 0xc1000000, v135
	v_mul_f32_e32 v135, v67, v135
	v_add_f32_e32 v144, v135, v135
	v_cmp_nlt_f32_e32 vcc, s4, v144
	s_and_saveexec_b64 s[0:1], vcc
	s_xor_b64 s[0:1], exec, s[0:1]
	v_mul_f32_e32 v143, 0x3fb8aa3b, v144
	v_exp_f32_e32 v143, v143
	s_nop 0
	v_sub_f32_e32 v143, 1.0, v143
	s_andn2_saveexec_b64 s[0:1], s[0:1]
	v_fmamk_f32 v143, v144, 0x3d2aaaab, v229
	v_fma_f32 v143, v144, v143, 0.5
	v_fma_f32 v143, v144, v143, 1.0
	v_mul_f32_e64 v143, v143, -v144
	s_or_b64 exec, exec, s[0:1]
	v_add_f32_e32 v128, v128, v56
	v_mul_f32_e32 v128, 0xbfb8aa3b, v128
	v_exp_f32_e32 v128, v128
	s_nop 0
	v_add_f32_e32 v128, 1.0, v128
	v_rcp_f32_e32 v128, v128
	s_nop 0
	v_mul_f32_e32 v128, 0xc1000000, v128
	v_mul_f32_e32 v128, v52, v128
	v_add_f32_e32 v145, v128, v128
	v_cmp_nlt_f32_e32 vcc, s4, v145
	s_and_saveexec_b64 s[0:1], vcc
	s_xor_b64 s[0:1], exec, s[0:1]
	v_mul_f32_e32 v144, 0x3fb8aa3b, v145
	v_exp_f32_e32 v144, v144
	s_nop 0
	v_sub_f32_e32 v144, 1.0, v144
	s_andn2_saveexec_b64 s[0:1], s[0:1]
	v_fmamk_f32 v144, v145, 0x3d2aaaab, v229
	v_fma_f32 v144, v145, v144, 0.5
	v_fma_f32 v144, v145, v144, 1.0
	v_mul_f32_e64 v144, v144, -v145
	s_or_b64 exec, exec, s[0:1]
	v_add_f32_e32 v129, v129, v57
	v_mul_f32_e32 v129, 0xbfb8aa3b, v129
	v_exp_f32_e32 v129, v129
	s_nop 0
	v_add_f32_e32 v129, 1.0, v129
	v_rcp_f32_e32 v129, v129
	s_nop 0
	v_mul_f32_e32 v129, 0xc1000000, v129
	v_mul_f32_e32 v129, v53, v129
	v_add_f32_e32 v146, v129, v129
	v_cmp_nlt_f32_e32 vcc, s4, v146
	s_and_saveexec_b64 s[0:1], vcc
	s_xor_b64 s[0:1], exec, s[0:1]
	v_mul_f32_e32 v145, 0x3fb8aa3b, v146
	v_exp_f32_e32 v145, v145
	s_nop 0
	v_sub_f32_e32 v145, 1.0, v145
	s_andn2_saveexec_b64 s[0:1], s[0:1]
	v_fmamk_f32 v145, v146, 0x3d2aaaab, v229
	v_fma_f32 v145, v146, v145, 0.5
	v_fma_f32 v145, v146, v145, 1.0
	v_mul_f32_e64 v145, v145, -v146
	s_or_b64 exec, exec, s[0:1]
	v_add_f32_e32 v130, v130, v58
	v_mul_f32_e32 v130, 0xbfb8aa3b, v130
	v_exp_f32_e32 v130, v130
	s_nop 0
	v_add_f32_e32 v130, 1.0, v130
	v_rcp_f32_e32 v130, v130
	s_nop 0
	v_mul_f32_e32 v130, 0xc1000000, v130
	v_mul_f32_e32 v130, v54, v130
	v_add_f32_e32 v146, v130, v130
	v_cmp_nlt_f32_e32 vcc, s4, v146
	s_and_saveexec_b64 s[0:1], vcc
	s_xor_b64 s[0:1], exec, s[0:1]
	v_mul_f32_e32 v146, 0x3fb8aa3b, v146
	v_exp_f32_e32 v146, v146
	s_nop 0
	v_sub_f32_e32 v147, 1.0, v146
	s_andn2_saveexec_b64 s[0:1], s[0:1]
	v_fmamk_f32 v147, v146, 0x3d2aaaab, v229
	v_fma_f32 v147, v146, v147, 0.5
	v_fma_f32 v147, v146, v147, 1.0
	v_mul_f32_e64 v147, v147, -v146
	s_or_b64 exec, exec, s[0:1]
	v_add_f32_e32 v131, v131, v59
	v_mul_f32_e32 v131, 0xbfb8aa3b, v131
	v_exp_f32_e32 v131, v131
	s_nop 0
	v_add_f32_e32 v131, 1.0, v131
	v_rcp_f32_e32 v131, v131
	s_nop 0
	v_mul_f32_e32 v131, 0xc1000000, v131
	v_mul_f32_e32 v131, v55, v131
	v_add_f32_e32 v148, v131, v131
	v_cmp_nlt_f32_e32 vcc, s4, v148
	s_and_saveexec_b64 s[0:1], vcc
	s_xor_b64 s[0:1], exec, s[0:1]
	v_mul_f32_e32 v146, 0x3fb8aa3b, v148
	v_exp_f32_e32 v146, v146
	s_nop 0
	v_sub_f32_e32 v146, 1.0, v146
	s_andn2_saveexec_b64 s[0:1], s[0:1]
	v_fmamk_f32 v146, v148, 0x3d2aaaab, v229
	v_fma_f32 v146, v148, v146, 0.5
	v_fma_f32 v146, v148, v146, 1.0
	v_mul_f32_e64 v146, v146, -v148
	s_or_b64 exec, exec, s[0:1]
	v_add_f32_e32 v126, v126, v38
	v_mul_f32_e32 v126, 0xbfb8aa3b, v126
	v_exp_f32_e32 v126, v126
	v_add_f32_e32 v125, v125, v37
	v_mul_f32_e32 v125, 0xbfb8aa3b, v125
	v_exp_f32_e32 v125, v125
	v_add_f32_e32 v124, v124, v36
	v_mul_f32_e32 v124, 0xbfb8aa3b, v124
	v_add_f32_e32 v126, 1.0, v126
	v_exp_f32_e32 v124, v124
	v_add_f32_e32 v123, v123, v35
	v_rcp_f32_e32 v126, v126
	v_mul_f32_e32 v123, 0xbfb8aa3b, v123
	v_sqrt_f32_e32 v147, v147
	v_add_f32_e32 v125, 1.0, v125
	v_exp_f32_e32 v123, v123
	v_add_f32_e32 v122, v122, v34
	v_rcp_f32_e32 v125, v125
	v_mul_f32_e32 v122, 0xbfb8aa3b, v122
	v_lshlrev_b32_e32 v148, 16, v159
	v_sqrt_f32_e32 v145, v145
	v_add_f32_e32 v124, 1.0, v124
	v_exp_f32_e32 v122, v122
; __device__ __forceinline__ unsigned pk2(float lo, float hi) { unsigned r; asm("v_cvt_pk_bf16_f32 %0, %1, %2" : "=v"(r) : "v"(lo), "v"(hi)); return r; }
; __device__ __forceinline__ float sigmoidf_(float x) { return __builtin_amdgcn_rcpf(1.0f + __expf(-x)); }
;     __device__ __forceinline__ void operator()(const f32x4 (&acc)[2][2][4][2], const Unit& u, int wr, int wc, int fr, int fq) const {
;     ...
;                     for (int j = 0; j < 4; ++j) { const int e = 4 * n + j;
;                         const float r = sigmoidf_(acc[ai][0][m][n][j] + br[e]), ig = sigmoidf_(acc[ai][1][m][n][j] + bi[e]);
;                         const float l = -8.0f * r * sp[e]; la[e] = l;
;                         const float x2 = 2.0f * l;
;                         const float om = x2 > -0.03125f ? -x2 * (1.0f + x2 * (0.5f + x2 * (0.16666667f + x2 * 0.041666668f))) : 1.0f - __expf(x2);
;                         uu[e] = __builtin_amdgcn_sqrtf(om) * (ig * xc[e]); }
;                 u32x4 w0, w1; w0.x = pk2(la[0], uu[0]); w0.y = pk2(la[1], uu[1]); w0.z = pk2(la[2], uu[2]); w0.w = pk2(la[3], uu[3]);
;                 w1.x = pk2(la[4], uu[4]); w1.y = pk2(la[5], uu[5]); w1.z = pk2(la[6], uu[6]); w1.w = pk2(la[7], uu[7]);
;                 *(u32x4*)(LU + off) = w0; *(u32x4*)(LU + off + 4) = w1; }
	v_add_f32_e32 v121, v121, v33
	v_mul_f32_e32 v126, v126, v148
	v_rcp_f32_e32 v124, v124
	v_mul_f32_e32 v121, 0xbfb8aa3b, v121
	v_mul_f32_e32 v126, v126, v147
	v_and_b32_e32 v147, 0xffff0000, v158
	v_sqrt_f32_e32 v144, v144
	v_add_f32_e32 v123, 1.0, v123
	v_exp_f32_e32 v121, v121
	v_add_f32_e32 v120, v120, v32
	v_mul_f32_e32 v125, v125, v147
	v_rcp_f32_e32 v123, v123
	v_mul_f32_e32 v120, 0xbfb8aa3b, v120
	v_mul_f32_e32 v125, v125, v145
	v_lshlrev_b32_e32 v145, 16, v158
	v_sqrt_f32_e32 v143, v143
	v_add_f32_e32 v122, 1.0, v122
	v_exp_f32_e32 v120, v120
	v_add_f32_e32 v127, v127, v39
	v_mul_f32_e32 v124, v124, v145
	v_rcp_f32_e32 v122, v122
	v_add_f32_e32 v112, v112, v68
	v_mul_f32_e32 v127, 0xbfb8aa3b, v127
	v_mul_f32_e32 v124, v124, v144
	v_and_b32_e32 v144, 0xffff0000, v157
	v_sqrt_f32_e32 v142, v142
	v_add_f32_e32 v121, 1.0, v121
	v_mul_f32_e32 v112, 0xbfb8aa3b, v112
	v_exp_f32_e32 v127, v127
	v_mul_f32_e32 v123, v123, v144
	v_rcp_f32_e32 v121, v121
	v_exp_f32_e32 v112, v112
	v_mul_f32_e32 v123, v123, v143
	v_lshlrev_b32_e32 v143, 16, v157
	v_sqrt_f32_e32 v141, v141
	v_add_f32_e32 v120, 1.0, v120
	v_mul_f32_e32 v122, v122, v143
	v_rcp_f32_e32 v120, v120
	v_mul_f32_e32 v122, v122, v142
	v_and_b32_e32 v142, 0xffff0000, v156
	v_add_f32_e32 v127, 1.0, v127
	v_mul_f32_e32 v121, v121, v142
	v_sqrt_f32_e32 v140, v140
	v_add_f32_e32 v112, 1.0, v112
	v_rcp_f32_e32 v127, v127
	v_mul_f32_e32 v121, v121, v141
	v_lshlrev_b32_e32 v141, 16, v156
	v_rcp_f32_e32 v112, v112
	v_mul_f32_e32 v120, v120, v141
	v_sqrt_f32_e32 v141, v146
	v_mul_f32_e32 v120, v120, v140
	v_and_b32_e32 v140, 0xffff0000, v159
	v_cvt_pk_bf16_f32 v124, v128, v124
	v_cvt_pk_bf16_f32 v125, v129, v125
	v_lshlrev_b64 v[128:129], 13, v[208:209]
	v_mul_f32_e32 v127, v127, v140
	v_lshl_add_u64 v[128:129], s[44:45], 0, v[128:129]
	v_mul_f32_e32 v112, 0xc1000000, v112
	v_mul_f32_e32 v127, v127, v141
	v_cvt_pk_bf16_f32 v120, v132, v120
	v_cvt_pk_bf16_f32 v121, v133, v121
	v_cvt_pk_bf16_f32 v122, v134, v122
	v_cvt_pk_bf16_f32 v123, v135, v123
	v_lshl_add_u64 v[128:129], v[196:197], 2, v[128:129]
	v_mul_f32_e32 v112, v64, v112
	v_cvt_pk_bf16_f32 v126, v130, v126
	v_cvt_pk_bf16_f32 v127, v131, v127
	global_store_dwordx4 v[128:129], v[120:123], off
	global_store_dwordx4 v[128:129], v[124:127], off offset:16
	s_nop 0
	v_add_f32_e32 v121, v112, v112
	v_cmp_nlt_f32_e32 vcc, s4, v121
	s_and_saveexec_b64 s[0:1], vcc
	s_xor_b64 s[0:1], exec, s[0:1]
	v_mul_f32_e32 v120, 0x3fb8aa3b, v121
	v_exp_f32_e32 v120, v120
	s_nop 0
	v_sub_f32_e32 v120, 1.0, v120
	s_andn2_saveexec_b64 s[0:1], s[0:1]
	v_fmamk_f32 v120, v121, 0x3d2aaaab, v229
	v_fma_f32 v120, v121, v120, 0.5
	v_fma_f32 v120, v121, v120, 1.0
	v_mul_f32_e64 v120, v120, -v121
	s_or_b64 exec, exec, s[0:1]
	v_add_f32_e32 v113, v113, v69
	v_mul_f32_e32 v113, 0xbfb8aa3b, v113
	v_exp_f32_e32 v113, v113
	s_nop 0
	v_add_f32_e32 v113, 1.0, v113
	v_rcp_f32_e32 v113, v113
	s_nop 0
	v_mul_f32_e32 v113, 0xc1000000, v113
	v_mul_f32_e32 v113, v65, v113
	v_add_f32_e32 v122, v113, v113
	v_cmp_nlt_f32_e32 vcc, s4, v122
	s_and_saveexec_b64 s[0:1], vcc
	s_xor_b64 s[0:1], exec, s[0:1]
	v_mul_f32_e32 v121, 0x3fb8aa3b, v122
	v_exp_f32_e32 v121, v121
	s_nop 0
	v_sub_f32_e32 v121, 1.0, v121
	s_andn2_saveexec_b64 s[0:1], s[0:1]
	v_fmamk_f32 v121, v122, 0x3d2aaaab, v229
	v_fma_f32 v121, v122, v121, 0.5
	v_fma_f32 v121, v122, v121, 1.0
	v_mul_f32_e64 v121, v121, -v122
	s_or_b64 exec, exec, s[0:1]
	v_add_f32_e32 v114, v114, v70
	v_mul_f32_e32 v114, 0xbfb8aa3b, v114
	v_exp_f32_e32 v114, v114
	s_nop 0
	v_add_f32_e32 v114, 1.0, v114
	v_rcp_f32_e32 v114, v114
	s_nop 0
	v_mul_f32_e32 v114, 0xc1000000, v114
	v_mul_f32_e32 v114, v66, v114
	v_add_f32_e32 v123, v114, v114
	v_cmp_nlt_f32_e32 vcc, s4, v123
	s_and_saveexec_b64 s[0:1], vcc
	s_xor_b64 s[0:1], exec, s[0:1]
	v_mul_f32_e32 v122, 0x3fb8aa3b, v123
	v_exp_f32_e32 v122, v122
	s_nop 0
	v_sub_f32_e32 v122, 1.0, v122
	s_andn2_saveexec_b64 s[0:1], s[0:1]
	v_fmamk_f32 v122, v123, 0x3d2aaaab, v229
	v_fma_f32 v122, v123, v122, 0.5
	v_fma_f32 v122, v123, v122, 1.0
	v_mul_f32_e64 v122, v122, -v123
	s_or_b64 exec, exec, s[0:1]
	v_add_f32_e32 v115, v115, v71
	v_mul_f32_e32 v115, 0xbfb8aa3b, v115
	v_exp_f32_e32 v115, v115
	s_nop 0
	v_add_f32_e32 v115, 1.0, v115
	v_rcp_f32_e32 v115, v115
	s_nop 0
	v_mul_f32_e32 v115, 0xc1000000, v115
	v_mul_f32_e32 v115, v67, v115
	v_add_f32_e32 v124, v115, v115
	v_cmp_nlt_f32_e32 vcc, s4, v124
	s_and_saveexec_b64 s[0:1], vcc
	s_xor_b64 s[0:1], exec, s[0:1]
	v_mul_f32_e32 v123, 0x3fb8aa3b, v124
	v_exp_f32_e32 v123, v123
	s_nop 0
	v_sub_f32_e32 v123, 1.0, v123
	s_andn2_saveexec_b64 s[0:1], s[0:1]
	v_fmamk_f32 v123, v124, 0x3d2aaaab, v229
	v_fma_f32 v123, v124, v123, 0.5
	v_fma_f32 v123, v124, v123, 1.0
	v_mul_f32_e64 v123, v123, -v124
	s_or_b64 exec, exec, s[0:1]
	v_add_f32_e32 v108, v108, v56
	v_mul_f32_e32 v108, 0xbfb8aa3b, v108
	v_exp_f32_e32 v108, v108
	s_nop 0
	v_add_f32_e32 v108, 1.0, v108
	v_rcp_f32_e32 v108, v108
	s_nop 0
	v_mul_f32_e32 v108, 0xc1000000, v108
	v_mul_f32_e32 v108, v52, v108
	v_add_f32_e32 v125, v108, v108
	v_cmp_nlt_f32_e32 vcc, s4, v125
	s_and_saveexec_b64 s[0:1], vcc
	s_xor_b64 s[0:1], exec, s[0:1]
	v_mul_f32_e32 v124, 0x3fb8aa3b, v125
	v_exp_f32_e32 v124, v124
	s_nop 0
	v_sub_f32_e32 v124, 1.0, v124
	s_andn2_saveexec_b64 s[0:1], s[0:1]
	v_fmamk_f32 v124, v125, 0x3d2aaaab, v229
	v_fma_f32 v124, v125, v124, 0.5
	v_fma_f32 v124, v125, v124, 1.0
	v_mul_f32_e64 v124, v124, -v125
	s_or_b64 exec, exec, s[0:1]
	v_add_f32_e32 v109, v109, v57
	v_mul_f32_e32 v109, 0xbfb8aa3b, v109
	v_exp_f32_e32 v109, v109
	s_nop 0
	v_add_f32_e32 v109, 1.0, v109
	v_rcp_f32_e32 v109, v109
	s_nop 0
; __device__ __forceinline__ unsigned pk2(float lo, float hi) { unsigned r; asm("v_cvt_pk_bf16_f32 %0, %1, %2" : "=v"(r) : "v"(lo), "v"(hi)); return r; }
; __device__ __forceinline__ float sigmoidf_(float x) { return __builtin_amdgcn_rcpf(1.0f + __expf(-x)); }
;     __device__ __forceinline__ void operator()(const f32x4 (&acc)[2][2][4][2], const Unit& u, int wr, int wc, int fr, int fq) const {
;     ...
;                     for (int j = 0; j < 4; ++j) { const int e = 4 * n + j;
;                         const float r = sigmoidf_(acc[ai][0][m][n][j] + br[e]), ig = sigmoidf_(acc[ai][1][m][n][j] + bi[e]);
;                         const float l = -8.0f * r * sp[e]; la[e] = l;
;                         const float x2 = 2.0f * l;
;                         const float om = x2 > -0.03125f ? -x2 * (1.0f + x2 * (0.5f + x2 * (0.16666667f + x2 * 0.041666668f))) : 1.0f - __expf(x2);
;                         uu[e] = __builtin_amdgcn_sqrtf(om) * (ig * xc[e]); }
;                 u32x4 w0, w1; w0.x = pk2(la[0], uu[0]); w0.y = pk2(la[1], uu[1]); w0.z = pk2(la[2], uu[2]); w0.w = pk2(la[3], uu[3]);
;                 w1.x = pk2(la[4], uu[4]); w1.y = pk2(la[5], uu[5]); w1.z = pk2(la[6], uu[6]); w1.w = pk2(la[7], uu[7]);
;                 *(u32x4*)(LU + off) = w0; *(u32x4*)(LU + off + 4) = w1; }
	v_mul_f32_e32 v109, 0xc1000000, v109
	v_mul_f32_e32 v109, v53, v109
	v_add_f32_e32 v126, v109, v109
	v_cmp_nlt_f32_e32 vcc, s4, v126
	s_and_saveexec_b64 s[0:1], vcc
	s_xor_b64 s[0:1], exec, s[0:1]
	v_mul_f32_e32 v125, 0x3fb8aa3b, v126
	v_exp_f32_e32 v125, v125
	s_nop 0
	v_sub_f32_e32 v125, 1.0, v125
	s_andn2_saveexec_b64 s[0:1], s[0:1]
	v_fmamk_f32 v125, v126, 0x3d2aaaab, v229
	v_fma_f32 v125, v126, v125, 0.5
	v_fma_f32 v125, v126, v125, 1.0
	v_mul_f32_e64 v125, v125, -v126
	s_or_b64 exec, exec, s[0:1]
	v_add_f32_e32 v110, v110, v58
	v_mul_f32_e32 v110, 0xbfb8aa3b, v110
	v_exp_f32_e32 v110, v110
	s_nop 0
	v_add_f32_e32 v110, 1.0, v110
	v_rcp_f32_e32 v110, v110
	s_nop 0
	v_mul_f32_e32 v110, 0xc1000000, v110
	v_mul_f32_e32 v110, v54, v110
	v_add_f32_e32 v126, v110, v110
	v_cmp_nlt_f32_e32 vcc, s4, v126
	s_and_saveexec_b64 s[0:1], vcc
	s_xor_b64 s[0:1], exec, s[0:1]
	v_mul_f32_e32 v126, 0x3fb8aa3b, v126
	v_exp_f32_e32 v126, v126
	s_nop 0
	v_sub_f32_e32 v127, 1.0, v126
	s_andn2_saveexec_b64 s[0:1], s[0:1]
	v_fmamk_f32 v127, v126, 0x3d2aaaab, v229
	v_fma_f32 v127, v126, v127, 0.5
	v_fma_f32 v127, v126, v127, 1.0
	v_mul_f32_e64 v127, v127, -v126
	s_or_b64 exec, exec, s[0:1]
	v_add_f32_e32 v111, v111, v59
	v_mul_f32_e32 v111, 0xbfb8aa3b, v111
	v_exp_f32_e32 v111, v111
	s_nop 0
	v_add_f32_e32 v111, 1.0, v111
	v_rcp_f32_e32 v111, v111
	s_nop 0
	v_mul_f32_e32 v111, 0xc1000000, v111
	v_mul_f32_e32 v111, v55, v111
	v_add_f32_e32 v128, v111, v111
	v_cmp_nlt_f32_e32 vcc, s4, v128
	s_and_saveexec_b64 s[0:1], vcc
	s_xor_b64 s[0:1], exec, s[0:1]
	v_mul_f32_e32 v126, 0x3fb8aa3b, v128
	v_exp_f32_e32 v126, v126
	s_nop 0
	v_sub_f32_e32 v126, 1.0, v126
	s_andn2_saveexec_b64 s[0:1], s[0:1]
	v_fmamk_f32 v126, v128, 0x3d2aaaab, v229
	v_fma_f32 v126, v128, v126, 0.5
	v_fma_f32 v126, v128, v126, 1.0
	v_mul_f32_e64 v126, v126, -v128
	s_or_b64 exec, exec, s[0:1]
	v_add_f32_e32 v106, v106, v38
	v_mul_f32_e32 v106, 0xbfb8aa3b, v106
	v_exp_f32_e32 v106, v106
	v_add_f32_e32 v105, v105, v37
	v_mul_f32_e32 v105, 0xbfb8aa3b, v105
	v_exp_f32_e32 v105, v105
	v_add_f32_e32 v104, v104, v36
	v_mul_f32_e32 v104, 0xbfb8aa3b, v104
	v_add_f32_e32 v106, 1.0, v106
	v_exp_f32_e32 v104, v104
	v_add_f32_e32 v103, v103, v35
	v_rcp_f32_e32 v106, v106
	v_mul_f32_e32 v103, 0xbfb8aa3b, v103
	v_sqrt_f32_e32 v127, v127
	v_add_f32_e32 v105, 1.0, v105
	v_exp_f32_e32 v103, v103
	v_add_f32_e32 v102, v102, v34
	v_rcp_f32_e32 v105, v105
	v_mul_f32_e32 v102, 0xbfb8aa3b, v102
	v_lshlrev_b32_e32 v128, 16, v139
	v_sqrt_f32_e32 v125, v125
	v_add_f32_e32 v104, 1.0, v104
	v_exp_f32_e32 v102, v102
	v_add_f32_e32 v101, v101, v33
	v_mul_f32_e32 v106, v106, v128
	v_rcp_f32_e32 v104, v104
	v_mul_f32_e32 v101, 0xbfb8aa3b, v101
	v_mul_f32_e32 v106, v106, v127
	v_and_b32_e32 v127, 0xffff0000, v138
	v_sqrt_f32_e32 v124, v124
	v_add_f32_e32 v103, 1.0, v103
	v_exp_f32_e32 v101, v101
	v_add_f32_e32 v100, v100, v32
	v_mul_f32_e32 v105, v105, v127
	v_rcp_f32_e32 v103, v103
	v_mul_f32_e32 v100, 0xbfb8aa3b, v100
	v_mul_f32_e32 v105, v105, v125
	v_lshlrev_b32_e32 v125, 16, v138
	v_sqrt_f32_e32 v123, v123
	v_add_f32_e32 v102, 1.0, v102
	v_exp_f32_e32 v100, v100
	v_add_f32_e32 v107, v107, v39
	v_mul_f32_e32 v104, v104, v125
	v_rcp_f32_e32 v102, v102
	v_add_f32_e32 v92, v92, v68
	v_mul_f32_e32 v107, 0xbfb8aa3b, v107
	v_mul_f32_e32 v104, v104, v124
	v_and_b32_e32 v124, 0xffff0000, v137
	v_sqrt_f32_e32 v122, v122
	v_add_f32_e32 v101, 1.0, v101
	v_mul_f32_e32 v92, 0xbfb8aa3b, v92
	v_exp_f32_e32 v107, v107
	v_mul_f32_e32 v103, v103, v124
	v_rcp_f32_e32 v101, v101
	v_exp_f32_e32 v92, v92
	v_mul_f32_e32 v103, v103, v123
	v_lshlrev_b32_e32 v123, 16, v137
	v_sqrt_f32_e32 v121, v121
	v_add_f32_e32 v100, 1.0, v100
	v_mul_f32_e32 v102, v102, v123
	v_rcp_f32_e32 v100, v100
	v_mul_f32_e32 v102, v102, v122
	v_and_b32_e32 v122, 0xffff0000, v136
	v_add_f32_e32 v107, 1.0, v107
	v_mul_f32_e32 v101, v101, v122
	v_sqrt_f32_e32 v120, v120
	v_add_f32_e32 v92, 1.0, v92
	v_rcp_f32_e32 v107, v107
	v_mul_f32_e32 v101, v101, v121
	v_lshlrev_b32_e32 v121, 16, v136
	v_rcp_f32_e32 v92, v92
	v_mul_f32_e32 v100, v100, v121
	v_sqrt_f32_e32 v121, v126
	v_mul_f32_e32 v100, v100, v120
	v_and_b32_e32 v120, 0xffff0000, v139
	v_cvt_pk_bf16_f32 v104, v108, v104
	v_cvt_pk_bf16_f32 v105, v109, v105
	v_lshlrev_b64 v[108:109], 13, v[206:207]
	v_mul_f32_e32 v107, v107, v120
	v_lshl_add_u64 v[108:109], s[44:45], 0, v[108:109]
	v_mul_f32_e32 v92, 0xc1000000, v92
	v_mul_f32_e32 v107, v107, v121
	v_cvt_pk_bf16_f32 v100, v112, v100
	v_cvt_pk_bf16_f32 v101, v113, v101
	v_cvt_pk_bf16_f32 v102, v114, v102
	v_cvt_pk_bf16_f32 v103, v115, v103
	v_lshl_add_u64 v[108:109], v[196:197], 2, v[108:109]
	v_mul_f32_e32 v92, v64, v92
	v_cvt_pk_bf16_f32 v106, v110, v106
	v_cvt_pk_bf16_f32 v107, v111, v107
	global_store_dwordx4 v[108:109], v[100:103], off
	global_store_dwordx4 v[108:109], v[104:107], off offset:16
	s_nop 0
	v_add_f32_e32 v101, v92, v92
	v_cmp_nlt_f32_e32 vcc, s4, v101
	s_and_saveexec_b64 s[0:1], vcc
	s_xor_b64 s[0:1], exec, s[0:1]
	v_mul_f32_e32 v100, 0x3fb8aa3b, v101
	v_exp_f32_e32 v100, v100
	s_nop 0
	v_sub_f32_e32 v100, 1.0, v100
	s_andn2_saveexec_b64 s[0:1], s[0:1]
	v_fmamk_f32 v100, v101, 0x3d2aaaab, v229
	v_fma_f32 v100, v101, v100, 0.5
	v_fma_f32 v100, v101, v100, 1.0
	v_mul_f32_e64 v100, v100, -v101
	s_or_b64 exec, exec, s[0:1]
	v_add_f32_e32 v93, v93, v69
	v_mul_f32_e32 v93, 0xbfb8aa3b, v93
	v_exp_f32_e32 v93, v93
	s_nop 0
	v_add_f32_e32 v93, 1.0, v93
	v_rcp_f32_e32 v93, v93
	s_nop 0
	v_mul_f32_e32 v93, 0xc1000000, v93
	v_mul_f32_e32 v93, v65, v93
	v_add_f32_e32 v102, v93, v93
	v_cmp_nlt_f32_e32 vcc, s4, v102
	s_and_saveexec_b64 s[0:1], vcc
	s_xor_b64 s[0:1], exec, s[0:1]
; __device__ __forceinline__ unsigned pk2(float lo, float hi) { unsigned r; asm("v_cvt_pk_bf16_f32 %0, %1, %2" : "=v"(r) : "v"(lo), "v"(hi)); return r; }
; __device__ __forceinline__ float sigmoidf_(float x) { return __builtin_amdgcn_rcpf(1.0f + __expf(-x)); }
;     __device__ __forceinline__ void operator()(const f32x4 (&acc)[2][2][4][2], const Unit& u, int wr, int wc, int fr, int fq) const {
;     ...
;                     for (int j = 0; j < 4; ++j) { const int e = 4 * n + j;
;                         const float r = sigmoidf_(acc[ai][0][m][n][j] + br[e]), ig = sigmoidf_(acc[ai][1][m][n][j] + bi[e]);
;                         const float l = -8.0f * r * sp[e]; la[e] = l;
;                         const float x2 = 2.0f * l;
;                         const float om = x2 > -0.03125f ? -x2 * (1.0f + x2 * (0.5f + x2 * (0.16666667f + x2 * 0.041666668f))) : 1.0f - __expf(x2);
;                         uu[e] = __builtin_amdgcn_sqrtf(om) * (ig * xc[e]); }
;                 u32x4 w0, w1; w0.x = pk2(la[0], uu[0]); w0.y = pk2(la[1], uu[1]); w0.z = pk2(la[2], uu[2]); w0.w = pk2(la[3], uu[3]);
;                 w1.x = pk2(la[4], uu[4]); w1.y = pk2(la[5], uu[5]); w1.z = pk2(la[6], uu[6]); w1.w = pk2(la[7], uu[7]);
;                 *(u32x4*)(LU + off) = w0; *(u32x4*)(LU + off + 4) = w1; }
	v_mul_f32_e32 v101, 0x3fb8aa3b, v102
	v_exp_f32_e32 v101, v101
	s_nop 0
	v_sub_f32_e32 v101, 1.0, v101
	s_andn2_saveexec_b64 s[0:1], s[0:1]
	v_fmamk_f32 v101, v102, 0x3d2aaaab, v229
	v_fma_f32 v101, v102, v101, 0.5
	v_fma_f32 v101, v102, v101, 1.0
	v_mul_f32_e64 v101, v101, -v102
	s_or_b64 exec, exec, s[0:1]
	v_add_f32_e32 v94, v94, v70
	v_mul_f32_e32 v94, 0xbfb8aa3b, v94
	v_exp_f32_e32 v94, v94
	s_nop 0
	v_add_f32_e32 v94, 1.0, v94
	v_rcp_f32_e32 v94, v94
	s_nop 0
	v_mul_f32_e32 v94, 0xc1000000, v94
	v_mul_f32_e32 v94, v66, v94
	v_add_f32_e32 v103, v94, v94
	v_cmp_nlt_f32_e32 vcc, s4, v103
	s_and_saveexec_b64 s[0:1], vcc
	s_xor_b64 s[0:1], exec, s[0:1]
	v_mul_f32_e32 v102, 0x3fb8aa3b, v103
	v_exp_f32_e32 v102, v102
	s_nop 0
	v_sub_f32_e32 v102, 1.0, v102
	s_andn2_saveexec_b64 s[0:1], s[0:1]
	v_fmamk_f32 v102, v103, 0x3d2aaaab, v229
	v_fma_f32 v102, v103, v102, 0.5
	v_fma_f32 v102, v103, v102, 1.0
	v_mul_f32_e64 v102, v102, -v103
	s_or_b64 exec, exec, s[0:1]
	v_add_f32_e32 v95, v95, v71
	v_mul_f32_e32 v95, 0xbfb8aa3b, v95
	v_exp_f32_e32 v95, v95
	s_nop 0
	v_add_f32_e32 v95, 1.0, v95
	v_rcp_f32_e32 v95, v95
	s_nop 0
	v_mul_f32_e32 v95, 0xc1000000, v95
	v_mul_f32_e32 v95, v67, v95
	v_add_f32_e32 v104, v95, v95
	v_cmp_nlt_f32_e32 vcc, s4, v104
	s_and_saveexec_b64 s[0:1], vcc
	s_xor_b64 s[0:1], exec, s[0:1]
	v_mul_f32_e32 v103, 0x3fb8aa3b, v104
	v_exp_f32_e32 v103, v103
	s_nop 0
	v_sub_f32_e32 v103, 1.0, v103
	s_andn2_saveexec_b64 s[0:1], s[0:1]
	v_fmamk_f32 v103, v104, 0x3d2aaaab, v229
	v_fma_f32 v103, v104, v103, 0.5
	v_fma_f32 v103, v104, v103, 1.0
	v_mul_f32_e64 v103, v103, -v104
	s_or_b64 exec, exec, s[0:1]
	v_add_f32_e32 v88, v88, v56
	v_mul_f32_e32 v88, 0xbfb8aa3b, v88
	v_exp_f32_e32 v88, v88
	s_nop 0
	v_add_f32_e32 v88, 1.0, v88
	v_rcp_f32_e32 v88, v88
	s_nop 0
	v_mul_f32_e32 v88, 0xc1000000, v88
	v_mul_f32_e32 v88, v52, v88
	v_add_f32_e32 v105, v88, v88
	v_cmp_nlt_f32_e32 vcc, s4, v105
	s_and_saveexec_b64 s[0:1], vcc
	s_xor_b64 s[0:1], exec, s[0:1]
	v_mul_f32_e32 v104, 0x3fb8aa3b, v105
	v_exp_f32_e32 v104, v104
	s_nop 0
	v_sub_f32_e32 v104, 1.0, v104
	s_andn2_saveexec_b64 s[0:1], s[0:1]
	v_fmamk_f32 v104, v105, 0x3d2aaaab, v229
	v_fma_f32 v104, v105, v104, 0.5
	v_fma_f32 v104, v105, v104, 1.0
	v_mul_f32_e64 v104, v104, -v105
	s_or_b64 exec, exec, s[0:1]
	v_add_f32_e32 v89, v89, v57
	v_mul_f32_e32 v89, 0xbfb8aa3b, v89
	v_exp_f32_e32 v89, v89
	s_nop 0
	v_add_f32_e32 v89, 1.0, v89
	v_rcp_f32_e32 v89, v89
	s_nop 0
	v_mul_f32_e32 v89, 0xc1000000, v89
	v_mul_f32_e32 v89, v53, v89
	v_add_f32_e32 v106, v89, v89
	v_cmp_nlt_f32_e32 vcc, s4, v106
	s_and_saveexec_b64 s[0:1], vcc
	s_xor_b64 s[0:1], exec, s[0:1]
	v_mul_f32_e32 v105, 0x3fb8aa3b, v106
	v_exp_f32_e32 v105, v105
	s_nop 0
	v_sub_f32_e32 v105, 1.0, v105
	s_andn2_saveexec_b64 s[0:1], s[0:1]
	v_fmamk_f32 v105, v106, 0x3d2aaaab, v229
	v_fma_f32 v105, v106, v105, 0.5
	v_fma_f32 v105, v106, v105, 1.0
	v_mul_f32_e64 v105, v105, -v106
	s_or_b64 exec, exec, s[0:1]
	v_add_f32_e32 v90, v90, v58
	v_mul_f32_e32 v90, 0xbfb8aa3b, v90
	v_exp_f32_e32 v90, v90
	s_nop 0
	v_add_f32_e32 v90, 1.0, v90
	v_rcp_f32_e32 v90, v90
	s_nop 0
	v_mul_f32_e32 v90, 0xc1000000, v90
	v_mul_f32_e32 v90, v54, v90
	v_add_f32_e32 v106, v90, v90
	v_cmp_nlt_f32_e32 vcc, s4, v106
	s_and_saveexec_b64 s[0:1], vcc
	s_xor_b64 s[0:1], exec, s[0:1]
	v_mul_f32_e32 v106, 0x3fb8aa3b, v106
	v_exp_f32_e32 v106, v106
	s_nop 0
	v_sub_f32_e32 v107, 1.0, v106
	s_andn2_saveexec_b64 s[0:1], s[0:1]
	v_fmamk_f32 v107, v106, 0x3d2aaaab, v229
	v_fma_f32 v107, v106, v107, 0.5
	v_fma_f32 v107, v106, v107, 1.0
	v_mul_f32_e64 v107, v107, -v106
	s_or_b64 exec, exec, s[0:1]
	v_add_f32_e32 v91, v91, v59
	v_mul_f32_e32 v91, 0xbfb8aa3b, v91
	v_exp_f32_e32 v91, v91
	s_nop 0
	v_add_f32_e32 v91, 1.0, v91
	v_rcp_f32_e32 v91, v91
	s_nop 0
	v_mul_f32_e32 v91, 0xc1000000, v91
	v_mul_f32_e32 v91, v55, v91
	v_add_f32_e32 v108, v91, v91
	v_cmp_nlt_f32_e32 vcc, s4, v108
	s_and_saveexec_b64 s[0:1], vcc
	s_xor_b64 s[0:1], exec, s[0:1]
	v_mul_f32_e32 v106, 0x3fb8aa3b, v108
	v_exp_f32_e32 v106, v106
	s_nop 0
	v_sub_f32_e32 v106, 1.0, v106
	s_andn2_saveexec_b64 s[0:1], s[0:1]
	v_fmamk_f32 v106, v108, 0x3d2aaaab, v229
	v_fma_f32 v106, v108, v106, 0.5
	v_fma_f32 v106, v108, v106, 1.0
	v_mul_f32_e64 v106, v106, -v108
	s_or_b64 exec, exec, s[0:1]
	v_add_f32_e32 v86, v86, v38
	v_mul_f32_e32 v86, 0xbfb8aa3b, v86
	v_exp_f32_e32 v86, v86
	v_add_f32_e32 v85, v85, v37
	v_mul_f32_e32 v85, 0xbfb8aa3b, v85
	v_exp_f32_e32 v85, v85
	v_add_f32_e32 v84, v84, v36
	v_mul_f32_e32 v84, 0xbfb8aa3b, v84
	v_add_f32_e32 v86, 1.0, v86
	v_exp_f32_e32 v84, v84
	v_add_f32_e32 v83, v83, v35
	v_rcp_f32_e32 v86, v86
	v_mul_f32_e32 v83, 0xbfb8aa3b, v83
	v_sqrt_f32_e32 v107, v107
	v_add_f32_e32 v85, 1.0, v85
	v_exp_f32_e32 v83, v83
	v_add_f32_e32 v82, v82, v34
	v_rcp_f32_e32 v85, v85
	v_mul_f32_e32 v82, 0xbfb8aa3b, v82
	v_lshlrev_b32_e32 v108, 16, v119
	v_sqrt_f32_e32 v105, v105
	v_add_f32_e32 v84, 1.0, v84
	v_exp_f32_e32 v82, v82
	v_add_f32_e32 v81, v81, v33
	v_mul_f32_e32 v86, v86, v108
	v_rcp_f32_e32 v84, v84
	v_mul_f32_e32 v81, 0xbfb8aa3b, v81
	v_mul_f32_e32 v86, v86, v107
	v_and_b32_e32 v107, 0xffff0000, v118
	v_sqrt_f32_e32 v104, v104
	v_add_f32_e32 v83, 1.0, v83
	v_exp_f32_e32 v81, v81
	v_add_f32_e32 v80, v80, v32
	v_mul_f32_e32 v85, v85, v107
	v_rcp_f32_e32 v83, v83
	v_mul_f32_e32 v80, 0xbfb8aa3b, v80
	v_mul_f32_e32 v85, v85, v105
	v_lshlrev_b32_e32 v105, 16, v118
	v_sqrt_f32_e32 v103, v103
	v_add_f32_e32 v82, 1.0, v82
	v_exp_f32_e32 v80, v80
	v_add_f32_e32 v87, v87, v39
	v_mul_f32_e32 v84, v84, v105
	v_rcp_f32_e32 v82, v82
	v_add_f32_e32 v72, v72, v68
	v_mul_f32_e32 v87, 0xbfb8aa3b, v87
; __device__ __forceinline__ unsigned pk2(float lo, float hi) { unsigned r; asm("v_cvt_pk_bf16_f32 %0, %1, %2" : "=v"(r) : "v"(lo), "v"(hi)); return r; }
; __device__ __forceinline__ float sigmoidf_(float x) { return __builtin_amdgcn_rcpf(1.0f + __expf(-x)); }
;     __device__ __forceinline__ void operator()(const f32x4 (&acc)[2][2][4][2], const Unit& u, int wr, int wc, int fr, int fq) const {
;     ...
;                     for (int j = 0; j < 4; ++j) { const int e = 4 * n + j;
;                         const float r = sigmoidf_(acc[ai][0][m][n][j] + br[e]), ig = sigmoidf_(acc[ai][1][m][n][j] + bi[e]);
;                         const float l = -8.0f * r * sp[e]; la[e] = l;
;                         const float x2 = 2.0f * l;
;                         const float om = x2 > -0.03125f ? -x2 * (1.0f + x2 * (0.5f + x2 * (0.16666667f + x2 * 0.041666668f))) : 1.0f - __expf(x2);
;                         uu[e] = __builtin_amdgcn_sqrtf(om) * (ig * xc[e]); }
;                 u32x4 w0, w1; w0.x = pk2(la[0], uu[0]); w0.y = pk2(la[1], uu[1]); w0.z = pk2(la[2], uu[2]); w0.w = pk2(la[3], uu[3]);
;                 w1.x = pk2(la[4], uu[4]); w1.y = pk2(la[5], uu[5]); w1.z = pk2(la[6], uu[6]); w1.w = pk2(la[7], uu[7]);
;                 *(u32x4*)(LU + off) = w0; *(u32x4*)(LU + off + 4) = w1; }
	v_mul_f32_e32 v84, v84, v104
	v_and_b32_e32 v104, 0xffff0000, v117
	v_sqrt_f32_e32 v102, v102
	v_add_f32_e32 v81, 1.0, v81
	v_mul_f32_e32 v72, 0xbfb8aa3b, v72
	v_exp_f32_e32 v87, v87
	v_mul_f32_e32 v83, v83, v104
	v_rcp_f32_e32 v81, v81
	v_exp_f32_e32 v72, v72
	v_mul_f32_e32 v83, v83, v103
	v_lshlrev_b32_e32 v103, 16, v117
	v_sqrt_f32_e32 v101, v101
	v_add_f32_e32 v80, 1.0, v80
	v_mul_f32_e32 v82, v82, v103
	v_rcp_f32_e32 v80, v80
	v_mul_f32_e32 v82, v82, v102
	v_and_b32_e32 v102, 0xffff0000, v116
	v_add_f32_e32 v87, 1.0, v87
	v_mul_f32_e32 v81, v81, v102
	v_sqrt_f32_e32 v100, v100
	v_add_f32_e32 v72, 1.0, v72
	v_rcp_f32_e32 v87, v87
	v_mul_f32_e32 v81, v81, v101
	v_lshlrev_b32_e32 v101, 16, v116
	v_rcp_f32_e32 v72, v72
	v_mul_f32_e32 v80, v80, v101
	v_sqrt_f32_e32 v101, v106
	v_mul_f32_e32 v80, v80, v100
	v_and_b32_e32 v100, 0xffff0000, v119
	v_cvt_pk_bf16_f32 v84, v88, v84
	v_cvt_pk_bf16_f32 v85, v89, v85
	v_lshlrev_b64 v[88:89], 13, v[204:205]
	v_mul_f32_e32 v87, v87, v100
	v_lshl_add_u64 v[88:89], s[44:45], 0, v[88:89]
	v_mul_f32_e32 v72, 0xc1000000, v72
	v_mul_f32_e32 v87, v87, v101
	v_cvt_pk_bf16_f32 v80, v92, v80
	v_cvt_pk_bf16_f32 v81, v93, v81
	v_cvt_pk_bf16_f32 v82, v94, v82
	v_cvt_pk_bf16_f32 v83, v95, v83
	v_lshl_add_u64 v[88:89], v[196:197], 2, v[88:89]
	v_mul_f32_e32 v72, v64, v72
	v_cvt_pk_bf16_f32 v86, v90, v86
	v_cvt_pk_bf16_f32 v87, v91, v87
	global_store_dwordx4 v[88:89], v[80:83], off
	global_store_dwordx4 v[88:89], v[84:87], off offset:16
	s_nop 0
	v_add_f32_e32 v81, v72, v72
	v_cmp_nlt_f32_e32 vcc, s4, v81
	s_and_saveexec_b64 s[0:1], vcc
	s_xor_b64 s[0:1], exec, s[0:1]
	v_mul_f32_e32 v80, 0x3fb8aa3b, v81
	v_exp_f32_e32 v80, v80
	s_nop 0
	v_sub_f32_e32 v80, 1.0, v80
	s_andn2_saveexec_b64 s[0:1], s[0:1]
	v_fmamk_f32 v80, v81, 0x3d2aaaab, v229
	v_fma_f32 v80, v81, v80, 0.5
	v_fma_f32 v80, v81, v80, 1.0
	v_mul_f32_e64 v80, v80, -v81
	s_or_b64 exec, exec, s[0:1]
	v_add_f32_e32 v73, v73, v69
	v_mul_f32_e32 v73, 0xbfb8aa3b, v73
	v_exp_f32_e32 v73, v73
	s_nop 0
	v_add_f32_e32 v73, 1.0, v73
	v_rcp_f32_e32 v73, v73
	s_nop 0
	v_mul_f32_e32 v73, 0xc1000000, v73
	v_mul_f32_e32 v73, v65, v73
	v_add_f32_e32 v82, v73, v73
	v_cmp_nlt_f32_e32 vcc, s4, v82
	s_and_saveexec_b64 s[0:1], vcc
	s_xor_b64 s[0:1], exec, s[0:1]
	v_mul_f32_e32 v81, 0x3fb8aa3b, v82
	v_exp_f32_e32 v81, v81
	s_nop 0
	v_sub_f32_e32 v81, 1.0, v81
	s_andn2_saveexec_b64 s[0:1], s[0:1]
	v_fmamk_f32 v81, v82, 0x3d2aaaab, v229
	v_fma_f32 v81, v82, v81, 0.5
	v_fma_f32 v81, v82, v81, 1.0
	v_mul_f32_e64 v81, v81, -v82
	s_or_b64 exec, exec, s[0:1]
	v_add_f32_e32 v74, v74, v70
	v_mul_f32_e32 v74, 0xbfb8aa3b, v74
	v_exp_f32_e32 v74, v74
	s_nop 0
	v_add_f32_e32 v74, 1.0, v74
	v_rcp_f32_e32 v74, v74
	s_nop 0
	v_mul_f32_e32 v74, 0xc1000000, v74
	v_mul_f32_e32 v74, v66, v74
	v_add_f32_e32 v83, v74, v74
	v_cmp_nlt_f32_e32 vcc, s4, v83
	s_and_saveexec_b64 s[0:1], vcc
	s_xor_b64 s[0:1], exec, s[0:1]
	v_mul_f32_e32 v82, 0x3fb8aa3b, v83
	v_exp_f32_e32 v82, v82
	s_nop 0
	v_sub_f32_e32 v82, 1.0, v82
	s_andn2_saveexec_b64 s[0:1], s[0:1]
	v_fmamk_f32 v82, v83, 0x3d2aaaab, v229
	v_fma_f32 v82, v83, v82, 0.5
	v_fma_f32 v82, v83, v82, 1.0
	v_mul_f32_e64 v82, v82, -v83
	s_or_b64 exec, exec, s[0:1]
	v_add_f32_e32 v75, v75, v71
	v_mul_f32_e32 v75, 0xbfb8aa3b, v75
	v_exp_f32_e32 v75, v75
	s_nop 0
	v_add_f32_e32 v75, 1.0, v75
	v_rcp_f32_e32 v75, v75
	s_nop 0
	v_mul_f32_e32 v75, 0xc1000000, v75
	v_mul_f32_e32 v75, v67, v75
	v_add_f32_e32 v84, v75, v75
	v_cmp_nlt_f32_e32 vcc, s4, v84
	s_and_saveexec_b64 s[0:1], vcc
	s_xor_b64 s[0:1], exec, s[0:1]
	v_mul_f32_e32 v83, 0x3fb8aa3b, v84
	v_exp_f32_e32 v83, v83
	s_nop 0
	v_sub_f32_e32 v83, 1.0, v83
	s_andn2_saveexec_b64 s[0:1], s[0:1]
	v_fmamk_f32 v83, v84, 0x3d2aaaab, v229
	v_fma_f32 v83, v84, v83, 0.5
	v_fma_f32 v83, v84, v83, 1.0
	v_mul_f32_e64 v83, v83, -v84
	s_or_b64 exec, exec, s[0:1]
	v_add_f32_e32 v60, v60, v56
	v_mul_f32_e32 v60, 0xbfb8aa3b, v60
	v_exp_f32_e32 v60, v60
	s_nop 0
	v_add_f32_e32 v60, 1.0, v60
	v_rcp_f32_e32 v60, v60
	s_nop 0
	v_mul_f32_e32 v60, 0xc1000000, v60
	v_mul_f32_e32 v60, v52, v60
	v_add_f32_e32 v85, v60, v60
	v_cmp_nlt_f32_e32 vcc, s4, v85
	s_and_saveexec_b64 s[0:1], vcc
	s_xor_b64 s[0:1], exec, s[0:1]
	v_mul_f32_e32 v84, 0x3fb8aa3b, v85
	v_exp_f32_e32 v84, v84
	s_nop 0
	v_sub_f32_e32 v84, 1.0, v84
	s_andn2_saveexec_b64 s[0:1], s[0:1]
	v_fmamk_f32 v84, v85, 0x3d2aaaab, v229
	v_fma_f32 v84, v85, v84, 0.5
	v_fma_f32 v84, v85, v84, 1.0
	v_mul_f32_e64 v84, v84, -v85
	s_or_b64 exec, exec, s[0:1]
	v_add_f32_e32 v61, v61, v57
	v_mul_f32_e32 v61, 0xbfb8aa3b, v61
	v_exp_f32_e32 v61, v61
	s_nop 0
	v_add_f32_e32 v61, 1.0, v61
	v_rcp_f32_e32 v61, v61
	s_nop 0
	v_mul_f32_e32 v61, 0xc1000000, v61
	v_mul_f32_e32 v61, v53, v61
	v_add_f32_e32 v86, v61, v61
	v_cmp_nlt_f32_e32 vcc, s4, v86
	s_and_saveexec_b64 s[0:1], vcc
	s_xor_b64 s[0:1], exec, s[0:1]
	v_mul_f32_e32 v85, 0x3fb8aa3b, v86
	v_exp_f32_e32 v85, v85
	s_nop 0
	v_sub_f32_e32 v85, 1.0, v85
	s_andn2_saveexec_b64 s[0:1], s[0:1]
	v_fmamk_f32 v85, v86, 0x3d2aaaab, v229
	v_fma_f32 v85, v86, v85, 0.5
	v_fma_f32 v85, v86, v85, 1.0
	v_mul_f32_e64 v85, v85, -v86
	s_or_b64 exec, exec, s[0:1]
	v_add_f32_e32 v62, v62, v58
	v_mul_f32_e32 v62, 0xbfb8aa3b, v62
	v_exp_f32_e32 v62, v62
	s_nop 0
	v_add_f32_e32 v62, 1.0, v62
	v_rcp_f32_e32 v62, v62
	s_nop 0
	v_mul_f32_e32 v62, 0xc1000000, v62
	v_mul_f32_e32 v62, v54, v62
	v_add_f32_e32 v86, v62, v62
	v_cmp_nlt_f32_e32 vcc, s4, v86
	s_and_saveexec_b64 s[0:1], vcc
	s_xor_b64 s[0:1], exec, s[0:1]
	v_mul_f32_e32 v86, 0x3fb8aa3b, v86
	v_exp_f32_e32 v86, v86
	s_nop 0
	v_sub_f32_e32 v87, 1.0, v86
	s_andn2_saveexec_b64 s[0:1], s[0:1]
	v_fmamk_f32 v87, v86, 0x3d2aaaab, v229
; __device__ __forceinline__ unsigned pk2(float lo, float hi) { unsigned r; asm("v_cvt_pk_bf16_f32 %0, %1, %2" : "=v"(r) : "v"(lo), "v"(hi)); return r; }
; __device__ __forceinline__ float sigmoidf_(float x) { return __builtin_amdgcn_rcpf(1.0f + __expf(-x)); }
;     __device__ __forceinline__ void operator()(const f32x4 (&acc)[2][2][4][2], const Unit& u, int wr, int wc, int fr, int fq) const {
;     ...
;         for (int ai = 0; ai < 2; ++ai)
; #pragma unroll
;             for (int m = 0; m < 4; ++m) { const size_t off = (size_t)(row0 + ai * HALF + m * 16) * LW + ch0;
;                 float xc[8]; unpack8(xraw[ai][m], xc);
;                 float la[8], uu[8];
; #pragma unroll
;                 for (int n = 0; n < 2; ++n)
; #pragma unroll
;                     for (int j = 0; j < 4; ++j) { const int e = 4 * n + j;
;                         const float r = sigmoidf_(acc[ai][0][m][n][j] + br[e]), ig = sigmoidf_(acc[ai][1][m][n][j] + bi[e]);
;                         const float l = -8.0f * r * sp[e]; la[e] = l;
;                         const float x2 = 2.0f * l;
;                         const float om = x2 > -0.03125f ? -x2 * (1.0f + x2 * (0.5f + x2 * (0.16666667f + x2 * 0.041666668f))) : 1.0f - __expf(x2);
;                         uu[e] = __builtin_amdgcn_sqrtf(om) * (ig * xc[e]); }
;                 u32x4 w0, w1; w0.x = pk2(la[0], uu[0]); w0.y = pk2(la[1], uu[1]); w0.z = pk2(la[2], uu[2]); w0.w = pk2(la[3], uu[3]);
;                 w1.x = pk2(la[4], uu[4]); w1.y = pk2(la[5], uu[5]); w1.z = pk2(la[6], uu[6]); w1.w = pk2(la[7], uu[7]);
;                 *(u32x4*)(LU + off) = w0; *(u32x4*)(LU + off + 4) = w1; }
	v_fma_f32 v87, v86, v87, 0.5
	v_fma_f32 v87, v86, v87, 1.0
	v_mul_f32_e64 v87, v87, -v86
	s_or_b64 exec, exec, s[0:1]
	v_add_f32_e32 v63, v63, v59
	v_mul_f32_e32 v63, 0xbfb8aa3b, v63
	v_exp_f32_e32 v63, v63
	s_nop 0
	v_add_f32_e32 v63, 1.0, v63
	v_rcp_f32_e32 v63, v63
	s_nop 0
	v_mul_f32_e32 v63, 0xc1000000, v63
	v_mul_f32_e32 v63, v55, v63
	v_add_f32_e32 v88, v63, v63
	v_cmp_nlt_f32_e32 vcc, s4, v88
	s_and_saveexec_b64 s[0:1], vcc
	s_xor_b64 s[0:1], exec, s[0:1]
	v_mul_f32_e32 v86, 0x3fb8aa3b, v88
	v_exp_f32_e32 v86, v86
	s_nop 0
	v_sub_f32_e32 v86, 1.0, v86
	s_andn2_saveexec_b64 s[0:1], s[0:1]
	v_fmamk_f32 v86, v88, 0x3d2aaaab, v229
	v_fma_f32 v86, v88, v86, 0.5
	v_fma_f32 v86, v88, v86, 1.0
	v_mul_f32_e64 v86, v86, -v88
	s_or_b64 exec, exec, s[0:1]
	v_add_f32_e32 v46, v46, v38
	v_mul_f32_e32 v46, 0xbfb8aa3b, v46
	v_exp_f32_e32 v46, v46
	v_add_f32_e32 v45, v45, v37
	v_mul_f32_e32 v45, 0xbfb8aa3b, v45
	v_exp_f32_e32 v45, v45
	v_add_f32_e32 v44, v44, v36
	v_mul_f32_e32 v44, 0xbfb8aa3b, v44
	v_add_f32_e32 v46, 1.0, v46
	v_exp_f32_e32 v44, v44
	v_add_f32_e32 v43, v43, v35
	v_rcp_f32_e32 v46, v46
	v_mul_f32_e32 v43, 0xbfb8aa3b, v43
	v_sqrt_f32_e32 v87, v87
	v_add_f32_e32 v45, 1.0, v45
	v_exp_f32_e32 v43, v43
	v_add_f32_e32 v42, v42, v34
	v_rcp_f32_e32 v45, v45
	v_mul_f32_e32 v42, 0xbfb8aa3b, v42
	v_lshlrev_b32_e32 v88, 16, v99
	v_sqrt_f32_e32 v85, v85
	v_add_f32_e32 v44, 1.0, v44
	v_exp_f32_e32 v42, v42
	v_add_f32_e32 v41, v41, v33
	v_mul_f32_e32 v46, v46, v88
	v_rcp_f32_e32 v44, v44
	v_mul_f32_e32 v41, 0xbfb8aa3b, v41
	v_mul_f32_e32 v46, v46, v87
	v_and_b32_e32 v87, 0xffff0000, v98
	v_sqrt_f32_e32 v84, v84
	v_add_f32_e32 v43, 1.0, v43
	v_exp_f32_e32 v41, v41
	v_add_f32_e32 v40, v40, v32
	v_mul_f32_e32 v45, v45, v87
	v_rcp_f32_e32 v43, v43
	v_mul_f32_e32 v40, 0xbfb8aa3b, v40
	v_mul_f32_e32 v45, v45, v85
	v_lshlrev_b32_e32 v85, 16, v98
	v_sqrt_f32_e32 v83, v83
	v_add_f32_e32 v42, 1.0, v42
	v_exp_f32_e32 v40, v40
	v_add_f32_e32 v47, v47, v39
	v_mul_f32_e32 v44, v44, v85
	v_rcp_f32_e32 v42, v42
	v_add_f32_e32 v28, v28, v68
	v_mul_f32_e32 v47, 0xbfb8aa3b, v47
	v_mul_f32_e32 v44, v44, v84
	v_and_b32_e32 v84, 0xffff0000, v97
	v_sqrt_f32_e32 v82, v82
	v_add_f32_e32 v41, 1.0, v41
	v_mul_f32_e32 v28, 0xbfb8aa3b, v28
	v_exp_f32_e32 v47, v47
	v_mul_f32_e32 v43, v43, v84
	v_rcp_f32_e32 v41, v41
	v_exp_f32_e32 v28, v28
	v_mul_f32_e32 v43, v43, v83
	v_lshlrev_b32_e32 v83, 16, v97
	v_sqrt_f32_e32 v81, v81
	v_add_f32_e32 v40, 1.0, v40
	v_mul_f32_e32 v42, v42, v83
	v_rcp_f32_e32 v40, v40
	v_mul_f32_e32 v42, v42, v82
	v_and_b32_e32 v82, 0xffff0000, v96
	v_add_f32_e32 v47, 1.0, v47
	v_mul_f32_e32 v41, v41, v82
	v_sqrt_f32_e32 v80, v80
	v_add_f32_e32 v28, 1.0, v28
	v_rcp_f32_e32 v47, v47
	v_mul_f32_e32 v41, v41, v81
	v_lshlrev_b32_e32 v81, 16, v96
	v_rcp_f32_e32 v28, v28
	v_mul_f32_e32 v40, v40, v81
	v_sqrt_f32_e32 v81, v86
	v_mul_f32_e32 v40, v40, v80
	v_and_b32_e32 v80, 0xffff0000, v99
	v_cvt_pk_bf16_f32 v44, v60, v44
	v_cvt_pk_bf16_f32 v45, v61, v45
	v_lshlrev_b64 v[60:61], 13, v[202:203]
	v_mul_f32_e32 v47, v47, v80
	v_lshl_add_u64 v[60:61], s[44:45], 0, v[60:61]
	v_mul_f32_e32 v28, 0xc1000000, v28
	v_mul_f32_e32 v47, v47, v81
	v_cvt_pk_bf16_f32 v40, v72, v40
	v_cvt_pk_bf16_f32 v41, v73, v41
	v_cvt_pk_bf16_f32 v42, v74, v42
	v_cvt_pk_bf16_f32 v43, v75, v43
	v_lshl_add_u64 v[60:61], v[196:197], 2, v[60:61]
	v_mul_f32_e32 v28, v64, v28
	v_cvt_pk_bf16_f32 v46, v62, v46
	v_cvt_pk_bf16_f32 v47, v63, v47
	global_store_dwordx4 v[60:61], v[40:43], off
	global_store_dwordx4 v[60:61], v[44:47], off offset:16
	s_nop 0
	v_add_f32_e32 v41, v28, v28
	v_cmp_nlt_f32_e32 vcc, s4, v41
	s_and_saveexec_b64 s[0:1], vcc
	s_xor_b64 s[0:1], exec, s[0:1]
	v_mul_f32_e32 v40, 0x3fb8aa3b, v41
	v_exp_f32_e32 v40, v40
	s_nop 0
	v_sub_f32_e32 v40, 1.0, v40
	s_andn2_saveexec_b64 s[0:1], s[0:1]
	v_fmamk_f32 v40, v41, 0x3d2aaaab, v229
	v_fma_f32 v40, v41, v40, 0.5
	v_fma_f32 v40, v41, v40, 1.0
	v_mul_f32_e64 v40, v40, -v41
	s_or_b64 exec, exec, s[0:1]
	v_add_f32_e32 v29, v29, v69
	v_mul_f32_e32 v29, 0xbfb8aa3b, v29
	v_exp_f32_e32 v29, v29
	s_nop 0
	v_add_f32_e32 v29, 1.0, v29
	v_rcp_f32_e32 v29, v29
	s_nop 0
	v_mul_f32_e32 v29, 0xc1000000, v29
	v_mul_f32_e32 v29, v65, v29
	v_add_f32_e32 v42, v29, v29
	v_cmp_nlt_f32_e32 vcc, s4, v42
	s_and_saveexec_b64 s[0:1], vcc
	s_xor_b64 s[0:1], exec, s[0:1]
	v_mul_f32_e32 v41, 0x3fb8aa3b, v42
	v_exp_f32_e32 v41, v41
	s_nop 0
	v_sub_f32_e32 v41, 1.0, v41
	s_andn2_saveexec_b64 s[0:1], s[0:1]
	v_fmamk_f32 v41, v42, 0x3d2aaaab, v229
	v_fma_f32 v41, v42, v41, 0.5
	v_fma_f32 v41, v42, v41, 1.0
	v_mul_f32_e64 v41, v41, -v42
	s_or_b64 exec, exec, s[0:1]
	v_add_f32_e32 v30, v30, v70
	v_mul_f32_e32 v30, 0xbfb8aa3b, v30
	v_exp_f32_e32 v30, v30
	s_nop 0
	v_add_f32_e32 v30, 1.0, v30
	v_rcp_f32_e32 v30, v30
	s_nop 0
	v_mul_f32_e32 v30, 0xc1000000, v30
	v_mul_f32_e32 v30, v66, v30
	v_add_f32_e32 v43, v30, v30
	v_cmp_nlt_f32_e32 vcc, s4, v43
	s_and_saveexec_b64 s[0:1], vcc
	s_xor_b64 s[0:1], exec, s[0:1]
	v_mul_f32_e32 v42, 0x3fb8aa3b, v43
	v_exp_f32_e32 v42, v42
	s_nop 0
	v_sub_f32_e32 v42, 1.0, v42
	s_andn2_saveexec_b64 s[0:1], s[0:1]
	v_fmamk_f32 v42, v43, 0x3d2aaaab, v229
	v_fma_f32 v42, v43, v42, 0.5
	v_fma_f32 v42, v43, v42, 1.0
	v_mul_f32_e64 v42, v42, -v43
	s_or_b64 exec, exec, s[0:1]
	v_add_f32_e32 v31, v31, v71
	v_mul_f32_e32 v31, 0xbfb8aa3b, v31
	v_exp_f32_e32 v31, v31
	s_nop 0
	v_add_f32_e32 v31, 1.0, v31
	v_rcp_f32_e32 v31, v31
	s_nop 0
	v_mul_f32_e32 v31, 0xc1000000, v31
	v_mul_f32_e32 v31, v67, v31
	v_add_f32_e32 v44, v31, v31
	v_cmp_nlt_f32_e32 vcc, s4, v44
	s_and_saveexec_b64 s[0:1], vcc
	s_xor_b64 s[0:1], exec, s[0:1]
	v_mul_f32_e32 v43, 0x3fb8aa3b, v44
; __device__ __forceinline__ unsigned pk2(float lo, float hi) { unsigned r; asm("v_cvt_pk_bf16_f32 %0, %1, %2" : "=v"(r) : "v"(lo), "v"(hi)); return r; }
; __device__ __forceinline__ float sigmoidf_(float x) { return __builtin_amdgcn_rcpf(1.0f + __expf(-x)); }
;     __device__ __forceinline__ void operator()(const f32x4 (&acc)[2][2][4][2], const Unit& u, int wr, int wc, int fr, int fq) const {
;     ...
;         for (int ai = 0; ai < 2; ++ai)
; #pragma unroll
;             for (int m = 0; m < 4; ++m) { const size_t off = (size_t)(row0 + ai * HALF + m * 16) * LW + ch0;
;                 float xc[8]; unpack8(xraw[ai][m], xc);
;                 float la[8], uu[8];
; #pragma unroll
;                 for (int n = 0; n < 2; ++n)
; #pragma unroll
;                     for (int j = 0; j < 4; ++j) { const int e = 4 * n + j;
;                         const float r = sigmoidf_(acc[ai][0][m][n][j] + br[e]), ig = sigmoidf_(acc[ai][1][m][n][j] + bi[e]);
;                         const float l = -8.0f * r * sp[e]; la[e] = l;
;                         const float x2 = 2.0f * l;
;                         const float om = x2 > -0.03125f ? -x2 * (1.0f + x2 * (0.5f + x2 * (0.16666667f + x2 * 0.041666668f))) : 1.0f - __expf(x2);
;                         uu[e] = __builtin_amdgcn_sqrtf(om) * (ig * xc[e]); }
;                 u32x4 w0, w1; w0.x = pk2(la[0], uu[0]); w0.y = pk2(la[1], uu[1]); w0.z = pk2(la[2], uu[2]); w0.w = pk2(la[3], uu[3]);
;                 w1.x = pk2(la[4], uu[4]); w1.y = pk2(la[5], uu[5]); w1.z = pk2(la[6], uu[6]); w1.w = pk2(la[7], uu[7]);
;                 *(u32x4*)(LU + off) = w0; *(u32x4*)(LU + off + 4) = w1; }
	v_exp_f32_e32 v43, v43
	s_nop 0
	v_sub_f32_e32 v43, 1.0, v43
	s_andn2_saveexec_b64 s[0:1], s[0:1]
	v_fmamk_f32 v43, v44, 0x3d2aaaab, v229
	v_fma_f32 v43, v44, v43, 0.5
	v_fma_f32 v43, v44, v43, 1.0
	v_mul_f32_e64 v43, v43, -v44
	s_or_b64 exec, exec, s[0:1]
	v_add_f32_e32 v24, v24, v56
	v_mul_f32_e32 v24, 0xbfb8aa3b, v24
	v_exp_f32_e32 v24, v24
	s_nop 0
	v_add_f32_e32 v24, 1.0, v24
	v_rcp_f32_e32 v24, v24
	s_nop 0
	v_mul_f32_e32 v24, 0xc1000000, v24
	v_mul_f32_e32 v24, v52, v24
	v_add_f32_e32 v45, v24, v24
	v_cmp_nlt_f32_e32 vcc, s4, v45
	s_and_saveexec_b64 s[0:1], vcc
	s_xor_b64 s[0:1], exec, s[0:1]
	v_mul_f32_e32 v44, 0x3fb8aa3b, v45
	v_exp_f32_e32 v44, v44
	s_nop 0
	v_sub_f32_e32 v44, 1.0, v44
	s_andn2_saveexec_b64 s[0:1], s[0:1]
	v_fmamk_f32 v44, v45, 0x3d2aaaab, v229
	v_fma_f32 v44, v45, v44, 0.5
	v_fma_f32 v44, v45, v44, 1.0
	v_mul_f32_e64 v44, v44, -v45
	s_or_b64 exec, exec, s[0:1]
	v_add_f32_e32 v25, v25, v57
	v_mul_f32_e32 v25, 0xbfb8aa3b, v25
	v_exp_f32_e32 v25, v25
	s_nop 0
	v_add_f32_e32 v25, 1.0, v25
	v_rcp_f32_e32 v25, v25
	s_nop 0
	v_mul_f32_e32 v25, 0xc1000000, v25
	v_mul_f32_e32 v25, v53, v25
	v_add_f32_e32 v46, v25, v25
	v_cmp_nlt_f32_e32 vcc, s4, v46
	s_and_saveexec_b64 s[0:1], vcc
	s_xor_b64 s[0:1], exec, s[0:1]
	v_mul_f32_e32 v45, 0x3fb8aa3b, v46
	v_exp_f32_e32 v45, v45
	s_nop 0
	v_sub_f32_e32 v45, 1.0, v45
	s_andn2_saveexec_b64 s[0:1], s[0:1]
	v_fmamk_f32 v45, v46, 0x3d2aaaab, v229
	v_fma_f32 v45, v46, v45, 0.5
	v_fma_f32 v45, v46, v45, 1.0
	v_mul_f32_e64 v45, v45, -v46
	s_or_b64 exec, exec, s[0:1]
	v_add_f32_e32 v26, v26, v58
	v_mul_f32_e32 v26, 0xbfb8aa3b, v26
	v_exp_f32_e32 v26, v26
	s_nop 0
	v_add_f32_e32 v26, 1.0, v26
	v_rcp_f32_e32 v26, v26
	s_nop 0
	v_mul_f32_e32 v26, 0xc1000000, v26
	v_mul_f32_e32 v26, v54, v26
	v_add_f32_e32 v46, v26, v26
	v_cmp_nlt_f32_e32 vcc, s4, v46
	s_and_saveexec_b64 s[0:1], vcc
	s_xor_b64 s[0:1], exec, s[0:1]
	v_mul_f32_e32 v46, 0x3fb8aa3b, v46
	v_exp_f32_e32 v46, v46
	s_nop 0
	v_sub_f32_e32 v47, 1.0, v46
	s_andn2_saveexec_b64 s[0:1], s[0:1]
	v_fmamk_f32 v47, v46, 0x3d2aaaab, v229
	v_fma_f32 v47, v46, v47, 0.5
	v_fma_f32 v47, v46, v47, 1.0
	v_mul_f32_e64 v47, v47, -v46
	s_or_b64 exec, exec, s[0:1]
	v_add_f32_e32 v27, v27, v59
	v_mul_f32_e32 v27, 0xbfb8aa3b, v27
	v_exp_f32_e32 v27, v27
	s_nop 0
	v_add_f32_e32 v27, 1.0, v27
	v_rcp_f32_e32 v27, v27
	s_nop 0
	v_mul_f32_e32 v27, 0xc1000000, v27
	v_mul_f32_e32 v27, v55, v27
	v_add_f32_e32 v60, v27, v27
	v_cmp_nlt_f32_e32 vcc, s4, v60
	s_and_saveexec_b64 s[0:1], vcc
	s_xor_b64 s[0:1], exec, s[0:1]
	v_mul_f32_e32 v46, 0x3fb8aa3b, v60
	v_exp_f32_e32 v46, v46
	s_nop 0
	v_sub_f32_e32 v46, 1.0, v46
	s_andn2_saveexec_b64 s[0:1], s[0:1]
	v_fmamk_f32 v46, v60, 0x3d2aaaab, v229
	v_fma_f32 v46, v60, v46, 0.5
	v_fma_f32 v46, v60, v46, 1.0
	v_mul_f32_e64 v46, v46, -v60
	s_or_b64 exec, exec, s[0:1]
	v_add_f32_e32 v22, v22, v38
	v_mul_f32_e32 v22, 0xbfb8aa3b, v22
	v_exp_f32_e32 v22, v22
	v_add_f32_e32 v21, v21, v37
	v_mul_f32_e32 v21, 0xbfb8aa3b, v21
	v_exp_f32_e32 v21, v21
	v_add_f32_e32 v20, v20, v36
	v_mul_f32_e32 v20, 0xbfb8aa3b, v20
	v_add_f32_e32 v22, 1.0, v22
	v_exp_f32_e32 v20, v20
	v_add_f32_e32 v19, v19, v35
	v_rcp_f32_e32 v22, v22
	v_mul_f32_e32 v19, 0xbfb8aa3b, v19
	v_sqrt_f32_e32 v47, v47
	v_add_f32_e32 v21, 1.0, v21
	v_exp_f32_e32 v19, v19
	v_add_f32_e32 v18, v18, v34
	v_rcp_f32_e32 v21, v21
	v_mul_f32_e32 v18, 0xbfb8aa3b, v18
	v_lshlrev_b32_e32 v60, 16, v79
	v_sqrt_f32_e32 v45, v45
	v_add_f32_e32 v20, 1.0, v20
	v_exp_f32_e32 v18, v18
	v_add_f32_e32 v17, v17, v33
	v_mul_f32_e32 v22, v22, v60
	v_rcp_f32_e32 v20, v20
	v_mul_f32_e32 v17, 0xbfb8aa3b, v17
	v_mul_f32_e32 v22, v22, v47
	v_and_b32_e32 v47, 0xffff0000, v78
	v_sqrt_f32_e32 v44, v44
	v_add_f32_e32 v19, 1.0, v19
	v_exp_f32_e32 v17, v17
	v_add_f32_e32 v16, v16, v32
	v_mul_f32_e32 v21, v21, v47
	v_rcp_f32_e32 v19, v19
	v_mul_f32_e32 v16, 0xbfb8aa3b, v16
	v_mul_f32_e32 v21, v21, v45
	v_lshlrev_b32_e32 v45, 16, v78
	v_sqrt_f32_e32 v43, v43
	v_add_f32_e32 v18, 1.0, v18
	v_exp_f32_e32 v16, v16
	v_add_f32_e32 v23, v23, v39
	v_mul_f32_e32 v20, v20, v45
	v_rcp_f32_e32 v18, v18
	v_add_f32_e32 v12, v12, v68
	v_mul_f32_e32 v23, 0xbfb8aa3b, v23
	v_mul_f32_e32 v20, v20, v44
	v_and_b32_e32 v44, 0xffff0000, v77
	v_sqrt_f32_e32 v42, v42
	v_add_f32_e32 v17, 1.0, v17
	v_mul_f32_e32 v12, 0xbfb8aa3b, v12
	v_exp_f32_e32 v23, v23
	v_mul_f32_e32 v19, v19, v44
	v_rcp_f32_e32 v17, v17
	v_exp_f32_e32 v12, v12
	v_mul_f32_e32 v19, v19, v43
	v_lshlrev_b32_e32 v43, 16, v77
	v_sqrt_f32_e32 v41, v41
	v_add_f32_e32 v16, 1.0, v16
	v_mul_f32_e32 v18, v18, v43
	v_rcp_f32_e32 v16, v16
	v_mul_f32_e32 v18, v18, v42
	v_and_b32_e32 v42, 0xffff0000, v76
	v_add_f32_e32 v23, 1.0, v23
	v_mul_f32_e32 v17, v17, v42
	v_sqrt_f32_e32 v40, v40
	v_add_f32_e32 v12, 1.0, v12
	v_rcp_f32_e32 v23, v23
	v_mul_f32_e32 v17, v17, v41
	v_lshlrev_b32_e32 v41, 16, v76
	v_rcp_f32_e32 v12, v12
	v_mul_f32_e32 v16, v16, v41
	v_sqrt_f32_e32 v41, v46
	v_mul_f32_e32 v16, v16, v40
	v_and_b32_e32 v40, 0xffff0000, v79
	v_cvt_pk_bf16_f32 v20, v24, v20
	v_cvt_pk_bf16_f32 v21, v25, v21
	v_lshlrev_b64 v[24:25], 13, v[200:201]
	v_mul_f32_e32 v23, v23, v40
	v_lshl_add_u64 v[24:25], s[44:45], 0, v[24:25]
	v_mul_f32_e32 v12, 0xc1000000, v12
	v_mul_f32_e32 v23, v23, v41
	v_cvt_pk_bf16_f32 v16, v28, v16
; __device__ __forceinline__ unsigned pk2(float lo, float hi) { unsigned r; asm("v_cvt_pk_bf16_f32 %0, %1, %2" : "=v"(r) : "v"(lo), "v"(hi)); return r; }
; __device__ __forceinline__ float sigmoidf_(float x) { return __builtin_amdgcn_rcpf(1.0f + __expf(-x)); }
;     __device__ __forceinline__ void operator()(const f32x4 (&acc)[2][2][4][2], const Unit& u, int wr, int wc, int fr, int fq) const {
;     ...
;         for (int ai = 0; ai < 2; ++ai)
; #pragma unroll
;             for (int m = 0; m < 4; ++m) { const size_t off = (size_t)(row0 + ai * HALF + m * 16) * LW + ch0;
;                 float xc[8]; unpack8(xraw[ai][m], xc);
;                 float la[8], uu[8];
; #pragma unroll
;                 for (int n = 0; n < 2; ++n)
; #pragma unroll
;                     for (int j = 0; j < 4; ++j) { const int e = 4 * n + j;
;                         const float r = sigmoidf_(acc[ai][0][m][n][j] + br[e]), ig = sigmoidf_(acc[ai][1][m][n][j] + bi[e]);
;                         const float l = -8.0f * r * sp[e]; la[e] = l;
;                         const float x2 = 2.0f * l;
;                         const float om = x2 > -0.03125f ? -x2 * (1.0f + x2 * (0.5f + x2 * (0.16666667f + x2 * 0.041666668f))) : 1.0f - __expf(x2);
;                         uu[e] = __builtin_amdgcn_sqrtf(om) * (ig * xc[e]); }
;                 u32x4 w0, w1; w0.x = pk2(la[0], uu[0]); w0.y = pk2(la[1], uu[1]); w0.z = pk2(la[2], uu[2]); w0.w = pk2(la[3], uu[3]);
;                 w1.x = pk2(la[4], uu[4]); w1.y = pk2(la[5], uu[5]); w1.z = pk2(la[6], uu[6]); w1.w = pk2(la[7], uu[7]);
;                 *(u32x4*)(LU + off) = w0; *(u32x4*)(LU + off + 4) = w1; }
	v_cvt_pk_bf16_f32 v17, v29, v17
	v_cvt_pk_bf16_f32 v18, v30, v18
	v_cvt_pk_bf16_f32 v19, v31, v19
	v_lshl_add_u64 v[24:25], v[196:197], 2, v[24:25]
	v_mul_f32_e32 v12, v64, v12
	v_cvt_pk_bf16_f32 v22, v26, v22
	v_cvt_pk_bf16_f32 v23, v27, v23
	global_store_dwordx4 v[24:25], v[16:19], off
	global_store_dwordx4 v[24:25], v[20:23], off offset:16
	s_nop 0
	v_add_f32_e32 v17, v12, v12
	v_cmp_nlt_f32_e32 vcc, s4, v17
	s_and_saveexec_b64 s[0:1], vcc
	s_xor_b64 s[0:1], exec, s[0:1]
	v_mul_f32_e32 v16, 0x3fb8aa3b, v17
	v_exp_f32_e32 v16, v16
	s_nop 0
	v_sub_f32_e32 v16, 1.0, v16
	s_andn2_saveexec_b64 s[0:1], s[0:1]
	v_fmamk_f32 v16, v17, 0x3d2aaaab, v229
	v_fma_f32 v16, v17, v16, 0.5
	v_fma_f32 v16, v17, v16, 1.0
	v_mul_f32_e64 v16, v16, -v17
	s_or_b64 exec, exec, s[0:1]
	v_add_f32_e32 v13, v13, v69
	v_mul_f32_e32 v13, 0xbfb8aa3b, v13
	v_exp_f32_e32 v13, v13
	s_nop 0
	v_add_f32_e32 v13, 1.0, v13
	v_rcp_f32_e32 v13, v13
	s_nop 0
	v_mul_f32_e32 v13, 0xc1000000, v13
	v_mul_f32_e32 v13, v65, v13
	v_add_f32_e32 v18, v13, v13
	v_cmp_nlt_f32_e32 vcc, s4, v18
	s_and_saveexec_b64 s[0:1], vcc
	s_xor_b64 s[0:1], exec, s[0:1]
	v_mul_f32_e32 v17, 0x3fb8aa3b, v18
	v_exp_f32_e32 v17, v17
	s_nop 0
	v_sub_f32_e32 v17, 1.0, v17
	s_andn2_saveexec_b64 s[0:1], s[0:1]
	v_fmamk_f32 v17, v18, 0x3d2aaaab, v229
	v_fma_f32 v17, v18, v17, 0.5
	v_fma_f32 v17, v18, v17, 1.0
	v_mul_f32_e64 v17, v17, -v18
	s_or_b64 exec, exec, s[0:1]
	v_add_f32_e32 v14, v14, v70
	v_mul_f32_e32 v14, 0xbfb8aa3b, v14
	v_exp_f32_e32 v14, v14
	s_nop 0
	v_add_f32_e32 v14, 1.0, v14
	v_rcp_f32_e32 v14, v14
	s_nop 0
	v_mul_f32_e32 v14, 0xc1000000, v14
	v_mul_f32_e32 v14, v66, v14
	v_add_f32_e32 v19, v14, v14
	v_cmp_nlt_f32_e32 vcc, s4, v19
	s_and_saveexec_b64 s[0:1], vcc
	s_xor_b64 s[0:1], exec, s[0:1]
	v_mul_f32_e32 v18, 0x3fb8aa3b, v19
	v_exp_f32_e32 v18, v18
	s_nop 0
	v_sub_f32_e32 v18, 1.0, v18
	s_andn2_saveexec_b64 s[0:1], s[0:1]
	v_fmamk_f32 v18, v19, 0x3d2aaaab, v229
	v_fma_f32 v18, v19, v18, 0.5
	v_fma_f32 v18, v19, v18, 1.0
	v_mul_f32_e64 v18, v18, -v19
	s_or_b64 exec, exec, s[0:1]
	v_add_f32_e32 v15, v15, v71
	v_mul_f32_e32 v15, 0xbfb8aa3b, v15
	v_exp_f32_e32 v15, v15
	s_nop 0
	v_add_f32_e32 v15, 1.0, v15
	v_rcp_f32_e32 v15, v15
	s_nop 0
	v_mul_f32_e32 v15, 0xc1000000, v15
	v_mul_f32_e32 v15, v67, v15
	v_add_f32_e32 v20, v15, v15
	v_cmp_nlt_f32_e32 vcc, s4, v20
	s_and_saveexec_b64 s[0:1], vcc
	s_xor_b64 s[0:1], exec, s[0:1]
	v_mul_f32_e32 v19, 0x3fb8aa3b, v20
	v_exp_f32_e32 v19, v19
	s_nop 0
	v_sub_f32_e32 v19, 1.0, v19
	s_andn2_saveexec_b64 s[0:1], s[0:1]
	v_fmamk_f32 v19, v20, 0x3d2aaaab, v229
	v_fma_f32 v19, v20, v19, 0.5
	v_fma_f32 v19, v20, v19, 1.0
	v_mul_f32_e64 v19, v19, -v20
	s_or_b64 exec, exec, s[0:1]
	v_add_f32_e32 v8, v8, v56
	v_mul_f32_e32 v8, 0xbfb8aa3b, v8
	v_exp_f32_e32 v8, v8
	s_nop 0
	v_add_f32_e32 v8, 1.0, v8
	v_rcp_f32_e32 v8, v8
	s_nop 0
	v_mul_f32_e32 v8, 0xc1000000, v8
	v_mul_f32_e32 v8, v52, v8
	v_add_f32_e32 v21, v8, v8
	v_cmp_nlt_f32_e32 vcc, s4, v21
	s_and_saveexec_b64 s[0:1], vcc
	s_xor_b64 s[0:1], exec, s[0:1]
	v_mul_f32_e32 v20, 0x3fb8aa3b, v21
	v_exp_f32_e32 v20, v20
	s_nop 0
	v_sub_f32_e32 v20, 1.0, v20
	s_andn2_saveexec_b64 s[0:1], s[0:1]
	v_fmamk_f32 v20, v21, 0x3d2aaaab, v229
	v_fma_f32 v20, v21, v20, 0.5
	v_fma_f32 v20, v21, v20, 1.0
	v_mul_f32_e64 v20, v20, -v21
	s_or_b64 exec, exec, s[0:1]
	v_add_f32_e32 v9, v9, v57
	v_mul_f32_e32 v9, 0xbfb8aa3b, v9
	v_exp_f32_e32 v9, v9
	s_nop 0
	v_add_f32_e32 v9, 1.0, v9
	v_rcp_f32_e32 v9, v9
	s_nop 0
	v_mul_f32_e32 v9, 0xc1000000, v9
	v_mul_f32_e32 v9, v53, v9
	v_add_f32_e32 v22, v9, v9
	v_cmp_nlt_f32_e32 vcc, s4, v22
	s_and_saveexec_b64 s[0:1], vcc
	s_xor_b64 s[0:1], exec, s[0:1]
	v_mul_f32_e32 v21, 0x3fb8aa3b, v22
	v_exp_f32_e32 v21, v21
	s_nop 0
	v_sub_f32_e32 v21, 1.0, v21
	s_andn2_saveexec_b64 s[0:1], s[0:1]
	v_fmamk_f32 v21, v22, 0x3d2aaaab, v229
	v_fma_f32 v21, v22, v21, 0.5
	v_fma_f32 v21, v22, v21, 1.0
	v_mul_f32_e64 v21, v21, -v22
	s_or_b64 exec, exec, s[0:1]
	v_add_f32_e32 v10, v10, v58
	v_mul_f32_e32 v10, 0xbfb8aa3b, v10
	v_exp_f32_e32 v10, v10
	s_nop 0
	v_add_f32_e32 v10, 1.0, v10
	v_rcp_f32_e32 v10, v10
	s_nop 0
	v_mul_f32_e32 v10, 0xc1000000, v10
	v_mul_f32_e32 v10, v54, v10
	v_add_f32_e32 v22, v10, v10
	v_cmp_nlt_f32_e32 vcc, s4, v22
	s_and_saveexec_b64 s[0:1], vcc
	s_xor_b64 s[0:1], exec, s[0:1]
	v_mul_f32_e32 v22, 0x3fb8aa3b, v22
	v_exp_f32_e32 v22, v22
	s_nop 0
	v_sub_f32_e32 v23, 1.0, v22
	s_andn2_saveexec_b64 s[0:1], s[0:1]
	v_fmamk_f32 v23, v22, 0x3d2aaaab, v229
	v_fma_f32 v23, v22, v23, 0.5
	v_fma_f32 v23, v22, v23, 1.0
	v_mul_f32_e64 v23, v23, -v22
	s_or_b64 exec, exec, s[0:1]
	v_add_f32_e32 v11, v11, v59
	v_mul_f32_e32 v11, 0xbfb8aa3b, v11
	v_exp_f32_e32 v11, v11
	s_nop 0
	v_add_f32_e32 v11, 1.0, v11
	v_rcp_f32_e32 v11, v11
	s_nop 0
	v_mul_f32_e32 v11, 0xc1000000, v11
	v_mul_f32_e32 v11, v55, v11
	v_add_f32_e32 v24, v11, v11
	v_cmp_nlt_f32_e32 vcc, s4, v24
	s_and_saveexec_b64 s[0:1], vcc
	s_xor_b64 s[0:1], exec, s[0:1]
	v_mul_f32_e32 v22, 0x3fb8aa3b, v24
	v_exp_f32_e32 v22, v22
	s_nop 0
	v_sub_f32_e32 v22, 1.0, v22
	s_andn2_saveexec_b64 s[0:1], s[0:1]
	s_cbranch_execz .LBB0_543
	v_fmamk_f32 v22, v24, 0x3d2aaaab, v229
	v_fma_f32 v22, v24, v22, 0.5
	v_fma_f32 v22, v24, v22, 1.0
	v_mul_f32_e64 v22, v22, -v24
	s_branch .LBB0_543

; #define LAS __attribute__((address_space(3)))
; __device__ __forceinline__ float bflo(unsigned w) { return __uint_as_float(w << 16); }
; __device__ __forceinline__ float bfhi(unsigned w) { return __uint_as_float(w & 0xffff0000u); }
; __device__ __forceinline__ void phase_scan(const Params& p, LAS unsigned char* lds) {
;     const int tid = threadIdx.x;
;     const unsigned* LU = (const unsigned*)(p.ws + WS_LA); bf16_t* YL = (bf16_t*)(p.ws + WS_YL);
;     LAS float* sA = (LAS float*)lds; LAS float* sH = sA + 512;
;     for (int item = blockIdx.x; item < 256; item += gridDim.x) {
;         const int b = item >> 6, c32 = tid & 31, ch = (item & 63) * 32 + c32, chunk = tid >> 5;
;         const size_t base = (size_t)(b * SEQ + chunk * 128) * LW + ch;
;         float h = 0.f, sla = 0.f;
; #pragma unroll 8
;         for (int s = 0; s < 128; ++s) { const unsigned lw = LU[base + (size_t)s * LW]; const float la = bflo(lw), u = bfhi(lw); h = __expf(la) * h + u; sla += la; }
.LBB0_858:
	s_or_b64 exec, exec, s[6:7]
	s_cmpk_lt_i32 s2, 0x100
	s_cselect_b64 s[56:57], -1, 0
	s_cmpk_gt_i32 s2, 0xff
	s_waitcnt lgkmcnt(0)
	s_barrier
	s_cbranch_scc1 .LBB0_877
	v_lshrrev_b32_e32 v128, 5, v212
	v_and_b32_e32 v129, 31, v212
	v_lshlrev_b32_e32 v130, 20, v128
	v_lshlrev_b32_e32 v148, 2, v129
	v_or_b32_e32 v130, v130, v148
	v_add_u32_e32 v131, 0x2000, v130
	v_add_u32_e32 v132, 0x4000, v130
	v_add_u32_e32 v133, 0x6000, v130
	v_lshlrev_b32_e32 v134, 19, v128
	v_lshl_or_b32 v134, v129, 1, v134
	v_add_u32_e32 v135, 0x1000, v134
	v_add_u32_e32 v136, 0x2000, v134
	v_add_u32_e32 v137, 0x3000, v134
	v_readlane_b32 s68, v254, 47
	v_readlane_b32 s69, v254, 48
.Lscan_top:
	s_mov_b32 s33, s2
.Lscan_item:
	s_lshr_b32 s0, s33, 6
	s_and_b32 s1, s33, 63
	s_lshl_b32 s42, s0, 24
	s_lshl_b32 s43, s1, 7
	s_add_u32 s42, s42, s43
	s_add_u32 s64, s84, 0x6d00000
	s_addc_u32 s65, s85, 0
	s_add_u32 s64, s64, s42
	s_addc_u32 s65, s65, 0
	s_lshl_b32 s42, s0, 23
	s_lshl_b32 s43, s1, 6
	s_add_u32 s42, s42, s43
	s_add_u32 s66, s84, 0x15b00000
	s_addc_u32 s67, s85, 0
	s_add_u32 s66, s66, s42
	s_addc_u32 s67, s67, 0
	s_lshl_b32 s42, s0, 13
	s_add_u32 s42, s42, s43
	s_add_u32 s42, s42, s43
	s_add_u32 s70, s68, 0x4854000
	s_addc_u32 s71, s69, 0
	s_add_u32 s70, s70, s42
	s_addc_u32 s71, s71, 0
	global_load_dword v0, v130, s[64:65]
	global_load_dword v1, v131, s[64:65]
	global_load_dword v2, v132, s[64:65]
	global_load_dword v3, v133, s[64:65]
	s_add_u32 s64, s64, 0x8000
	s_addc_u32 s65, s65, 0
	global_load_dword v4, v130, s[64:65]
	global_load_dword v5, v131, s[64:65]
	global_load_dword v6, v132, s[64:65]
	global_load_dword v7, v133, s[64:65]
	s_add_u32 s64, s64, 0x8000
	s_addc_u32 s65, s65, 0
	global_load_dword v8, v130, s[64:65]
	global_load_dword v9, v131, s[64:65]
	global_load_dword v10, v132, s[64:65]
	global_load_dword v11, v133, s[64:65]
	s_add_u32 s64, s64, 0x8000
	s_addc_u32 s65, s65, 0
	global_load_dword v12, v130, s[64:65]
	global_load_dword v13, v131, s[64:65]
	global_load_dword v14, v132, s[64:65]
	global_load_dword v15, v133, s[64:65]
	s_add_u32 s64, s64, 0x8000
	s_addc_u32 s65, s65, 0
	global_load_dword v16, v130, s[64:65]
	global_load_dword v17, v131, s[64:65]
	global_load_dword v18, v132, s[64:65]
	global_load_dword v19, v133, s[64:65]
	s_add_u32 s64, s64, 0x8000
	s_addc_u32 s65, s65, 0
	global_load_dword v20, v130, s[64:65]
	global_load_dword v21, v131, s[64:65]
	global_load_dword v22, v132, s[64:65]
	global_load_dword v23, v133, s[64:65]
	s_add_u32 s64, s64, 0x8000
	s_addc_u32 s65, s65, 0
	global_load_dword v24, v130, s[64:65]
	global_load_dword v25, v131, s[64:65]
	global_load_dword v26, v132, s[64:65]
	global_load_dword v27, v133, s[64:65]
	s_add_u32 s64, s64, 0x8000
	s_addc_u32 s65, s65, 0
	global_load_dword v28, v130, s[64:65]
	global_load_dword v29, v131, s[64:65]
	global_load_dword v30, v132, s[64:65]
	global_load_dword v31, v133, s[64:65]
	s_add_u32 s64, s64, 0x8000
	s_addc_u32 s65, s65, 0
	global_load_dword v32, v130, s[64:65]
	global_load_dword v33, v131, s[64:65]
	global_load_dword v34, v132, s[64:65]
	global_load_dword v35, v133, s[64:65]
	s_add_u32 s64, s64, 0x8000
	s_addc_u32 s65, s65, 0
	global_load_dword v36, v130, s[64:65]
	global_load_dword v37, v131, s[64:65]
	global_load_dword v38, v132, s[64:65]
	global_load_dword v39, v133, s[64:65]
	s_add_u32 s64, s64, 0x8000
	s_addc_u32 s65, s65, 0
	global_load_dword v40, v130, s[64:65]
	global_load_dword v41, v131, s[64:65]
	global_load_dword v42, v132, s[64:65]
	global_load_dword v43, v133, s[64:65]
	s_add_u32 s64, s64, 0x8000
	s_addc_u32 s65, s65, 0
	global_load_dword v44, v130, s[64:65]
	global_load_dword v45, v131, s[64:65]
	global_load_dword v46, v132, s[64:65]
	global_load_dword v47, v133, s[64:65]
	s_add_u32 s64, s64, 0x8000
	s_addc_u32 s65, s65, 0
	global_load_dword v48, v130, s[64:65]
	global_load_dword v49, v131, s[64:65]
	global_load_dword v50, v132, s[64:65]
	global_load_dword v51, v133, s[64:65]
	s_add_u32 s64, s64, 0x8000
	s_addc_u32 s65, s65, 0
	global_load_dword v52, v130, s[64:65]
	global_load_dword v53, v131, s[64:65]
	global_load_dword v54, v132, s[64:65]
	global_load_dword v55, v133, s[64:65]
	s_add_u32 s64, s64, 0x8000
	s_addc_u32 s65, s65, 0
	global_load_dword v56, v130, s[64:65]
	global_load_dword v57, v131, s[64:65]
	global_load_dword v58, v132, s[64:65]
	global_load_dword v59, v133, s[64:65]
	s_add_u32 s64, s64, 0x8000
	s_addc_u32 s65, s65, 0
	global_load_dword v60, v130, s[64:65]
	global_load_dword v61, v131, s[64:65]
	global_load_dword v62, v132, s[64:65]
	global_load_dword v63, v133, s[64:65]
	s_add_u32 s64, s64, 0x8000
	s_addc_u32 s65, s65, 0
	v_mov_b32_e32 v138, 0
	v_mov_b32_e32 v139, 0
	s_waitcnt vmcnt(63)
	v_lshlrev_b32_e32 v140, 16, v0
	v_and_b32_e32 v142, 0xffff0000, v0
	v_mul_f32_e32 v141, 0x3fb8aa3b, v140
	v_exp_f32_e32 v141, v141
	v_add_f32_e32 v139, v139, v140
	v_fma_f32 v138, v141, v138, v142
	global_load_dword v64, v130, s[64:65]
	s_waitcnt vmcnt(63)
	v_lshlrev_b32_e32 v143, 16, v1
	v_and_b32_e32 v145, 0xffff0000, v1
	v_mul_f32_e32 v144, 0x3fb8aa3b, v143
	v_exp_f32_e32 v144, v144
	v_add_f32_e32 v139, v139, v143
	v_fma_f32 v138, v144, v138, v145
	global_load_dword v65, v131, s[64:65]
	s_waitcnt vmcnt(63)
	v_lshlrev_b32_e32 v140, 16, v2
	v_and_b32_e32 v142, 0xffff0000, v2
	v_mul_f32_e32 v141, 0x3fb8aa3b, v140
	v_exp_f32_e32 v141, v141
	v_add_f32_e32 v139, v139, v140
	v_fma_f32 v138, v141, v138, v142
	global_load_dword v66, v132, s[64:65]
	s_waitcnt vmcnt(63)
	v_lshlrev_b32_e32 v143, 16, v3
	v_and_b32_e32 v145, 0xffff0000, v3
	v_mul_f32_e32 v144, 0x3fb8aa3b, v143
	v_exp_f32_e32 v144, v144
	v_add_f32_e32 v139, v139, v143
	v_fma_f32 v138, v144, v138, v145
	global_load_dword v67, v133, s[64:65]
	s_add_u32 s64, s64, 0x8000
	s_addc_u32 s65, s65, 0
	s_waitcnt vmcnt(63)
; __device__ __forceinline__ float bflo(unsigned w) { return __uint_as_float(w << 16); }
; __device__ __forceinline__ float bfhi(unsigned w) { return __uint_as_float(w & 0xffff0000u); }
; __device__ __forceinline__ void phase_scan(const Params& p, LAS unsigned char* lds) {
;     ...
;         float h = 0.f, sla = 0.f;
; #pragma unroll 8
;         for (int s = 0; s < 128; ++s) { const unsigned lw = LU[base + (size_t)s * LW]; const float la = bflo(lw), u = bfhi(lw); h = __expf(la) * h + u; sla += la; }
	v_lshlrev_b32_e32 v140, 16, v4
	v_and_b32_e32 v142, 0xffff0000, v4
	v_mul_f32_e32 v141, 0x3fb8aa3b, v140
	v_exp_f32_e32 v141, v141
	v_add_f32_e32 v139, v139, v140
	v_fma_f32 v138, v141, v138, v142
	global_load_dword v68, v130, s[64:65]
	s_waitcnt vmcnt(63)
	v_lshlrev_b32_e32 v143, 16, v5
	v_and_b32_e32 v145, 0xffff0000, v5
	v_mul_f32_e32 v144, 0x3fb8aa3b, v143
	v_exp_f32_e32 v144, v144
	v_add_f32_e32 v139, v139, v143
	v_fma_f32 v138, v144, v138, v145
	global_load_dword v69, v131, s[64:65]
	s_waitcnt vmcnt(63)
	v_lshlrev_b32_e32 v140, 16, v6
	v_and_b32_e32 v142, 0xffff0000, v6
	v_mul_f32_e32 v141, 0x3fb8aa3b, v140
	v_exp_f32_e32 v141, v141
	v_add_f32_e32 v139, v139, v140
	v_fma_f32 v138, v141, v138, v142
	global_load_dword v70, v132, s[64:65]
	s_waitcnt vmcnt(63)
	v_lshlrev_b32_e32 v143, 16, v7
	v_and_b32_e32 v145, 0xffff0000, v7
	v_mul_f32_e32 v144, 0x3fb8aa3b, v143
	v_exp_f32_e32 v144, v144
	v_add_f32_e32 v139, v139, v143
	v_fma_f32 v138, v144, v138, v145
	global_load_dword v71, v133, s[64:65]
	s_add_u32 s64, s64, 0x8000
	s_addc_u32 s65, s65, 0
	s_waitcnt vmcnt(63)
	v_lshlrev_b32_e32 v140, 16, v8
	v_and_b32_e32 v142, 0xffff0000, v8
	v_mul_f32_e32 v141, 0x3fb8aa3b, v140
	v_exp_f32_e32 v141, v141
	v_add_f32_e32 v139, v139, v140
	v_fma_f32 v138, v141, v138, v142
	global_load_dword v72, v130, s[64:65]
	s_waitcnt vmcnt(63)
	v_lshlrev_b32_e32 v143, 16, v9
	v_and_b32_e32 v145, 0xffff0000, v9
	v_mul_f32_e32 v144, 0x3fb8aa3b, v143
	v_exp_f32_e32 v144, v144
	v_add_f32_e32 v139, v139, v143
	v_fma_f32 v138, v144, v138, v145
	global_load_dword v73, v131, s[64:65]
	s_waitcnt vmcnt(63)
	v_lshlrev_b32_e32 v140, 16, v10
	v_and_b32_e32 v142, 0xffff0000, v10
	v_mul_f32_e32 v141, 0x3fb8aa3b, v140
	v_exp_f32_e32 v141, v141
	v_add_f32_e32 v139, v139, v140
	v_fma_f32 v138, v141, v138, v142
	global_load_dword v74, v132, s[64:65]
	s_waitcnt vmcnt(63)
	v_lshlrev_b32_e32 v143, 16, v11
	v_and_b32_e32 v145, 0xffff0000, v11
	v_mul_f32_e32 v144, 0x3fb8aa3b, v143
	v_exp_f32_e32 v144, v144
	v_add_f32_e32 v139, v139, v143
	v_fma_f32 v138, v144, v138, v145
	global_load_dword v75, v133, s[64:65]
	s_add_u32 s64, s64, 0x8000
	s_addc_u32 s65, s65, 0
	s_waitcnt vmcnt(63)
	v_lshlrev_b32_e32 v140, 16, v12
	v_and_b32_e32 v142, 0xffff0000, v12
	v_mul_f32_e32 v141, 0x3fb8aa3b, v140
	v_exp_f32_e32 v141, v141
	v_add_f32_e32 v139, v139, v140
	v_fma_f32 v138, v141, v138, v142
	global_load_dword v76, v130, s[64:65]
	s_waitcnt vmcnt(63)
	v_lshlrev_b32_e32 v143, 16, v13
	v_and_b32_e32 v145, 0xffff0000, v13
	v_mul_f32_e32 v144, 0x3fb8aa3b, v143
	v_exp_f32_e32 v144, v144
	v_add_f32_e32 v139, v139, v143
	v_fma_f32 v138, v144, v138, v145
	global_load_dword v77, v131, s[64:65]
	s_waitcnt vmcnt(63)
	v_lshlrev_b32_e32 v140, 16, v14
	v_and_b32_e32 v142, 0xffff0000, v14
	v_mul_f32_e32 v141, 0x3fb8aa3b, v140
	v_exp_f32_e32 v141, v141
	v_add_f32_e32 v139, v139, v140
	v_fma_f32 v138, v141, v138, v142
	global_load_dword v78, v132, s[64:65]
	s_waitcnt vmcnt(63)
	v_lshlrev_b32_e32 v143, 16, v15
	v_and_b32_e32 v145, 0xffff0000, v15
	v_mul_f32_e32 v144, 0x3fb8aa3b, v143
	v_exp_f32_e32 v144, v144
	v_add_f32_e32 v139, v139, v143
	v_fma_f32 v138, v144, v138, v145
	global_load_dword v79, v133, s[64:65]
	s_add_u32 s64, s64, 0x8000
	s_addc_u32 s65, s65, 0
	s_waitcnt vmcnt(63)
	v_lshlrev_b32_e32 v140, 16, v16
	v_and_b32_e32 v142, 0xffff0000, v16
	v_mul_f32_e32 v141, 0x3fb8aa3b, v140
	v_exp_f32_e32 v141, v141
	v_add_f32_e32 v139, v139, v140
	v_fma_f32 v138, v141, v138, v142
	global_load_dword v80, v130, s[64:65]
	s_waitcnt vmcnt(63)
	v_lshlrev_b32_e32 v143, 16, v17
	v_and_b32_e32 v145, 0xffff0000, v17
	v_mul_f32_e32 v144, 0x3fb8aa3b, v143
	v_exp_f32_e32 v144, v144
	v_add_f32_e32 v139, v139, v143
	v_fma_f32 v138, v144, v138, v145
	global_load_dword v81, v131, s[64:65]
	s_waitcnt vmcnt(63)
	v_lshlrev_b32_e32 v140, 16, v18
	v_and_b32_e32 v142, 0xffff0000, v18
	v_mul_f32_e32 v141, 0x3fb8aa3b, v140
	v_exp_f32_e32 v141, v141
	v_add_f32_e32 v139, v139, v140
	v_fma_f32 v138, v141, v138, v142
	global_load_dword v82, v132, s[64:65]
	s_waitcnt vmcnt(63)
	v_lshlrev_b32_e32 v143, 16, v19
	v_and_b32_e32 v145, 0xffff0000, v19
	v_mul_f32_e32 v144, 0x3fb8aa3b, v143
	v_exp_f32_e32 v144, v144
	v_add_f32_e32 v139, v139, v143
	v_fma_f32 v138, v144, v138, v145
	global_load_dword v83, v133, s[64:65]
	s_add_u32 s64, s64, 0x8000
	s_addc_u32 s65, s65, 0
	s_waitcnt vmcnt(63)
	v_lshlrev_b32_e32 v140, 16, v20
	v_and_b32_e32 v142, 0xffff0000, v20
	v_mul_f32_e32 v141, 0x3fb8aa3b, v140
	v_exp_f32_e32 v141, v141
	v_add_f32_e32 v139, v139, v140
	v_fma_f32 v138, v141, v138, v142
	global_load_dword v84, v130, s[64:65]
	s_waitcnt vmcnt(63)
	v_lshlrev_b32_e32 v143, 16, v21
	v_and_b32_e32 v145, 0xffff0000, v21
	v_mul_f32_e32 v144, 0x3fb8aa3b, v143
	v_exp_f32_e32 v144, v144
	v_add_f32_e32 v139, v139, v143
	v_fma_f32 v138, v144, v138, v145
	global_load_dword v85, v131, s[64:65]
	s_waitcnt vmcnt(63)
	v_lshlrev_b32_e32 v140, 16, v22
	v_and_b32_e32 v142, 0xffff0000, v22
	v_mul_f32_e32 v141, 0x3fb8aa3b, v140
	v_exp_f32_e32 v141, v141
	v_add_f32_e32 v139, v139, v140
	v_fma_f32 v138, v141, v138, v142
	global_load_dword v86, v132, s[64:65]
	s_waitcnt vmcnt(63)
	v_lshlrev_b32_e32 v143, 16, v23
	v_and_b32_e32 v145, 0xffff0000, v23
	v_mul_f32_e32 v144, 0x3fb8aa3b, v143
	v_exp_f32_e32 v144, v144
	v_add_f32_e32 v139, v139, v143
	v_fma_f32 v138, v144, v138, v145
	global_load_dword v87, v133, s[64:65]
	s_add_u32 s64, s64, 0x8000
	s_addc_u32 s65, s65, 0
	s_waitcnt vmcnt(63)
	v_lshlrev_b32_e32 v140, 16, v24
	v_and_b32_e32 v142, 0xffff0000, v24
	v_mul_f32_e32 v141, 0x3fb8aa3b, v140
	v_exp_f32_e32 v141, v141
	v_add_f32_e32 v139, v139, v140
	v_fma_f32 v138, v141, v138, v142
	global_load_dword v88, v130, s[64:65]
	s_waitcnt vmcnt(63)
; __device__ __forceinline__ float bflo(unsigned w) { return __uint_as_float(w << 16); }
; __device__ __forceinline__ float bfhi(unsigned w) { return __uint_as_float(w & 0xffff0000u); }
; __device__ __forceinline__ void phase_scan(const Params& p, LAS unsigned char* lds) {
;     ...
;         float h = 0.f, sla = 0.f;
; #pragma unroll 8
;         for (int s = 0; s < 128; ++s) { const unsigned lw = LU[base + (size_t)s * LW]; const float la = bflo(lw), u = bfhi(lw); h = __expf(la) * h + u; sla += la; }
	v_lshlrev_b32_e32 v143, 16, v25
	v_and_b32_e32 v145, 0xffff0000, v25
	v_mul_f32_e32 v144, 0x3fb8aa3b, v143
	v_exp_f32_e32 v144, v144
	v_add_f32_e32 v139, v139, v143
	v_fma_f32 v138, v144, v138, v145
	global_load_dword v89, v131, s[64:65]
	s_waitcnt vmcnt(63)
	v_lshlrev_b32_e32 v140, 16, v26
	v_and_b32_e32 v142, 0xffff0000, v26
	v_mul_f32_e32 v141, 0x3fb8aa3b, v140
	v_exp_f32_e32 v141, v141
	v_add_f32_e32 v139, v139, v140
	v_fma_f32 v138, v141, v138, v142
	global_load_dword v90, v132, s[64:65]
	s_waitcnt vmcnt(63)
	v_lshlrev_b32_e32 v143, 16, v27
	v_and_b32_e32 v145, 0xffff0000, v27
	v_mul_f32_e32 v144, 0x3fb8aa3b, v143
	v_exp_f32_e32 v144, v144
	v_add_f32_e32 v139, v139, v143
	v_fma_f32 v138, v144, v138, v145
	global_load_dword v91, v133, s[64:65]
	s_add_u32 s64, s64, 0x8000
	s_addc_u32 s65, s65, 0
	s_waitcnt vmcnt(63)
	v_lshlrev_b32_e32 v140, 16, v28
	v_and_b32_e32 v142, 0xffff0000, v28
	v_mul_f32_e32 v141, 0x3fb8aa3b, v140
	v_exp_f32_e32 v141, v141
	v_add_f32_e32 v139, v139, v140
	v_fma_f32 v138, v141, v138, v142
	global_load_dword v92, v130, s[64:65]
	s_waitcnt vmcnt(63)
	v_lshlrev_b32_e32 v143, 16, v29
	v_and_b32_e32 v145, 0xffff0000, v29
	v_mul_f32_e32 v144, 0x3fb8aa3b, v143
	v_exp_f32_e32 v144, v144
	v_add_f32_e32 v139, v139, v143
	v_fma_f32 v138, v144, v138, v145
	global_load_dword v93, v131, s[64:65]
	s_waitcnt vmcnt(63)
	v_lshlrev_b32_e32 v140, 16, v30
	v_and_b32_e32 v142, 0xffff0000, v30
	v_mul_f32_e32 v141, 0x3fb8aa3b, v140
	v_exp_f32_e32 v141, v141
	v_add_f32_e32 v139, v139, v140
	v_fma_f32 v138, v141, v138, v142
	global_load_dword v94, v132, s[64:65]
	s_waitcnt vmcnt(63)
	v_lshlrev_b32_e32 v143, 16, v31
	v_and_b32_e32 v145, 0xffff0000, v31
	v_mul_f32_e32 v144, 0x3fb8aa3b, v143
	v_exp_f32_e32 v144, v144
	v_add_f32_e32 v139, v139, v143
	v_fma_f32 v138, v144, v138, v145
	global_load_dword v95, v133, s[64:65]
	s_add_u32 s64, s64, 0x8000
	s_addc_u32 s65, s65, 0
	s_waitcnt vmcnt(63)
	v_lshlrev_b32_e32 v140, 16, v32
	v_and_b32_e32 v142, 0xffff0000, v32
	v_mul_f32_e32 v141, 0x3fb8aa3b, v140
	v_exp_f32_e32 v141, v141
	v_add_f32_e32 v139, v139, v140
	v_fma_f32 v138, v141, v138, v142
	global_load_dword v96, v130, s[64:65]
	s_waitcnt vmcnt(63)
	v_lshlrev_b32_e32 v143, 16, v33
	v_and_b32_e32 v145, 0xffff0000, v33
	v_mul_f32_e32 v144, 0x3fb8aa3b, v143
	v_exp_f32_e32 v144, v144
	v_add_f32_e32 v139, v139, v143
	v_fma_f32 v138, v144, v138, v145
	global_load_dword v97, v131, s[64:65]
	s_waitcnt vmcnt(63)
	v_lshlrev_b32_e32 v140, 16, v34
	v_and_b32_e32 v142, 0xffff0000, v34
	v_mul_f32_e32 v141, 0x3fb8aa3b, v140
	v_exp_f32_e32 v141, v141
	v_add_f32_e32 v139, v139, v140
	v_fma_f32 v138, v141, v138, v142
	global_load_dword v98, v132, s[64:65]
	s_waitcnt vmcnt(63)
	v_lshlrev_b32_e32 v143, 16, v35
	v_and_b32_e32 v145, 0xffff0000, v35
	v_mul_f32_e32 v144, 0x3fb8aa3b, v143
	v_exp_f32_e32 v144, v144
	v_add_f32_e32 v139, v139, v143
	v_fma_f32 v138, v144, v138, v145
	global_load_dword v99, v133, s[64:65]
	s_add_u32 s64, s64, 0x8000
	s_addc_u32 s65, s65, 0
	s_waitcnt vmcnt(63)
	v_lshlrev_b32_e32 v140, 16, v36
	v_and_b32_e32 v142, 0xffff0000, v36
	v_mul_f32_e32 v141, 0x3fb8aa3b, v140
	v_exp_f32_e32 v141, v141
	v_add_f32_e32 v139, v139, v140
	v_fma_f32 v138, v141, v138, v142
	global_load_dword v100, v130, s[64:65]
	s_waitcnt vmcnt(63)
	v_lshlrev_b32_e32 v143, 16, v37
	v_and_b32_e32 v145, 0xffff0000, v37
	v_mul_f32_e32 v144, 0x3fb8aa3b, v143
	v_exp_f32_e32 v144, v144
	v_add_f32_e32 v139, v139, v143
	v_fma_f32 v138, v144, v138, v145
	global_load_dword v101, v131, s[64:65]
	s_waitcnt vmcnt(63)
	v_lshlrev_b32_e32 v140, 16, v38
	v_and_b32_e32 v142, 0xffff0000, v38
	v_mul_f32_e32 v141, 0x3fb8aa3b, v140
	v_exp_f32_e32 v141, v141
	v_add_f32_e32 v139, v139, v140
	v_fma_f32 v138, v141, v138, v142
	global_load_dword v102, v132, s[64:65]
	s_waitcnt vmcnt(63)
	v_lshlrev_b32_e32 v143, 16, v39
	v_and_b32_e32 v145, 0xffff0000, v39
	v_mul_f32_e32 v144, 0x3fb8aa3b, v143
	v_exp_f32_e32 v144, v144
	v_add_f32_e32 v139, v139, v143
	v_fma_f32 v138, v144, v138, v145
	global_load_dword v103, v133, s[64:65]
	s_add_u32 s64, s64, 0x8000
	s_addc_u32 s65, s65, 0
	s_waitcnt vmcnt(63)
	v_lshlrev_b32_e32 v140, 16, v40
	v_and_b32_e32 v142, 0xffff0000, v40
	v_mul_f32_e32 v141, 0x3fb8aa3b, v140
	v_exp_f32_e32 v141, v141
	v_add_f32_e32 v139, v139, v140
	v_fma_f32 v138, v141, v138, v142
	global_load_dword v104, v130, s[64:65]
	s_waitcnt vmcnt(63)
	v_lshlrev_b32_e32 v143, 16, v41
	v_and_b32_e32 v145, 0xffff0000, v41
	v_mul_f32_e32 v144, 0x3fb8aa3b, v143
	v_exp_f32_e32 v144, v144
	v_add_f32_e32 v139, v139, v143
	v_fma_f32 v138, v144, v138, v145
	global_load_dword v105, v131, s[64:65]
	s_waitcnt vmcnt(63)
	v_lshlrev_b32_e32 v140, 16, v42
	v_and_b32_e32 v142, 0xffff0000, v42
	v_mul_f32_e32 v141, 0x3fb8aa3b, v140
	v_exp_f32_e32 v141, v141
	v_add_f32_e32 v139, v139, v140
	v_fma_f32 v138, v141, v138, v142
	global_load_dword v106, v132, s[64:65]
	s_waitcnt vmcnt(63)
	v_lshlrev_b32_e32 v143, 16, v43
	v_and_b32_e32 v145, 0xffff0000, v43
	v_mul_f32_e32 v144, 0x3fb8aa3b, v143
	v_exp_f32_e32 v144, v144
	v_add_f32_e32 v139, v139, v143
	v_fma_f32 v138, v144, v138, v145
	global_load_dword v107, v133, s[64:65]
	s_add_u32 s64, s64, 0x8000
	s_addc_u32 s65, s65, 0
	s_waitcnt vmcnt(63)
	v_lshlrev_b32_e32 v140, 16, v44
	v_and_b32_e32 v142, 0xffff0000, v44
	v_mul_f32_e32 v141, 0x3fb8aa3b, v140
	v_exp_f32_e32 v141, v141
	v_add_f32_e32 v139, v139, v140
	v_fma_f32 v138, v141, v138, v142
	global_load_dword v108, v130, s[64:65]
	s_waitcnt vmcnt(63)
	v_lshlrev_b32_e32 v143, 16, v45
	v_and_b32_e32 v145, 0xffff0000, v45
	v_mul_f32_e32 v144, 0x3fb8aa3b, v143
	v_exp_f32_e32 v144, v144
	v_add_f32_e32 v139, v139, v143
	v_fma_f32 v138, v144, v138, v145
	global_load_dword v109, v131, s[64:65]
	s_waitcnt vmcnt(63)
; __device__ __forceinline__ float bflo(unsigned w) { return __uint_as_float(w << 16); }
; __device__ __forceinline__ float bfhi(unsigned w) { return __uint_as_float(w & 0xffff0000u); }
; __device__ __forceinline__ void phase_scan(const Params& p, LAS unsigned char* lds) {
;     ...
;         float h = 0.f, sla = 0.f;
; #pragma unroll 8
;         for (int s = 0; s < 128; ++s) { const unsigned lw = LU[base + (size_t)s * LW]; const float la = bflo(lw), u = bfhi(lw); h = __expf(la) * h + u; sla += la; }
	v_lshlrev_b32_e32 v140, 16, v46
	v_and_b32_e32 v142, 0xffff0000, v46
	v_mul_f32_e32 v141, 0x3fb8aa3b, v140
	v_exp_f32_e32 v141, v141
	v_add_f32_e32 v139, v139, v140
	v_fma_f32 v138, v141, v138, v142
	global_load_dword v110, v132, s[64:65]
	s_waitcnt vmcnt(63)
	v_lshlrev_b32_e32 v143, 16, v47
	v_and_b32_e32 v145, 0xffff0000, v47
	v_mul_f32_e32 v144, 0x3fb8aa3b, v143
	v_exp_f32_e32 v144, v144
	v_add_f32_e32 v139, v139, v143
	v_fma_f32 v138, v144, v138, v145
	global_load_dword v111, v133, s[64:65]
	s_add_u32 s64, s64, 0x8000
	s_addc_u32 s65, s65, 0
	s_waitcnt vmcnt(63)
	v_lshlrev_b32_e32 v140, 16, v48
	v_and_b32_e32 v142, 0xffff0000, v48
	v_mul_f32_e32 v141, 0x3fb8aa3b, v140
	v_exp_f32_e32 v141, v141
	v_add_f32_e32 v139, v139, v140
	v_fma_f32 v138, v141, v138, v142
	global_load_dword v112, v130, s[64:65]
	s_waitcnt vmcnt(63)
	v_lshlrev_b32_e32 v143, 16, v49
	v_and_b32_e32 v145, 0xffff0000, v49
	v_mul_f32_e32 v144, 0x3fb8aa3b, v143
	v_exp_f32_e32 v144, v144
	v_add_f32_e32 v139, v139, v143
	v_fma_f32 v138, v144, v138, v145
	global_load_dword v113, v131, s[64:65]
	s_waitcnt vmcnt(63)
	v_lshlrev_b32_e32 v140, 16, v50
	v_and_b32_e32 v142, 0xffff0000, v50
	v_mul_f32_e32 v141, 0x3fb8aa3b, v140
	v_exp_f32_e32 v141, v141
	v_add_f32_e32 v139, v139, v140
	v_fma_f32 v138, v141, v138, v142
	global_load_dword v114, v132, s[64:65]
	s_waitcnt vmcnt(63)
	v_lshlrev_b32_e32 v143, 16, v51
	v_and_b32_e32 v145, 0xffff0000, v51
	v_mul_f32_e32 v144, 0x3fb8aa3b, v143
	v_exp_f32_e32 v144, v144
	v_add_f32_e32 v139, v139, v143
	v_fma_f32 v138, v144, v138, v145
	global_load_dword v115, v133, s[64:65]
	s_add_u32 s64, s64, 0x8000
	s_addc_u32 s65, s65, 0
	s_waitcnt vmcnt(63)
	v_lshlrev_b32_e32 v140, 16, v52
	v_and_b32_e32 v142, 0xffff0000, v52
	v_mul_f32_e32 v141, 0x3fb8aa3b, v140
	v_exp_f32_e32 v141, v141
	v_add_f32_e32 v139, v139, v140
	v_fma_f32 v138, v141, v138, v142
	global_load_dword v116, v130, s[64:65]
	s_waitcnt vmcnt(63)
	v_lshlrev_b32_e32 v143, 16, v53
	v_and_b32_e32 v145, 0xffff0000, v53
	v_mul_f32_e32 v144, 0x3fb8aa3b, v143
	v_exp_f32_e32 v144, v144
	v_add_f32_e32 v139, v139, v143
	v_fma_f32 v138, v144, v138, v145
	global_load_dword v117, v131, s[64:65]
	s_waitcnt vmcnt(63)
	v_lshlrev_b32_e32 v140, 16, v54
	v_and_b32_e32 v142, 0xffff0000, v54
	v_mul_f32_e32 v141, 0x3fb8aa3b, v140
	v_exp_f32_e32 v141, v141
	v_add_f32_e32 v139, v139, v140
	v_fma_f32 v138, v141, v138, v142
	global_load_dword v118, v132, s[64:65]
	s_waitcnt vmcnt(63)
	v_lshlrev_b32_e32 v143, 16, v55
	v_and_b32_e32 v145, 0xffff0000, v55
	v_mul_f32_e32 v144, 0x3fb8aa3b, v143
	v_exp_f32_e32 v144, v144
	v_add_f32_e32 v139, v139, v143
	v_fma_f32 v138, v144, v138, v145
	global_load_dword v119, v133, s[64:65]
	s_add_u32 s64, s64, 0x8000
	s_addc_u32 s65, s65, 0
	s_waitcnt vmcnt(63)
	v_lshlrev_b32_e32 v140, 16, v56
	v_and_b32_e32 v142, 0xffff0000, v56
	v_mul_f32_e32 v141, 0x3fb8aa3b, v140
	v_exp_f32_e32 v141, v141
	v_add_f32_e32 v139, v139, v140
	v_fma_f32 v138, v141, v138, v142
	global_load_dword v120, v130, s[64:65]
	s_waitcnt vmcnt(63)
	v_lshlrev_b32_e32 v143, 16, v57
	v_and_b32_e32 v145, 0xffff0000, v57
	v_mul_f32_e32 v144, 0x3fb8aa3b, v143
	v_exp_f32_e32 v144, v144
	v_add_f32_e32 v139, v139, v143
	v_fma_f32 v138, v144, v138, v145
	global_load_dword v121, v131, s[64:65]
	s_waitcnt vmcnt(63)
	v_lshlrev_b32_e32 v140, 16, v58
	v_and_b32_e32 v142, 0xffff0000, v58
	v_mul_f32_e32 v141, 0x3fb8aa3b, v140
	v_exp_f32_e32 v141, v141
	v_add_f32_e32 v139, v139, v140
	v_fma_f32 v138, v141, v138, v142
	global_load_dword v122, v132, s[64:65]
	s_waitcnt vmcnt(63)
	v_lshlrev_b32_e32 v143, 16, v59
	v_and_b32_e32 v145, 0xffff0000, v59
	v_mul_f32_e32 v144, 0x3fb8aa3b, v143
	v_exp_f32_e32 v144, v144
	v_add_f32_e32 v139, v139, v143
	v_fma_f32 v138, v144, v138, v145
	global_load_dword v123, v133, s[64:65]
	s_add_u32 s64, s64, 0x8000
	s_addc_u32 s65, s65, 0
	s_waitcnt vmcnt(63)
	v_lshlrev_b32_e32 v140, 16, v60
	v_and_b32_e32 v142, 0xffff0000, v60
	v_mul_f32_e32 v141, 0x3fb8aa3b, v140
	v_exp_f32_e32 v141, v141
	v_add_f32_e32 v139, v139, v140
	v_fma_f32 v138, v141, v138, v142
	global_load_dword v124, v130, s[64:65]
	s_waitcnt vmcnt(63)
	v_lshlrev_b32_e32 v143, 16, v61
	v_and_b32_e32 v145, 0xffff0000, v61
	v_mul_f32_e32 v144, 0x3fb8aa3b, v143
	v_exp_f32_e32 v144, v144
	v_add_f32_e32 v139, v139, v143
	v_fma_f32 v138, v144, v138, v145
	global_load_dword v125, v131, s[64:65]
	s_waitcnt vmcnt(63)
	v_lshlrev_b32_e32 v140, 16, v62
	v_and_b32_e32 v142, 0xffff0000, v62
	v_mul_f32_e32 v141, 0x3fb8aa3b, v140
	v_exp_f32_e32 v141, v141
	v_add_f32_e32 v139, v139, v140
	v_fma_f32 v138, v141, v138, v142
	global_load_dword v126, v132, s[64:65]
	s_waitcnt vmcnt(63)
	v_lshlrev_b32_e32 v143, 16, v63
	v_and_b32_e32 v145, 0xffff0000, v63
	v_mul_f32_e32 v144, 0x3fb8aa3b, v143
	v_exp_f32_e32 v144, v144
	v_add_f32_e32 v139, v139, v143
	v_fma_f32 v138, v144, v138, v145
	global_load_dword v127, v133, s[64:65]
	s_waitcnt vmcnt(63)
	v_lshlrev_b32_e32 v140, 16, v64
	v_and_b32_e32 v142, 0xffff0000, v64
	v_mul_f32_e32 v141, 0x3fb8aa3b, v140
	v_exp_f32_e32 v141, v141
	v_add_f32_e32 v139, v139, v140
	v_fma_f32 v138, v141, v138, v142
	s_waitcnt vmcnt(62)
	v_lshlrev_b32_e32 v143, 16, v65
	v_and_b32_e32 v145, 0xffff0000, v65
	v_mul_f32_e32 v144, 0x3fb8aa3b, v143
	v_exp_f32_e32 v144, v144
	v_add_f32_e32 v139, v139, v143
	v_fma_f32 v138, v144, v138, v145
	s_waitcnt vmcnt(61)
	v_lshlrev_b32_e32 v140, 16, v66
	v_and_b32_e32 v142, 0xffff0000, v66
	v_mul_f32_e32 v141, 0x3fb8aa3b, v140
	v_exp_f32_e32 v141, v141
	v_add_f32_e32 v139, v139, v140
	v_fma_f32 v138, v141, v138, v142
	s_waitcnt vmcnt(60)
; __device__ __forceinline__ float bflo(unsigned w) { return __uint_as_float(w << 16); }
; __device__ __forceinline__ float bfhi(unsigned w) { return __uint_as_float(w & 0xffff0000u); }
; __device__ __forceinline__ void phase_scan(const Params& p, LAS unsigned char* lds) {
;     ...
;         float h = 0.f, sla = 0.f;
; #pragma unroll 8
;         for (int s = 0; s < 128; ++s) { const unsigned lw = LU[base + (size_t)s * LW]; const float la = bflo(lw), u = bfhi(lw); h = __expf(la) * h + u; sla += la; }
	v_lshlrev_b32_e32 v143, 16, v67
	v_and_b32_e32 v145, 0xffff0000, v67
	v_mul_f32_e32 v144, 0x3fb8aa3b, v143
	v_exp_f32_e32 v144, v144
	v_add_f32_e32 v139, v139, v143
	v_fma_f32 v138, v144, v138, v145
	s_waitcnt vmcnt(59)
	v_lshlrev_b32_e32 v140, 16, v68
	v_and_b32_e32 v142, 0xffff0000, v68
	v_mul_f32_e32 v141, 0x3fb8aa3b, v140
	v_exp_f32_e32 v141, v141
	v_add_f32_e32 v139, v139, v140
	v_fma_f32 v138, v141, v138, v142
	s_waitcnt vmcnt(58)
	v_lshlrev_b32_e32 v143, 16, v69
	v_and_b32_e32 v145, 0xffff0000, v69
	v_mul_f32_e32 v144, 0x3fb8aa3b, v143
	v_exp_f32_e32 v144, v144
	v_add_f32_e32 v139, v139, v143
	v_fma_f32 v138, v144, v138, v145
	s_waitcnt vmcnt(57)
	v_lshlrev_b32_e32 v140, 16, v70
	v_and_b32_e32 v142, 0xffff0000, v70
	v_mul_f32_e32 v141, 0x3fb8aa3b, v140
	v_exp_f32_e32 v141, v141
	v_add_f32_e32 v139, v139, v140
	v_fma_f32 v138, v141, v138, v142
	s_waitcnt vmcnt(56)
	v_lshlrev_b32_e32 v143, 16, v71
	v_and_b32_e32 v145, 0xffff0000, v71
	v_mul_f32_e32 v144, 0x3fb8aa3b, v143
	v_exp_f32_e32 v144, v144
	v_add_f32_e32 v139, v139, v143
	v_fma_f32 v138, v144, v138, v145
	s_waitcnt vmcnt(55)
	v_lshlrev_b32_e32 v140, 16, v72
	v_and_b32_e32 v142, 0xffff0000, v72
	v_mul_f32_e32 v141, 0x3fb8aa3b, v140
	v_exp_f32_e32 v141, v141
	v_add_f32_e32 v139, v139, v140
	v_fma_f32 v138, v141, v138, v142
	s_waitcnt vmcnt(54)
	v_lshlrev_b32_e32 v143, 16, v73
	v_and_b32_e32 v145, 0xffff0000, v73
	v_mul_f32_e32 v144, 0x3fb8aa3b, v143
	v_exp_f32_e32 v144, v144
	v_add_f32_e32 v139, v139, v143
	v_fma_f32 v138, v144, v138, v145
	s_waitcnt vmcnt(53)
	v_lshlrev_b32_e32 v140, 16, v74
	v_and_b32_e32 v142, 0xffff0000, v74
	v_mul_f32_e32 v141, 0x3fb8aa3b, v140
	v_exp_f32_e32 v141, v141
	v_add_f32_e32 v139, v139, v140
	v_fma_f32 v138, v141, v138, v142
	s_waitcnt vmcnt(52)
	v_lshlrev_b32_e32 v143, 16, v75
	v_and_b32_e32 v145, 0xffff0000, v75
	v_mul_f32_e32 v144, 0x3fb8aa3b, v143
	v_exp_f32_e32 v144, v144
	v_add_f32_e32 v139, v139, v143
	v_fma_f32 v138, v144, v138, v145
	s_waitcnt vmcnt(51)
	v_lshlrev_b32_e32 v140, 16, v76
	v_and_b32_e32 v142, 0xffff0000, v76
	v_mul_f32_e32 v141, 0x3fb8aa3b, v140
	v_exp_f32_e32 v141, v141
	v_add_f32_e32 v139, v139, v140
	v_fma_f32 v138, v141, v138, v142
	s_waitcnt vmcnt(50)
	v_lshlrev_b32_e32 v143, 16, v77
	v_and_b32_e32 v145, 0xffff0000, v77
	v_mul_f32_e32 v144, 0x3fb8aa3b, v143
	v_exp_f32_e32 v144, v144
	v_add_f32_e32 v139, v139, v143
	v_fma_f32 v138, v144, v138, v145
	s_waitcnt vmcnt(49)
	v_lshlrev_b32_e32 v140, 16, v78
	v_and_b32_e32 v142, 0xffff0000, v78
	v_mul_f32_e32 v141, 0x3fb8aa3b, v140
	v_exp_f32_e32 v141, v141
	v_add_f32_e32 v139, v139, v140
	v_fma_f32 v138, v141, v138, v142
	s_waitcnt vmcnt(48)
	v_lshlrev_b32_e32 v143, 16, v79
	v_and_b32_e32 v145, 0xffff0000, v79
	v_mul_f32_e32 v144, 0x3fb8aa3b, v143
	v_exp_f32_e32 v144, v144
	v_add_f32_e32 v139, v139, v143
	v_fma_f32 v138, v144, v138, v145
	s_waitcnt vmcnt(47)
	v_lshlrev_b32_e32 v140, 16, v80
	v_and_b32_e32 v142, 0xffff0000, v80
	v_mul_f32_e32 v141, 0x3fb8aa3b, v140
	v_exp_f32_e32 v141, v141
	v_add_f32_e32 v139, v139, v140
	v_fma_f32 v138, v141, v138, v142
	s_waitcnt vmcnt(46)
	v_lshlrev_b32_e32 v143, 16, v81
	v_and_b32_e32 v145, 0xffff0000, v81
	v_mul_f32_e32 v144, 0x3fb8aa3b, v143
	v_exp_f32_e32 v144, v144
	v_add_f32_e32 v139, v139, v143
	v_fma_f32 v138, v144, v138, v145
	s_waitcnt vmcnt(45)
	v_lshlrev_b32_e32 v140, 16, v82
	v_and_b32_e32 v142, 0xffff0000, v82
	v_mul_f32_e32 v141, 0x3fb8aa3b, v140
	v_exp_f32_e32 v141, v141
	v_add_f32_e32 v139, v139, v140
	v_fma_f32 v138, v141, v138, v142
	s_waitcnt vmcnt(44)
	v_lshlrev_b32_e32 v143, 16, v83
	v_and_b32_e32 v145, 0xffff0000, v83
	v_mul_f32_e32 v144, 0x3fb8aa3b, v143
	v_exp_f32_e32 v144, v144
	v_add_f32_e32 v139, v139, v143
	v_fma_f32 v138, v144, v138, v145
	s_waitcnt vmcnt(43)
	v_lshlrev_b32_e32 v140, 16, v84
	v_and_b32_e32 v142, 0xffff0000, v84
	v_mul_f32_e32 v141, 0x3fb8aa3b, v140
	v_exp_f32_e32 v141, v141
	v_add_f32_e32 v139, v139, v140
	v_fma_f32 v138, v141, v138, v142
	s_waitcnt vmcnt(42)
	v_lshlrev_b32_e32 v143, 16, v85
	v_and_b32_e32 v145, 0xffff0000, v85
	v_mul_f32_e32 v144, 0x3fb8aa3b, v143
	v_exp_f32_e32 v144, v144
	v_add_f32_e32 v139, v139, v143
	v_fma_f32 v138, v144, v138, v145
	s_waitcnt vmcnt(41)
	v_lshlrev_b32_e32 v140, 16, v86
	v_and_b32_e32 v142, 0xffff0000, v86
	v_mul_f32_e32 v141, 0x3fb8aa3b, v140
	v_exp_f32_e32 v141, v141
	v_add_f32_e32 v139, v139, v140
	v_fma_f32 v138, v141, v138, v142
	s_waitcnt vmcnt(40)
	v_lshlrev_b32_e32 v143, 16, v87
	v_and_b32_e32 v145, 0xffff0000, v87
	v_mul_f32_e32 v144, 0x3fb8aa3b, v143
	v_exp_f32_e32 v144, v144
	v_add_f32_e32 v139, v139, v143
	v_fma_f32 v138, v144, v138, v145
	s_waitcnt vmcnt(39)
	v_lshlrev_b32_e32 v140, 16, v88
	v_and_b32_e32 v142, 0xffff0000, v88
	v_mul_f32_e32 v141, 0x3fb8aa3b, v140
	v_exp_f32_e32 v141, v141
	v_add_f32_e32 v139, v139, v140
	v_fma_f32 v138, v141, v138, v142
	s_waitcnt vmcnt(38)
	v_lshlrev_b32_e32 v143, 16, v89
	v_and_b32_e32 v145, 0xffff0000, v89
	v_mul_f32_e32 v144, 0x3fb8aa3b, v143
	v_exp_f32_e32 v144, v144
	v_add_f32_e32 v139, v139, v143
	v_fma_f32 v138, v144, v138, v145
	s_waitcnt vmcnt(37)
	v_lshlrev_b32_e32 v140, 16, v90
	v_and_b32_e32 v142, 0xffff0000, v90
	v_mul_f32_e32 v141, 0x3fb8aa3b, v140
	v_exp_f32_e32 v141, v141
	v_add_f32_e32 v139, v139, v140
	v_fma_f32 v138, v141, v138, v142
	s_waitcnt vmcnt(36)
	v_lshlrev_b32_e32 v143, 16, v91
	v_and_b32_e32 v145, 0xffff0000, v91
	v_mul_f32_e32 v144, 0x3fb8aa3b, v143
	v_exp_f32_e32 v144, v144
	v_add_f32_e32 v139, v139, v143
	v_fma_f32 v138, v144, v138, v145
	s_waitcnt vmcnt(35)
	v_lshlrev_b32_e32 v140, 16, v92
	v_and_b32_e32 v142, 0xffff0000, v92
	v_mul_f32_e32 v141, 0x3fb8aa3b, v140
	v_exp_f32_e32 v141, v141
	v_add_f32_e32 v139, v139, v140
	v_fma_f32 v138, v141, v138, v142
	s_waitcnt vmcnt(34)
; __device__ __forceinline__ float bflo(unsigned w) { return __uint_as_float(w << 16); }
; __device__ __forceinline__ float bfhi(unsigned w) { return __uint_as_float(w & 0xffff0000u); }
; __device__ __forceinline__ void phase_scan(const Params& p, LAS unsigned char* lds) {
;     ...
;         float h = 0.f, sla = 0.f;
; #pragma unroll 8
;         for (int s = 0; s < 128; ++s) { const unsigned lw = LU[base + (size_t)s * LW]; const float la = bflo(lw), u = bfhi(lw); h = __expf(la) * h + u; sla += la; }
	v_lshlrev_b32_e32 v143, 16, v93
	v_and_b32_e32 v145, 0xffff0000, v93
	v_mul_f32_e32 v144, 0x3fb8aa3b, v143
	v_exp_f32_e32 v144, v144
	v_add_f32_e32 v139, v139, v143
	v_fma_f32 v138, v144, v138, v145
	s_waitcnt vmcnt(33)
	v_lshlrev_b32_e32 v140, 16, v94
	v_and_b32_e32 v142, 0xffff0000, v94
	v_mul_f32_e32 v141, 0x3fb8aa3b, v140
	v_exp_f32_e32 v141, v141
	v_add_f32_e32 v139, v139, v140
	v_fma_f32 v138, v141, v138, v142
	s_waitcnt vmcnt(32)
	v_lshlrev_b32_e32 v143, 16, v95
	v_and_b32_e32 v145, 0xffff0000, v95
	v_mul_f32_e32 v144, 0x3fb8aa3b, v143
	v_exp_f32_e32 v144, v144
	v_add_f32_e32 v139, v139, v143
	v_fma_f32 v138, v144, v138, v145
	s_waitcnt vmcnt(31)
	v_lshlrev_b32_e32 v140, 16, v96
	v_and_b32_e32 v142, 0xffff0000, v96
	v_mul_f32_e32 v141, 0x3fb8aa3b, v140
	v_exp_f32_e32 v141, v141
	v_add_f32_e32 v139, v139, v140
	v_fma_f32 v138, v141, v138, v142
	s_waitcnt vmcnt(30)
	v_lshlrev_b32_e32 v143, 16, v97
	v_and_b32_e32 v145, 0xffff0000, v97
	v_mul_f32_e32 v144, 0x3fb8aa3b, v143
	v_exp_f32_e32 v144, v144
	v_add_f32_e32 v139, v139, v143
	v_fma_f32 v138, v144, v138, v145
	s_waitcnt vmcnt(29)
	v_lshlrev_b32_e32 v140, 16, v98
	v_and_b32_e32 v142, 0xffff0000, v98
	v_mul_f32_e32 v141, 0x3fb8aa3b, v140
	v_exp_f32_e32 v141, v141
	v_add_f32_e32 v139, v139, v140
	v_fma_f32 v138, v141, v138, v142
	s_waitcnt vmcnt(28)
	v_lshlrev_b32_e32 v143, 16, v99
	v_and_b32_e32 v145, 0xffff0000, v99
	v_mul_f32_e32 v144, 0x3fb8aa3b, v143
	v_exp_f32_e32 v144, v144
	v_add_f32_e32 v139, v139, v143
	v_fma_f32 v138, v144, v138, v145
	s_waitcnt vmcnt(27)
	v_lshlrev_b32_e32 v140, 16, v100
	v_and_b32_e32 v142, 0xffff0000, v100
	v_mul_f32_e32 v141, 0x3fb8aa3b, v140
	v_exp_f32_e32 v141, v141
	v_add_f32_e32 v139, v139, v140
	v_fma_f32 v138, v141, v138, v142
	s_waitcnt vmcnt(26)
	v_lshlrev_b32_e32 v143, 16, v101
	v_and_b32_e32 v145, 0xffff0000, v101
	v_mul_f32_e32 v144, 0x3fb8aa3b, v143
	v_exp_f32_e32 v144, v144
	v_add_f32_e32 v139, v139, v143
	v_fma_f32 v138, v144, v138, v145
	s_waitcnt vmcnt(25)
	v_lshlrev_b32_e32 v140, 16, v102
	v_and_b32_e32 v142, 0xffff0000, v102
	v_mul_f32_e32 v141, 0x3fb8aa3b, v140
	v_exp_f32_e32 v141, v141
	v_add_f32_e32 v139, v139, v140
	v_fma_f32 v138, v141, v138, v142
	s_waitcnt vmcnt(24)
	v_lshlrev_b32_e32 v143, 16, v103
	v_and_b32_e32 v145, 0xffff0000, v103
	v_mul_f32_e32 v144, 0x3fb8aa3b, v143
	v_exp_f32_e32 v144, v144
	v_add_f32_e32 v139, v139, v143
	v_fma_f32 v138, v144, v138, v145
	s_waitcnt vmcnt(23)
	v_lshlrev_b32_e32 v140, 16, v104
	v_and_b32_e32 v142, 0xffff0000, v104
	v_mul_f32_e32 v141, 0x3fb8aa3b, v140
	v_exp_f32_e32 v141, v141
	v_add_f32_e32 v139, v139, v140
	v_fma_f32 v138, v141, v138, v142
	s_waitcnt vmcnt(22)
	v_lshlrev_b32_e32 v143, 16, v105
	v_and_b32_e32 v145, 0xffff0000, v105
	v_mul_f32_e32 v144, 0x3fb8aa3b, v143
	v_exp_f32_e32 v144, v144
	v_add_f32_e32 v139, v139, v143
	v_fma_f32 v138, v144, v138, v145
	s_waitcnt vmcnt(21)
	v_lshlrev_b32_e32 v140, 16, v106
	v_and_b32_e32 v142, 0xffff0000, v106
	v_mul_f32_e32 v141, 0x3fb8aa3b, v140
	v_exp_f32_e32 v141, v141
	v_add_f32_e32 v139, v139, v140
	v_fma_f32 v138, v141, v138, v142
	s_waitcnt vmcnt(20)
	v_lshlrev_b32_e32 v143, 16, v107
	v_and_b32_e32 v145, 0xffff0000, v107
	v_mul_f32_e32 v144, 0x3fb8aa3b, v143
	v_exp_f32_e32 v144, v144
	v_add_f32_e32 v139, v139, v143
	v_fma_f32 v138, v144, v138, v145
	s_waitcnt vmcnt(19)
	v_lshlrev_b32_e32 v140, 16, v108
	v_and_b32_e32 v142, 0xffff0000, v108
	v_mul_f32_e32 v141, 0x3fb8aa3b, v140
	v_exp_f32_e32 v141, v141
	v_add_f32_e32 v139, v139, v140
	v_fma_f32 v138, v141, v138, v142
	s_waitcnt vmcnt(18)
	v_lshlrev_b32_e32 v143, 16, v109
	v_and_b32_e32 v145, 0xffff0000, v109
	v_mul_f32_e32 v144, 0x3fb8aa3b, v143
	v_exp_f32_e32 v144, v144
	v_add_f32_e32 v139, v139, v143
	v_fma_f32 v138, v144, v138, v145
	s_waitcnt vmcnt(17)
	v_lshlrev_b32_e32 v140, 16, v110
	v_and_b32_e32 v142, 0xffff0000, v110
	v_mul_f32_e32 v141, 0x3fb8aa3b, v140
	v_exp_f32_e32 v141, v141
	v_add_f32_e32 v139, v139, v140
	v_fma_f32 v138, v141, v138, v142
	s_waitcnt vmcnt(16)
	v_lshlrev_b32_e32 v143, 16, v111
	v_and_b32_e32 v145, 0xffff0000, v111
	v_mul_f32_e32 v144, 0x3fb8aa3b, v143
	v_exp_f32_e32 v144, v144
	v_add_f32_e32 v139, v139, v143
	v_fma_f32 v138, v144, v138, v145
	s_waitcnt vmcnt(15)
	v_lshlrev_b32_e32 v140, 16, v112
	v_and_b32_e32 v142, 0xffff0000, v112
	v_mul_f32_e32 v141, 0x3fb8aa3b, v140
	v_exp_f32_e32 v141, v141
	v_add_f32_e32 v139, v139, v140
	v_fma_f32 v138, v141, v138, v142
	s_waitcnt vmcnt(14)
	v_lshlrev_b32_e32 v143, 16, v113
	v_and_b32_e32 v145, 0xffff0000, v113
	v_mul_f32_e32 v144, 0x3fb8aa3b, v143
	v_exp_f32_e32 v144, v144
	v_add_f32_e32 v139, v139, v143
	v_fma_f32 v138, v144, v138, v145
	s_waitcnt vmcnt(13)
	v_lshlrev_b32_e32 v140, 16, v114
	v_and_b32_e32 v142, 0xffff0000, v114
	v_mul_f32_e32 v141, 0x3fb8aa3b, v140
	v_exp_f32_e32 v141, v141
	v_add_f32_e32 v139, v139, v140
	v_fma_f32 v138, v141, v138, v142
	s_waitcnt vmcnt(12)
	v_lshlrev_b32_e32 v143, 16, v115
	v_and_b32_e32 v145, 0xffff0000, v115
	v_mul_f32_e32 v144, 0x3fb8aa3b, v143
	v_exp_f32_e32 v144, v144
	v_add_f32_e32 v139, v139, v143
	v_fma_f32 v138, v144, v138, v145
	s_waitcnt vmcnt(11)
	v_lshlrev_b32_e32 v140, 16, v116
	v_and_b32_e32 v142, 0xffff0000, v116
	v_mul_f32_e32 v141, 0x3fb8aa3b, v140
	v_exp_f32_e32 v141, v141
	v_add_f32_e32 v139, v139, v140
	v_fma_f32 v138, v141, v138, v142
	s_waitcnt vmcnt(10)
	v_lshlrev_b32_e32 v143, 16, v117
	v_and_b32_e32 v145, 0xffff0000, v117
	v_mul_f32_e32 v144, 0x3fb8aa3b, v143
	v_exp_f32_e32 v144, v144
	v_add_f32_e32 v139, v139, v143
	v_fma_f32 v138, v144, v138, v145
	s_waitcnt vmcnt(9)
; __device__ __forceinline__ float bflo(unsigned w) { return __uint_as_float(w << 16); }
; __device__ __forceinline__ float bfhi(unsigned w) { return __uint_as_float(w & 0xffff0000u); }
; __device__ __forceinline__ void phase_scan(const Params& p, LAS unsigned char* lds) {
;     ...
;         for (int s = 0; s < 128; ++s) { const unsigned lw = LU[base + (size_t)s * LW]; const float la = bflo(lw), u = bfhi(lw); h = __expf(la) * h + u; sla += la; }
;         sA[chunk * 32 + c32] = __expf(sla); sH[chunk * 32 + c32] = h;
;         __syncthreads();
;         float hin = 0.f;
;         for (int j = 0; j < chunk; ++j) hin = sA[j * 32 + c32] * hin + sH[j * 32 + c32];
;         h = hin;
	v_lshlrev_b32_e32 v140, 16, v118
	v_and_b32_e32 v142, 0xffff0000, v118
	v_mul_f32_e32 v141, 0x3fb8aa3b, v140
	v_exp_f32_e32 v141, v141
	v_add_f32_e32 v139, v139, v140
	v_fma_f32 v138, v141, v138, v142
	s_waitcnt vmcnt(8)
	v_lshlrev_b32_e32 v143, 16, v119
	v_and_b32_e32 v145, 0xffff0000, v119
	v_mul_f32_e32 v144, 0x3fb8aa3b, v143
	v_exp_f32_e32 v144, v144
	v_add_f32_e32 v139, v139, v143
	v_fma_f32 v138, v144, v138, v145
	s_waitcnt vmcnt(7)
	v_lshlrev_b32_e32 v140, 16, v120
	v_and_b32_e32 v142, 0xffff0000, v120
	v_mul_f32_e32 v141, 0x3fb8aa3b, v140
	v_exp_f32_e32 v141, v141
	v_add_f32_e32 v139, v139, v140
	v_fma_f32 v138, v141, v138, v142
	s_waitcnt vmcnt(6)
	v_lshlrev_b32_e32 v143, 16, v121
	v_and_b32_e32 v145, 0xffff0000, v121
	v_mul_f32_e32 v144, 0x3fb8aa3b, v143
	v_exp_f32_e32 v144, v144
	v_add_f32_e32 v139, v139, v143
	v_fma_f32 v138, v144, v138, v145
	s_waitcnt vmcnt(5)
	v_lshlrev_b32_e32 v140, 16, v122
	v_and_b32_e32 v142, 0xffff0000, v122
	v_mul_f32_e32 v141, 0x3fb8aa3b, v140
	v_exp_f32_e32 v141, v141
	v_add_f32_e32 v139, v139, v140
	v_fma_f32 v138, v141, v138, v142
	s_waitcnt vmcnt(4)
	v_lshlrev_b32_e32 v143, 16, v123
	v_and_b32_e32 v145, 0xffff0000, v123
	v_mul_f32_e32 v144, 0x3fb8aa3b, v143
	v_exp_f32_e32 v144, v144
	v_add_f32_e32 v139, v139, v143
	v_fma_f32 v138, v144, v138, v145
	s_waitcnt vmcnt(3)
	v_lshlrev_b32_e32 v140, 16, v124
	v_and_b32_e32 v142, 0xffff0000, v124
	v_mul_f32_e32 v141, 0x3fb8aa3b, v140
	v_exp_f32_e32 v141, v141
	v_add_f32_e32 v139, v139, v140
	v_fma_f32 v138, v141, v138, v142
	s_waitcnt vmcnt(2)
	v_lshlrev_b32_e32 v143, 16, v125
	v_and_b32_e32 v145, 0xffff0000, v125
	v_mul_f32_e32 v144, 0x3fb8aa3b, v143
	v_exp_f32_e32 v144, v144
	v_add_f32_e32 v139, v139, v143
	v_fma_f32 v138, v144, v138, v145
	s_waitcnt vmcnt(1)
	v_lshlrev_b32_e32 v140, 16, v126
	v_and_b32_e32 v142, 0xffff0000, v126
	v_mul_f32_e32 v141, 0x3fb8aa3b, v140
	v_exp_f32_e32 v141, v141
	v_add_f32_e32 v139, v139, v140
	v_fma_f32 v138, v141, v138, v142
	s_waitcnt vmcnt(0)
	v_lshlrev_b32_e32 v143, 16, v127
	v_and_b32_e32 v145, 0xffff0000, v127
	v_mul_f32_e32 v144, 0x3fb8aa3b, v143
	v_exp_f32_e32 v144, v144
	v_add_f32_e32 v139, v139, v143
	v_fma_f32 v138, v144, v138, v145
	v_mul_f32_e32 v140, 0x3fb8aa3b, v139
	v_exp_f32_e32 v140, v140
	s_nop 1
	ds_write_b32 v185, v140
	ds_write_b32 v185, v138 offset:2048
	s_waitcnt lgkmcnt(0)
	s_barrier
	ds_read_b32 v150, v148 offset:0
	ds_read_b32 v165, v148 offset:2048
	ds_read_b32 v151, v148 offset:128
	ds_read_b32 v166, v148 offset:2176
	ds_read_b32 v152, v148 offset:256
	ds_read_b32 v167, v148 offset:2304
	ds_read_b32 v153, v148 offset:384
	ds_read_b32 v168, v148 offset:2432
	ds_read_b32 v154, v148 offset:512
	ds_read_b32 v169, v148 offset:2560
	ds_read_b32 v155, v148 offset:640
	ds_read_b32 v170, v148 offset:2688
	ds_read_b32 v156, v148 offset:768
	ds_read_b32 v171, v148 offset:2816
	ds_read_b32 v157, v148 offset:896
	ds_read_b32 v172, v148 offset:2944
	ds_read_b32 v158, v148 offset:1024
	ds_read_b32 v173, v148 offset:3072
	ds_read_b32 v159, v148 offset:1152
	ds_read_b32 v174, v148 offset:3200
	ds_read_b32 v160, v148 offset:1280
	ds_read_b32 v175, v148 offset:3328
	ds_read_b32 v161, v148 offset:1408
	ds_read_b32 v176, v148 offset:3456
	ds_read_b32 v162, v148 offset:1536
	ds_read_b32 v177, v148 offset:3584
	ds_read_b32 v163, v148 offset:1664
	ds_read_b32 v178, v148 offset:3712
	ds_read_b32 v164, v148 offset:1792
	ds_read_b32 v179, v148 offset:3840
	v_cmp_eq_u32_e64 s[4:5], 1, v128
	v_cmp_eq_u32_e64 s[6:7], 2, v128
	v_cmp_eq_u32_e64 s[8:9], 3, v128
	v_cmp_eq_u32_e64 s[10:11], 4, v128
	v_cmp_eq_u32_e64 s[12:13], 5, v128
	v_cmp_eq_u32_e64 s[14:15], 6, v128
	v_cmp_eq_u32_e64 s[16:17], 7, v128
	v_cmp_eq_u32_e64 s[18:19], 8, v128
	v_cmp_eq_u32_e64 s[20:21], 9, v128
	v_cmp_eq_u32_e64 s[22:23], 10, v128
	v_cmp_eq_u32_e64 s[24:25], 11, v128
	v_cmp_eq_u32_e64 s[26:27], 12, v128
	v_cmp_eq_u32_e64 s[28:29], 13, v128
	v_cmp_eq_u32_e64 s[30:31], 14, v128
	v_cmp_eq_u32_e64 s[58:59], 15, v128
	v_mov_b32_e32 v141, 0
	v_mov_b32_e32 v142, 0
	s_waitcnt lgkmcnt(15)
	v_fma_f32 v141, v150, v141, v165
	v_cndmask_b32_e64 v142, v142, v141, s[4:5]
	s_waitcnt lgkmcnt(15)
	v_fma_f32 v141, v151, v141, v166
	v_cndmask_b32_e64 v142, v142, v141, s[6:7]
	s_waitcnt lgkmcnt(15)
	v_fma_f32 v141, v152, v141, v167
	v_cndmask_b32_e64 v142, v142, v141, s[8:9]
	s_waitcnt lgkmcnt(15)
	v_fma_f32 v141, v153, v141, v168
	v_cndmask_b32_e64 v142, v142, v141, s[10:11]
	s_waitcnt lgkmcnt(15)
	v_fma_f32 v141, v154, v141, v169
	v_cndmask_b32_e64 v142, v142, v141, s[12:13]
	s_waitcnt lgkmcnt(15)
	v_fma_f32 v141, v155, v141, v170
	v_cndmask_b32_e64 v142, v142, v141, s[14:15]
	s_waitcnt lgkmcnt(15)
	v_fma_f32 v141, v156, v141, v171
	v_cndmask_b32_e64 v142, v142, v141, s[16:17]
	s_waitcnt lgkmcnt(14)
	v_fma_f32 v141, v157, v141, v172
	v_cndmask_b32_e64 v142, v142, v141, s[18:19]
	s_waitcnt lgkmcnt(12)
	v_fma_f32 v141, v158, v141, v173
	v_cndmask_b32_e64 v142, v142, v141, s[20:21]
	s_waitcnt lgkmcnt(10)
	v_fma_f32 v141, v159, v141, v174
	v_cndmask_b32_e64 v142, v142, v141, s[22:23]
	s_waitcnt lgkmcnt(8)
	v_fma_f32 v141, v160, v141, v175
	v_cndmask_b32_e64 v142, v142, v141, s[24:25]
	s_waitcnt lgkmcnt(6)
	v_fma_f32 v141, v161, v141, v176
	v_cndmask_b32_e64 v142, v142, v141, s[26:27]
	s_waitcnt lgkmcnt(4)
	v_fma_f32 v141, v162, v141, v177
	v_cndmask_b32_e64 v142, v142, v141, s[28:29]
	s_waitcnt lgkmcnt(2)
	v_fma_f32 v141, v163, v141, v178
	v_cndmask_b32_e64 v142, v142, v141, s[30:31]
	s_waitcnt lgkmcnt(0)
; __device__ __forceinline__ unsigned pk2(float lo, float hi) { unsigned r; asm("v_cvt_pk_bf16_f32 %0, %1, %2" : "=v"(r) : "v"(lo), "v"(hi)); return r; }
; __device__ __forceinline__ float bflo(unsigned w) { return __uint_as_float(w << 16); }
; __device__ __forceinline__ float bfhi(unsigned w) { return __uint_as_float(w & 0xffff0000u); }
; __device__ __forceinline__ void phase_scan(const Params& p, LAS unsigned char* lds) {
;     ...
; #pragma unroll 8
;         for (int s = 0; s < 128; ++s) { const unsigned lw = __builtin_nontemporal_load(LU + base + (size_t)s * LW); const float la = bflo(lw), u = bfhi(lw); h = __expf(la) * h + u;
;             YL[base + (size_t)s * LW] = (bf16_t)(pk2(h, h) & 0xffffu); }
	v_fma_f32 v141, v164, v141, v179
	v_cndmask_b32_e64 v142, v142, v141, s[58:59]
	v_lshlrev_b32_e32 v140, 16, v0
	v_mul_f32_e32 v140, 0x3fb8aa3b, v140
	v_exp_f32_e32 v140, v140
	v_and_b32_e32 v0, 0xffff0000, v0
	v_fma_f32 v142, v140, v142, v0
	v_cvt_pk_bf16_f32 v0, v142, v142
	global_store_short v134, v0, s[66:67]
	v_lshlrev_b32_e32 v143, 16, v1
	v_mul_f32_e32 v143, 0x3fb8aa3b, v143
	v_exp_f32_e32 v143, v143
	v_and_b32_e32 v1, 0xffff0000, v1
	v_fma_f32 v142, v143, v142, v1
	v_cvt_pk_bf16_f32 v1, v142, v142
	global_store_short v135, v1, s[66:67]
	v_lshlrev_b32_e32 v140, 16, v2
	v_mul_f32_e32 v140, 0x3fb8aa3b, v140
	v_exp_f32_e32 v140, v140
	v_and_b32_e32 v2, 0xffff0000, v2
	v_fma_f32 v142, v140, v142, v2
	v_cvt_pk_bf16_f32 v2, v142, v142
	global_store_short v136, v2, s[66:67]
	v_lshlrev_b32_e32 v143, 16, v3
	v_mul_f32_e32 v143, 0x3fb8aa3b, v143
	v_exp_f32_e32 v143, v143
	v_and_b32_e32 v3, 0xffff0000, v3
	v_fma_f32 v142, v143, v142, v3
	v_cvt_pk_bf16_f32 v3, v142, v142
	global_store_short v137, v3, s[66:67]
	s_add_u32 s66, s66, 0x4000
	s_addc_u32 s67, s67, 0
	v_lshlrev_b32_e32 v140, 16, v4
	v_mul_f32_e32 v140, 0x3fb8aa3b, v140
	v_exp_f32_e32 v140, v140
	v_and_b32_e32 v4, 0xffff0000, v4
	v_fma_f32 v142, v140, v142, v4
	v_cvt_pk_bf16_f32 v4, v142, v142
	global_store_short v134, v4, s[66:67]
	v_lshlrev_b32_e32 v143, 16, v5
	v_mul_f32_e32 v143, 0x3fb8aa3b, v143
	v_exp_f32_e32 v143, v143
	v_and_b32_e32 v5, 0xffff0000, v5
	v_fma_f32 v142, v143, v142, v5
	v_cvt_pk_bf16_f32 v5, v142, v142
	global_store_short v135, v5, s[66:67]
	v_lshlrev_b32_e32 v140, 16, v6
	v_mul_f32_e32 v140, 0x3fb8aa3b, v140
	v_exp_f32_e32 v140, v140
	v_and_b32_e32 v6, 0xffff0000, v6
	v_fma_f32 v142, v140, v142, v6
	v_cvt_pk_bf16_f32 v6, v142, v142
	global_store_short v136, v6, s[66:67]
	v_lshlrev_b32_e32 v143, 16, v7
	v_mul_f32_e32 v143, 0x3fb8aa3b, v143
	v_exp_f32_e32 v143, v143
	v_and_b32_e32 v7, 0xffff0000, v7
	v_fma_f32 v142, v143, v142, v7
	v_cvt_pk_bf16_f32 v7, v142, v142
	global_store_short v137, v7, s[66:67]
	s_add_u32 s66, s66, 0x4000
	s_addc_u32 s67, s67, 0
	v_lshlrev_b32_e32 v140, 16, v8
	v_mul_f32_e32 v140, 0x3fb8aa3b, v140
	v_exp_f32_e32 v140, v140
	v_and_b32_e32 v8, 0xffff0000, v8
	v_fma_f32 v142, v140, v142, v8
	v_cvt_pk_bf16_f32 v8, v142, v142
	global_store_short v134, v8, s[66:67]
	v_lshlrev_b32_e32 v143, 16, v9
	v_mul_f32_e32 v143, 0x3fb8aa3b, v143
	v_exp_f32_e32 v143, v143
	v_and_b32_e32 v9, 0xffff0000, v9
	v_fma_f32 v142, v143, v142, v9
	v_cvt_pk_bf16_f32 v9, v142, v142
	global_store_short v135, v9, s[66:67]
	v_lshlrev_b32_e32 v140, 16, v10
	v_mul_f32_e32 v140, 0x3fb8aa3b, v140
	v_exp_f32_e32 v140, v140
	v_and_b32_e32 v10, 0xffff0000, v10
	v_fma_f32 v142, v140, v142, v10
	v_cvt_pk_bf16_f32 v10, v142, v142
	global_store_short v136, v10, s[66:67]
	v_lshlrev_b32_e32 v143, 16, v11
	v_mul_f32_e32 v143, 0x3fb8aa3b, v143
	v_exp_f32_e32 v143, v143
	v_and_b32_e32 v11, 0xffff0000, v11
	v_fma_f32 v142, v143, v142, v11
	v_cvt_pk_bf16_f32 v11, v142, v142
	global_store_short v137, v11, s[66:67]
	s_add_u32 s66, s66, 0x4000
	s_addc_u32 s67, s67, 0
	v_lshlrev_b32_e32 v140, 16, v12
	v_mul_f32_e32 v140, 0x3fb8aa3b, v140
	v_exp_f32_e32 v140, v140
	v_and_b32_e32 v12, 0xffff0000, v12
	v_fma_f32 v142, v140, v142, v12
	v_cvt_pk_bf16_f32 v12, v142, v142
	global_store_short v134, v12, s[66:67]
	v_lshlrev_b32_e32 v143, 16, v13
	v_mul_f32_e32 v143, 0x3fb8aa3b, v143
	v_exp_f32_e32 v143, v143
	v_and_b32_e32 v13, 0xffff0000, v13
	v_fma_f32 v142, v143, v142, v13
	v_cvt_pk_bf16_f32 v13, v142, v142
	global_store_short v135, v13, s[66:67]
	v_lshlrev_b32_e32 v140, 16, v14
	v_mul_f32_e32 v140, 0x3fb8aa3b, v140
	v_exp_f32_e32 v140, v140
	v_and_b32_e32 v14, 0xffff0000, v14
	v_fma_f32 v142, v140, v142, v14
	v_cvt_pk_bf16_f32 v14, v142, v142
	global_store_short v136, v14, s[66:67]
	v_lshlrev_b32_e32 v143, 16, v15
	v_mul_f32_e32 v143, 0x3fb8aa3b, v143
	v_exp_f32_e32 v143, v143
	v_and_b32_e32 v15, 0xffff0000, v15
	v_fma_f32 v142, v143, v142, v15
	v_cvt_pk_bf16_f32 v15, v142, v142
	global_store_short v137, v15, s[66:67]
	s_add_u32 s66, s66, 0x4000
	s_addc_u32 s67, s67, 0
	v_lshlrev_b32_e32 v140, 16, v16
	v_mul_f32_e32 v140, 0x3fb8aa3b, v140
	v_exp_f32_e32 v140, v140
	v_and_b32_e32 v16, 0xffff0000, v16
	v_fma_f32 v142, v140, v142, v16
	v_cvt_pk_bf16_f32 v16, v142, v142
	global_store_short v134, v16, s[66:67]
	v_lshlrev_b32_e32 v143, 16, v17
	v_mul_f32_e32 v143, 0x3fb8aa3b, v143
	v_exp_f32_e32 v143, v143
	v_and_b32_e32 v17, 0xffff0000, v17
	v_fma_f32 v142, v143, v142, v17
	v_cvt_pk_bf16_f32 v17, v142, v142
	global_store_short v135, v17, s[66:67]
	v_lshlrev_b32_e32 v140, 16, v18
	v_mul_f32_e32 v140, 0x3fb8aa3b, v140
	v_exp_f32_e32 v140, v140
	v_and_b32_e32 v18, 0xffff0000, v18
	v_fma_f32 v142, v140, v142, v18
	v_cvt_pk_bf16_f32 v18, v142, v142
	global_store_short v136, v18, s[66:67]
	v_lshlrev_b32_e32 v143, 16, v19
	v_mul_f32_e32 v143, 0x3fb8aa3b, v143
	v_exp_f32_e32 v143, v143
	v_and_b32_e32 v19, 0xffff0000, v19
	v_fma_f32 v142, v143, v142, v19
	v_cvt_pk_bf16_f32 v19, v142, v142
	global_store_short v137, v19, s[66:67]
	s_add_u32 s66, s66, 0x4000
	s_addc_u32 s67, s67, 0
	v_lshlrev_b32_e32 v140, 16, v20
	v_mul_f32_e32 v140, 0x3fb8aa3b, v140
	v_exp_f32_e32 v140, v140
	v_and_b32_e32 v20, 0xffff0000, v20
	v_fma_f32 v142, v140, v142, v20
	v_cvt_pk_bf16_f32 v20, v142, v142
	global_store_short v134, v20, s[66:67]
	v_lshlrev_b32_e32 v143, 16, v21
	v_mul_f32_e32 v143, 0x3fb8aa3b, v143
	v_exp_f32_e32 v143, v143
	v_and_b32_e32 v21, 0xffff0000, v21
	v_fma_f32 v142, v143, v142, v21
	v_cvt_pk_bf16_f32 v21, v142, v142
	global_store_short v135, v21, s[66:67]
	v_lshlrev_b32_e32 v140, 16, v22
	v_mul_f32_e32 v140, 0x3fb8aa3b, v140
; __device__ __forceinline__ unsigned pk2(float lo, float hi) { unsigned r; asm("v_cvt_pk_bf16_f32 %0, %1, %2" : "=v"(r) : "v"(lo), "v"(hi)); return r; }
; __device__ __forceinline__ float bflo(unsigned w) { return __uint_as_float(w << 16); }
; __device__ __forceinline__ float bfhi(unsigned w) { return __uint_as_float(w & 0xffff0000u); }
; __device__ __forceinline__ void phase_scan(const Params& p, LAS unsigned char* lds) {
;     ...
; #pragma unroll 8
;         for (int s = 0; s < 128; ++s) { const unsigned lw = __builtin_nontemporal_load(LU + base + (size_t)s * LW); const float la = bflo(lw), u = bfhi(lw); h = __expf(la) * h + u;
;             YL[base + (size_t)s * LW] = (bf16_t)(pk2(h, h) & 0xffffu); }
	v_exp_f32_e32 v140, v140
	v_and_b32_e32 v22, 0xffff0000, v22
	v_fma_f32 v142, v140, v142, v22
	v_cvt_pk_bf16_f32 v22, v142, v142
	global_store_short v136, v22, s[66:67]
	v_lshlrev_b32_e32 v143, 16, v23
	v_mul_f32_e32 v143, 0x3fb8aa3b, v143
	v_exp_f32_e32 v143, v143
	v_and_b32_e32 v23, 0xffff0000, v23
	v_fma_f32 v142, v143, v142, v23
	v_cvt_pk_bf16_f32 v23, v142, v142
	global_store_short v137, v23, s[66:67]
	s_add_u32 s66, s66, 0x4000
	s_addc_u32 s67, s67, 0
	v_lshlrev_b32_e32 v140, 16, v24
	v_mul_f32_e32 v140, 0x3fb8aa3b, v140
	v_exp_f32_e32 v140, v140
	v_and_b32_e32 v24, 0xffff0000, v24
	v_fma_f32 v142, v140, v142, v24
	v_cvt_pk_bf16_f32 v24, v142, v142
	global_store_short v134, v24, s[66:67]
	v_lshlrev_b32_e32 v143, 16, v25
	v_mul_f32_e32 v143, 0x3fb8aa3b, v143
	v_exp_f32_e32 v143, v143
	v_and_b32_e32 v25, 0xffff0000, v25
	v_fma_f32 v142, v143, v142, v25
	v_cvt_pk_bf16_f32 v25, v142, v142
	global_store_short v135, v25, s[66:67]
	v_lshlrev_b32_e32 v140, 16, v26
	v_mul_f32_e32 v140, 0x3fb8aa3b, v140
	v_exp_f32_e32 v140, v140
	v_and_b32_e32 v26, 0xffff0000, v26
	v_fma_f32 v142, v140, v142, v26
	v_cvt_pk_bf16_f32 v26, v142, v142
	global_store_short v136, v26, s[66:67]
	v_lshlrev_b32_e32 v143, 16, v27
	v_mul_f32_e32 v143, 0x3fb8aa3b, v143
	v_exp_f32_e32 v143, v143
	v_and_b32_e32 v27, 0xffff0000, v27
	v_fma_f32 v142, v143, v142, v27
	v_cvt_pk_bf16_f32 v27, v142, v142
	global_store_short v137, v27, s[66:67]
	s_add_u32 s66, s66, 0x4000
	s_addc_u32 s67, s67, 0
	v_lshlrev_b32_e32 v140, 16, v28
	v_mul_f32_e32 v140, 0x3fb8aa3b, v140
	v_exp_f32_e32 v140, v140
	v_and_b32_e32 v28, 0xffff0000, v28
	v_fma_f32 v142, v140, v142, v28
	v_cvt_pk_bf16_f32 v28, v142, v142
	global_store_short v134, v28, s[66:67]
	v_lshlrev_b32_e32 v143, 16, v29
	v_mul_f32_e32 v143, 0x3fb8aa3b, v143
	v_exp_f32_e32 v143, v143
	v_and_b32_e32 v29, 0xffff0000, v29
	v_fma_f32 v142, v143, v142, v29
	v_cvt_pk_bf16_f32 v29, v142, v142
	global_store_short v135, v29, s[66:67]
	v_lshlrev_b32_e32 v140, 16, v30
	v_mul_f32_e32 v140, 0x3fb8aa3b, v140
	v_exp_f32_e32 v140, v140
	v_and_b32_e32 v30, 0xffff0000, v30
	v_fma_f32 v142, v140, v142, v30
	v_cvt_pk_bf16_f32 v30, v142, v142
	global_store_short v136, v30, s[66:67]
	v_lshlrev_b32_e32 v143, 16, v31
	v_mul_f32_e32 v143, 0x3fb8aa3b, v143
	v_exp_f32_e32 v143, v143
	v_and_b32_e32 v31, 0xffff0000, v31
	v_fma_f32 v142, v143, v142, v31
	v_cvt_pk_bf16_f32 v31, v142, v142
	global_store_short v137, v31, s[66:67]
	s_add_u32 s66, s66, 0x4000
	s_addc_u32 s67, s67, 0
	v_lshlrev_b32_e32 v140, 16, v32
	v_mul_f32_e32 v140, 0x3fb8aa3b, v140
	v_exp_f32_e32 v140, v140
	v_and_b32_e32 v32, 0xffff0000, v32
	v_fma_f32 v142, v140, v142, v32
	v_cvt_pk_bf16_f32 v32, v142, v142
	global_store_short v134, v32, s[66:67]
	v_lshlrev_b32_e32 v143, 16, v33
	v_mul_f32_e32 v143, 0x3fb8aa3b, v143
	v_exp_f32_e32 v143, v143
	v_and_b32_e32 v33, 0xffff0000, v33
	v_fma_f32 v142, v143, v142, v33
	v_cvt_pk_bf16_f32 v33, v142, v142
	global_store_short v135, v33, s[66:67]
	v_lshlrev_b32_e32 v140, 16, v34
	v_mul_f32_e32 v140, 0x3fb8aa3b, v140
	v_exp_f32_e32 v140, v140
	v_and_b32_e32 v34, 0xffff0000, v34
	v_fma_f32 v142, v140, v142, v34
	v_cvt_pk_bf16_f32 v34, v142, v142
	global_store_short v136, v34, s[66:67]
	v_lshlrev_b32_e32 v143, 16, v35
	v_mul_f32_e32 v143, 0x3fb8aa3b, v143
	v_exp_f32_e32 v143, v143
	v_and_b32_e32 v35, 0xffff0000, v35
	v_fma_f32 v142, v143, v142, v35
	v_cvt_pk_bf16_f32 v35, v142, v142
	global_store_short v137, v35, s[66:67]
	s_add_u32 s66, s66, 0x4000
	s_addc_u32 s67, s67, 0
	v_lshlrev_b32_e32 v140, 16, v36
	v_mul_f32_e32 v140, 0x3fb8aa3b, v140
	v_exp_f32_e32 v140, v140
	v_and_b32_e32 v36, 0xffff0000, v36
	v_fma_f32 v142, v140, v142, v36
	v_cvt_pk_bf16_f32 v36, v142, v142
	global_store_short v134, v36, s[66:67]
	v_lshlrev_b32_e32 v143, 16, v37
	v_mul_f32_e32 v143, 0x3fb8aa3b, v143
	v_exp_f32_e32 v143, v143
	v_and_b32_e32 v37, 0xffff0000, v37
	v_fma_f32 v142, v143, v142, v37
	v_cvt_pk_bf16_f32 v37, v142, v142
	global_store_short v135, v37, s[66:67]
	v_lshlrev_b32_e32 v140, 16, v38
	v_mul_f32_e32 v140, 0x3fb8aa3b, v140
	v_exp_f32_e32 v140, v140
	v_and_b32_e32 v38, 0xffff0000, v38
	v_fma_f32 v142, v140, v142, v38
	v_cvt_pk_bf16_f32 v38, v142, v142
	global_store_short v136, v38, s[66:67]
	v_lshlrev_b32_e32 v143, 16, v39
	v_mul_f32_e32 v143, 0x3fb8aa3b, v143
	v_exp_f32_e32 v143, v143
	v_and_b32_e32 v39, 0xffff0000, v39
	v_fma_f32 v142, v143, v142, v39
	v_cvt_pk_bf16_f32 v39, v142, v142
	global_store_short v137, v39, s[66:67]
	s_add_u32 s66, s66, 0x4000
	s_addc_u32 s67, s67, 0
	v_lshlrev_b32_e32 v140, 16, v40
	v_mul_f32_e32 v140, 0x3fb8aa3b, v140
	v_exp_f32_e32 v140, v140
	v_and_b32_e32 v40, 0xffff0000, v40
	v_fma_f32 v142, v140, v142, v40
	v_cvt_pk_bf16_f32 v40, v142, v142
	global_store_short v134, v40, s[66:67]
	v_lshlrev_b32_e32 v143, 16, v41
	v_mul_f32_e32 v143, 0x3fb8aa3b, v143
	v_exp_f32_e32 v143, v143
	v_and_b32_e32 v41, 0xffff0000, v41
	v_fma_f32 v142, v143, v142, v41
	v_cvt_pk_bf16_f32 v41, v142, v142
	global_store_short v135, v41, s[66:67]
	v_lshlrev_b32_e32 v140, 16, v42
	v_mul_f32_e32 v140, 0x3fb8aa3b, v140
	v_exp_f32_e32 v140, v140
	v_and_b32_e32 v42, 0xffff0000, v42
	v_fma_f32 v142, v140, v142, v42
	v_cvt_pk_bf16_f32 v42, v142, v142
	global_store_short v136, v42, s[66:67]
	v_lshlrev_b32_e32 v143, 16, v43
	v_mul_f32_e32 v143, 0x3fb8aa3b, v143
	v_exp_f32_e32 v143, v143
	v_and_b32_e32 v43, 0xffff0000, v43
	v_fma_f32 v142, v143, v142, v43
	v_cvt_pk_bf16_f32 v43, v142, v142
	global_store_short v137, v43, s[66:67]
	s_add_u32 s66, s66, 0x4000
	s_addc_u32 s67, s67, 0
	v_lshlrev_b32_e32 v140, 16, v44
	v_mul_f32_e32 v140, 0x3fb8aa3b, v140
	v_exp_f32_e32 v140, v140
; __device__ __forceinline__ unsigned pk2(float lo, float hi) { unsigned r; asm("v_cvt_pk_bf16_f32 %0, %1, %2" : "=v"(r) : "v"(lo), "v"(hi)); return r; }
; __device__ __forceinline__ float bflo(unsigned w) { return __uint_as_float(w << 16); }
; __device__ __forceinline__ float bfhi(unsigned w) { return __uint_as_float(w & 0xffff0000u); }
; __device__ __forceinline__ void phase_scan(const Params& p, LAS unsigned char* lds) {
;     ...
; #pragma unroll 8
;         for (int s = 0; s < 128; ++s) { const unsigned lw = __builtin_nontemporal_load(LU + base + (size_t)s * LW); const float la = bflo(lw), u = bfhi(lw); h = __expf(la) * h + u;
;             YL[base + (size_t)s * LW] = (bf16_t)(pk2(h, h) & 0xffffu); }
	v_and_b32_e32 v44, 0xffff0000, v44
	v_fma_f32 v142, v140, v142, v44
	v_cvt_pk_bf16_f32 v44, v142, v142
	global_store_short v134, v44, s[66:67]
	v_lshlrev_b32_e32 v143, 16, v45
	v_mul_f32_e32 v143, 0x3fb8aa3b, v143
	v_exp_f32_e32 v143, v143
	v_and_b32_e32 v45, 0xffff0000, v45
	v_fma_f32 v142, v143, v142, v45
	v_cvt_pk_bf16_f32 v45, v142, v142
	global_store_short v135, v45, s[66:67]
	v_lshlrev_b32_e32 v140, 16, v46
	v_mul_f32_e32 v140, 0x3fb8aa3b, v140
	v_exp_f32_e32 v140, v140
	v_and_b32_e32 v46, 0xffff0000, v46
	v_fma_f32 v142, v140, v142, v46
	v_cvt_pk_bf16_f32 v46, v142, v142
	global_store_short v136, v46, s[66:67]
	v_lshlrev_b32_e32 v143, 16, v47
	v_mul_f32_e32 v143, 0x3fb8aa3b, v143
	v_exp_f32_e32 v143, v143
	v_and_b32_e32 v47, 0xffff0000, v47
	v_fma_f32 v142, v143, v142, v47
	v_cvt_pk_bf16_f32 v47, v142, v142
	global_store_short v137, v47, s[66:67]
	s_add_u32 s66, s66, 0x4000
	s_addc_u32 s67, s67, 0
	v_lshlrev_b32_e32 v140, 16, v48
	v_mul_f32_e32 v140, 0x3fb8aa3b, v140
	v_exp_f32_e32 v140, v140
	v_and_b32_e32 v48, 0xffff0000, v48
	v_fma_f32 v142, v140, v142, v48
	v_cvt_pk_bf16_f32 v48, v142, v142
	global_store_short v134, v48, s[66:67]
	v_lshlrev_b32_e32 v143, 16, v49
	v_mul_f32_e32 v143, 0x3fb8aa3b, v143
	v_exp_f32_e32 v143, v143
	v_and_b32_e32 v49, 0xffff0000, v49
	v_fma_f32 v142, v143, v142, v49
	v_cvt_pk_bf16_f32 v49, v142, v142
	global_store_short v135, v49, s[66:67]
	v_lshlrev_b32_e32 v140, 16, v50
	v_mul_f32_e32 v140, 0x3fb8aa3b, v140
	v_exp_f32_e32 v140, v140
	v_and_b32_e32 v50, 0xffff0000, v50
	v_fma_f32 v142, v140, v142, v50
	v_cvt_pk_bf16_f32 v50, v142, v142
	global_store_short v136, v50, s[66:67]
	v_lshlrev_b32_e32 v143, 16, v51
	v_mul_f32_e32 v143, 0x3fb8aa3b, v143
	v_exp_f32_e32 v143, v143
	v_and_b32_e32 v51, 0xffff0000, v51
	v_fma_f32 v142, v143, v142, v51
	v_cvt_pk_bf16_f32 v51, v142, v142
	global_store_short v137, v51, s[66:67]
	s_add_u32 s66, s66, 0x4000
	s_addc_u32 s67, s67, 0
	v_lshlrev_b32_e32 v140, 16, v52
	v_mul_f32_e32 v140, 0x3fb8aa3b, v140
	v_exp_f32_e32 v140, v140
	v_and_b32_e32 v52, 0xffff0000, v52
	v_fma_f32 v142, v140, v142, v52
	v_cvt_pk_bf16_f32 v52, v142, v142
	global_store_short v134, v52, s[66:67]
	v_lshlrev_b32_e32 v143, 16, v53
	v_mul_f32_e32 v143, 0x3fb8aa3b, v143
	v_exp_f32_e32 v143, v143
	v_and_b32_e32 v53, 0xffff0000, v53
	v_fma_f32 v142, v143, v142, v53
	v_cvt_pk_bf16_f32 v53, v142, v142
	global_store_short v135, v53, s[66:67]
	v_lshlrev_b32_e32 v140, 16, v54
	v_mul_f32_e32 v140, 0x3fb8aa3b, v140
	v_exp_f32_e32 v140, v140
	v_and_b32_e32 v54, 0xffff0000, v54
	v_fma_f32 v142, v140, v142, v54
	v_cvt_pk_bf16_f32 v54, v142, v142
	global_store_short v136, v54, s[66:67]
	v_lshlrev_b32_e32 v143, 16, v55
	v_mul_f32_e32 v143, 0x3fb8aa3b, v143
	v_exp_f32_e32 v143, v143
	v_and_b32_e32 v55, 0xffff0000, v55
	v_fma_f32 v142, v143, v142, v55
	v_cvt_pk_bf16_f32 v55, v142, v142
	global_store_short v137, v55, s[66:67]
	s_add_u32 s66, s66, 0x4000
	s_addc_u32 s67, s67, 0
	v_lshlrev_b32_e32 v140, 16, v56
	v_mul_f32_e32 v140, 0x3fb8aa3b, v140
	v_exp_f32_e32 v140, v140
	v_and_b32_e32 v56, 0xffff0000, v56
	v_fma_f32 v142, v140, v142, v56
	v_cvt_pk_bf16_f32 v56, v142, v142
	global_store_short v134, v56, s[66:67]
	v_lshlrev_b32_e32 v143, 16, v57
	v_mul_f32_e32 v143, 0x3fb8aa3b, v143
	v_exp_f32_e32 v143, v143
	v_and_b32_e32 v57, 0xffff0000, v57
	v_fma_f32 v142, v143, v142, v57
	v_cvt_pk_bf16_f32 v57, v142, v142
	global_store_short v135, v57, s[66:67]
	v_lshlrev_b32_e32 v140, 16, v58
	v_mul_f32_e32 v140, 0x3fb8aa3b, v140
	v_exp_f32_e32 v140, v140
	v_and_b32_e32 v58, 0xffff0000, v58
	v_fma_f32 v142, v140, v142, v58
	v_cvt_pk_bf16_f32 v58, v142, v142
	global_store_short v136, v58, s[66:67]
	v_lshlrev_b32_e32 v143, 16, v59
	v_mul_f32_e32 v143, 0x3fb8aa3b, v143
	v_exp_f32_e32 v143, v143
	v_and_b32_e32 v59, 0xffff0000, v59
	v_fma_f32 v142, v143, v142, v59
	v_cvt_pk_bf16_f32 v59, v142, v142
	global_store_short v137, v59, s[66:67]
	s_add_u32 s66, s66, 0x4000
	s_addc_u32 s67, s67, 0
	v_lshlrev_b32_e32 v140, 16, v60
	v_mul_f32_e32 v140, 0x3fb8aa3b, v140
	v_exp_f32_e32 v140, v140
	v_and_b32_e32 v60, 0xffff0000, v60
	v_fma_f32 v142, v140, v142, v60
	v_cvt_pk_bf16_f32 v60, v142, v142
	global_store_short v134, v60, s[66:67]
	v_lshlrev_b32_e32 v143, 16, v61
	v_mul_f32_e32 v143, 0x3fb8aa3b, v143
	v_exp_f32_e32 v143, v143
	v_and_b32_e32 v61, 0xffff0000, v61
	v_fma_f32 v142, v143, v142, v61
	v_cvt_pk_bf16_f32 v61, v142, v142
	global_store_short v135, v61, s[66:67]
	v_lshlrev_b32_e32 v140, 16, v62
	v_mul_f32_e32 v140, 0x3fb8aa3b, v140
	v_exp_f32_e32 v140, v140
	v_and_b32_e32 v62, 0xffff0000, v62
	v_fma_f32 v142, v140, v142, v62
	v_cvt_pk_bf16_f32 v62, v142, v142
	global_store_short v136, v62, s[66:67]
	v_lshlrev_b32_e32 v143, 16, v63
	v_mul_f32_e32 v143, 0x3fb8aa3b, v143
	v_exp_f32_e32 v143, v143
	v_and_b32_e32 v63, 0xffff0000, v63
	v_fma_f32 v142, v143, v142, v63
	v_cvt_pk_bf16_f32 v63, v142, v142
	global_store_short v137, v63, s[66:67]
	s_add_u32 s66, s66, 0x4000
	s_addc_u32 s67, s67, 0
	v_lshlrev_b32_e32 v140, 16, v64
	v_mul_f32_e32 v140, 0x3fb8aa3b, v140
	v_exp_f32_e32 v140, v140
	v_and_b32_e32 v64, 0xffff0000, v64
	v_fma_f32 v142, v140, v142, v64
	v_cvt_pk_bf16_f32 v64, v142, v142
	global_store_short v134, v64, s[66:67]
	v_lshlrev_b32_e32 v143, 16, v65
	v_mul_f32_e32 v143, 0x3fb8aa3b, v143
	v_exp_f32_e32 v143, v143
	v_and_b32_e32 v65, 0xffff0000, v65
	v_fma_f32 v142, v143, v142, v65
	v_cvt_pk_bf16_f32 v65, v142, v142
	global_store_short v135, v65, s[66:67]
	v_lshlrev_b32_e32 v140, 16, v66
	v_mul_f32_e32 v140, 0x3fb8aa3b, v140
	v_exp_f32_e32 v140, v140
	v_and_b32_e32 v66, 0xffff0000, v66
	v_fma_f32 v142, v140, v142, v66
; __device__ __forceinline__ unsigned pk2(float lo, float hi) { unsigned r; asm("v_cvt_pk_bf16_f32 %0, %1, %2" : "=v"(r) : "v"(lo), "v"(hi)); return r; }
; __device__ __forceinline__ float bflo(unsigned w) { return __uint_as_float(w << 16); }
; __device__ __forceinline__ float bfhi(unsigned w) { return __uint_as_float(w & 0xffff0000u); }
; __device__ __forceinline__ void phase_scan(const Params& p, LAS unsigned char* lds) {
;     ...
; #pragma unroll 8
;         for (int s = 0; s < 128; ++s) { const unsigned lw = __builtin_nontemporal_load(LU + base + (size_t)s * LW); const float la = bflo(lw), u = bfhi(lw); h = __expf(la) * h + u;
;             YL[base + (size_t)s * LW] = (bf16_t)(pk2(h, h) & 0xffffu); }
	v_cvt_pk_bf16_f32 v66, v142, v142
	global_store_short v136, v66, s[66:67]
	v_lshlrev_b32_e32 v143, 16, v67
	v_mul_f32_e32 v143, 0x3fb8aa3b, v143
	v_exp_f32_e32 v143, v143
	v_and_b32_e32 v67, 0xffff0000, v67
	v_fma_f32 v142, v143, v142, v67
	v_cvt_pk_bf16_f32 v67, v142, v142
	global_store_short v137, v67, s[66:67]
	s_add_u32 s66, s66, 0x4000
	s_addc_u32 s67, s67, 0
	v_lshlrev_b32_e32 v140, 16, v68
	v_mul_f32_e32 v140, 0x3fb8aa3b, v140
	v_exp_f32_e32 v140, v140
	v_and_b32_e32 v68, 0xffff0000, v68
	v_fma_f32 v142, v140, v142, v68
	v_cvt_pk_bf16_f32 v68, v142, v142
	global_store_short v134, v68, s[66:67]
	v_lshlrev_b32_e32 v143, 16, v69
	v_mul_f32_e32 v143, 0x3fb8aa3b, v143
	v_exp_f32_e32 v143, v143
	v_and_b32_e32 v69, 0xffff0000, v69
	v_fma_f32 v142, v143, v142, v69
	v_cvt_pk_bf16_f32 v69, v142, v142
	global_store_short v135, v69, s[66:67]
	v_lshlrev_b32_e32 v140, 16, v70
	v_mul_f32_e32 v140, 0x3fb8aa3b, v140
	v_exp_f32_e32 v140, v140
	v_and_b32_e32 v70, 0xffff0000, v70
	v_fma_f32 v142, v140, v142, v70
	v_cvt_pk_bf16_f32 v70, v142, v142
	global_store_short v136, v70, s[66:67]
	v_lshlrev_b32_e32 v143, 16, v71
	v_mul_f32_e32 v143, 0x3fb8aa3b, v143
	v_exp_f32_e32 v143, v143
	v_and_b32_e32 v71, 0xffff0000, v71
	v_fma_f32 v142, v143, v142, v71
	v_cvt_pk_bf16_f32 v71, v142, v142
	global_store_short v137, v71, s[66:67]
	s_add_u32 s66, s66, 0x4000
	s_addc_u32 s67, s67, 0
	v_lshlrev_b32_e32 v140, 16, v72
	v_mul_f32_e32 v140, 0x3fb8aa3b, v140
	v_exp_f32_e32 v140, v140
	v_and_b32_e32 v72, 0xffff0000, v72
	v_fma_f32 v142, v140, v142, v72
	v_cvt_pk_bf16_f32 v72, v142, v142
	global_store_short v134, v72, s[66:67]
	v_lshlrev_b32_e32 v143, 16, v73
	v_mul_f32_e32 v143, 0x3fb8aa3b, v143
	v_exp_f32_e32 v143, v143
	v_and_b32_e32 v73, 0xffff0000, v73
	v_fma_f32 v142, v143, v142, v73
	v_cvt_pk_bf16_f32 v73, v142, v142
	global_store_short v135, v73, s[66:67]
	v_lshlrev_b32_e32 v140, 16, v74
	v_mul_f32_e32 v140, 0x3fb8aa3b, v140
	v_exp_f32_e32 v140, v140
	v_and_b32_e32 v74, 0xffff0000, v74
	v_fma_f32 v142, v140, v142, v74
	v_cvt_pk_bf16_f32 v74, v142, v142
	global_store_short v136, v74, s[66:67]
	v_lshlrev_b32_e32 v143, 16, v75
	v_mul_f32_e32 v143, 0x3fb8aa3b, v143
	v_exp_f32_e32 v143, v143
	v_and_b32_e32 v75, 0xffff0000, v75
	v_fma_f32 v142, v143, v142, v75
	v_cvt_pk_bf16_f32 v75, v142, v142
	global_store_short v137, v75, s[66:67]
	s_add_u32 s66, s66, 0x4000
	s_addc_u32 s67, s67, 0
	v_lshlrev_b32_e32 v140, 16, v76
	v_mul_f32_e32 v140, 0x3fb8aa3b, v140
	v_exp_f32_e32 v140, v140
	v_and_b32_e32 v76, 0xffff0000, v76
	v_fma_f32 v142, v140, v142, v76
	v_cvt_pk_bf16_f32 v76, v142, v142
	global_store_short v134, v76, s[66:67]
	v_lshlrev_b32_e32 v143, 16, v77
	v_mul_f32_e32 v143, 0x3fb8aa3b, v143
	v_exp_f32_e32 v143, v143
	v_and_b32_e32 v77, 0xffff0000, v77
	v_fma_f32 v142, v143, v142, v77
	v_cvt_pk_bf16_f32 v77, v142, v142
	global_store_short v135, v77, s[66:67]
	v_lshlrev_b32_e32 v140, 16, v78
	v_mul_f32_e32 v140, 0x3fb8aa3b, v140
	v_exp_f32_e32 v140, v140
	v_and_b32_e32 v78, 0xffff0000, v78
	v_fma_f32 v142, v140, v142, v78
	v_cvt_pk_bf16_f32 v78, v142, v142
	global_store_short v136, v78, s[66:67]
	v_lshlrev_b32_e32 v143, 16, v79
	v_mul_f32_e32 v143, 0x3fb8aa3b, v143
	v_exp_f32_e32 v143, v143
	v_and_b32_e32 v79, 0xffff0000, v79
	v_fma_f32 v142, v143, v142, v79
	v_cvt_pk_bf16_f32 v79, v142, v142
	global_store_short v137, v79, s[66:67]
	s_add_u32 s66, s66, 0x4000
	s_addc_u32 s67, s67, 0
	v_lshlrev_b32_e32 v140, 16, v80
	v_mul_f32_e32 v140, 0x3fb8aa3b, v140
	v_exp_f32_e32 v140, v140
	v_and_b32_e32 v80, 0xffff0000, v80
	v_fma_f32 v142, v140, v142, v80
	v_cvt_pk_bf16_f32 v80, v142, v142
	global_store_short v134, v80, s[66:67]
	v_lshlrev_b32_e32 v143, 16, v81
	v_mul_f32_e32 v143, 0x3fb8aa3b, v143
	v_exp_f32_e32 v143, v143
	v_and_b32_e32 v81, 0xffff0000, v81
	v_fma_f32 v142, v143, v142, v81
	v_cvt_pk_bf16_f32 v81, v142, v142
	global_store_short v135, v81, s[66:67]
	v_lshlrev_b32_e32 v140, 16, v82
	v_mul_f32_e32 v140, 0x3fb8aa3b, v140
	v_exp_f32_e32 v140, v140
	v_and_b32_e32 v82, 0xffff0000, v82
	v_fma_f32 v142, v140, v142, v82
	v_cvt_pk_bf16_f32 v82, v142, v142
	global_store_short v136, v82, s[66:67]
	v_lshlrev_b32_e32 v143, 16, v83
	v_mul_f32_e32 v143, 0x3fb8aa3b, v143
	v_exp_f32_e32 v143, v143
	v_and_b32_e32 v83, 0xffff0000, v83
	v_fma_f32 v142, v143, v142, v83
	v_cvt_pk_bf16_f32 v83, v142, v142
	global_store_short v137, v83, s[66:67]
	s_add_u32 s66, s66, 0x4000
	s_addc_u32 s67, s67, 0
	v_lshlrev_b32_e32 v140, 16, v84
	v_mul_f32_e32 v140, 0x3fb8aa3b, v140
	v_exp_f32_e32 v140, v140
	v_and_b32_e32 v84, 0xffff0000, v84
	v_fma_f32 v142, v140, v142, v84
	v_cvt_pk_bf16_f32 v84, v142, v142
	global_store_short v134, v84, s[66:67]
	v_lshlrev_b32_e32 v143, 16, v85
	v_mul_f32_e32 v143, 0x3fb8aa3b, v143
	v_exp_f32_e32 v143, v143
	v_and_b32_e32 v85, 0xffff0000, v85
	v_fma_f32 v142, v143, v142, v85
	v_cvt_pk_bf16_f32 v85, v142, v142
	global_store_short v135, v85, s[66:67]
	v_lshlrev_b32_e32 v140, 16, v86
	v_mul_f32_e32 v140, 0x3fb8aa3b, v140
	v_exp_f32_e32 v140, v140
	v_and_b32_e32 v86, 0xffff0000, v86
	v_fma_f32 v142, v140, v142, v86
	v_cvt_pk_bf16_f32 v86, v142, v142
	global_store_short v136, v86, s[66:67]
	v_lshlrev_b32_e32 v143, 16, v87
	v_mul_f32_e32 v143, 0x3fb8aa3b, v143
	v_exp_f32_e32 v143, v143
	v_and_b32_e32 v87, 0xffff0000, v87
	v_fma_f32 v142, v143, v142, v87
	v_cvt_pk_bf16_f32 v87, v142, v142
	global_store_short v137, v87, s[66:67]
	s_add_u32 s66, s66, 0x4000
	s_addc_u32 s67, s67, 0
	v_lshlrev_b32_e32 v140, 16, v88
	v_mul_f32_e32 v140, 0x3fb8aa3b, v140
	v_exp_f32_e32 v140, v140
	v_and_b32_e32 v88, 0xffff0000, v88
	v_fma_f32 v142, v140, v142, v88
	v_cvt_pk_bf16_f32 v88, v142, v142
; __device__ __forceinline__ unsigned pk2(float lo, float hi) { unsigned r; asm("v_cvt_pk_bf16_f32 %0, %1, %2" : "=v"(r) : "v"(lo), "v"(hi)); return r; }
; __device__ __forceinline__ float bflo(unsigned w) { return __uint_as_float(w << 16); }
; __device__ __forceinline__ float bfhi(unsigned w) { return __uint_as_float(w & 0xffff0000u); }
; __device__ __forceinline__ void phase_scan(const Params& p, LAS unsigned char* lds) {
;     ...
; #pragma unroll 8
;         for (int s = 0; s < 128; ++s) { const unsigned lw = __builtin_nontemporal_load(LU + base + (size_t)s * LW); const float la = bflo(lw), u = bfhi(lw); h = __expf(la) * h + u;
;             YL[base + (size_t)s * LW] = (bf16_t)(pk2(h, h) & 0xffffu); }
	global_store_short v134, v88, s[66:67]
	v_lshlrev_b32_e32 v143, 16, v89
	v_mul_f32_e32 v143, 0x3fb8aa3b, v143
	v_exp_f32_e32 v143, v143
	v_and_b32_e32 v89, 0xffff0000, v89
	v_fma_f32 v142, v143, v142, v89
	v_cvt_pk_bf16_f32 v89, v142, v142
	global_store_short v135, v89, s[66:67]
	v_lshlrev_b32_e32 v140, 16, v90
	v_mul_f32_e32 v140, 0x3fb8aa3b, v140
	v_exp_f32_e32 v140, v140
	v_and_b32_e32 v90, 0xffff0000, v90
	v_fma_f32 v142, v140, v142, v90
	v_cvt_pk_bf16_f32 v90, v142, v142
	global_store_short v136, v90, s[66:67]
	v_lshlrev_b32_e32 v143, 16, v91
	v_mul_f32_e32 v143, 0x3fb8aa3b, v143
	v_exp_f32_e32 v143, v143
	v_and_b32_e32 v91, 0xffff0000, v91
	v_fma_f32 v142, v143, v142, v91
	v_cvt_pk_bf16_f32 v91, v142, v142
	global_store_short v137, v91, s[66:67]
	s_add_u32 s66, s66, 0x4000
	s_addc_u32 s67, s67, 0
	v_lshlrev_b32_e32 v140, 16, v92
	v_mul_f32_e32 v140, 0x3fb8aa3b, v140
	v_exp_f32_e32 v140, v140
	v_and_b32_e32 v92, 0xffff0000, v92
	v_fma_f32 v142, v140, v142, v92
	v_cvt_pk_bf16_f32 v92, v142, v142
	global_store_short v134, v92, s[66:67]
	v_lshlrev_b32_e32 v143, 16, v93
	v_mul_f32_e32 v143, 0x3fb8aa3b, v143
	v_exp_f32_e32 v143, v143
	v_and_b32_e32 v93, 0xffff0000, v93
	v_fma_f32 v142, v143, v142, v93
	v_cvt_pk_bf16_f32 v93, v142, v142
	global_store_short v135, v93, s[66:67]
	v_lshlrev_b32_e32 v140, 16, v94
	v_mul_f32_e32 v140, 0x3fb8aa3b, v140
	v_exp_f32_e32 v140, v140
	v_and_b32_e32 v94, 0xffff0000, v94
	v_fma_f32 v142, v140, v142, v94
	v_cvt_pk_bf16_f32 v94, v142, v142
	global_store_short v136, v94, s[66:67]
	v_lshlrev_b32_e32 v143, 16, v95
	v_mul_f32_e32 v143, 0x3fb8aa3b, v143
	v_exp_f32_e32 v143, v143
	v_and_b32_e32 v95, 0xffff0000, v95
	v_fma_f32 v142, v143, v142, v95
	v_cvt_pk_bf16_f32 v95, v142, v142
	global_store_short v137, v95, s[66:67]
	s_add_u32 s66, s66, 0x4000
	s_addc_u32 s67, s67, 0
	v_lshlrev_b32_e32 v140, 16, v96
	v_mul_f32_e32 v140, 0x3fb8aa3b, v140
	v_exp_f32_e32 v140, v140
	v_and_b32_e32 v96, 0xffff0000, v96
	v_fma_f32 v142, v140, v142, v96
	v_cvt_pk_bf16_f32 v96, v142, v142
	global_store_short v134, v96, s[66:67]
	v_lshlrev_b32_e32 v143, 16, v97
	v_mul_f32_e32 v143, 0x3fb8aa3b, v143
	v_exp_f32_e32 v143, v143
	v_and_b32_e32 v97, 0xffff0000, v97
	v_fma_f32 v142, v143, v142, v97
	v_cvt_pk_bf16_f32 v97, v142, v142
	global_store_short v135, v97, s[66:67]
	v_lshlrev_b32_e32 v140, 16, v98
	v_mul_f32_e32 v140, 0x3fb8aa3b, v140
	v_exp_f32_e32 v140, v140
	v_and_b32_e32 v98, 0xffff0000, v98
	v_fma_f32 v142, v140, v142, v98
	v_cvt_pk_bf16_f32 v98, v142, v142
	global_store_short v136, v98, s[66:67]
	v_lshlrev_b32_e32 v143, 16, v99
	v_mul_f32_e32 v143, 0x3fb8aa3b, v143
	v_exp_f32_e32 v143, v143
	v_and_b32_e32 v99, 0xffff0000, v99
	v_fma_f32 v142, v143, v142, v99
	v_cvt_pk_bf16_f32 v99, v142, v142
	global_store_short v137, v99, s[66:67]
	s_add_u32 s66, s66, 0x4000
	s_addc_u32 s67, s67, 0
	v_lshlrev_b32_e32 v140, 16, v100
	v_mul_f32_e32 v140, 0x3fb8aa3b, v140
	v_exp_f32_e32 v140, v140
	v_and_b32_e32 v100, 0xffff0000, v100
	v_fma_f32 v142, v140, v142, v100
	v_cvt_pk_bf16_f32 v100, v142, v142
	global_store_short v134, v100, s[66:67]
	v_lshlrev_b32_e32 v143, 16, v101
	v_mul_f32_e32 v143, 0x3fb8aa3b, v143
	v_exp_f32_e32 v143, v143
	v_and_b32_e32 v101, 0xffff0000, v101
	v_fma_f32 v142, v143, v142, v101
	v_cvt_pk_bf16_f32 v101, v142, v142
	global_store_short v135, v101, s[66:67]
	v_lshlrev_b32_e32 v140, 16, v102
	v_mul_f32_e32 v140, 0x3fb8aa3b, v140
	v_exp_f32_e32 v140, v140
	v_and_b32_e32 v102, 0xffff0000, v102
	v_fma_f32 v142, v140, v142, v102
	v_cvt_pk_bf16_f32 v102, v142, v142
	global_store_short v136, v102, s[66:67]
	v_lshlrev_b32_e32 v143, 16, v103
	v_mul_f32_e32 v143, 0x3fb8aa3b, v143
	v_exp_f32_e32 v143, v143
	v_and_b32_e32 v103, 0xffff0000, v103
	v_fma_f32 v142, v143, v142, v103
	v_cvt_pk_bf16_f32 v103, v142, v142
	global_store_short v137, v103, s[66:67]
	s_add_u32 s66, s66, 0x4000
	s_addc_u32 s67, s67, 0
	v_lshlrev_b32_e32 v140, 16, v104
	v_mul_f32_e32 v140, 0x3fb8aa3b, v140
	v_exp_f32_e32 v140, v140
	v_and_b32_e32 v104, 0xffff0000, v104
	v_fma_f32 v142, v140, v142, v104
	v_cvt_pk_bf16_f32 v104, v142, v142
	global_store_short v134, v104, s[66:67]
	v_lshlrev_b32_e32 v143, 16, v105
	v_mul_f32_e32 v143, 0x3fb8aa3b, v143
	v_exp_f32_e32 v143, v143
	v_and_b32_e32 v105, 0xffff0000, v105
	v_fma_f32 v142, v143, v142, v105
	v_cvt_pk_bf16_f32 v105, v142, v142
	global_store_short v135, v105, s[66:67]
	v_lshlrev_b32_e32 v140, 16, v106
	v_mul_f32_e32 v140, 0x3fb8aa3b, v140
	v_exp_f32_e32 v140, v140
	v_and_b32_e32 v106, 0xffff0000, v106
	v_fma_f32 v142, v140, v142, v106
	v_cvt_pk_bf16_f32 v106, v142, v142
	global_store_short v136, v106, s[66:67]
	v_lshlrev_b32_e32 v143, 16, v107
	v_mul_f32_e32 v143, 0x3fb8aa3b, v143
	v_exp_f32_e32 v143, v143
	v_and_b32_e32 v107, 0xffff0000, v107
	v_fma_f32 v142, v143, v142, v107
	v_cvt_pk_bf16_f32 v107, v142, v142
	global_store_short v137, v107, s[66:67]
	s_add_u32 s66, s66, 0x4000
	s_addc_u32 s67, s67, 0
	v_lshlrev_b32_e32 v140, 16, v108
	v_mul_f32_e32 v140, 0x3fb8aa3b, v140
	v_exp_f32_e32 v140, v140
	v_and_b32_e32 v108, 0xffff0000, v108
	v_fma_f32 v142, v140, v142, v108
	v_cvt_pk_bf16_f32 v108, v142, v142
	global_store_short v134, v108, s[66:67]
; __device__ __forceinline__ unsigned pk2(float lo, float hi) { unsigned r; asm("v_cvt_pk_bf16_f32 %0, %1, %2" : "=v"(r) : "v"(lo), "v"(hi)); return r; }
; __device__ __forceinline__ float bflo(unsigned w) { return __uint_as_float(w << 16); }
; __device__ __forceinline__ float bfhi(unsigned w) { return __uint_as_float(w & 0xffff0000u); }
; __device__ __forceinline__ void phase_scan(const Params& p, LAS unsigned char* lds) {
;     ...
; #pragma unroll 8
;         for (int s = 0; s < 128; ++s) { const unsigned lw = __builtin_nontemporal_load(LU + base + (size_t)s * LW); const float la = bflo(lw), u = bfhi(lw); h = __expf(la) * h + u;
;             YL[base + (size_t)s * LW] = (bf16_t)(pk2(h, h) & 0xffffu); }
;         if (chunk == 15) p.out[O_LHP + b * LW + ch] = h;
;         __syncthreads();
;     }
	v_lshlrev_b32_e32 v143, 16, v109
	v_mul_f32_e32 v143, 0x3fb8aa3b, v143
	v_exp_f32_e32 v143, v143
	v_and_b32_e32 v109, 0xffff0000, v109
	v_fma_f32 v142, v143, v142, v109
	v_cvt_pk_bf16_f32 v109, v142, v142
	global_store_short v135, v109, s[66:67]
	v_lshlrev_b32_e32 v140, 16, v110
	v_mul_f32_e32 v140, 0x3fb8aa3b, v140
	v_exp_f32_e32 v140, v140
	v_and_b32_e32 v110, 0xffff0000, v110
	v_fma_f32 v142, v140, v142, v110
	v_cvt_pk_bf16_f32 v110, v142, v142
	global_store_short v136, v110, s[66:67]
	v_lshlrev_b32_e32 v143, 16, v111
	v_mul_f32_e32 v143, 0x3fb8aa3b, v143
	v_exp_f32_e32 v143, v143
	v_and_b32_e32 v111, 0xffff0000, v111
	v_fma_f32 v142, v143, v142, v111
	v_cvt_pk_bf16_f32 v111, v142, v142
	global_store_short v137, v111, s[66:67]
	s_add_u32 s66, s66, 0x4000
	s_addc_u32 s67, s67, 0
	v_lshlrev_b32_e32 v140, 16, v112
	v_mul_f32_e32 v140, 0x3fb8aa3b, v140
	v_exp_f32_e32 v140, v140
	v_and_b32_e32 v112, 0xffff0000, v112
	v_fma_f32 v142, v140, v142, v112
	v_cvt_pk_bf16_f32 v112, v142, v142
	global_store_short v134, v112, s[66:67]
	v_lshlrev_b32_e32 v143, 16, v113
	v_mul_f32_e32 v143, 0x3fb8aa3b, v143
	v_exp_f32_e32 v143, v143
	v_and_b32_e32 v113, 0xffff0000, v113
	v_fma_f32 v142, v143, v142, v113
	v_cvt_pk_bf16_f32 v113, v142, v142
	global_store_short v135, v113, s[66:67]
	v_lshlrev_b32_e32 v140, 16, v114
	v_mul_f32_e32 v140, 0x3fb8aa3b, v140
	v_exp_f32_e32 v140, v140
	v_and_b32_e32 v114, 0xffff0000, v114
	v_fma_f32 v142, v140, v142, v114
	v_cvt_pk_bf16_f32 v114, v142, v142
	global_store_short v136, v114, s[66:67]
	v_lshlrev_b32_e32 v143, 16, v115
	v_mul_f32_e32 v143, 0x3fb8aa3b, v143
	v_exp_f32_e32 v143, v143
	v_and_b32_e32 v115, 0xffff0000, v115
	v_fma_f32 v142, v143, v142, v115
	v_cvt_pk_bf16_f32 v115, v142, v142
	global_store_short v137, v115, s[66:67]
	s_add_u32 s66, s66, 0x4000
	s_addc_u32 s67, s67, 0
	v_lshlrev_b32_e32 v140, 16, v116
	v_mul_f32_e32 v140, 0x3fb8aa3b, v140
	v_exp_f32_e32 v140, v140
	v_and_b32_e32 v116, 0xffff0000, v116
	v_fma_f32 v142, v140, v142, v116
	v_cvt_pk_bf16_f32 v116, v142, v142
	global_store_short v134, v116, s[66:67]
	v_lshlrev_b32_e32 v143, 16, v117
	v_mul_f32_e32 v143, 0x3fb8aa3b, v143
	v_exp_f32_e32 v143, v143
	v_and_b32_e32 v117, 0xffff0000, v117
	v_fma_f32 v142, v143, v142, v117
	v_cvt_pk_bf16_f32 v117, v142, v142
	global_store_short v135, v117, s[66:67]
	v_lshlrev_b32_e32 v140, 16, v118
	v_mul_f32_e32 v140, 0x3fb8aa3b, v140
	v_exp_f32_e32 v140, v140
	v_and_b32_e32 v118, 0xffff0000, v118
	v_fma_f32 v142, v140, v142, v118
	v_cvt_pk_bf16_f32 v118, v142, v142
	global_store_short v136, v118, s[66:67]
	v_lshlrev_b32_e32 v143, 16, v119
	v_mul_f32_e32 v143, 0x3fb8aa3b, v143
	v_exp_f32_e32 v143, v143
	v_and_b32_e32 v119, 0xffff0000, v119
	v_fma_f32 v142, v143, v142, v119
	v_cvt_pk_bf16_f32 v119, v142, v142
	global_store_short v137, v119, s[66:67]
	s_add_u32 s66, s66, 0x4000
	s_addc_u32 s67, s67, 0
	v_lshlrev_b32_e32 v140, 16, v120
	v_mul_f32_e32 v140, 0x3fb8aa3b, v140
	v_exp_f32_e32 v140, v140
	v_and_b32_e32 v120, 0xffff0000, v120
	v_fma_f32 v142, v140, v142, v120
	v_cvt_pk_bf16_f32 v120, v142, v142
	global_store_short v134, v120, s[66:67]
	v_lshlrev_b32_e32 v143, 16, v121
	v_mul_f32_e32 v143, 0x3fb8aa3b, v143
	v_exp_f32_e32 v143, v143
	v_and_b32_e32 v121, 0xffff0000, v121
	v_fma_f32 v142, v143, v142, v121
	v_cvt_pk_bf16_f32 v121, v142, v142
	global_store_short v135, v121, s[66:67]
	v_lshlrev_b32_e32 v140, 16, v122
	v_mul_f32_e32 v140, 0x3fb8aa3b, v140
	v_exp_f32_e32 v140, v140
	v_and_b32_e32 v122, 0xffff0000, v122
	v_fma_f32 v142, v140, v142, v122
	v_cvt_pk_bf16_f32 v122, v142, v142
	global_store_short v136, v122, s[66:67]
	v_lshlrev_b32_e32 v143, 16, v123
	v_mul_f32_e32 v143, 0x3fb8aa3b, v143
	v_exp_f32_e32 v143, v143
	v_and_b32_e32 v123, 0xffff0000, v123
	v_fma_f32 v142, v143, v142, v123
	v_cvt_pk_bf16_f32 v123, v142, v142
	global_store_short v137, v123, s[66:67]
	s_add_u32 s66, s66, 0x4000
	s_addc_u32 s67, s67, 0
	v_lshlrev_b32_e32 v140, 16, v124
	v_mul_f32_e32 v140, 0x3fb8aa3b, v140
	v_exp_f32_e32 v140, v140
	v_and_b32_e32 v124, 0xffff0000, v124
	v_fma_f32 v142, v140, v142, v124
	v_cvt_pk_bf16_f32 v124, v142, v142
	global_store_short v134, v124, s[66:67]
	v_lshlrev_b32_e32 v143, 16, v125
	v_mul_f32_e32 v143, 0x3fb8aa3b, v143
	v_exp_f32_e32 v143, v143
	v_and_b32_e32 v125, 0xffff0000, v125
	v_fma_f32 v142, v143, v142, v125
	v_cvt_pk_bf16_f32 v125, v142, v142
	global_store_short v135, v125, s[66:67]
	v_lshlrev_b32_e32 v140, 16, v126
	v_mul_f32_e32 v140, 0x3fb8aa3b, v140
	v_exp_f32_e32 v140, v140
	v_and_b32_e32 v126, 0xffff0000, v126
	v_fma_f32 v142, v140, v142, v126
	v_cvt_pk_bf16_f32 v126, v142, v142
	global_store_short v136, v126, s[66:67]
	v_lshlrev_b32_e32 v143, 16, v127
	v_mul_f32_e32 v143, 0x3fb8aa3b, v143
	v_exp_f32_e32 v143, v143
	v_and_b32_e32 v127, 0xffff0000, v127
	v_fma_f32 v142, v143, v142, v127
	v_cvt_pk_bf16_f32 v127, v142, v142
	global_store_short v137, v127, s[66:67]
	v_cmp_eq_u32_e64 s[60:61], 15, v128
	s_and_saveexec_b64 s[62:63], s[60:61]
	s_cbranch_execz .Lscan_nolast
	global_store_dword v148, v142, s[70:71]
.Lscan_nolast:
	s_or_b64 exec, exec, s[62:63]
	s_add_i32 s33, s33, s86
	s_cmpk_gt_i32 s33, 0xff
	s_barrier
	s_cbranch_scc0 .Lscan_item

; #define PG8_STAGE(bufoff, gbase, voff) do { _Pragma("unroll") for (int _i = 0; _i < 2; ++_i) \
;         __builtin_amdgcn_global_load_lds((const unsigned*)((const char*)(gbase) + (voff)[_i]), (LAS unsigned*)(lds + (bufoff) + ldsw + _i * 8192), 16, 0, 0); } while (0)
; #define PG8_LDA(dst, b, h) do { _Pragma("unroll") for (int m = 0; m < 4; ++m) _Pragma("unroll") for (int k = 0; k < 2; ++k) dst[m][k] = *(const LAS bf16x8*)(lds + PG8_SA(b, h) + aoff + m * 2048 + k * 1024); } while (0)
; #define PG8_LDB(dst, b, h) do { _Pragma("unroll") for (int n = 0; n < 2; ++n) _Pragma("unroll") for (int k = 0; k < 2; ++k) dst[n][k] = *(const LAS bf16x8*)(lds + PG8_SB(b, h) + boff + n * 2048 + k * 1024); } while (0)
; #define PG8_MMA(ai, bj, At, Bt) do { __builtin_amdgcn_s_setprio(1); _Pragma("unroll") for (int m = 0; m < 4; ++m) _Pragma("unroll") for (int n = 0; n < 2; ++n) _Pragma("unroll") for (int k = 0; k < 2; ++k) \
;         acc[ai][bj][m][n] = __builtin_amdgcn_mfma_f32_16x16x32_bf16(Bt[n][k], At[m][k], acc[ai][bj][m][n], 0, 0, 0); __builtin_amdgcn_s_setprio(0); } while (0)
; #define PG8_WAIT_V(n) asm volatile("s_waitcnt vmcnt(" #n ")" ::: "memory")
; #define PG8_WAIT_L(n) asm volatile("s_waitcnt lgkmcnt(" #n ")" ::: "memory")
; #define PG8_BAR __builtin_amdgcn_s_barrier()
; #define PG8_SCHED __builtin_amdgcn_sched_barrier(0)
; template <class Epi, class S_t>
; __device__ __forceinline__ void gemm_phase(LAS unsigned char* lds, int lda, int ldb, const S_t& S, const Epi& E) {
;     ...
;             PG8_LDB(B0, 0, 0); PG8_SCHED; PG8_LDA(At, 0, 0); PG8_STAGE(PG8_SA(1, 1), a1 + hstepA, voffA);
;             PG8_WAIT_L(8); PG8_BAR; PG8_WAIT_L(0); PG8_MMA(0, 0, At, B0); PG8_BAR; PG8_SCHED;
;             PG8_LDB(B1, 0, 1); PG8_STAGE(PG8_SB(0, 0), b2, voffB);
;             PG8_BAR; PG8_WAIT_L(0); PG8_MMA(0, 1, At, B1); PG8_BAR;
;             PG8_LDA(At, 0, 1); PG8_STAGE(PG8_SA(0, 0), a2, voffA);
;             PG8_BAR; PG8_WAIT_L(0); PG8_MMA(1, 0, At, B0); PG8_BAR; PG8_SCHED;
;             PG8_STAGE(PG8_SB(0, 1), b2 + hstepB, voffB);
;             PG8_WAIT_V(6); PG8_BAR; PG8_MMA(1, 1, At, B1); PG8_BAR;
.LBB0_945:
	ds_read_b128 v[140:143], v149
	ds_read_b128 v[152:155], v149 offset:1024
	ds_read_b128 v[156:159], v149 offset:2048
	ds_read_b128 v[160:163], v149 offset:3072
	s_add_u32 s33, s60, 0xfffc0080
	s_addc_u32 s52, s61, -1
	s_cmp_eq_u32 s43, 12
	s_cselect_b32 s67, s59, s52
	s_cselect_b32 s66, s58, s33
	s_cselect_b32 s63, s57, s1
	s_cselect_b32 s62, s56, s0
	s_add_i32 m0, s16, 0xc000
	ds_read_b128 v[164:167], v150
	ds_read_b128 v[168:171], v150 offset:1024
	ds_read_b128 v[172:175], v150 offset:2048
	ds_read_b128 v[176:179], v150 offset:3072
	ds_read_b128 v[180:183], v150 offset:4096
	ds_read_b128 v[186:189], v150 offset:5120
	ds_read_b128 v[190:193], v150 offset:6144
	ds_read_b128 v[194:197], v150 offset:7168
	global_load_lds_dwordx4 v136, s[60:61]
	s_add_i32 m0, s16, 0xe000
	s_nop 0
	global_load_lds_dwordx4 v138, s[60:61]
	s_waitcnt lgkmcnt(8)
	s_barrier
	s_waitcnt lgkmcnt(0)
	s_setprio 1
	s_waitcnt lgkmcnt(0)
	v_mfma_f32_16x16x32_bf16 v[124:127], v[140:143], v[164:167], v[124:127]
	v_mfma_f32_16x16x32_bf16 v[120:123], v[156:159], v[164:167], v[120:123]
	v_mfma_f32_16x16x32_bf16 v[116:119], v[140:143], v[172:175], v[116:119]
	v_mfma_f32_16x16x32_bf16 v[108:111], v[156:159], v[172:175], v[108:111]
	v_mfma_f32_16x16x32_bf16 v[96:99], v[140:143], v[180:183], v[96:99]
	v_mfma_f32_16x16x32_bf16 v[88:91], v[156:159], v[180:183], v[88:91]
	v_mfma_f32_16x16x32_bf16 v[80:83], v[140:143], v[190:193], v[80:83]
	v_mfma_f32_16x16x32_bf16 v[72:75], v[156:159], v[190:193], v[72:75]
	v_mfma_f32_16x16x32_bf16 v[124:127], v[152:155], v[168:171], v[124:127]
	v_mfma_f32_16x16x32_bf16 v[120:123], v[160:163], v[168:171], v[120:123]
	v_mfma_f32_16x16x32_bf16 v[116:119], v[152:155], v[176:179], v[116:119]
	v_mfma_f32_16x16x32_bf16 v[108:111], v[160:163], v[176:179], v[108:111]
	v_mfma_f32_16x16x32_bf16 v[96:99], v[152:155], v[186:189], v[96:99]
	v_mfma_f32_16x16x32_bf16 v[88:91], v[160:163], v[186:189], v[88:91]
	v_mfma_f32_16x16x32_bf16 v[80:83], v[152:155], v[194:197], v[80:83]
	v_mfma_f32_16x16x32_bf16 v[72:75], v[160:163], v[194:197], v[72:75]
	s_setprio 0
	s_barrier
	s_add_i32 s33, s88, s5
	s_add_u32 s98, s62, s10
	s_addc_u32 s99, s63, s11
	s_mov_b32 m0, s33
	ds_read_b128 v[198:201], v151
	ds_read_b128 v[202:205], v151 offset:1024
	ds_read_b128 v[206:209], v151 offset:2048
	ds_read_b128 v[222:225], v151 offset:3072
	global_load_lds_dwordx4 v130, s[62:63]
	s_add_i32 m0, s33, 0x2000
	s_nop 0
	global_load_lds_dwordx4 v134, s[62:63]
	s_barrier
	s_waitcnt lgkmcnt(0)
	s_setprio 1
	s_waitcnt lgkmcnt(0)
	v_mfma_f32_16x16x32_bf16 v[112:115], v[198:201], v[164:167], v[112:115]
	v_mfma_f32_16x16x32_bf16 v[104:107], v[206:209], v[164:167], v[104:107]
	v_mfma_f32_16x16x32_bf16 v[100:103], v[198:201], v[172:175], v[100:103]
	v_mfma_f32_16x16x32_bf16 v[92:95], v[206:209], v[172:175], v[92:95]
	v_mfma_f32_16x16x32_bf16 v[84:87], v[198:201], v[180:183], v[84:87]
	v_mfma_f32_16x16x32_bf16 v[76:79], v[206:209], v[180:183], v[76:79]
	v_mfma_f32_16x16x32_bf16 v[68:71], v[198:201], v[190:193], v[68:71]
	v_mfma_f32_16x16x32_bf16 v[64:67], v[206:209], v[190:193], v[64:67]
	v_mfma_f32_16x16x32_bf16 v[112:115], v[202:205], v[168:171], v[112:115]
	v_mfma_f32_16x16x32_bf16 v[104:107], v[222:225], v[168:171], v[104:107]
	v_mfma_f32_16x16x32_bf16 v[100:103], v[202:205], v[176:179], v[100:103]
	v_mfma_f32_16x16x32_bf16 v[92:95], v[222:225], v[176:179], v[92:95]
	v_mfma_f32_16x16x32_bf16 v[84:87], v[202:205], v[186:189], v[84:87]
	v_mfma_f32_16x16x32_bf16 v[76:79], v[222:225], v[186:189], v[76:79]
	v_mfma_f32_16x16x32_bf16 v[68:71], v[202:205], v[194:197], v[68:71]
	v_mfma_f32_16x16x32_bf16 v[64:67], v[222:225], v[194:197], v[64:67]
	s_setprio 0
	s_mov_b32 m0, s16
	s_add_u32 s100, s66, s10
	s_addc_u32 s101, s67, s11
	s_barrier
	ds_read_b128 v[164:167], v150 offset:16384
	ds_read_b128 v[168:171], v150 offset:17408
	ds_read_b128 v[172:175], v150 offset:18432
	ds_read_b128 v[176:179], v150 offset:19456
	ds_read_b128 v[180:183], v150 offset:20480
	ds_read_b128 v[186:189], v150 offset:21504
	ds_read_b128 v[190:193], v150 offset:22528
	ds_read_b128 v[194:197], v150 offset:23552
	global_load_lds_dwordx4 v128, s[66:67]
	s_mov_b32 m0, s17
	s_nop 0
	global_load_lds_dwordx4 v132, s[66:67]
	s_barrier
	s_waitcnt lgkmcnt(0)
	s_setprio 1
	s_waitcnt lgkmcnt(0)
	v_mfma_f32_16x16x32_bf16 v[60:63], v[140:143], v[164:167], v[60:63]
	v_mfma_f32_16x16x32_bf16 v[56:59], v[156:159], v[164:167], v[56:59]
	v_mfma_f32_16x16x32_bf16 v[48:51], v[140:143], v[172:175], v[48:51]
	v_mfma_f32_16x16x32_bf16 v[40:43], v[156:159], v[172:175], v[40:43]
	v_mfma_f32_16x16x32_bf16 v[32:35], v[140:143], v[180:183], v[32:35]
	v_mfma_f32_16x16x32_bf16 v[24:27], v[156:159], v[180:183], v[24:27]
	v_mfma_f32_16x16x32_bf16 v[16:19], v[140:143], v[190:193], v[16:19]
	v_mfma_f32_16x16x32_bf16 v[8:11], v[156:159], v[190:193], v[8:11]
	v_mfma_f32_16x16x32_bf16 v[60:63], v[152:155], v[168:171], v[60:63]
	v_mfma_f32_16x16x32_bf16 v[56:59], v[160:163], v[168:171], v[56:59]
	v_mfma_f32_16x16x32_bf16 v[48:51], v[152:155], v[176:179], v[48:51]
	v_mfma_f32_16x16x32_bf16 v[40:43], v[160:163], v[176:179], v[40:43]
	v_mfma_f32_16x16x32_bf16 v[32:35], v[152:155], v[186:189], v[32:35]
	v_mfma_f32_16x16x32_bf16 v[24:27], v[160:163], v[186:189], v[24:27]
	v_mfma_f32_16x16x32_bf16 v[16:19], v[152:155], v[194:197], v[16:19]
	v_mfma_f32_16x16x32_bf16 v[8:11], v[160:163], v[194:197], v[8:11]
	s_setprio 0
	s_barrier
	s_add_u32 s52, s62, 0x40000
	s_addc_u32 s53, s63, 0
	s_add_i32 s33, s89, s5
	s_mov_b32 m0, s33
	s_nop 0
	global_load_lds_dwordx4 v130, s[52:53]
	s_add_i32 m0, s33, 0x2000
	s_nop 0
	global_load_lds_dwordx4 v134, s[52:53]
	s_waitcnt vmcnt(6)
	s_barrier
; #define PG8_STAGE(bufoff, gbase, voff) do { _Pragma("unroll") for (int _i = 0; _i < 2; ++_i) \
;         __builtin_amdgcn_global_load_lds((const unsigned*)((const char*)(gbase) + (voff)[_i]), (LAS unsigned*)(lds + (bufoff) + ldsw + _i * 8192), 16, 0, 0); } while (0)
; #define PG8_LDA(dst, b, h) do { _Pragma("unroll") for (int m = 0; m < 4; ++m) _Pragma("unroll") for (int k = 0; k < 2; ++k) dst[m][k] = *(const LAS bf16x8*)(lds + PG8_SA(b, h) + aoff + m * 2048 + k * 1024); } while (0)
; #define PG8_LDB(dst, b, h) do { _Pragma("unroll") for (int n = 0; n < 2; ++n) _Pragma("unroll") for (int k = 0; k < 2; ++k) dst[n][k] = *(const LAS bf16x8*)(lds + PG8_SB(b, h) + boff + n * 2048 + k * 1024); } while (0)
; #define PG8_MMA(ai, bj, At, Bt) do { __builtin_amdgcn_s_setprio(1); _Pragma("unroll") for (int m = 0; m < 4; ++m) _Pragma("unroll") for (int n = 0; n < 2; ++n) _Pragma("unroll") for (int k = 0; k < 2; ++k) \
;         acc[ai][bj][m][n] = __builtin_amdgcn_mfma_f32_16x16x32_bf16(Bt[n][k], At[m][k], acc[ai][bj][m][n], 0, 0, 0); __builtin_amdgcn_s_setprio(0); } while (0)
; #define PG8_WAIT_V(n) asm volatile("s_waitcnt vmcnt(" #n ")" ::: "memory")
; #define PG8_WAIT_L(n) asm volatile("s_waitcnt lgkmcnt(" #n ")" ::: "memory")
; #define PG8_BAR __builtin_amdgcn_s_barrier()
; #define PG8_SCHED __builtin_amdgcn_sched_barrier(0)
; template <class Epi, class S_t>
; __device__ __forceinline__ void gemm_phase(LAS unsigned char* lds, int lda, int ldb, const S_t& S, const Epi& E) {
;     ...
;             PG8_WAIT_V(6); PG8_BAR; PG8_MMA(1, 1, At, B1); PG8_BAR;
;             PG8_LDB(B0, 1, 0); PG8_SCHED; PG8_LDA(At, 1, 0); PG8_STAGE(PG8_SA(0, 1), a2 + hstepA, voffA);
;             PG8_WAIT_L(8); PG8_BAR; PG8_WAIT_L(0); PG8_MMA(0, 0, At, B0); PG8_BAR; PG8_SCHED;
;             PG8_LDB(B1, 1, 1); PG8_STAGE(PG8_SB(1, 0), b3, voffB);
;             PG8_BAR; PG8_WAIT_L(0); PG8_MMA(0, 1, At, B1); PG8_BAR;
;             PG8_LDA(At, 1, 1); PG8_STAGE(PG8_SA(1, 0), a3, voffA);
;             PG8_BAR; PG8_WAIT_L(0); PG8_MMA(1, 0, At, B0); PG8_BAR; PG8_SCHED;
	s_setprio 1
	v_mfma_f32_16x16x32_bf16 v[52:55], v[198:201], v[164:167], v[52:55]
	v_mfma_f32_16x16x32_bf16 v[44:47], v[206:209], v[164:167], v[44:47]
	v_mfma_f32_16x16x32_bf16 v[36:39], v[198:201], v[172:175], v[36:39]
	v_mfma_f32_16x16x32_bf16 v[28:31], v[206:209], v[172:175], v[28:31]
	v_mfma_f32_16x16x32_bf16 v[20:23], v[198:201], v[180:183], v[20:23]
	v_mfma_f32_16x16x32_bf16 v[12:15], v[206:209], v[180:183], v[12:15]
	v_mfma_f32_16x16x32_bf16 v[4:7], v[198:201], v[190:193], v[4:7]
	v_mfma_f32_16x16x32_bf16 v[0:3], v[206:209], v[190:193], v[0:3]
	v_mfma_f32_16x16x32_bf16 v[52:55], v[202:205], v[168:171], v[52:55]
	v_mfma_f32_16x16x32_bf16 v[44:47], v[222:225], v[168:171], v[44:47]
	v_mfma_f32_16x16x32_bf16 v[36:39], v[202:205], v[176:179], v[36:39]
	v_mfma_f32_16x16x32_bf16 v[28:31], v[222:225], v[176:179], v[28:31]
	v_mfma_f32_16x16x32_bf16 v[20:23], v[202:205], v[186:189], v[20:23]
	v_mfma_f32_16x16x32_bf16 v[12:15], v[222:225], v[186:189], v[12:15]
	v_mfma_f32_16x16x32_bf16 v[4:7], v[202:205], v[194:197], v[4:7]
	v_mfma_f32_16x16x32_bf16 v[0:3], v[222:225], v[194:197], v[0:3]
	s_setprio 0
	v_add_u32_e32 v160, s90, v147
	s_barrier
	ds_read_b128 v[140:143], v160
	ds_read_b128 v[152:155], v160 offset:1024
	ds_read_b128 v[156:159], v160 offset:2048
	ds_read_b128 v[160:163], v160 offset:3072
	s_add_u32 s52, s66, 0x40000
	s_addc_u32 s53, s67, 0
	s_mov_b32 m0, s20
	ds_read_b128 v[164:167], v150 offset:32768
	ds_read_b128 v[168:171], v150 offset:33792
	ds_read_b128 v[172:175], v150 offset:34816
	ds_read_b128 v[176:179], v150 offset:35840
	ds_read_b128 v[180:183], v150 offset:36864
	ds_read_b128 v[186:189], v150 offset:37888
	ds_read_b128 v[190:193], v150 offset:38912
	ds_read_b128 v[194:197], v150 offset:39936
	global_load_lds_dwordx4 v128, s[52:53]
	s_mov_b32 m0, s21
	s_nop 0
	global_load_lds_dwordx4 v132, s[52:53]
	s_waitcnt lgkmcnt(8)
	s_barrier
	s_waitcnt lgkmcnt(0)
	s_setprio 1
	s_waitcnt lgkmcnt(0)
	v_mfma_f32_16x16x32_bf16 v[124:127], v[140:143], v[164:167], v[124:127]
	v_mfma_f32_16x16x32_bf16 v[120:123], v[156:159], v[164:167], v[120:123]
	v_mfma_f32_16x16x32_bf16 v[116:119], v[140:143], v[172:175], v[116:119]
	v_mfma_f32_16x16x32_bf16 v[108:111], v[156:159], v[172:175], v[108:111]
	v_mfma_f32_16x16x32_bf16 v[96:99], v[140:143], v[180:183], v[96:99]
	v_mfma_f32_16x16x32_bf16 v[88:91], v[156:159], v[180:183], v[88:91]
	v_mfma_f32_16x16x32_bf16 v[80:83], v[140:143], v[190:193], v[80:83]
	v_mfma_f32_16x16x32_bf16 v[72:75], v[156:159], v[190:193], v[72:75]
	v_mfma_f32_16x16x32_bf16 v[124:127], v[152:155], v[168:171], v[124:127]
	v_mfma_f32_16x16x32_bf16 v[120:123], v[160:163], v[168:171], v[120:123]
	v_mfma_f32_16x16x32_bf16 v[116:119], v[152:155], v[176:179], v[116:119]
	v_mfma_f32_16x16x32_bf16 v[108:111], v[160:163], v[176:179], v[108:111]
	v_mfma_f32_16x16x32_bf16 v[96:99], v[152:155], v[186:189], v[96:99]
	v_mfma_f32_16x16x32_bf16 v[88:91], v[160:163], v[186:189], v[88:91]
	v_mfma_f32_16x16x32_bf16 v[80:83], v[152:155], v[194:197], v[80:83]
	v_mfma_f32_16x16x32_bf16 v[72:75], v[160:163], v[194:197], v[72:75]
	s_setprio 0
	s_barrier
	s_add_i32 s33, s90, s5
	v_add_u32_e32 v185, s91, v147
	s_mov_b32 m0, s33
	ds_read_b128 v[198:201], v185
	ds_read_b128 v[202:205], v185 offset:1024
	ds_read_b128 v[206:209], v185 offset:2048
	ds_read_b128 v[222:225], v185 offset:3072
	global_load_lds_dwordx4 v130, s[98:99]
	s_add_i32 m0, s33, 0x2000
	s_nop 0
	global_load_lds_dwordx4 v134, s[98:99]
	s_barrier
	s_waitcnt lgkmcnt(0)
	s_setprio 1
	s_waitcnt lgkmcnt(0)
	v_mfma_f32_16x16x32_bf16 v[112:115], v[198:201], v[164:167], v[112:115]
	v_mfma_f32_16x16x32_bf16 v[104:107], v[206:209], v[164:167], v[104:107]
	v_mfma_f32_16x16x32_bf16 v[100:103], v[198:201], v[172:175], v[100:103]
	v_mfma_f32_16x16x32_bf16 v[92:95], v[206:209], v[172:175], v[92:95]
	v_mfma_f32_16x16x32_bf16 v[84:87], v[198:201], v[180:183], v[84:87]
	v_mfma_f32_16x16x32_bf16 v[76:79], v[206:209], v[180:183], v[76:79]
	v_mfma_f32_16x16x32_bf16 v[68:71], v[198:201], v[190:193], v[68:71]
	v_mfma_f32_16x16x32_bf16 v[64:67], v[206:209], v[190:193], v[64:67]
	v_mfma_f32_16x16x32_bf16 v[112:115], v[202:205], v[168:171], v[112:115]
	v_mfma_f32_16x16x32_bf16 v[104:107], v[222:225], v[168:171], v[104:107]
	v_mfma_f32_16x16x32_bf16 v[100:103], v[202:205], v[176:179], v[100:103]
	v_mfma_f32_16x16x32_bf16 v[92:95], v[222:225], v[176:179], v[92:95]
	v_mfma_f32_16x16x32_bf16 v[84:87], v[202:205], v[186:189], v[84:87]
	v_mfma_f32_16x16x32_bf16 v[76:79], v[222:225], v[186:189], v[76:79]
	v_mfma_f32_16x16x32_bf16 v[68:71], v[202:205], v[194:197], v[68:71]
	v_mfma_f32_16x16x32_bf16 v[64:67], v[222:225], v[194:197], v[64:67]
	s_setprio 0
	s_mov_b32 m0, s35
	s_barrier
	ds_read_b128 v[164:167], v150 offset:49152
	ds_read_b128 v[168:171], v150 offset:50176
	ds_read_b128 v[172:175], v150 offset:51200
	ds_read_b128 v[176:179], v150 offset:52224
	ds_read_b128 v[180:183], v150 offset:53248
	ds_read_b128 v[186:189], v150 offset:54272
	ds_read_b128 v[190:193], v150 offset:55296
	ds_read_b128 v[194:197], v150 offset:56320
	global_load_lds_dwordx4 v128, s[100:101]
	s_mov_b32 m0, s64
	s_nop 0
	global_load_lds_dwordx4 v132, s[100:101]
	s_barrier
; #define PG8_STAGE(bufoff, gbase, voff) do { _Pragma("unroll") for (int _i = 0; _i < 2; ++_i) \
;         __builtin_amdgcn_global_load_lds((const unsigned*)((const char*)(gbase) + (voff)[_i]), (LAS unsigned*)(lds + (bufoff) + ldsw + _i * 8192), 16, 0, 0); } while (0)
; #define PG8_MMA(ai, bj, At, Bt) do { __builtin_amdgcn_s_setprio(1); _Pragma("unroll") for (int m = 0; m < 4; ++m) _Pragma("unroll") for (int n = 0; n < 2; ++n) _Pragma("unroll") for (int k = 0; k < 2; ++k) \
;         acc[ai][bj][m][n] = __builtin_amdgcn_mfma_f32_16x16x32_bf16(Bt[n][k], At[m][k], acc[ai][bj][m][n], 0, 0, 0); __builtin_amdgcn_s_setprio(0); } while (0)
; #define PG8_WAIT_V(n) asm volatile("s_waitcnt vmcnt(" #n ")" ::: "memory")
; #define PG8_WAIT_L(n) asm volatile("s_waitcnt lgkmcnt(" #n ")" ::: "memory")
; template <class Epi, class S_t>
; __device__ __forceinline__ void gemm_phase(LAS unsigned char* lds, int lda, int ldb, const S_t& S, const Epi& E) {
;     ...
;             PG8_BAR; PG8_WAIT_L(0); PG8_MMA(1, 0, At, B0); PG8_BAR; PG8_SCHED;
;             PG8_STAGE(PG8_SB(1, 1), b3 + hstepB, voffB);
;             PG8_WAIT_V(6); PG8_BAR; PG8_MMA(1, 1, At, B1); PG8_BAR;
;     __device__ __forceinline__ void operator()(const f32x4 (&acc)[2][2][4][2], const Unit& u, int wr, int wc, int fr, int fq) const {
;         const int row0 = u.pm * BM + wr * 64 + fr, col0 = u.pn * BM + wc * 32 + 8 * fq;
;         if (ADD && u.tag >= 2000) {
;             unsigned* f = flags + P7_FLAG(u.tag - 2000); unsigned sp = 0;
;             while ((unsigned)__builtin_amdgcn_readfirstlane(__hip_atomic_load(f, __ATOMIC_RELAXED, __HIP_MEMORY_SCOPE_AGENT)) < 8u) { __builtin_amdgcn_s_sleep(2); if (++sp > (1u << 20)) break; }
;             __builtin_amdgcn_fence(__ATOMIC_ACQUIRE, "agent");
;             asm volatile("s_waitcnt vmcnt(0)" ::: "memory");
;         }
; #pragma unroll
;         for (int ai = 0; ai < 2; ++ai) {
;             u32x4 gr[4][2], orw[4][2];
;             asm volatile("" ::: "memory");
; #pragma unroll
;             for (int m = 0; m < 4; ++m)
; #pragma unroll
;                 for (int bj = 0; bj < 2; ++bj) { const int row = row0 + ai * HALF + m * 16, col = col0 + bj * HALF;
;                     gr[m][bj] = *(const u32x4*)(Z + (size_t)row * INW + gcol0 + col);
;                     if (ADD) orw[m][bj] = *(const u32x4*)(MG + (size_t)row * DM + col); }
	s_waitcnt lgkmcnt(0)
	s_setprio 1
	s_waitcnt lgkmcnt(0)
	v_mfma_f32_16x16x32_bf16 v[60:63], v[140:143], v[164:167], v[60:63]
	v_mfma_f32_16x16x32_bf16 v[56:59], v[156:159], v[164:167], v[56:59]
	v_mfma_f32_16x16x32_bf16 v[48:51], v[140:143], v[172:175], v[48:51]
	v_mfma_f32_16x16x32_bf16 v[40:43], v[156:159], v[172:175], v[40:43]
	v_mfma_f32_16x16x32_bf16 v[32:35], v[140:143], v[180:183], v[32:35]
	v_mfma_f32_16x16x32_bf16 v[24:27], v[156:159], v[180:183], v[24:27]
	v_mfma_f32_16x16x32_bf16 v[16:19], v[140:143], v[190:193], v[16:19]
	v_mfma_f32_16x16x32_bf16 v[8:11], v[156:159], v[190:193], v[8:11]
	v_mfma_f32_16x16x32_bf16 v[60:63], v[152:155], v[168:171], v[60:63]
	v_mfma_f32_16x16x32_bf16 v[56:59], v[160:163], v[168:171], v[56:59]
	v_mfma_f32_16x16x32_bf16 v[48:51], v[152:155], v[176:179], v[48:51]
	v_mfma_f32_16x16x32_bf16 v[40:43], v[160:163], v[176:179], v[40:43]
	v_mfma_f32_16x16x32_bf16 v[32:35], v[152:155], v[186:189], v[32:35]
	v_mfma_f32_16x16x32_bf16 v[24:27], v[160:163], v[186:189], v[24:27]
	v_mfma_f32_16x16x32_bf16 v[16:19], v[152:155], v[194:197], v[16:19]
	v_mfma_f32_16x16x32_bf16 v[8:11], v[160:163], v[194:197], v[8:11]
	s_setprio 0
	s_barrier
	s_add_u32 s52, s62, 0x40080
	s_addc_u32 s53, s63, 0
	s_add_i32 s33, s91, s5
	s_mov_b32 m0, s33
	s_nop 0
	global_load_lds_dwordx4 v130, s[52:53]
	s_add_i32 m0, s33, 0x2000
	s_nop 0
	global_load_lds_dwordx4 v134, s[52:53]
	s_waitcnt vmcnt(6)
	s_barrier
	s_setprio 1
	v_mfma_f32_16x16x32_bf16 v[52:55], v[198:201], v[164:167], v[52:55]
	v_mfma_f32_16x16x32_bf16 v[44:47], v[206:209], v[164:167], v[44:47]
	v_mfma_f32_16x16x32_bf16 v[36:39], v[198:201], v[172:175], v[36:39]
	v_mfma_f32_16x16x32_bf16 v[28:31], v[206:209], v[172:175], v[28:31]
	v_mfma_f32_16x16x32_bf16 v[20:23], v[198:201], v[180:183], v[20:23]
	v_mfma_f32_16x16x32_bf16 v[12:15], v[206:209], v[180:183], v[12:15]
	v_mfma_f32_16x16x32_bf16 v[4:7], v[198:201], v[190:193], v[4:7]
	v_mfma_f32_16x16x32_bf16 v[0:3], v[206:209], v[190:193], v[0:3]
	v_mfma_f32_16x16x32_bf16 v[52:55], v[202:205], v[168:171], v[52:55]
	v_mfma_f32_16x16x32_bf16 v[44:47], v[222:225], v[168:171], v[44:47]
	v_mfma_f32_16x16x32_bf16 v[36:39], v[202:205], v[176:179], v[36:39]
	v_mfma_f32_16x16x32_bf16 v[28:31], v[222:225], v[176:179], v[28:31]
	v_mfma_f32_16x16x32_bf16 v[20:23], v[202:205], v[186:189], v[20:23]
	v_mfma_f32_16x16x32_bf16 v[12:15], v[222:225], v[186:189], v[12:15]
	v_mfma_f32_16x16x32_bf16 v[4:7], v[202:205], v[194:197], v[4:7]
	v_mfma_f32_16x16x32_bf16 v[0:3], v[222:225], v[194:197], v[0:3]
	s_setprio 0
	s_add_i32 s43, s43, 2
	s_add_u32 s60, s60, 0x100
	s_addc_u32 s61, s61, 0
	s_add_u32 s0, s0, 0x100
	s_addc_u32 s1, s1, 0
	s_cmp_gt_u32 s43, 13
	s_barrier
	s_cbranch_scc0 .LBB0_945
	v_lshl_or_b32 v140, s42, 8, v148
	v_lshl_add_u32 v142, s8, 8, v146
	v_ashrrev_i32_e32 v141, 31, v140
	v_mov_b64_e32 v[144:145], s[46:47]
	v_mad_i64_i32 v[152:153], s[0:1], v142, s69, v[144:145]
	v_lshlrev_b64 v[140:141], 1, v[140:141]
	v_or_b32_e32 v168, 16, v142
	v_lshl_add_u64 v[156:157], v[152:153], 0, v[140:141]
	v_mad_i64_i32 v[160:161], s[0:1], v168, s69, v[144:145]
	global_load_dwordx4 v[152:155], v[156:157], off
	s_nop 0
	global_load_dwordx4 v[156:159], v[156:157], off offset:256
	v_lshl_add_u64 v[164:165], v[160:161], 0, v[140:141]
	global_load_dwordx4 v[160:163], v[164:165], off
	v_or_b32_e32 v186, 32, v142
	global_load_dwordx4 v[164:167], v[164:165], off offset:256
	v_or_b32_e32 v188, 48, v142
	v_ashrrev_i32_e32 v143, 31, v142
	v_mad_i64_i32 v[170:171], s[0:1], v186, s69, v[144:145]
	v_mad_i64_i32 v[172:173], s[0:1], v188, s69, v[144:145]
	v_ashrrev_i32_e32 v169, 31, v168
	v_lshlrev_b64 v[174:175], 12, v[142:143]
	v_lshl_add_u64 v[176:177], v[170:171], 0, v[140:141]
	v_lshl_add_u64 v[180:181], v[172:173], 0, v[140:141]
	v_lshl_add_u64 v[190:191], s[44:45], 0, v[174:175]
	v_lshlrev_b64 v[192:193], 12, v[168:169]
	global_load_dwordx4 v[168:171], v[176:177], off
	global_load_dwordx4 v[172:175], v[176:177], off offset:256
	s_nop 0
	global_load_dwordx4 v[176:179], v[180:181], off
	s_nop 0
	global_load_dwordx4 v[180:183], v[180:181], off offset:256
	v_lshl_add_u64 v[190:191], v[190:191], 0, v[140:141]
	v_ashrrev_i32_e32 v187, 31, v186
	v_ashrrev_i32_e32 v189, 31, v188
	s_cmpk_lt_i32 s70, 0x3e8
	s_waitcnt vmcnt(0)
; __device__ __forceinline__ u32x4 pack8(const float (&f)[8]) { u32x4 w; w.x = pk2(f[0], f[1]); w.y = pk2(f[2], f[3]); w.z = pk2(f[4], f[5]); w.w = pk2(f[6], f[7]); return w; }
;     __device__ __forceinline__ void operator()(const f32x4 (&acc)[2][2][4][2], const Unit& u, int wr, int wc, int fr, int fq) const {
;     ...
;             for (int m = 0; m < 4; ++m)
; #pragma unroll
;                 for (int bj = 0; bj < 2; ++bj) { const int row = row0 + ai * HALF + m * 16, col = col0 + bj * HALF;
;                     float g[8], o[8]; unpack8(gr[m][bj], g);
;                     if (ADD) unpack8(orw[m][bj], o);
; #pragma unroll
;                     for (int n = 0; n < 2; ++n)
; #pragma unroll
;                         for (int j = 0; j < 4; ++j) { const int e = 4 * n + j; o[e] = ADD ? o[e] + g[e] * acc[ai][bj][m][n][j] : g[e] * acc[ai][bj][m][n][j]; }
;                     *(u32x4*)(MG + (size_t)row * DM + col) = pack8(o); }
	v_lshlrev_b32_e32 v143, 16, v152
	v_and_b32_e32 v152, 0xffff0000, v152
	v_lshlrev_b32_e32 v185, 16, v153
	v_and_b32_e32 v153, 0xffff0000, v153
	v_lshlrev_b32_e32 v194, 16, v154
	v_and_b32_e32 v154, 0xffff0000, v154
	v_lshlrev_b32_e32 v195, 16, v155
	v_and_b32_e32 v155, 0xffff0000, v155
	v_lshlrev_b32_e32 v196, 16, v156
	v_and_b32_e32 v156, 0xffff0000, v156
	v_lshlrev_b32_e32 v197, 16, v157
	v_and_b32_e32 v157, 0xffff0000, v157
	v_lshlrev_b32_e32 v198, 16, v158
	v_and_b32_e32 v158, 0xffff0000, v158
	v_lshlrev_b32_e32 v199, 16, v159
	v_and_b32_e32 v159, 0xffff0000, v159
	v_lshlrev_b32_e32 v200, 16, v160
	v_and_b32_e32 v160, 0xffff0000, v160
	v_lshlrev_b32_e32 v201, 16, v161
	v_lshlrev_b32_e32 v202, 16, v162
	v_and_b32_e32 v162, 0xffff0000, v162
	v_mul_f32_e32 v124, v124, v143
	v_mul_f32_e32 v125, v125, v152
	v_mul_f32_e32 v126, v126, v185
	v_mul_f32_e32 v127, v127, v153
	v_mul_f32_e32 v120, v120, v194
	v_mul_f32_e32 v121, v121, v154
	v_mul_f32_e32 v122, v122, v195
	v_mul_f32_e32 v123, v123, v155
	v_mul_f32_e32 v112, v112, v196
	v_mul_f32_e32 v113, v113, v156
	v_mul_f32_e32 v114, v114, v197
	v_mul_f32_e32 v115, v115, v157
	v_mul_f32_e32 v143, v104, v198
	v_mul_f32_e32 v152, v105, v158
	v_mul_f32_e32 v153, v106, v199
	v_mul_f32_e32 v154, v107, v159
	v_cvt_pk_bf16_f32 v104, v124, v125
	v_cvt_pk_bf16_f32 v105, v126, v127
	v_cvt_pk_bf16_f32 v106, v120, v121
	v_cvt_pk_bf16_f32 v107, v122, v123
	v_and_b32_e32 v161, 0xffff0000, v161
	v_cvt_pk_bf16_f32 v112, v112, v113
	v_cvt_pk_bf16_f32 v113, v114, v115
	v_cvt_pk_bf16_f32 v114, v143, v152
	v_cvt_pk_bf16_f32 v115, v153, v154
	global_store_dwordx4 v[190:191], v[104:107], off
	global_store_dwordx4 v[190:191], v[112:115], off offset:256
	v_mul_f32_e32 v108, v108, v202
	v_mul_f32_e32 v104, v116, v200
	v_mul_f32_e32 v105, v117, v160
	v_mul_f32_e32 v106, v118, v201
	v_mul_f32_e32 v109, v109, v162
	v_lshlrev_b32_e32 v203, 16, v163
	v_and_b32_e32 v163, 0xffff0000, v163
	v_mul_f32_e32 v107, v119, v161
	v_cvt_pk_bf16_f32 v104, v104, v105
	v_cvt_pk_bf16_f32 v105, v106, v107
	v_cvt_pk_bf16_f32 v106, v108, v109
	v_lshl_add_u64 v[108:109], s[44:45], 0, v[192:193]
	v_mul_f32_e32 v110, v110, v203
	v_mul_f32_e32 v111, v111, v163
	v_cvt_pk_bf16_f32 v107, v110, v111
	v_lshl_add_u64 v[108:109], v[108:109], 0, v[140:141]
	global_store_dwordx4 v[108:109], v[104:107], off
	v_lshlrev_b32_e32 v110, 16, v166
	v_and_b32_e32 v111, 0xffff0000, v166
	v_lshlrev_b32_e32 v104, 16, v164
	v_and_b32_e32 v105, 0xffff0000, v164
	v_lshlrev_b32_e32 v106, 16, v165
	v_and_b32_e32 v107, 0xffff0000, v165
	v_and_b32_e32 v113, 0xffff0000, v167
	v_lshlrev_b32_e32 v112, 16, v167
	v_mul_f32_e32 v100, v100, v104
	v_mul_f32_e32 v101, v101, v105
	v_mul_f32_e32 v102, v102, v106
	v_mul_f32_e32 v103, v103, v107
	v_mul_f32_e32 v104, v92, v110
	v_mul_f32_e32 v105, v93, v111
	v_mul_f32_e32 v95, v95, v113
	v_cvt_pk_bf16_f32 v92, v100, v101
	v_cvt_pk_bf16_f32 v93, v102, v103
	v_mul_f32_e32 v106, v94, v112
	v_cvt_pk_bf16_f32 v94, v104, v105
	v_cvt_pk_bf16_f32 v95, v106, v95
	global_store_dwordx4 v[108:109], v[92:95], off offset:256
	v_and_b32_e32 v105, 0xffff0000, v171
	v_lshlrev_b32_e32 v100, 16, v169
	v_lshlrev_b64 v[92:93], 12, v[186:187]
	v_lshlrev_b32_e32 v94, 16, v168
	v_and_b32_e32 v95, 0xffff0000, v168
	v_and_b32_e32 v101, 0xffff0000, v169
	v_lshlrev_b32_e32 v102, 16, v170
	v_and_b32_e32 v103, 0xffff0000, v170
	v_lshlrev_b32_e32 v104, 16, v171
	v_mul_f32_e32 v91, v91, v105
	v_lshl_add_u64 v[92:93], s[44:45], 0, v[92:93]
	v_mul_f32_e32 v94, v96, v94
	v_mul_f32_e32 v95, v97, v95
	v_mul_f32_e32 v96, v98, v100
	v_mul_f32_e32 v97, v99, v101
	v_mul_f32_e32 v98, v88, v102
	v_mul_f32_e32 v99, v89, v103
	v_mul_f32_e32 v100, v90, v104
	v_cvt_pk_bf16_f32 v88, v94, v95
	v_cvt_pk_bf16_f32 v89, v96, v97
	v_cvt_pk_bf16_f32 v90, v98, v99
	v_cvt_pk_bf16_f32 v91, v100, v91
	v_lshl_add_u64 v[92:93], v[92:93], 0, v[140:141]
	global_store_dwordx4 v[92:93], v[88:91], off
	v_lshlrev_b32_e32 v94, 16, v174
	v_and_b32_e32 v95, 0xffff0000, v174
	v_lshlrev_b32_e32 v88, 16, v172
	v_and_b32_e32 v89, 0xffff0000, v172
	v_lshlrev_b32_e32 v90, 16, v173
	v_and_b32_e32 v91, 0xffff0000, v173
	v_and_b32_e32 v97, 0xffff0000, v175
	v_lshlrev_b32_e32 v96, 16, v175
	v_mul_f32_e32 v84, v84, v88
	v_mul_f32_e32 v85, v85, v89
	v_mul_f32_e32 v86, v86, v90
	v_mul_f32_e32 v87, v87, v91
	v_mul_f32_e32 v88, v76, v94
	v_mul_f32_e32 v89, v77, v95
	v_mul_f32_e32 v79, v79, v97
	v_cvt_pk_bf16_f32 v76, v84, v85
	v_cvt_pk_bf16_f32 v77, v86, v87
	v_mul_f32_e32 v90, v78, v96
	v_cvt_pk_bf16_f32 v78, v88, v89
	v_cvt_pk_bf16_f32 v79, v90, v79
	global_store_dwordx4 v[92:93], v[76:79], off offset:256
	v_and_b32_e32 v89, 0xffff0000, v179
	v_lshlrev_b32_e32 v84, 16, v177
	v_lshlrev_b64 v[76:77], 12, v[188:189]
	v_lshlrev_b32_e32 v78, 16, v176
	v_and_b32_e32 v79, 0xffff0000, v176
	v_and_b32_e32 v85, 0xffff0000, v177
	v_lshlrev_b32_e32 v86, 16, v178
	v_and_b32_e32 v87, 0xffff0000, v178
	v_lshlrev_b32_e32 v88, 16, v179
	v_mul_f32_e32 v75, v75, v89
	v_lshl_add_u64 v[76:77], s[44:45], 0, v[76:77]
	v_mul_f32_e32 v78, v80, v78
	v_mul_f32_e32 v79, v81, v79
	v_mul_f32_e32 v80, v82, v84
	v_mul_f32_e32 v81, v83, v85
	v_mul_f32_e32 v82, v72, v86
	v_mul_f32_e32 v83, v73, v87
	v_mul_f32_e32 v84, v74, v88
	v_cvt_pk_bf16_f32 v72, v78, v79
	v_cvt_pk_bf16_f32 v73, v80, v81
	v_cvt_pk_bf16_f32 v74, v82, v83
	v_cvt_pk_bf16_f32 v75, v84, v75
	v_lshl_add_u64 v[76:77], v[76:77], 0, v[140:141]
	global_store_dwordx4 v[76:77], v[72:75], off
	v_lshlrev_b32_e32 v78, 16, v182
	v_and_b32_e32 v79, 0xffff0000, v182
	v_lshlrev_b32_e32 v72, 16, v180
	v_and_b32_e32 v73, 0xffff0000, v180
	v_lshlrev_b32_e32 v74, 16, v181
	v_and_b32_e32 v75, 0xffff0000, v181
; __device__ __forceinline__ u32x4 pack8(const float (&f)[8]) { u32x4 w; w.x = pk2(f[0], f[1]); w.y = pk2(f[2], f[3]); w.z = pk2(f[4], f[5]); w.w = pk2(f[6], f[7]); return w; }
;     __device__ __forceinline__ void operator()(const f32x4 (&acc)[2][2][4][2], const Unit& u, int wr, int wc, int fr, int fq) const {
;     ...
;             for (int m = 0; m < 4; ++m)
; #pragma unroll
;                 for (int bj = 0; bj < 2; ++bj) { const int row = row0 + ai * HALF + m * 16, col = col0 + bj * HALF;
;                     gr[m][bj] = *(const u32x4*)(Z + (size_t)row * INW + gcol0 + col);
;                     if (ADD) orw[m][bj] = *(const u32x4*)(MG + (size_t)row * DM + col); }
;     ...
;                     float g[8], o[8]; unpack8(gr[m][bj], g);
;                     if (ADD) unpack8(orw[m][bj], o);
; #pragma unroll
;                     for (int n = 0; n < 2; ++n)
; #pragma unroll
;                         for (int j = 0; j < 4; ++j) { const int e = 4 * n + j; o[e] = ADD ? o[e] + g[e] * acc[ai][bj][m][n][j] : g[e] * acc[ai][bj][m][n][j]; }
;                     *(u32x4*)(MG + (size_t)row * DM + col) = pack8(o); }
	v_and_b32_e32 v81, 0xffff0000, v183
	v_lshlrev_b32_e32 v80, 16, v183
	v_mul_f32_e32 v68, v68, v72
	v_mul_f32_e32 v69, v69, v73
	v_mul_f32_e32 v70, v70, v74
	v_mul_f32_e32 v71, v71, v75
	v_mul_f32_e32 v72, v64, v78
	v_mul_f32_e32 v73, v65, v79
	v_mul_f32_e32 v67, v67, v81
	v_cvt_pk_bf16_f32 v64, v68, v69
	v_cvt_pk_bf16_f32 v65, v70, v71
	v_add_u32_e32 v96, 0x80, v142
	v_mul_f32_e32 v74, v66, v80
	v_cvt_pk_bf16_f32 v66, v72, v73
	v_cvt_pk_bf16_f32 v67, v74, v67
	global_store_dwordx4 v[76:77], v[64:67], off offset:256
	v_add_u32_e32 v98, 0x90, v142
	v_mad_i64_i32 v[72:73], s[0:1], v98, s69, v[144:145]
	v_mad_i64_i32 v[64:65], s[0:1], v96, s69, v[144:145]
	v_lshl_add_u64 v[68:69], v[64:65], 0, v[140:141]
	global_load_dwordx4 v[64:67], v[68:69], off
	s_nop 0
	global_load_dwordx4 v[68:71], v[68:69], off offset:256
	v_lshl_add_u64 v[76:77], v[72:73], 0, v[140:141]
	global_load_dwordx4 v[72:75], v[76:77], off
	v_add_u32_e32 v100, 0xa0, v142
	global_load_dwordx4 v[76:79], v[76:77], off offset:256
	v_mad_i64_i32 v[80:81], s[0:1], v100, s69, v[144:145]
	v_lshl_add_u64 v[84:85], v[80:81], 0, v[140:141]
	global_load_dwordx4 v[80:83], v[84:85], off
	s_nop 0
	global_load_dwordx4 v[84:87], v[84:85], off offset:256
	v_add_u32_e32 v102, 0xb0, v142
	v_mad_i64_i32 v[88:89], s[0:1], v102, s69, v[144:145]
	v_lshl_add_u64 v[92:93], v[88:89], 0, v[140:141]
	global_load_dwordx4 v[88:91], v[92:93], off
	s_nop 0
	global_load_dwordx4 v[92:95], v[92:93], off offset:256
	v_ashrrev_i32_e32 v97, 31, v96
	v_lshlrev_b64 v[96:97], 12, v[96:97]
	v_ashrrev_i32_e32 v99, 31, v98
	v_ashrrev_i32_e32 v101, 31, v100
	v_ashrrev_i32_e32 v103, 31, v102
	s_waitcnt vmcnt(0)
; __device__ __forceinline__ u32x4 pack8(const float (&f)[8]) { u32x4 w; w.x = pk2(f[0], f[1]); w.y = pk2(f[2], f[3]); w.z = pk2(f[4], f[5]); w.w = pk2(f[6], f[7]); return w; }
;     __device__ __forceinline__ void operator()(const f32x4 (&acc)[2][2][4][2], const Unit& u, int wr, int wc, int fr, int fq) const {
;     ...
;             for (int m = 0; m < 4; ++m)
; #pragma unroll
;                 for (int bj = 0; bj < 2; ++bj) { const int row = row0 + ai * HALF + m * 16, col = col0 + bj * HALF;
;                     float g[8], o[8]; unpack8(gr[m][bj], g);
;                     if (ADD) unpack8(orw[m][bj], o);
; #pragma unroll
;                     for (int n = 0; n < 2; ++n)
; #pragma unroll
;                         for (int j = 0; j < 4; ++j) { const int e = 4 * n + j; o[e] = ADD ? o[e] + g[e] * acc[ai][bj][m][n][j] : g[e] * acc[ai][bj][m][n][j]; }
;                     *(u32x4*)(MG + (size_t)row * DM + col) = pack8(o); }
;         }
;         if (!ADD && u.tag >= 1000) {
;             asm volatile("s_waitcnt vmcnt(0)" ::: "memory");
;             __builtin_amdgcn_fence(__ATOMIC_RELEASE, "agent");
;             asm volatile("s_waitcnt vmcnt(0)" ::: "memory");
;             if ((threadIdx.x & 63) == 0) __hip_atomic_fetch_add(flags + P7_FLAG(u.tag - 1000), 1u, __ATOMIC_RELAXED, __HIP_MEMORY_SCOPE_AGENT);
;         }
	v_lshlrev_b32_e32 v104, 16, v64
	v_and_b32_e32 v64, 0xffff0000, v64
	v_lshlrev_b32_e32 v105, 16, v65
	v_and_b32_e32 v65, 0xffff0000, v65
	v_lshlrev_b32_e32 v106, 16, v66
	v_and_b32_e32 v66, 0xffff0000, v66
	v_lshlrev_b32_e32 v107, 16, v67
	v_and_b32_e32 v67, 0xffff0000, v67
	v_mul_f32_e32 v60, v60, v104
	v_mul_f32_e32 v61, v61, v64
	v_mul_f32_e32 v63, v63, v65
	v_mul_f32_e32 v64, v56, v106
	v_mul_f32_e32 v65, v57, v66
	v_mul_f32_e32 v59, v59, v67
	v_cvt_pk_bf16_f32 v56, v60, v61
	v_lshl_add_u64 v[60:61], s[44:45], 0, v[96:97]
	v_mul_f32_e32 v62, v62, v105
	v_mul_f32_e32 v66, v58, v107
	v_cvt_pk_bf16_f32 v57, v62, v63
	v_cvt_pk_bf16_f32 v58, v64, v65
	v_cvt_pk_bf16_f32 v59, v66, v59
	v_lshl_add_u64 v[60:61], v[60:61], 0, v[140:141]
	v_and_b32_e32 v65, 0xffff0000, v71
	global_store_dwordx4 v[60:61], v[56:59], off
	v_lshlrev_b32_e32 v62, 16, v70
	v_and_b32_e32 v63, 0xffff0000, v70
	v_lshlrev_b32_e32 v56, 16, v68
	v_and_b32_e32 v57, 0xffff0000, v68
	v_lshlrev_b32_e32 v58, 16, v69
	v_and_b32_e32 v59, 0xffff0000, v69
	v_lshlrev_b32_e32 v64, 16, v71
	v_mul_f32_e32 v47, v47, v65
	v_mul_f32_e32 v52, v52, v56
	v_mul_f32_e32 v53, v53, v57
	v_mul_f32_e32 v54, v54, v58
	v_mul_f32_e32 v55, v55, v59
	v_mul_f32_e32 v56, v44, v62
	v_mul_f32_e32 v57, v45, v63
	v_mul_f32_e32 v58, v46, v64
	v_cvt_pk_bf16_f32 v44, v52, v53
	v_cvt_pk_bf16_f32 v45, v54, v55
	v_cvt_pk_bf16_f32 v47, v58, v47
	v_cvt_pk_bf16_f32 v46, v56, v57
	global_store_dwordx4 v[60:61], v[44:47], off offset:256
	v_and_b32_e32 v53, 0xffff0000, v73
	v_and_b32_e32 v57, 0xffff0000, v75
	v_lshlrev_b64 v[44:45], 12, v[98:99]
	v_and_b32_e32 v47, 0xffff0000, v72
	v_lshlrev_b32_e32 v46, 16, v72
	v_lshlrev_b32_e32 v52, 16, v73
	v_lshlrev_b32_e32 v54, 16, v74
	v_and_b32_e32 v55, 0xffff0000, v74
	v_lshlrev_b32_e32 v56, 16, v75
	v_mul_f32_e32 v47, v49, v47
	v_mul_f32_e32 v49, v51, v53
	v_mul_f32_e32 v43, v43, v57
	v_lshl_add_u64 v[44:45], s[44:45], 0, v[44:45]
	v_mul_f32_e32 v46, v48, v46
	v_mul_f32_e32 v48, v50, v52
	v_mul_f32_e32 v50, v40, v54
	v_mul_f32_e32 v51, v41, v55
	v_mul_f32_e32 v52, v42, v56
	v_cvt_pk_bf16_f32 v40, v46, v47
	v_cvt_pk_bf16_f32 v41, v48, v49
	v_cvt_pk_bf16_f32 v42, v50, v51
	v_cvt_pk_bf16_f32 v43, v52, v43
	v_lshl_add_u64 v[44:45], v[44:45], 0, v[140:141]
	v_and_b32_e32 v49, 0xffff0000, v79
	global_store_dwordx4 v[44:45], v[40:43], off
	v_lshlrev_b32_e32 v46, 16, v78
	v_and_b32_e32 v47, 0xffff0000, v78
	v_lshlrev_b32_e32 v40, 16, v76
	v_and_b32_e32 v41, 0xffff0000, v76
	v_lshlrev_b32_e32 v42, 16, v77
	v_and_b32_e32 v43, 0xffff0000, v77
	v_lshlrev_b32_e32 v48, 16, v79
	v_mul_f32_e32 v31, v31, v49
	v_mul_f32_e32 v36, v36, v40
	v_mul_f32_e32 v37, v37, v41
	v_mul_f32_e32 v38, v38, v42
	v_mul_f32_e32 v39, v39, v43
	v_mul_f32_e32 v40, v28, v46
	v_mul_f32_e32 v41, v29, v47
	v_mul_f32_e32 v42, v30, v48
	v_cvt_pk_bf16_f32 v28, v36, v37
	v_cvt_pk_bf16_f32 v29, v38, v39
	v_cvt_pk_bf16_f32 v31, v42, v31
	v_cvt_pk_bf16_f32 v30, v40, v41
	global_store_dwordx4 v[44:45], v[28:31], off offset:256
	v_and_b32_e32 v37, 0xffff0000, v81
	v_and_b32_e32 v41, 0xffff0000, v83
	v_lshlrev_b64 v[28:29], 12, v[100:101]
	v_and_b32_e32 v31, 0xffff0000, v80
	v_lshlrev_b32_e32 v30, 16, v80
	v_lshlrev_b32_e32 v36, 16, v81
	v_lshlrev_b32_e32 v38, 16, v82
	v_and_b32_e32 v39, 0xffff0000, v82
	v_lshlrev_b32_e32 v40, 16, v83
	v_mul_f32_e32 v31, v33, v31
	v_mul_f32_e32 v33, v35, v37
	v_mul_f32_e32 v27, v27, v41
	v_lshl_add_u64 v[28:29], s[44:45], 0, v[28:29]
	v_mul_f32_e32 v30, v32, v30
	v_mul_f32_e32 v32, v34, v36
	v_mul_f32_e32 v34, v24, v38
	v_mul_f32_e32 v35, v25, v39
	v_mul_f32_e32 v36, v26, v40
	v_cvt_pk_bf16_f32 v24, v30, v31
	v_cvt_pk_bf16_f32 v25, v32, v33
	v_cvt_pk_bf16_f32 v26, v34, v35
	v_cvt_pk_bf16_f32 v27, v36, v27
	v_lshl_add_u64 v[28:29], v[28:29], 0, v[140:141]
	v_and_b32_e32 v33, 0xffff0000, v87
	global_store_dwordx4 v[28:29], v[24:27], off
	v_lshlrev_b32_e32 v30, 16, v86
	v_and_b32_e32 v31, 0xffff0000, v86
	v_lshlrev_b32_e32 v24, 16, v84
	v_and_b32_e32 v25, 0xffff0000, v84
	v_lshlrev_b32_e32 v26, 16, v85
	v_and_b32_e32 v27, 0xffff0000, v85
	v_lshlrev_b32_e32 v32, 16, v87
	v_mul_f32_e32 v15, v15, v33
	v_mul_f32_e32 v20, v20, v24
	v_mul_f32_e32 v21, v21, v25
	v_mul_f32_e32 v22, v22, v26
	v_mul_f32_e32 v23, v23, v27
	v_mul_f32_e32 v24, v12, v30
	v_mul_f32_e32 v25, v13, v31
	v_mul_f32_e32 v26, v14, v32
	v_cvt_pk_bf16_f32 v12, v20, v21
	v_cvt_pk_bf16_f32 v13, v22, v23
	v_cvt_pk_bf16_f32 v15, v26, v15
	v_cvt_pk_bf16_f32 v14, v24, v25
	global_store_dwordx4 v[28:29], v[12:15], off offset:256
	v_and_b32_e32 v21, 0xffff0000, v89
	v_and_b32_e32 v25, 0xffff0000, v91
	v_lshlrev_b64 v[12:13], 12, v[102:103]
	v_and_b32_e32 v15, 0xffff0000, v88
	v_lshlrev_b32_e32 v14, 16, v88
	v_lshlrev_b32_e32 v20, 16, v89
	v_lshlrev_b32_e32 v22, 16, v90
	v_and_b32_e32 v23, 0xffff0000, v90
	v_lshlrev_b32_e32 v24, 16, v91
	v_mul_f32_e32 v15, v17, v15
	v_mul_f32_e32 v17, v19, v21
	v_mul_f32_e32 v11, v11, v25
	v_lshl_add_u64 v[12:13], s[44:45], 0, v[12:13]
	v_mul_f32_e32 v14, v16, v14
	v_mul_f32_e32 v16, v18, v20
	v_mul_f32_e32 v18, v8, v22
	v_mul_f32_e32 v19, v9, v23
	v_mul_f32_e32 v20, v10, v24
	v_cvt_pk_bf16_f32 v8, v14, v15
	v_cvt_pk_bf16_f32 v9, v16, v17
	v_cvt_pk_bf16_f32 v10, v18, v19
	v_cvt_pk_bf16_f32 v11, v20, v11
	v_lshl_add_u64 v[12:13], v[12:13], 0, v[140:141]
	v_and_b32_e32 v17, 0xffff0000, v95
	global_store_dwordx4 v[12:13], v[8:11], off
	v_lshlrev_b32_e32 v14, 16, v94
	v_and_b32_e32 v15, 0xffff0000, v94
	v_lshlrev_b32_e32 v8, 16, v92
	v_and_b32_e32 v9, 0xffff0000, v92
	v_lshlrev_b32_e32 v10, 16, v93
	v_and_b32_e32 v11, 0xffff0000, v93
	v_lshlrev_b32_e32 v16, 16, v95
	v_mul_f32_e32 v3, v3, v17
	v_mul_f32_e32 v4, v4, v8
	v_mul_f32_e32 v5, v5, v9
	v_mul_f32_e32 v6, v6, v10
	v_mul_f32_e32 v7, v7, v11
	v_mul_f32_e32 v8, v0, v14
	v_mul_f32_e32 v9, v1, v15
	v_mul_f32_e32 v10, v2, v16
	v_cvt_pk_bf16_f32 v0, v4, v5
	v_cvt_pk_bf16_f32 v1, v6, v7
	v_cvt_pk_bf16_f32 v2, v8, v9
	v_cvt_pk_bf16_f32 v3, v10, v3
	global_store_dwordx4 v[12:13], v[0:3], off offset:256
	s_cbranch_scc1 .LBB0_941
	s_waitcnt vmcnt(0)
	buffer_wbl2 sc1
	s_waitcnt vmcnt(0) lgkmcnt(0)
	s_waitcnt vmcnt(0)
	s_and_saveexec_b64 s[0:1], s[6:7]
	s_cbranch_execz .LBB0_940
	s_mov_b64 s[52:53], exec
	v_mbcnt_lo_u32_b32 v0, s52, 0
	v_mbcnt_hi_u32_b32 v0, s53, v0
	v_cmp_eq_u32_e32 vcc, 0, v0
	s_and_b64 s[42:43], exec, vcc
	s_mov_b64 exec, s[42:43]
	s_cbranch_execz .LBB0_940
	s_lshl_b32 s8, s70, 6
	s_lshl_b64 s[42:43], s[8:9], 2
	v_readlane_b32 s56, v255, 1
	v_readlane_b32 s57, v255, 2
	s_add_u32 s8, s56, s42
	s_addc_u32 s33, s57, s43
	s_add_u32 s42, s8, 0xfffc4e00
	s_addc_u32 s43, s33, -1
	s_bcnt1_i32_b64 s8, s[52:53]
	v_mov_b32_e32 v0, s8
	global_atomic_add v131, v0, s[42:43]
	s_branch .LBB0_940

; #define PG8_STAGE(bufoff, gbase, voff) do { _Pragma("unroll") for (int _i = 0; _i < 2; ++_i) \
;         __builtin_amdgcn_global_load_lds((const unsigned*)((const char*)(gbase) + (voff)[_i]), (LAS unsigned*)(lds + (bufoff) + ldsw + _i * 8192), 16, 0, 0); } while (0)
; #define PG8_LDA(dst, b, h) do { _Pragma("unroll") for (int m = 0; m < 4; ++m) _Pragma("unroll") for (int k = 0; k < 2; ++k) dst[m][k] = *(const LAS bf16x8*)(lds + PG8_SA(b, h) + aoff + m * 2048 + k * 1024); } while (0)
; #define PG8_LDB(dst, b, h) do { _Pragma("unroll") for (int n = 0; n < 2; ++n) _Pragma("unroll") for (int k = 0; k < 2; ++k) dst[n][k] = *(const LAS bf16x8*)(lds + PG8_SB(b, h) + boff + n * 2048 + k * 1024); } while (0)
; #define PG8_MMA(ai, bj, At, Bt) do { __builtin_amdgcn_s_setprio(1); _Pragma("unroll") for (int m = 0; m < 4; ++m) _Pragma("unroll") for (int n = 0; n < 2; ++n) _Pragma("unroll") for (int k = 0; k < 2; ++k) \
;         acc[ai][bj][m][n] = __builtin_amdgcn_mfma_f32_16x16x32_bf16(Bt[n][k], At[m][k], acc[ai][bj][m][n], 0, 0, 0); __builtin_amdgcn_s_setprio(0); } while (0)
; #define PG8_WAIT_V(n) asm volatile("s_waitcnt vmcnt(" #n ")" ::: "memory")
; #define PG8_WAIT_L(n) asm volatile("s_waitcnt lgkmcnt(" #n ")" ::: "memory")
; #define PG8_BAR __builtin_amdgcn_s_barrier()
; #define PG8_SCHED __builtin_amdgcn_sched_barrier(0)
; template <class Epi, class S_t>
; __device__ __forceinline__ void gemm_phase(LAS unsigned char* lds, int lda, int ldb, const S_t& S, const Epi& E) {
;     ...
;             PG8_LDB(B0, 0, 0); PG8_SCHED; PG8_LDA(At, 0, 0); PG8_STAGE(PG8_SA(1, 1), a1 + hstepA, voffA);
;             PG8_WAIT_L(8); PG8_BAR; PG8_WAIT_L(0); PG8_MMA(0, 0, At, B0); PG8_BAR; PG8_SCHED;
;             PG8_LDB(B1, 0, 1); PG8_STAGE(PG8_SB(0, 0), b2, voffB);
;             PG8_BAR; PG8_WAIT_L(0); PG8_MMA(0, 1, At, B1); PG8_BAR;
;             PG8_LDA(At, 0, 1); PG8_STAGE(PG8_SA(0, 0), a2, voffA);
;             PG8_BAR; PG8_WAIT_L(0); PG8_MMA(1, 0, At, B0); PG8_BAR; PG8_SCHED;
;             PG8_STAGE(PG8_SB(0, 1), b2 + hstepB, voffB);
;             PG8_WAIT_V(6); PG8_BAR; PG8_MMA(1, 1, At, B1); PG8_BAR;
.LBB0_966:
	ds_read_b128 v[128:131], v169
	ds_read_b128 v[132:135], v169 offset:1024
	ds_read_b128 v[136:139], v169 offset:2048
	ds_read_b128 v[140:143], v169 offset:3072
	s_add_u32 s33, s56, 0xfff80080
	s_addc_u32 s58, s57, -1
	s_cmp_eq_u32 s43, 28
	s_cselect_b32 s61, s55, s58
	s_cselect_b32 s60, s54, s33
	s_cselect_b32 s59, s49, s1
	s_cselect_b32 s58, s48, s0
	s_add_i32 m0, s16, 0xc000
	ds_read_b128 v[156:159], v170
	ds_read_b128 v[160:163], v170 offset:1024
	ds_read_b128 v[172:175], v170 offset:2048
	ds_read_b128 v[176:179], v170 offset:3072
	ds_read_b128 v[180:183], v170 offset:4096
	ds_read_b128 v[186:189], v170 offset:5120
	ds_read_b128 v[190:193], v170 offset:6144
	ds_read_b128 v[194:197], v170 offset:7168
	global_load_lds_dwordx4 v152, s[56:57]
	s_add_i32 m0, s16, 0xe000
	s_nop 0
	global_load_lds_dwordx4 v154, s[56:57]
	s_waitcnt lgkmcnt(8)
	s_barrier
	s_waitcnt lgkmcnt(0)
	s_setprio 1
	s_waitcnt lgkmcnt(0)
	v_mfma_f32_16x16x32_bf16 v[124:127], v[128:131], v[156:159], v[124:127]
	v_mfma_f32_16x16x32_bf16 v[120:123], v[136:139], v[156:159], v[120:123]
	v_mfma_f32_16x16x32_bf16 v[108:111], v[128:131], v[172:175], v[108:111]
	v_mfma_f32_16x16x32_bf16 v[104:107], v[136:139], v[172:175], v[104:107]
	v_mfma_f32_16x16x32_bf16 v[92:95], v[128:131], v[180:183], v[92:95]
	v_mfma_f32_16x16x32_bf16 v[88:91], v[136:139], v[180:183], v[88:91]
	v_mfma_f32_16x16x32_bf16 v[76:79], v[128:131], v[190:193], v[76:79]
	v_mfma_f32_16x16x32_bf16 v[72:75], v[136:139], v[190:193], v[72:75]
	v_mfma_f32_16x16x32_bf16 v[124:127], v[132:135], v[160:163], v[124:127]
	v_mfma_f32_16x16x32_bf16 v[120:123], v[140:143], v[160:163], v[120:123]
	v_mfma_f32_16x16x32_bf16 v[108:111], v[132:135], v[176:179], v[108:111]
	v_mfma_f32_16x16x32_bf16 v[104:107], v[140:143], v[176:179], v[104:107]
	v_mfma_f32_16x16x32_bf16 v[92:95], v[132:135], v[186:189], v[92:95]
	v_mfma_f32_16x16x32_bf16 v[88:91], v[140:143], v[186:189], v[88:91]
	v_mfma_f32_16x16x32_bf16 v[76:79], v[132:135], v[194:197], v[76:79]
	v_mfma_f32_16x16x32_bf16 v[72:75], v[140:143], v[194:197], v[72:75]
	s_setprio 0
	s_barrier
	s_add_i32 s33, s88, s5
	s_add_u32 s98, s58, s8
	s_addc_u32 s99, s59, s9
	s_mov_b32 m0, s33
	ds_read_b128 v[198:201], v171
	ds_read_b128 v[202:205], v171 offset:1024
	ds_read_b128 v[206:209], v171 offset:2048
	ds_read_b128 v[222:225], v171 offset:3072
	global_load_lds_dwordx4 v146, s[58:59]
	s_add_i32 m0, s33, 0x2000
	s_nop 0
	global_load_lds_dwordx4 v150, s[58:59]
	s_barrier
	s_waitcnt lgkmcnt(0)
	s_setprio 1
	s_waitcnt lgkmcnt(0)
	v_mfma_f32_16x16x32_bf16 v[116:119], v[198:201], v[156:159], v[116:119]
	v_mfma_f32_16x16x32_bf16 v[112:115], v[206:209], v[156:159], v[112:115]
	v_mfma_f32_16x16x32_bf16 v[100:103], v[198:201], v[172:175], v[100:103]
	v_mfma_f32_16x16x32_bf16 v[96:99], v[206:209], v[172:175], v[96:99]
	v_mfma_f32_16x16x32_bf16 v[84:87], v[198:201], v[180:183], v[84:87]
	v_mfma_f32_16x16x32_bf16 v[80:83], v[206:209], v[180:183], v[80:83]
	v_mfma_f32_16x16x32_bf16 v[68:71], v[198:201], v[190:193], v[68:71]
	v_mfma_f32_16x16x32_bf16 v[64:67], v[206:209], v[190:193], v[64:67]
	v_mfma_f32_16x16x32_bf16 v[116:119], v[202:205], v[160:163], v[116:119]
	v_mfma_f32_16x16x32_bf16 v[112:115], v[222:225], v[160:163], v[112:115]
	v_mfma_f32_16x16x32_bf16 v[100:103], v[202:205], v[176:179], v[100:103]
	v_mfma_f32_16x16x32_bf16 v[96:99], v[222:225], v[176:179], v[96:99]
	v_mfma_f32_16x16x32_bf16 v[84:87], v[202:205], v[186:189], v[84:87]
	v_mfma_f32_16x16x32_bf16 v[80:83], v[222:225], v[186:189], v[80:83]
	v_mfma_f32_16x16x32_bf16 v[68:71], v[202:205], v[194:197], v[68:71]
	v_mfma_f32_16x16x32_bf16 v[64:67], v[222:225], v[194:197], v[64:67]
	s_setprio 0
	s_mov_b32 m0, s16
	s_add_u32 s100, s60, s8
	s_addc_u32 s101, s61, s9
	s_barrier
	ds_read_b128 v[156:159], v170 offset:16384
	ds_read_b128 v[160:163], v170 offset:17408
	ds_read_b128 v[172:175], v170 offset:18432
	ds_read_b128 v[176:179], v170 offset:19456
	ds_read_b128 v[180:183], v170 offset:20480
	ds_read_b128 v[186:189], v170 offset:21504
	ds_read_b128 v[190:193], v170 offset:22528
	ds_read_b128 v[194:197], v170 offset:23552
	global_load_lds_dwordx4 v144, s[60:61]
	s_mov_b32 m0, s17
	s_nop 0
	global_load_lds_dwordx4 v148, s[60:61]
	s_barrier
	s_waitcnt lgkmcnt(0)
	s_setprio 1
	s_waitcnt lgkmcnt(0)
	v_mfma_f32_16x16x32_bf16 v[60:63], v[128:131], v[156:159], v[60:63]
	v_mfma_f32_16x16x32_bf16 v[56:59], v[136:139], v[156:159], v[56:59]
	v_mfma_f32_16x16x32_bf16 v[44:47], v[128:131], v[172:175], v[44:47]
	v_mfma_f32_16x16x32_bf16 v[40:43], v[136:139], v[172:175], v[40:43]
	v_mfma_f32_16x16x32_bf16 v[28:31], v[128:131], v[180:183], v[28:31]
	v_mfma_f32_16x16x32_bf16 v[24:27], v[136:139], v[180:183], v[24:27]
	v_mfma_f32_16x16x32_bf16 v[12:15], v[128:131], v[190:193], v[12:15]
	v_mfma_f32_16x16x32_bf16 v[8:11], v[136:139], v[190:193], v[8:11]
	v_mfma_f32_16x16x32_bf16 v[60:63], v[132:135], v[160:163], v[60:63]
	v_mfma_f32_16x16x32_bf16 v[56:59], v[140:143], v[160:163], v[56:59]
	v_mfma_f32_16x16x32_bf16 v[44:47], v[132:135], v[176:179], v[44:47]
	v_mfma_f32_16x16x32_bf16 v[40:43], v[140:143], v[176:179], v[40:43]
	v_mfma_f32_16x16x32_bf16 v[28:31], v[132:135], v[186:189], v[28:31]
	v_mfma_f32_16x16x32_bf16 v[24:27], v[140:143], v[186:189], v[24:27]
	v_mfma_f32_16x16x32_bf16 v[12:15], v[132:135], v[194:197], v[12:15]
	v_mfma_f32_16x16x32_bf16 v[8:11], v[140:143], v[194:197], v[8:11]
	s_setprio 0
	s_barrier
	s_add_u32 s64, s58, 0x80000
	s_addc_u32 s65, s59, 0
	s_add_i32 s33, s89, s5
	s_mov_b32 m0, s33
	s_nop 0
	global_load_lds_dwordx4 v146, s[64:65]
	s_add_i32 m0, s33, 0x2000
	s_nop 0
	global_load_lds_dwordx4 v150, s[64:65]
	s_waitcnt vmcnt(6)
	s_barrier
; #define PG8_STAGE(bufoff, gbase, voff) do { _Pragma("unroll") for (int _i = 0; _i < 2; ++_i) \
;         __builtin_amdgcn_global_load_lds((const unsigned*)((const char*)(gbase) + (voff)[_i]), (LAS unsigned*)(lds + (bufoff) + ldsw + _i * 8192), 16, 0, 0); } while (0)
; #define PG8_LDA(dst, b, h) do { _Pragma("unroll") for (int m = 0; m < 4; ++m) _Pragma("unroll") for (int k = 0; k < 2; ++k) dst[m][k] = *(const LAS bf16x8*)(lds + PG8_SA(b, h) + aoff + m * 2048 + k * 1024); } while (0)
; #define PG8_LDB(dst, b, h) do { _Pragma("unroll") for (int n = 0; n < 2; ++n) _Pragma("unroll") for (int k = 0; k < 2; ++k) dst[n][k] = *(const LAS bf16x8*)(lds + PG8_SB(b, h) + boff + n * 2048 + k * 1024); } while (0)
; #define PG8_MMA(ai, bj, At, Bt) do { __builtin_amdgcn_s_setprio(1); _Pragma("unroll") for (int m = 0; m < 4; ++m) _Pragma("unroll") for (int n = 0; n < 2; ++n) _Pragma("unroll") for (int k = 0; k < 2; ++k) \
;         acc[ai][bj][m][n] = __builtin_amdgcn_mfma_f32_16x16x32_bf16(Bt[n][k], At[m][k], acc[ai][bj][m][n], 0, 0, 0); __builtin_amdgcn_s_setprio(0); } while (0)
; #define PG8_WAIT_V(n) asm volatile("s_waitcnt vmcnt(" #n ")" ::: "memory")
; #define PG8_WAIT_L(n) asm volatile("s_waitcnt lgkmcnt(" #n ")" ::: "memory")
; #define PG8_BAR __builtin_amdgcn_s_barrier()
; #define PG8_SCHED __builtin_amdgcn_sched_barrier(0)
; template <class Epi, class S_t>
; __device__ __forceinline__ void gemm_phase(LAS unsigned char* lds, int lda, int ldb, const S_t& S, const Epi& E) {
;     ...
;             PG8_WAIT_V(6); PG8_BAR; PG8_MMA(1, 1, At, B1); PG8_BAR;
;             PG8_LDB(B0, 1, 0); PG8_SCHED; PG8_LDA(At, 1, 0); PG8_STAGE(PG8_SA(0, 1), a2 + hstepA, voffA);
;             PG8_WAIT_L(8); PG8_BAR; PG8_WAIT_L(0); PG8_MMA(0, 0, At, B0); PG8_BAR; PG8_SCHED;
;             PG8_LDB(B1, 1, 1); PG8_STAGE(PG8_SB(1, 0), b3, voffB);
;             PG8_BAR; PG8_WAIT_L(0); PG8_MMA(0, 1, At, B1); PG8_BAR;
;             PG8_LDA(At, 1, 1); PG8_STAGE(PG8_SA(1, 0), a3, voffA);
;             PG8_BAR; PG8_WAIT_L(0); PG8_MMA(1, 0, At, B0); PG8_BAR; PG8_SCHED;
	s_setprio 1
	v_mfma_f32_16x16x32_bf16 v[52:55], v[198:201], v[156:159], v[52:55]
	v_mfma_f32_16x16x32_bf16 v[48:51], v[206:209], v[156:159], v[48:51]
	v_mfma_f32_16x16x32_bf16 v[36:39], v[198:201], v[172:175], v[36:39]
	v_mfma_f32_16x16x32_bf16 v[32:35], v[206:209], v[172:175], v[32:35]
	v_mfma_f32_16x16x32_bf16 v[20:23], v[198:201], v[180:183], v[20:23]
	v_mfma_f32_16x16x32_bf16 v[16:19], v[206:209], v[180:183], v[16:19]
	v_mfma_f32_16x16x32_bf16 v[4:7], v[198:201], v[190:193], v[4:7]
	v_mfma_f32_16x16x32_bf16 v[0:3], v[206:209], v[190:193], v[0:3]
	v_mfma_f32_16x16x32_bf16 v[52:55], v[202:205], v[160:163], v[52:55]
	v_mfma_f32_16x16x32_bf16 v[48:51], v[222:225], v[160:163], v[48:51]
	v_mfma_f32_16x16x32_bf16 v[36:39], v[202:205], v[176:179], v[36:39]
	v_mfma_f32_16x16x32_bf16 v[32:35], v[222:225], v[176:179], v[32:35]
	v_mfma_f32_16x16x32_bf16 v[20:23], v[202:205], v[186:189], v[20:23]
	v_mfma_f32_16x16x32_bf16 v[16:19], v[222:225], v[186:189], v[16:19]
	v_mfma_f32_16x16x32_bf16 v[4:7], v[202:205], v[194:197], v[4:7]
	v_mfma_f32_16x16x32_bf16 v[0:3], v[222:225], v[194:197], v[0:3]
	s_setprio 0
	v_add_u32_e32 v140, s90, v167
	s_barrier
	ds_read_b128 v[128:131], v140
	ds_read_b128 v[132:135], v140 offset:1024
	ds_read_b128 v[136:139], v140 offset:2048
	ds_read_b128 v[140:143], v140 offset:3072
	s_add_u32 s60, s60, 0x80000
	s_addc_u32 s61, s61, 0
	s_mov_b32 m0, s20
	ds_read_b128 v[156:159], v170 offset:32768
	ds_read_b128 v[160:163], v170 offset:33792
	ds_read_b128 v[172:175], v170 offset:34816
	ds_read_b128 v[176:179], v170 offset:35840
	ds_read_b128 v[180:183], v170 offset:36864
	ds_read_b128 v[186:189], v170 offset:37888
	ds_read_b128 v[190:193], v170 offset:38912
	ds_read_b128 v[194:197], v170 offset:39936
	global_load_lds_dwordx4 v144, s[60:61]
	s_mov_b32 m0, s21
	s_nop 0
	global_load_lds_dwordx4 v148, s[60:61]
	s_waitcnt lgkmcnt(8)
	s_barrier
	s_waitcnt lgkmcnt(0)
	s_setprio 1
	s_waitcnt lgkmcnt(0)
	v_mfma_f32_16x16x32_bf16 v[124:127], v[128:131], v[156:159], v[124:127]
	v_mfma_f32_16x16x32_bf16 v[120:123], v[136:139], v[156:159], v[120:123]
	v_mfma_f32_16x16x32_bf16 v[108:111], v[128:131], v[172:175], v[108:111]
	v_mfma_f32_16x16x32_bf16 v[104:107], v[136:139], v[172:175], v[104:107]
	v_mfma_f32_16x16x32_bf16 v[92:95], v[128:131], v[180:183], v[92:95]
	v_mfma_f32_16x16x32_bf16 v[88:91], v[136:139], v[180:183], v[88:91]
	v_mfma_f32_16x16x32_bf16 v[76:79], v[128:131], v[190:193], v[76:79]
	v_mfma_f32_16x16x32_bf16 v[72:75], v[136:139], v[190:193], v[72:75]
	v_mfma_f32_16x16x32_bf16 v[124:127], v[132:135], v[160:163], v[124:127]
	v_mfma_f32_16x16x32_bf16 v[120:123], v[140:143], v[160:163], v[120:123]
	v_mfma_f32_16x16x32_bf16 v[108:111], v[132:135], v[176:179], v[108:111]
	v_mfma_f32_16x16x32_bf16 v[104:107], v[140:143], v[176:179], v[104:107]
	v_mfma_f32_16x16x32_bf16 v[92:95], v[132:135], v[186:189], v[92:95]
	v_mfma_f32_16x16x32_bf16 v[88:91], v[140:143], v[186:189], v[88:91]
	v_mfma_f32_16x16x32_bf16 v[76:79], v[132:135], v[194:197], v[76:79]
	v_mfma_f32_16x16x32_bf16 v[72:75], v[140:143], v[194:197], v[72:75]
	s_setprio 0
	s_barrier
	s_add_i32 s33, s90, s5
	v_add_u32_e32 v185, s91, v167
	s_mov_b32 m0, s33
	ds_read_b128 v[198:201], v185
	ds_read_b128 v[202:205], v185 offset:1024
	ds_read_b128 v[206:209], v185 offset:2048
	ds_read_b128 v[222:225], v185 offset:3072
	global_load_lds_dwordx4 v146, s[98:99]
	s_add_i32 m0, s33, 0x2000
	s_nop 0
	global_load_lds_dwordx4 v150, s[98:99]
	s_barrier
	s_waitcnt lgkmcnt(0)
	s_setprio 1
	s_waitcnt lgkmcnt(0)
	v_mfma_f32_16x16x32_bf16 v[116:119], v[198:201], v[156:159], v[116:119]
	v_mfma_f32_16x16x32_bf16 v[112:115], v[206:209], v[156:159], v[112:115]
	v_mfma_f32_16x16x32_bf16 v[100:103], v[198:201], v[172:175], v[100:103]
	v_mfma_f32_16x16x32_bf16 v[96:99], v[206:209], v[172:175], v[96:99]
	v_mfma_f32_16x16x32_bf16 v[84:87], v[198:201], v[180:183], v[84:87]
	v_mfma_f32_16x16x32_bf16 v[80:83], v[206:209], v[180:183], v[80:83]
	v_mfma_f32_16x16x32_bf16 v[68:71], v[198:201], v[190:193], v[68:71]
	v_mfma_f32_16x16x32_bf16 v[64:67], v[206:209], v[190:193], v[64:67]
	v_mfma_f32_16x16x32_bf16 v[116:119], v[202:205], v[160:163], v[116:119]
	v_mfma_f32_16x16x32_bf16 v[112:115], v[222:225], v[160:163], v[112:115]
	v_mfma_f32_16x16x32_bf16 v[100:103], v[202:205], v[176:179], v[100:103]
	v_mfma_f32_16x16x32_bf16 v[96:99], v[222:225], v[176:179], v[96:99]
	v_mfma_f32_16x16x32_bf16 v[84:87], v[202:205], v[186:189], v[84:87]
	v_mfma_f32_16x16x32_bf16 v[80:83], v[222:225], v[186:189], v[80:83]
	v_mfma_f32_16x16x32_bf16 v[68:71], v[202:205], v[194:197], v[68:71]
	v_mfma_f32_16x16x32_bf16 v[64:67], v[222:225], v[194:197], v[64:67]
	s_setprio 0
	s_mov_b32 m0, s35
	s_barrier
; #define PG8_STAGE(bufoff, gbase, voff) do { _Pragma("unroll") for (int _i = 0; _i < 2; ++_i) \
;         __builtin_amdgcn_global_load_lds((const unsigned*)((const char*)(gbase) + (voff)[_i]), (LAS unsigned*)(lds + (bufoff) + ldsw + _i * 8192), 16, 0, 0); } while (0)
; #define PG8_LDA(dst, b, h) do { _Pragma("unroll") for (int m = 0; m < 4; ++m) _Pragma("unroll") for (int k = 0; k < 2; ++k) dst[m][k] = *(const LAS bf16x8*)(lds + PG8_SA(b, h) + aoff + m * 2048 + k * 1024); } while (0)
; #define PG8_MMA(ai, bj, At, Bt) do { __builtin_amdgcn_s_setprio(1); _Pragma("unroll") for (int m = 0; m < 4; ++m) _Pragma("unroll") for (int n = 0; n < 2; ++n) _Pragma("unroll") for (int k = 0; k < 2; ++k) \
;         acc[ai][bj][m][n] = __builtin_amdgcn_mfma_f32_16x16x32_bf16(Bt[n][k], At[m][k], acc[ai][bj][m][n], 0, 0, 0); __builtin_amdgcn_s_setprio(0); } while (0)
; #define PG8_WAIT_V(n) asm volatile("s_waitcnt vmcnt(" #n ")" ::: "memory")
; #define PG8_WAIT_L(n) asm volatile("s_waitcnt lgkmcnt(" #n ")" ::: "memory")
; #define PG8_BAR __builtin_amdgcn_s_barrier()
; #define PG8_SCHED __builtin_amdgcn_sched_barrier(0)
; template <class Epi, class S_t>
; __device__ __forceinline__ void gemm_phase(LAS unsigned char* lds, int lda, int ldb, const S_t& S, const Epi& E) {
;     ...
;             PG8_LDA(At, 1, 1); PG8_STAGE(PG8_SA(1, 0), a3, voffA);
;             PG8_BAR; PG8_WAIT_L(0); PG8_MMA(1, 0, At, B0); PG8_BAR; PG8_SCHED;
;             PG8_STAGE(PG8_SB(1, 1), b3 + hstepB, voffB);
;             PG8_WAIT_V(6); PG8_BAR; PG8_MMA(1, 1, At, B1); PG8_BAR;
;     __device__ __forceinline__ void operator()(const f32x4 (&acc)[2][2][4][2], const Unit& u, int wr, int wc, int fr, int fq) const {
;     ...
;         if (ADD && u.tag >= 2000) {
;             unsigned* f = flags + P7_FLAG(u.tag - 2000); unsigned sp = 0;
;             while ((unsigned)__builtin_amdgcn_readfirstlane(__hip_atomic_load(f, __ATOMIC_RELAXED, __HIP_MEMORY_SCOPE_AGENT)) < 8u) { __builtin_amdgcn_s_sleep(2); if (++sp > (1u << 20)) break; }
	ds_read_b128 v[156:159], v170 offset:49152
	ds_read_b128 v[160:163], v170 offset:50176
	ds_read_b128 v[172:175], v170 offset:51200
	ds_read_b128 v[176:179], v170 offset:52224
	ds_read_b128 v[180:183], v170 offset:53248
	ds_read_b128 v[186:189], v170 offset:54272
	ds_read_b128 v[190:193], v170 offset:55296
	ds_read_b128 v[194:197], v170 offset:56320
	global_load_lds_dwordx4 v144, s[100:101]
	s_mov_b32 m0, s47
	s_nop 0
	global_load_lds_dwordx4 v148, s[100:101]
	s_barrier
	s_waitcnt lgkmcnt(0)
	s_setprio 1
	s_waitcnt lgkmcnt(0)
	v_mfma_f32_16x16x32_bf16 v[60:63], v[128:131], v[156:159], v[60:63]
	v_mfma_f32_16x16x32_bf16 v[56:59], v[136:139], v[156:159], v[56:59]
	v_mfma_f32_16x16x32_bf16 v[44:47], v[128:131], v[172:175], v[44:47]
	v_mfma_f32_16x16x32_bf16 v[40:43], v[136:139], v[172:175], v[40:43]
	v_mfma_f32_16x16x32_bf16 v[28:31], v[128:131], v[180:183], v[28:31]
	v_mfma_f32_16x16x32_bf16 v[24:27], v[136:139], v[180:183], v[24:27]
	v_mfma_f32_16x16x32_bf16 v[12:15], v[128:131], v[190:193], v[12:15]
	v_mfma_f32_16x16x32_bf16 v[8:11], v[136:139], v[190:193], v[8:11]
	v_mfma_f32_16x16x32_bf16 v[60:63], v[132:135], v[160:163], v[60:63]
	v_mfma_f32_16x16x32_bf16 v[56:59], v[140:143], v[160:163], v[56:59]
	v_mfma_f32_16x16x32_bf16 v[44:47], v[132:135], v[176:179], v[44:47]
	v_mfma_f32_16x16x32_bf16 v[40:43], v[140:143], v[176:179], v[40:43]
	v_mfma_f32_16x16x32_bf16 v[28:31], v[132:135], v[186:189], v[28:31]
	v_mfma_f32_16x16x32_bf16 v[24:27], v[140:143], v[186:189], v[24:27]
	v_mfma_f32_16x16x32_bf16 v[12:15], v[132:135], v[194:197], v[12:15]
	v_mfma_f32_16x16x32_bf16 v[8:11], v[140:143], v[194:197], v[8:11]
	s_setprio 0
	s_barrier
	s_add_u32 s58, s58, 0x80080
	s_addc_u32 s59, s59, 0
	s_add_i32 s33, s91, s5
	s_mov_b32 m0, s33
	s_nop 0
	global_load_lds_dwordx4 v146, s[58:59]
	s_add_i32 m0, s33, 0x2000
	s_nop 0
	global_load_lds_dwordx4 v150, s[58:59]
	s_waitcnt vmcnt(6)
	s_barrier
	s_setprio 1
	v_mfma_f32_16x16x32_bf16 v[52:55], v[198:201], v[156:159], v[52:55]
	v_mfma_f32_16x16x32_bf16 v[48:51], v[206:209], v[156:159], v[48:51]
	v_mfma_f32_16x16x32_bf16 v[36:39], v[198:201], v[172:175], v[36:39]
	v_mfma_f32_16x16x32_bf16 v[32:35], v[206:209], v[172:175], v[32:35]
	v_mfma_f32_16x16x32_bf16 v[20:23], v[198:201], v[180:183], v[20:23]
	v_mfma_f32_16x16x32_bf16 v[16:19], v[206:209], v[180:183], v[16:19]
	v_mfma_f32_16x16x32_bf16 v[4:7], v[198:201], v[190:193], v[4:7]
	v_mfma_f32_16x16x32_bf16 v[0:3], v[206:209], v[190:193], v[0:3]
	v_mfma_f32_16x16x32_bf16 v[52:55], v[202:205], v[160:163], v[52:55]
	v_mfma_f32_16x16x32_bf16 v[48:51], v[222:225], v[160:163], v[48:51]
	v_mfma_f32_16x16x32_bf16 v[36:39], v[202:205], v[176:179], v[36:39]
	v_mfma_f32_16x16x32_bf16 v[32:35], v[222:225], v[176:179], v[32:35]
	v_mfma_f32_16x16x32_bf16 v[20:23], v[202:205], v[186:189], v[20:23]
	v_mfma_f32_16x16x32_bf16 v[16:19], v[222:225], v[186:189], v[16:19]
	v_mfma_f32_16x16x32_bf16 v[4:7], v[202:205], v[194:197], v[4:7]
	v_mfma_f32_16x16x32_bf16 v[0:3], v[222:225], v[194:197], v[0:3]
	s_setprio 0
	s_add_i32 s43, s43, 2
	s_add_u32 s56, s56, 0x100
	s_addc_u32 s57, s57, 0
	s_add_u32 s0, s0, 0x100
	s_addc_u32 s1, s1, 0
	s_cmp_gt_u32 s43, 29
	s_barrier
	s_cbranch_scc0 .LBB0_966
	s_cmpk_lt_i32 s6, 0x7d0
	s_cbranch_scc1 .LBB0_962
	s_lshl_b32 s6, s6, 6
	s_lshl_b64 s[0:1], s[6:7], 2
	v_readlane_b32 s48, v255, 1
	v_readlane_b32 s49, v255, 2
	s_add_u32 s0, s48, s0
	s_addc_u32 s1, s49, s1
	s_add_u32 s0, s0, 0xfff86600
	s_addc_u32 s1, s1, -1
	s_mov_b32 s6, 0x100001
	s_branch .LBB0_970

; #define PG8_STAGE(bufoff, gbase, voff) do { _Pragma("unroll") for (int _i = 0; _i < 2; ++_i) \
;         __builtin_amdgcn_global_load_lds((const unsigned*)((const char*)(gbase) + (voff)[_i]), (LAS unsigned*)(lds + (bufoff) + ldsw + _i * 8192), 16, 0, 0); } while (0)
; #define PG8_LDA(dst, b, h) do { _Pragma("unroll") for (int m = 0; m < 4; ++m) _Pragma("unroll") for (int k = 0; k < 2; ++k) dst[m][k] = *(const LAS bf16x8*)(lds + PG8_SA(b, h) + aoff + m * 2048 + k * 1024); } while (0)
; #define PG8_LDB(dst, b, h) do { _Pragma("unroll") for (int n = 0; n < 2; ++n) _Pragma("unroll") for (int k = 0; k < 2; ++k) dst[n][k] = *(const LAS bf16x8*)(lds + PG8_SB(b, h) + boff + n * 2048 + k * 1024); } while (0)
; #define PG8_MMA(ai, bj, At, Bt) do { __builtin_amdgcn_s_setprio(1); _Pragma("unroll") for (int m = 0; m < 4; ++m) _Pragma("unroll") for (int n = 0; n < 2; ++n) _Pragma("unroll") for (int k = 0; k < 2; ++k) \
;         acc[ai][bj][m][n] = __builtin_amdgcn_mfma_f32_16x16x32_bf16(Bt[n][k], At[m][k], acc[ai][bj][m][n], 0, 0, 0); __builtin_amdgcn_s_setprio(0); } while (0)
; #define PG8_WAIT_V(n) asm volatile("s_waitcnt vmcnt(" #n ")" ::: "memory")
; #define PG8_WAIT_L(n) asm volatile("s_waitcnt lgkmcnt(" #n ")" ::: "memory")
; #define PG8_BAR __builtin_amdgcn_s_barrier()
; #define PG8_SCHED __builtin_amdgcn_sched_barrier(0)
; template <class Epi, class S_t>
; __device__ __forceinline__ void gemm_phase(LAS unsigned char* lds, int lda, int ldb, const S_t& S, const Epi& E) {
;     ...
;             PG8_LDB(B0, 0, 0); PG8_SCHED; PG8_LDA(At, 0, 0); PG8_STAGE(PG8_SA(1, 1), a1 + hstepA, voffA);
;             PG8_WAIT_L(8); PG8_BAR; PG8_WAIT_L(0); PG8_MMA(0, 0, At, B0); PG8_BAR; PG8_SCHED;
;             PG8_LDB(B1, 0, 1); PG8_STAGE(PG8_SB(0, 0), b2, voffB);
;             PG8_BAR; PG8_WAIT_L(0); PG8_MMA(0, 1, At, B1); PG8_BAR;
;             PG8_LDA(At, 0, 1); PG8_STAGE(PG8_SA(0, 0), a2, voffA);
;             PG8_BAR; PG8_WAIT_L(0); PG8_MMA(1, 0, At, B0); PG8_BAR; PG8_SCHED;
;             PG8_STAGE(PG8_SB(0, 1), b2 + hstepB, voffB);
;             PG8_WAIT_V(6); PG8_BAR; PG8_MMA(1, 1, At, B1); PG8_BAR;
.LBB0_1051:
	ds_read_b128 v[150:153], v146
	ds_read_b128 v[154:157], v146 offset:1024
	ds_read_b128 v[158:161], v146 offset:2048
	ds_read_b128 v[162:165], v146 offset:3072
	s_add_i32 s70, s62, 2
	s_add_u32 s33, s60, 0xfff80080
	s_addc_u32 s63, s61, -1
	s_cmp_eq_u32 s0, s62
	s_cselect_b32 s62, s56, s1
	s_cselect_b32 s67, s59, s63
	s_cselect_b32 s66, s58, s33
	s_cselect_b32 s63, s57, s69
	s_add_i32 m0, s16, 0xc000
	ds_read_b128 v[166:169], v147
	ds_read_b128 v[170:173], v147 offset:1024
	ds_read_b128 v[174:177], v147 offset:2048
	ds_read_b128 v[178:181], v147 offset:3072
	ds_read_b128 v[186:189], v147 offset:4096
	ds_read_b128 v[190:193], v147 offset:5120
	ds_read_b128 v[194:197], v147 offset:6144
	ds_read_b128 v[198:201], v147 offset:7168
	global_load_lds_dwordx4 v136, s[60:61]
	s_add_i32 m0, s16, 0xe000
	s_nop 0
	global_load_lds_dwordx4 v138, s[60:61]
	s_waitcnt lgkmcnt(8)
	s_barrier
	s_waitcnt lgkmcnt(0)
	s_setprio 1
	s_waitcnt lgkmcnt(0)
	v_mfma_f32_16x16x32_bf16 v[124:127], v[150:153], v[166:169], v[124:127]
	v_mfma_f32_16x16x32_bf16 v[120:123], v[158:161], v[166:169], v[120:123]
	v_mfma_f32_16x16x32_bf16 v[112:115], v[150:153], v[174:177], v[112:115]
	v_mfma_f32_16x16x32_bf16 v[104:107], v[158:161], v[174:177], v[104:107]
	v_mfma_f32_16x16x32_bf16 v[96:99], v[150:153], v[186:189], v[96:99]
	v_mfma_f32_16x16x32_bf16 v[88:91], v[158:161], v[186:189], v[88:91]
	v_mfma_f32_16x16x32_bf16 v[80:83], v[150:153], v[194:197], v[80:83]
	v_mfma_f32_16x16x32_bf16 v[72:75], v[158:161], v[194:197], v[72:75]
	v_mfma_f32_16x16x32_bf16 v[124:127], v[154:157], v[170:173], v[124:127]
	v_mfma_f32_16x16x32_bf16 v[120:123], v[162:165], v[170:173], v[120:123]
	v_mfma_f32_16x16x32_bf16 v[112:115], v[154:157], v[178:181], v[112:115]
	v_mfma_f32_16x16x32_bf16 v[104:107], v[162:165], v[178:181], v[104:107]
	v_mfma_f32_16x16x32_bf16 v[96:99], v[154:157], v[190:193], v[96:99]
	v_mfma_f32_16x16x32_bf16 v[88:91], v[162:165], v[190:193], v[88:91]
	v_mfma_f32_16x16x32_bf16 v[80:83], v[154:157], v[198:201], v[80:83]
	v_mfma_f32_16x16x32_bf16 v[72:75], v[162:165], v[198:201], v[72:75]
	s_setprio 0
	s_barrier
	s_add_i32 s33, s88, s5
	s_add_u32 s98, s62, s12
	s_addc_u32 s99, s63, s13
	s_mov_b32 m0, s33
	ds_read_b128 v[202:205], v148
	ds_read_b128 v[206:209], v148 offset:1024
	ds_read_b128 v[222:225], v148 offset:2048
	ds_read_b128 v[226:229], v148 offset:3072
	global_load_lds_dwordx4 v130, s[62:63]
	s_add_i32 m0, s33, 0x2000
	s_nop 0
	global_load_lds_dwordx4 v134, s[62:63]
	s_barrier
	s_waitcnt lgkmcnt(0)
	s_setprio 1
	s_waitcnt lgkmcnt(0)
	v_mfma_f32_16x16x32_bf16 v[116:119], v[202:205], v[166:169], v[116:119]
	v_mfma_f32_16x16x32_bf16 v[108:111], v[222:225], v[166:169], v[108:111]
	v_mfma_f32_16x16x32_bf16 v[100:103], v[202:205], v[174:177], v[100:103]
	v_mfma_f32_16x16x32_bf16 v[92:95], v[222:225], v[174:177], v[92:95]
	v_mfma_f32_16x16x32_bf16 v[84:87], v[202:205], v[186:189], v[84:87]
	v_mfma_f32_16x16x32_bf16 v[76:79], v[222:225], v[186:189], v[76:79]
	v_mfma_f32_16x16x32_bf16 v[68:71], v[202:205], v[194:197], v[68:71]
	v_mfma_f32_16x16x32_bf16 v[64:67], v[222:225], v[194:197], v[64:67]
	v_mfma_f32_16x16x32_bf16 v[116:119], v[206:209], v[170:173], v[116:119]
	v_mfma_f32_16x16x32_bf16 v[108:111], v[226:229], v[170:173], v[108:111]
	v_mfma_f32_16x16x32_bf16 v[100:103], v[206:209], v[178:181], v[100:103]
	v_mfma_f32_16x16x32_bf16 v[92:95], v[226:229], v[178:181], v[92:95]
	v_mfma_f32_16x16x32_bf16 v[84:87], v[206:209], v[190:193], v[84:87]
	v_mfma_f32_16x16x32_bf16 v[76:79], v[226:229], v[190:193], v[76:79]
	v_mfma_f32_16x16x32_bf16 v[68:71], v[206:209], v[198:201], v[68:71]
	v_mfma_f32_16x16x32_bf16 v[64:67], v[226:229], v[198:201], v[64:67]
	s_setprio 0
	s_mov_b32 m0, s16
	s_add_u32 s100, s66, s12
	s_addc_u32 s101, s67, s13
	s_barrier
	ds_read_b128 v[166:169], v147 offset:16384
	ds_read_b128 v[170:173], v147 offset:17408
	ds_read_b128 v[174:177], v147 offset:18432
	ds_read_b128 v[178:181], v147 offset:19456
	ds_read_b128 v[186:189], v147 offset:20480
	ds_read_b128 v[190:193], v147 offset:21504
	ds_read_b128 v[194:197], v147 offset:22528
	ds_read_b128 v[198:201], v147 offset:23552
	global_load_lds_dwordx4 v128, s[66:67]
	s_mov_b32 m0, s17
	s_nop 0
	global_load_lds_dwordx4 v132, s[66:67]
	s_barrier
	s_waitcnt lgkmcnt(0)
	s_setprio 1
	s_waitcnt lgkmcnt(0)
	v_mfma_f32_16x16x32_bf16 v[60:63], v[150:153], v[166:169], v[60:63]
	v_mfma_f32_16x16x32_bf16 v[56:59], v[158:161], v[166:169], v[56:59]
	v_mfma_f32_16x16x32_bf16 v[52:55], v[150:153], v[174:177], v[52:55]
	v_mfma_f32_16x16x32_bf16 v[44:47], v[158:161], v[174:177], v[44:47]
	v_mfma_f32_16x16x32_bf16 v[36:39], v[150:153], v[186:189], v[36:39]
	v_mfma_f32_16x16x32_bf16 v[28:31], v[158:161], v[186:189], v[28:31]
	v_mfma_f32_16x16x32_bf16 v[20:23], v[150:153], v[194:197], v[20:23]
	v_mfma_f32_16x16x32_bf16 v[12:15], v[158:161], v[194:197], v[12:15]
	v_mfma_f32_16x16x32_bf16 v[60:63], v[154:157], v[170:173], v[60:63]
	v_mfma_f32_16x16x32_bf16 v[56:59], v[162:165], v[170:173], v[56:59]
	v_mfma_f32_16x16x32_bf16 v[52:55], v[154:157], v[178:181], v[52:55]
	v_mfma_f32_16x16x32_bf16 v[44:47], v[162:165], v[178:181], v[44:47]
	v_mfma_f32_16x16x32_bf16 v[36:39], v[154:157], v[190:193], v[36:39]
	v_mfma_f32_16x16x32_bf16 v[28:31], v[162:165], v[190:193], v[28:31]
	v_mfma_f32_16x16x32_bf16 v[20:23], v[154:157], v[198:201], v[20:23]
	v_mfma_f32_16x16x32_bf16 v[12:15], v[162:165], v[198:201], v[12:15]
	s_setprio 0
	s_barrier
	s_add_u32 s72, s62, 0x80000
	s_addc_u32 s73, s63, 0
	s_add_i32 s33, s89, s5
	s_mov_b32 m0, s33
	s_nop 0
	global_load_lds_dwordx4 v130, s[72:73]
	s_add_i32 m0, s33, 0x2000
	s_nop 0
	global_load_lds_dwordx4 v134, s[72:73]
	s_waitcnt vmcnt(6)
	s_barrier
; #define PG8_STAGE(bufoff, gbase, voff) do { _Pragma("unroll") for (int _i = 0; _i < 2; ++_i) \
;         __builtin_amdgcn_global_load_lds((const unsigned*)((const char*)(gbase) + (voff)[_i]), (LAS unsigned*)(lds + (bufoff) + ldsw + _i * 8192), 16, 0, 0); } while (0)
; #define PG8_LDA(dst, b, h) do { _Pragma("unroll") for (int m = 0; m < 4; ++m) _Pragma("unroll") for (int k = 0; k < 2; ++k) dst[m][k] = *(const LAS bf16x8*)(lds + PG8_SA(b, h) + aoff + m * 2048 + k * 1024); } while (0)
; #define PG8_LDB(dst, b, h) do { _Pragma("unroll") for (int n = 0; n < 2; ++n) _Pragma("unroll") for (int k = 0; k < 2; ++k) dst[n][k] = *(const LAS bf16x8*)(lds + PG8_SB(b, h) + boff + n * 2048 + k * 1024); } while (0)
; #define PG8_MMA(ai, bj, At, Bt) do { __builtin_amdgcn_s_setprio(1); _Pragma("unroll") for (int m = 0; m < 4; ++m) _Pragma("unroll") for (int n = 0; n < 2; ++n) _Pragma("unroll") for (int k = 0; k < 2; ++k) \
;         acc[ai][bj][m][n] = __builtin_amdgcn_mfma_f32_16x16x32_bf16(Bt[n][k], At[m][k], acc[ai][bj][m][n], 0, 0, 0); __builtin_amdgcn_s_setprio(0); } while (0)
; #define PG8_WAIT_V(n) asm volatile("s_waitcnt vmcnt(" #n ")" ::: "memory")
; #define PG8_WAIT_L(n) asm volatile("s_waitcnt lgkmcnt(" #n ")" ::: "memory")
; #define PG8_BAR __builtin_amdgcn_s_barrier()
; #define PG8_SCHED __builtin_amdgcn_sched_barrier(0)
; template <class Epi, class S_t>
; __device__ __forceinline__ void gemm_phase(LAS unsigned char* lds, int lda, int ldb, const S_t& S, const Epi& E) {
;     ...
;             PG8_WAIT_V(6); PG8_BAR; PG8_MMA(1, 1, At, B1); PG8_BAR;
;             PG8_LDB(B0, 1, 0); PG8_SCHED; PG8_LDA(At, 1, 0); PG8_STAGE(PG8_SA(0, 1), a2 + hstepA, voffA);
;             PG8_WAIT_L(8); PG8_BAR; PG8_WAIT_L(0); PG8_MMA(0, 0, At, B0); PG8_BAR; PG8_SCHED;
;             PG8_LDB(B1, 1, 1); PG8_STAGE(PG8_SB(1, 0), b3, voffB);
;             PG8_BAR; PG8_WAIT_L(0); PG8_MMA(0, 1, At, B1); PG8_BAR;
;             PG8_LDA(At, 1, 1); PG8_STAGE(PG8_SA(1, 0), a3, voffA);
;             PG8_BAR; PG8_WAIT_L(0); PG8_MMA(1, 0, At, B0); PG8_BAR; PG8_SCHED;
	s_setprio 1
	v_mfma_f32_16x16x32_bf16 v[48:51], v[202:205], v[166:169], v[48:51]
	v_mfma_f32_16x16x32_bf16 v[40:43], v[222:225], v[166:169], v[40:43]
	v_mfma_f32_16x16x32_bf16 v[32:35], v[202:205], v[174:177], v[32:35]
	v_mfma_f32_16x16x32_bf16 v[24:27], v[222:225], v[174:177], v[24:27]
	v_mfma_f32_16x16x32_bf16 v[16:19], v[202:205], v[186:189], v[16:19]
	v_mfma_f32_16x16x32_bf16 v[8:11], v[222:225], v[186:189], v[8:11]
	v_mfma_f32_16x16x32_bf16 v[4:7], v[202:205], v[194:197], v[4:7]
	v_mfma_f32_16x16x32_bf16 v[0:3], v[222:225], v[194:197], v[0:3]
	v_mfma_f32_16x16x32_bf16 v[48:51], v[206:209], v[170:173], v[48:51]
	v_mfma_f32_16x16x32_bf16 v[40:43], v[226:229], v[170:173], v[40:43]
	v_mfma_f32_16x16x32_bf16 v[32:35], v[206:209], v[178:181], v[32:35]
	v_mfma_f32_16x16x32_bf16 v[24:27], v[226:229], v[178:181], v[24:27]
	v_mfma_f32_16x16x32_bf16 v[16:19], v[206:209], v[190:193], v[16:19]
	v_mfma_f32_16x16x32_bf16 v[8:11], v[226:229], v[190:193], v[8:11]
	v_mfma_f32_16x16x32_bf16 v[4:7], v[206:209], v[198:201], v[4:7]
	v_mfma_f32_16x16x32_bf16 v[0:3], v[226:229], v[198:201], v[0:3]
	s_setprio 0
	v_add_u32_e32 v149, s90, v143
	s_barrier
	ds_read_b128 v[150:153], v149
	ds_read_b128 v[154:157], v149 offset:1024
	ds_read_b128 v[158:161], v149 offset:2048
	ds_read_b128 v[162:165], v149 offset:3072
	s_add_u32 s66, s66, 0x80000
	s_addc_u32 s67, s67, 0
	s_mov_b32 m0, s20
	ds_read_b128 v[166:169], v147 offset:32768
	ds_read_b128 v[170:173], v147 offset:33792
	ds_read_b128 v[174:177], v147 offset:34816
	ds_read_b128 v[178:181], v147 offset:35840
	ds_read_b128 v[186:189], v147 offset:36864
	ds_read_b128 v[190:193], v147 offset:37888
	ds_read_b128 v[194:197], v147 offset:38912
	ds_read_b128 v[198:201], v147 offset:39936
	global_load_lds_dwordx4 v128, s[66:67]
	s_mov_b32 m0, s21
	s_nop 0
	global_load_lds_dwordx4 v132, s[66:67]
	s_waitcnt lgkmcnt(8)
	s_barrier
	s_waitcnt lgkmcnt(0)
	s_setprio 1
	s_waitcnt lgkmcnt(0)
	v_mfma_f32_16x16x32_bf16 v[124:127], v[150:153], v[166:169], v[124:127]
	v_mfma_f32_16x16x32_bf16 v[120:123], v[158:161], v[166:169], v[120:123]
	v_mfma_f32_16x16x32_bf16 v[112:115], v[150:153], v[174:177], v[112:115]
	v_mfma_f32_16x16x32_bf16 v[104:107], v[158:161], v[174:177], v[104:107]
	v_mfma_f32_16x16x32_bf16 v[96:99], v[150:153], v[186:189], v[96:99]
	v_mfma_f32_16x16x32_bf16 v[88:91], v[158:161], v[186:189], v[88:91]
	v_mfma_f32_16x16x32_bf16 v[80:83], v[150:153], v[194:197], v[80:83]
	v_mfma_f32_16x16x32_bf16 v[72:75], v[158:161], v[194:197], v[72:75]
	v_mfma_f32_16x16x32_bf16 v[124:127], v[154:157], v[170:173], v[124:127]
	v_mfma_f32_16x16x32_bf16 v[120:123], v[162:165], v[170:173], v[120:123]
	v_mfma_f32_16x16x32_bf16 v[112:115], v[154:157], v[178:181], v[112:115]
	v_mfma_f32_16x16x32_bf16 v[104:107], v[162:165], v[178:181], v[104:107]
	v_mfma_f32_16x16x32_bf16 v[96:99], v[154:157], v[190:193], v[96:99]
	v_mfma_f32_16x16x32_bf16 v[88:91], v[162:165], v[190:193], v[88:91]
	v_mfma_f32_16x16x32_bf16 v[80:83], v[154:157], v[198:201], v[80:83]
	v_mfma_f32_16x16x32_bf16 v[72:75], v[162:165], v[198:201], v[72:75]
	s_setprio 0
	s_barrier
	s_add_i32 s33, s90, s5
	v_add_u32_e32 v149, s91, v143
	s_mov_b32 m0, s33
	ds_read_b128 v[202:205], v149
	ds_read_b128 v[206:209], v149 offset:1024
	ds_read_b128 v[222:225], v149 offset:2048
	ds_read_b128 v[226:229], v149 offset:3072
	global_load_lds_dwordx4 v130, s[98:99]
	s_add_i32 m0, s33, 0x2000
	s_nop 0
	global_load_lds_dwordx4 v134, s[98:99]
	s_barrier
	s_waitcnt lgkmcnt(0)
	s_setprio 1
	s_waitcnt lgkmcnt(0)
	v_mfma_f32_16x16x32_bf16 v[116:119], v[202:205], v[166:169], v[116:119]
	v_mfma_f32_16x16x32_bf16 v[108:111], v[222:225], v[166:169], v[108:111]
	v_mfma_f32_16x16x32_bf16 v[100:103], v[202:205], v[174:177], v[100:103]
	v_mfma_f32_16x16x32_bf16 v[92:95], v[222:225], v[174:177], v[92:95]
	v_mfma_f32_16x16x32_bf16 v[84:87], v[202:205], v[186:189], v[84:87]
	v_mfma_f32_16x16x32_bf16 v[76:79], v[222:225], v[186:189], v[76:79]
	v_mfma_f32_16x16x32_bf16 v[68:71], v[202:205], v[194:197], v[68:71]
	v_mfma_f32_16x16x32_bf16 v[64:67], v[222:225], v[194:197], v[64:67]
	v_mfma_f32_16x16x32_bf16 v[116:119], v[206:209], v[170:173], v[116:119]
	v_mfma_f32_16x16x32_bf16 v[108:111], v[226:229], v[170:173], v[108:111]
	v_mfma_f32_16x16x32_bf16 v[100:103], v[206:209], v[178:181], v[100:103]
	v_mfma_f32_16x16x32_bf16 v[92:95], v[226:229], v[178:181], v[92:95]
	v_mfma_f32_16x16x32_bf16 v[84:87], v[206:209], v[190:193], v[84:87]
	v_mfma_f32_16x16x32_bf16 v[76:79], v[226:229], v[190:193], v[76:79]
	v_mfma_f32_16x16x32_bf16 v[68:71], v[206:209], v[198:201], v[68:71]
	v_mfma_f32_16x16x32_bf16 v[64:67], v[226:229], v[198:201], v[64:67]
	s_setprio 0
	s_mov_b32 m0, s35
	s_barrier
	ds_read_b128 v[166:169], v147 offset:49152
	ds_read_b128 v[170:173], v147 offset:50176
	ds_read_b128 v[174:177], v147 offset:51200
	ds_read_b128 v[178:181], v147 offset:52224
	ds_read_b128 v[186:189], v147 offset:53248
	ds_read_b128 v[190:193], v147 offset:54272
	ds_read_b128 v[194:197], v147 offset:55296
	ds_read_b128 v[198:201], v147 offset:56320
	global_load_lds_dwordx4 v128, s[100:101]
	s_mov_b32 m0, s52
	s_nop 0
	global_load_lds_dwordx4 v132, s[100:101]
	s_barrier
; #define PG8_STAGE(bufoff, gbase, voff) do { _Pragma("unroll") for (int _i = 0; _i < 2; ++_i) \
;         __builtin_amdgcn_global_load_lds((const unsigned*)((const char*)(gbase) + (voff)[_i]), (LAS unsigned*)(lds + (bufoff) + ldsw + _i * 8192), 16, 0, 0); } while (0)
; #define PG8_MMA(ai, bj, At, Bt) do { __builtin_amdgcn_s_setprio(1); _Pragma("unroll") for (int m = 0; m < 4; ++m) _Pragma("unroll") for (int n = 0; n < 2; ++n) _Pragma("unroll") for (int k = 0; k < 2; ++k) \
;         acc[ai][bj][m][n] = __builtin_amdgcn_mfma_f32_16x16x32_bf16(Bt[n][k], At[m][k], acc[ai][bj][m][n], 0, 0, 0); __builtin_amdgcn_s_setprio(0); } while (0)
; #define PG8_WAIT_V(n) asm volatile("s_waitcnt vmcnt(" #n ")" ::: "memory")
; #define PG8_BAR __builtin_amdgcn_s_barrier()
; template <class Epi, class S_t>
; __device__ __forceinline__ void gemm_phase(LAS unsigned char* lds, int lda, int ldb, const S_t& S, const Epi& E) {
;     ...
;             PG8_STAGE(PG8_SB(1, 1), b3 + hstepB, voffB);
;             PG8_WAIT_V(6); PG8_BAR; PG8_MMA(1, 1, At, B1); PG8_BAR;
;     __device__ __forceinline__ void operator()(const f32x4 (&acc)[2][2][4][2], const Unit& u, int wr, int wc, int fr, int fq) const {
;     ...
;             const int row0 = (u.pm - 32) * BM + wr * 64 + fr;
;             float* Op = Os + (size_t)(u.tag - 1) * (1024ull * DM);
; #pragma unroll
;             for (int ai = 0; ai < 2; ++ai)
; #pragma unroll
;                 for (int m = 0; m < 4; ++m) { float* rowp = Op + (size_t)(row0 + ai * HALF + m * 16) * DM + col0;
; #pragma unroll
;                     for (int bj = 0; bj < 2; ++bj)
; #pragma unroll
;                         for (int n = 0; n < 2; ++n) *(f32x4*)(rowp + bj * HALF + 4 * n) = acc[ai][bj][m][n]; }
	s_waitcnt lgkmcnt(0)
	s_setprio 1
	s_waitcnt lgkmcnt(0)
	v_mfma_f32_16x16x32_bf16 v[60:63], v[150:153], v[166:169], v[60:63]
	v_mfma_f32_16x16x32_bf16 v[56:59], v[158:161], v[166:169], v[56:59]
	v_mfma_f32_16x16x32_bf16 v[52:55], v[150:153], v[174:177], v[52:55]
	v_mfma_f32_16x16x32_bf16 v[44:47], v[158:161], v[174:177], v[44:47]
	v_mfma_f32_16x16x32_bf16 v[36:39], v[150:153], v[186:189], v[36:39]
	v_mfma_f32_16x16x32_bf16 v[28:31], v[158:161], v[186:189], v[28:31]
	v_mfma_f32_16x16x32_bf16 v[20:23], v[150:153], v[194:197], v[20:23]
	v_mfma_f32_16x16x32_bf16 v[12:15], v[158:161], v[194:197], v[12:15]
	v_mfma_f32_16x16x32_bf16 v[60:63], v[154:157], v[170:173], v[60:63]
	v_mfma_f32_16x16x32_bf16 v[56:59], v[162:165], v[170:173], v[56:59]
	v_mfma_f32_16x16x32_bf16 v[52:55], v[154:157], v[178:181], v[52:55]
	v_mfma_f32_16x16x32_bf16 v[44:47], v[162:165], v[178:181], v[44:47]
	v_mfma_f32_16x16x32_bf16 v[36:39], v[154:157], v[190:193], v[36:39]
	v_mfma_f32_16x16x32_bf16 v[28:31], v[162:165], v[190:193], v[28:31]
	v_mfma_f32_16x16x32_bf16 v[20:23], v[154:157], v[198:201], v[20:23]
	v_mfma_f32_16x16x32_bf16 v[12:15], v[162:165], v[198:201], v[12:15]
	s_setprio 0
	s_barrier
	s_add_u32 s62, s62, 0x80080
	s_addc_u32 s63, s63, 0
	s_add_i32 s33, s91, s5
	s_mov_b32 m0, s33
	s_nop 0
	global_load_lds_dwordx4 v130, s[62:63]
	s_add_i32 m0, s33, 0x2000
	s_nop 0
	global_load_lds_dwordx4 v134, s[62:63]
	s_waitcnt vmcnt(6)
	s_barrier
	s_setprio 1
	v_mfma_f32_16x16x32_bf16 v[48:51], v[202:205], v[166:169], v[48:51]
	v_mfma_f32_16x16x32_bf16 v[40:43], v[222:225], v[166:169], v[40:43]
	v_mfma_f32_16x16x32_bf16 v[32:35], v[202:205], v[174:177], v[32:35]
	v_mfma_f32_16x16x32_bf16 v[24:27], v[222:225], v[174:177], v[24:27]
	v_mfma_f32_16x16x32_bf16 v[16:19], v[202:205], v[186:189], v[16:19]
	v_mfma_f32_16x16x32_bf16 v[8:11], v[222:225], v[186:189], v[8:11]
	v_mfma_f32_16x16x32_bf16 v[4:7], v[202:205], v[194:197], v[4:7]
	v_mfma_f32_16x16x32_bf16 v[0:3], v[222:225], v[194:197], v[0:3]
	v_mfma_f32_16x16x32_bf16 v[48:51], v[206:209], v[170:173], v[48:51]
	v_mfma_f32_16x16x32_bf16 v[40:43], v[226:229], v[170:173], v[40:43]
	v_mfma_f32_16x16x32_bf16 v[32:35], v[206:209], v[178:181], v[32:35]
	v_mfma_f32_16x16x32_bf16 v[24:27], v[226:229], v[178:181], v[24:27]
	v_mfma_f32_16x16x32_bf16 v[16:19], v[206:209], v[190:193], v[16:19]
	v_mfma_f32_16x16x32_bf16 v[8:11], v[226:229], v[190:193], v[8:11]
	v_mfma_f32_16x16x32_bf16 v[4:7], v[206:209], v[198:201], v[4:7]
	v_mfma_f32_16x16x32_bf16 v[0:3], v[226:229], v[198:201], v[0:3]
	s_setprio 0
	s_add_u32 s60, s60, 0x100
	s_addc_u32 s61, s61, 0
	s_add_u32 s1, s1, 0x100
	s_addc_u32 s69, s69, 0
	s_cmp_ge_u32 s70, s42
	s_mov_b32 s62, s70
	s_barrier
	s_cbranch_scc0 .LBB0_1051
	v_lshl_or_b32 v140, s43, 8, v145
	s_lshl_b32 s33, s8, 8
	s_cmp_lg_u32 s68, 0
	v_ashrrev_i32_e32 v141, 31, v140
	s_cbranch_scc0 .LBB0_1054
	s_add_i32 s8, s68, -1
	s_lshl_b64 s[0:1], s[8:9], 23
	v_add_u32_e32 v150, s33, v144
	s_add_u32 s0, s10, s0
	v_or_b32_e32 v156, 16, v150
	s_addc_u32 s1, s11, s1
	v_ashrrev_i32_e32 v151, 31, v150
	v_ashrrev_i32_e32 v157, 31, v156
	v_lshl_add_u64 v[152:153], v[140:141], 2, s[0:1]
	v_lshlrev_b64 v[154:155], 13, v[150:151]
	v_lshlrev_b64 v[156:157], 13, v[156:157]
	v_lshl_add_u64 v[154:155], v[152:153], 0, v[154:155]
	v_lshl_add_u64 v[156:157], v[152:153], 0, v[156:157]
	global_store_dwordx4 v[154:155], v[124:127], off
	global_store_dwordx4 v[154:155], v[120:123], off offset:16
	global_store_dwordx4 v[154:155], v[116:119], off offset:512
	global_store_dwordx4 v[154:155], v[108:111], off offset:528
	global_store_dwordx4 v[156:157], v[112:115], off
	global_store_dwordx4 v[156:157], v[104:107], off offset:16
	global_store_dwordx4 v[156:157], v[100:103], off offset:512
	global_store_dwordx4 v[156:157], v[92:95], off offset:528
	v_or_b32_e32 v156, 32, v150
	v_or_b32_e32 v150, 48, v150
	v_ashrrev_i32_e32 v157, 31, v156
	v_ashrrev_i32_e32 v151, 31, v150
	v_lshlrev_b64 v[156:157], 13, v[156:157]
	v_lshlrev_b64 v[150:151], 13, v[150:151]
	v_lshl_add_u64 v[156:157], v[152:153], 0, v[156:157]
	v_lshl_add_u64 v[150:151], v[152:153], 0, v[150:151]
	s_mov_b64 s[0:1], 0x100000
	global_store_dwordx4 v[156:157], v[96:99], off
	global_store_dwordx4 v[156:157], v[88:91], off offset:16
	global_store_dwordx4 v[156:157], v[84:87], off offset:512
	global_store_dwordx4 v[156:157], v[76:79], off offset:528
	global_store_dwordx4 v[150:151], v[80:83], off
	global_store_dwordx4 v[150:151], v[72:75], off offset:16
	global_store_dwordx4 v[150:151], v[68:71], off offset:512
	global_store_dwordx4 v[150:151], v[64:67], off offset:528
	v_lshl_add_u64 v[150:151], v[154:155], 0, s[0:1]
	s_mov_b32 s0, 0x100000
	v_add_co_u32_e32 v152, vcc, s0, v154
	s_mov_b64 s[0:1], 0x120000
	s_nop 0
	v_addc_co_u32_e32 v153, vcc, 0, v155, vcc
	global_store_dwordx4 v[152:153], v[60:63], off
	global_store_dwordx4 v[150:151], v[56:59], off offset:16
	global_store_dwordx4 v[150:151], v[48:51], off offset:512
	global_store_dwordx4 v[150:151], v[40:43], off offset:528
	v_lshl_add_u64 v[150:151], v[154:155], 0, s[0:1]
	s_mov_b32 s0, 0x120000
	v_add_co_u32_e32 v152, vcc, s0, v154
	s_mov_b64 s[0:1], 0x140000
	s_nop 0
	v_addc_co_u32_e32 v153, vcc, 0, v155, vcc
	global_store_dwordx4 v[152:153], v[52:55], off
	global_store_dwordx4 v[150:151], v[44:47], off offset:16
	global_store_dwordx4 v[150:151], v[32:35], off offset:512
	global_store_dwordx4 v[150:151], v[24:27], off offset:528
	v_lshl_add_u64 v[150:151], v[154:155], 0, s[0:1]
	s_mov_b32 s0, 0x140000
	v_add_co_u32_e32 v152, vcc, s0, v154
	s_mov_b64 s[0:1], 0x160000
	s_nop 0
	v_addc_co_u32_e32 v153, vcc, 0, v155, vcc
	global_store_dwordx4 v[152:153], v[36:39], off
	global_store_dwordx4 v[150:151], v[28:31], off offset:16
	global_store_dwordx4 v[150:151], v[16:19], off offset:512
	global_store_dwordx4 v[150:151], v[8:11], off offset:528
	v_add_co_u32_e32 v152, vcc, 0x160000, v154
	v_lshl_add_u64 v[150:151], v[154:155], 0, s[0:1]
	s_nop 0
	v_addc_co_u32_e32 v153, vcc, 0, v155, vcc
	global_store_dwordx4 v[152:153], v[20:23], off
	global_store_dwordx4 v[150:151], v[12:15], off offset:16
	global_store_dwordx4 v[150:151], v[4:7], off offset:512
	global_store_dwordx4 v[150:151], v[0:3], off offset:528
	s_cbranch_execnz .LBB0_1047
	s_branch .LBB0_1046

; #define PG8_STAGE(bufoff, gbase, voff) do { _Pragma("unroll") for (int _i = 0; _i < 2; ++_i) \
;         __builtin_amdgcn_global_load_lds((const unsigned*)((const char*)(gbase) + (voff)[_i]), (LAS unsigned*)(lds + (bufoff) + ldsw + _i * 8192), 16, 0, 0); } while (0)
; #define PG8_LDA(dst, b, h) do { _Pragma("unroll") for (int m = 0; m < 4; ++m) _Pragma("unroll") for (int k = 0; k < 2; ++k) dst[m][k] = *(const LAS bf16x8*)(lds + PG8_SA(b, h) + aoff + m * 2048 + k * 1024); } while (0)
; #define PG8_LDB(dst, b, h) do { _Pragma("unroll") for (int n = 0; n < 2; ++n) _Pragma("unroll") for (int k = 0; k < 2; ++k) dst[n][k] = *(const LAS bf16x8*)(lds + PG8_SB(b, h) + boff + n * 2048 + k * 1024); } while (0)
; #define PG8_MMA(ai, bj, At, Bt) do { __builtin_amdgcn_s_setprio(1); _Pragma("unroll") for (int m = 0; m < 4; ++m) _Pragma("unroll") for (int n = 0; n < 2; ++n) _Pragma("unroll") for (int k = 0; k < 2; ++k) \
;         acc[ai][bj][m][n] = __builtin_amdgcn_mfma_f32_16x16x32_bf16(Bt[n][k], At[m][k], acc[ai][bj][m][n], 0, 0, 0); __builtin_amdgcn_s_setprio(0); } while (0)
; #define PG8_WAIT_V(n) asm volatile("s_waitcnt vmcnt(" #n ")" ::: "memory")
; #define PG8_WAIT_L(n) asm volatile("s_waitcnt lgkmcnt(" #n ")" ::: "memory")
; #define PG8_BAR __builtin_amdgcn_s_barrier()
; #define PG8_SCHED __builtin_amdgcn_sched_barrier(0)
; template <class Epi, class S_t>
; __device__ __forceinline__ void gemm_phase(LAS unsigned char* lds, int lda, int ldb, const S_t& S, const Epi& E) {
;     ...
;             PG8_LDB(B0, 0, 0); PG8_SCHED; PG8_LDA(At, 0, 0); PG8_STAGE(PG8_SA(1, 1), a1 + hstepA, voffA);
;             PG8_WAIT_L(8); PG8_BAR; PG8_WAIT_L(0); PG8_MMA(0, 0, At, B0); PG8_BAR; PG8_SCHED;
;             PG8_LDB(B1, 0, 1); PG8_STAGE(PG8_SB(0, 0), b2, voffB);
;             PG8_BAR; PG8_WAIT_L(0); PG8_MMA(0, 1, At, B1); PG8_BAR;
;             PG8_LDA(At, 0, 1); PG8_STAGE(PG8_SA(0, 0), a2, voffA);
;             PG8_BAR; PG8_WAIT_L(0); PG8_MMA(1, 0, At, B0); PG8_BAR; PG8_SCHED;
;             PG8_STAGE(PG8_SB(0, 1), b2 + hstepB, voffB);
;             PG8_WAIT_V(6); PG8_BAR; PG8_MMA(1, 1, At, B1); PG8_BAR;
.LBB0_1200:
	ds_read_b128 v[128:131], v223
	ds_read_b128 v[132:135], v223 offset:1024
	ds_read_b128 v[136:139], v223 offset:2048
	ds_read_b128 v[140:143], v223 offset:3072
	s_add_u32 s33, s74, 0xfff80080
	s_addc_u32 s43, s75, -1
	s_cmp_eq_u32 s5, 28
	s_cselect_b32 s79, s69, s43
	s_cselect_b32 s78, s68, s33
	s_cselect_b32 s77, s71, s1
	s_cselect_b32 s76, s70, s0
	s_add_i32 m0, s7, 0xc000
	ds_read_b128 v[144:147], v246
	ds_read_b128 v[148:151], v246 offset:1024
	ds_read_b128 v[152:155], v246 offset:2048
	ds_read_b128 v[156:159], v246 offset:3072
	ds_read_b128 v[160:163], v246 offset:4096
	ds_read_b128 v[164:167], v246 offset:5120
	ds_read_b128 v[168:171], v246 offset:6144
	ds_read_b128 v[172:175], v246 offset:7168
	global_load_lds_dwordx4 v236, s[74:75]
	s_add_i32 m0, s7, 0xe000
	s_nop 0
	global_load_lds_dwordx4 v238, s[74:75]
	s_waitcnt lgkmcnt(8)
	s_barrier
	s_waitcnt lgkmcnt(0)
	s_setprio 1
	s_waitcnt lgkmcnt(0)
	v_mfma_f32_16x16x32_bf16 v[124:127], v[128:131], v[144:147], v[124:127]
	v_mfma_f32_16x16x32_bf16 v[120:123], v[136:139], v[144:147], v[120:123]
	v_mfma_f32_16x16x32_bf16 v[116:119], v[128:131], v[152:155], v[116:119]
	v_mfma_f32_16x16x32_bf16 v[108:111], v[136:139], v[152:155], v[108:111]
	v_mfma_f32_16x16x32_bf16 v[100:103], v[128:131], v[160:163], v[100:103]
	v_mfma_f32_16x16x32_bf16 v[92:95], v[136:139], v[160:163], v[92:95]
	v_mfma_f32_16x16x32_bf16 v[84:87], v[128:131], v[168:171], v[84:87]
	v_mfma_f32_16x16x32_bf16 v[76:79], v[136:139], v[168:171], v[76:79]
	v_mfma_f32_16x16x32_bf16 v[124:127], v[132:135], v[148:151], v[124:127]
	v_mfma_f32_16x16x32_bf16 v[120:123], v[140:143], v[148:151], v[120:123]
	v_mfma_f32_16x16x32_bf16 v[116:119], v[132:135], v[156:159], v[116:119]
	v_mfma_f32_16x16x32_bf16 v[108:111], v[140:143], v[156:159], v[108:111]
	v_mfma_f32_16x16x32_bf16 v[100:103], v[132:135], v[164:167], v[100:103]
	v_mfma_f32_16x16x32_bf16 v[92:95], v[140:143], v[164:167], v[92:95]
	v_mfma_f32_16x16x32_bf16 v[84:87], v[132:135], v[172:175], v[84:87]
	v_mfma_f32_16x16x32_bf16 v[76:79], v[140:143], v[172:175], v[76:79]
	s_setprio 0
	s_barrier
	s_add_i32 s33, s88, s64
	s_add_u32 s98, s76, s38
	s_addc_u32 s99, s77, s39
	s_mov_b32 m0, s33
	ds_read_b128 v[176:179], v247
	ds_read_b128 v[180:183], v247 offset:1024
	ds_read_b128 v[184:187], v247 offset:2048
	ds_read_b128 v[188:191], v247 offset:3072
	global_load_lds_dwordx4 v228, s[76:77]
	s_add_i32 m0, s33, 0x2000
	s_nop 0
	global_load_lds_dwordx4 v224, s[76:77]
	s_barrier
	s_waitcnt lgkmcnt(0)
	s_setprio 1
	s_waitcnt lgkmcnt(0)
	v_mfma_f32_16x16x32_bf16 v[112:115], v[176:179], v[144:147], v[112:115]
	v_mfma_f32_16x16x32_bf16 v[104:107], v[184:187], v[144:147], v[104:107]
	v_mfma_f32_16x16x32_bf16 v[96:99], v[176:179], v[152:155], v[96:99]
	v_mfma_f32_16x16x32_bf16 v[88:91], v[184:187], v[152:155], v[88:91]
	v_mfma_f32_16x16x32_bf16 v[80:83], v[176:179], v[160:163], v[80:83]
	v_mfma_f32_16x16x32_bf16 v[72:75], v[184:187], v[160:163], v[72:75]
	v_mfma_f32_16x16x32_bf16 v[68:71], v[176:179], v[168:171], v[68:71]
	v_mfma_f32_16x16x32_bf16 v[64:67], v[184:187], v[168:171], v[64:67]
	v_mfma_f32_16x16x32_bf16 v[112:115], v[180:183], v[148:151], v[112:115]
	v_mfma_f32_16x16x32_bf16 v[104:107], v[188:191], v[148:151], v[104:107]
	v_mfma_f32_16x16x32_bf16 v[96:99], v[180:183], v[156:159], v[96:99]
	v_mfma_f32_16x16x32_bf16 v[88:91], v[188:191], v[156:159], v[88:91]
	v_mfma_f32_16x16x32_bf16 v[80:83], v[180:183], v[164:167], v[80:83]
	v_mfma_f32_16x16x32_bf16 v[72:75], v[188:191], v[164:167], v[72:75]
	v_mfma_f32_16x16x32_bf16 v[68:71], v[180:183], v[172:175], v[68:71]
	v_mfma_f32_16x16x32_bf16 v[64:67], v[188:191], v[172:175], v[64:67]
	s_setprio 0
	s_mov_b32 m0, s7
	s_add_u32 s100, s78, s38
	s_addc_u32 s101, s79, s39
	s_barrier
	ds_read_b128 v[144:147], v246 offset:16384
	ds_read_b128 v[148:151], v246 offset:17408
	ds_read_b128 v[152:155], v246 offset:18432
	ds_read_b128 v[156:159], v246 offset:19456
	ds_read_b128 v[160:163], v246 offset:20480
	ds_read_b128 v[164:167], v246 offset:21504
	ds_read_b128 v[168:171], v246 offset:22528
	ds_read_b128 v[172:175], v246 offset:23552
	global_load_lds_dwordx4 v230, s[78:79]
	s_mov_b32 m0, s35
	s_nop 0
	global_load_lds_dwordx4 v226, s[78:79]
	s_barrier
	s_waitcnt lgkmcnt(0)
	s_setprio 1
	s_waitcnt lgkmcnt(0)
	v_mfma_f32_16x16x32_bf16 v[60:63], v[128:131], v[144:147], v[60:63]
	v_mfma_f32_16x16x32_bf16 v[56:59], v[136:139], v[144:147], v[56:59]
	v_mfma_f32_16x16x32_bf16 v[52:55], v[128:131], v[152:155], v[52:55]
	v_mfma_f32_16x16x32_bf16 v[44:47], v[136:139], v[152:155], v[44:47]
	v_mfma_f32_16x16x32_bf16 v[36:39], v[128:131], v[160:163], v[36:39]
	v_mfma_f32_16x16x32_bf16 v[28:31], v[136:139], v[160:163], v[28:31]
	v_mfma_f32_16x16x32_bf16 v[20:23], v[128:131], v[168:171], v[20:23]
	v_mfma_f32_16x16x32_bf16 v[12:15], v[136:139], v[168:171], v[12:15]
	v_mfma_f32_16x16x32_bf16 v[60:63], v[132:135], v[148:151], v[60:63]
	v_mfma_f32_16x16x32_bf16 v[56:59], v[140:143], v[148:151], v[56:59]
	v_mfma_f32_16x16x32_bf16 v[52:55], v[132:135], v[156:159], v[52:55]
	v_mfma_f32_16x16x32_bf16 v[44:47], v[140:143], v[156:159], v[44:47]
	v_mfma_f32_16x16x32_bf16 v[36:39], v[132:135], v[164:167], v[36:39]
	v_mfma_f32_16x16x32_bf16 v[28:31], v[140:143], v[164:167], v[28:31]
	v_mfma_f32_16x16x32_bf16 v[20:23], v[132:135], v[172:175], v[20:23]
	v_mfma_f32_16x16x32_bf16 v[12:15], v[140:143], v[172:175], v[12:15]
	s_setprio 0
	s_barrier
	s_add_u32 s52, s76, 0x80000
	s_addc_u32 s53, s77, 0
	s_add_i32 s33, s89, s64
	s_mov_b32 m0, s33
	s_nop 0
	global_load_lds_dwordx4 v228, s[52:53]
	s_add_i32 m0, s33, 0x2000
	s_nop 0
	global_load_lds_dwordx4 v224, s[52:53]
	s_waitcnt vmcnt(6)
	s_barrier
; #define PG8_STAGE(bufoff, gbase, voff) do { _Pragma("unroll") for (int _i = 0; _i < 2; ++_i) \
;         __builtin_amdgcn_global_load_lds((const unsigned*)((const char*)(gbase) + (voff)[_i]), (LAS unsigned*)(lds + (bufoff) + ldsw + _i * 8192), 16, 0, 0); } while (0)
; #define PG8_LDA(dst, b, h) do { _Pragma("unroll") for (int m = 0; m < 4; ++m) _Pragma("unroll") for (int k = 0; k < 2; ++k) dst[m][k] = *(const LAS bf16x8*)(lds + PG8_SA(b, h) + aoff + m * 2048 + k * 1024); } while (0)
; #define PG8_LDB(dst, b, h) do { _Pragma("unroll") for (int n = 0; n < 2; ++n) _Pragma("unroll") for (int k = 0; k < 2; ++k) dst[n][k] = *(const LAS bf16x8*)(lds + PG8_SB(b, h) + boff + n * 2048 + k * 1024); } while (0)
; #define PG8_MMA(ai, bj, At, Bt) do { __builtin_amdgcn_s_setprio(1); _Pragma("unroll") for (int m = 0; m < 4; ++m) _Pragma("unroll") for (int n = 0; n < 2; ++n) _Pragma("unroll") for (int k = 0; k < 2; ++k) \
;         acc[ai][bj][m][n] = __builtin_amdgcn_mfma_f32_16x16x32_bf16(Bt[n][k], At[m][k], acc[ai][bj][m][n], 0, 0, 0); __builtin_amdgcn_s_setprio(0); } while (0)
; #define PG8_WAIT_V(n) asm volatile("s_waitcnt vmcnt(" #n ")" ::: "memory")
; #define PG8_WAIT_L(n) asm volatile("s_waitcnt lgkmcnt(" #n ")" ::: "memory")
; #define PG8_BAR __builtin_amdgcn_s_barrier()
; #define PG8_SCHED __builtin_amdgcn_sched_barrier(0)
; template <class Epi, class S_t>
; __device__ __forceinline__ void gemm_phase(LAS unsigned char* lds, int lda, int ldb, const S_t& S, const Epi& E) {
;     ...
;             PG8_WAIT_V(6); PG8_BAR; PG8_MMA(1, 1, At, B1); PG8_BAR;
;             PG8_LDB(B0, 1, 0); PG8_SCHED; PG8_LDA(At, 1, 0); PG8_STAGE(PG8_SA(0, 1), a2 + hstepA, voffA);
;             PG8_WAIT_L(8); PG8_BAR; PG8_WAIT_L(0); PG8_MMA(0, 0, At, B0); PG8_BAR; PG8_SCHED;
;             PG8_LDB(B1, 1, 1); PG8_STAGE(PG8_SB(1, 0), b3, voffB);
;             PG8_BAR; PG8_WAIT_L(0); PG8_MMA(0, 1, At, B1); PG8_BAR;
;             PG8_LDA(At, 1, 1); PG8_STAGE(PG8_SA(1, 0), a3, voffA);
;             PG8_BAR; PG8_WAIT_L(0); PG8_MMA(1, 0, At, B0); PG8_BAR; PG8_SCHED;
	s_setprio 1
	v_mfma_f32_16x16x32_bf16 v[48:51], v[176:179], v[144:147], v[48:51]
	v_mfma_f32_16x16x32_bf16 v[40:43], v[184:187], v[144:147], v[40:43]
	v_mfma_f32_16x16x32_bf16 v[32:35], v[176:179], v[152:155], v[32:35]
	v_mfma_f32_16x16x32_bf16 v[24:27], v[184:187], v[152:155], v[24:27]
	v_mfma_f32_16x16x32_bf16 v[16:19], v[176:179], v[160:163], v[16:19]
	v_mfma_f32_16x16x32_bf16 v[8:11], v[184:187], v[160:163], v[8:11]
	v_mfma_f32_16x16x32_bf16 v[4:7], v[176:179], v[168:171], v[4:7]
	v_mfma_f32_16x16x32_bf16 v[0:3], v[184:187], v[168:171], v[0:3]
	v_mfma_f32_16x16x32_bf16 v[48:51], v[180:183], v[148:151], v[48:51]
	v_mfma_f32_16x16x32_bf16 v[40:43], v[188:191], v[148:151], v[40:43]
	v_mfma_f32_16x16x32_bf16 v[32:35], v[180:183], v[156:159], v[32:35]
	v_mfma_f32_16x16x32_bf16 v[24:27], v[188:191], v[156:159], v[24:27]
	v_mfma_f32_16x16x32_bf16 v[16:19], v[180:183], v[164:167], v[16:19]
	v_mfma_f32_16x16x32_bf16 v[8:11], v[188:191], v[164:167], v[8:11]
	v_mfma_f32_16x16x32_bf16 v[4:7], v[180:183], v[172:175], v[4:7]
	v_mfma_f32_16x16x32_bf16 v[0:3], v[188:191], v[172:175], v[0:3]
	s_setprio 0
	v_add_u32_e32 v140, s90, v215
	s_barrier
	ds_read_b128 v[128:131], v140
	ds_read_b128 v[132:135], v140 offset:1024
	ds_read_b128 v[136:139], v140 offset:2048
	ds_read_b128 v[140:143], v140 offset:3072
	s_add_u32 s52, s78, 0x80000
	s_addc_u32 s53, s79, 0
	s_mov_b32 m0, s92
	ds_read_b128 v[144:147], v246 offset:32768
	ds_read_b128 v[148:151], v246 offset:33792
	ds_read_b128 v[152:155], v246 offset:34816
	ds_read_b128 v[156:159], v246 offset:35840
	ds_read_b128 v[160:163], v246 offset:36864
	ds_read_b128 v[164:167], v246 offset:37888
	ds_read_b128 v[168:171], v246 offset:38912
	ds_read_b128 v[172:175], v246 offset:39936
	global_load_lds_dwordx4 v230, s[52:53]
	s_mov_b32 m0, s50
	s_nop 0
	global_load_lds_dwordx4 v226, s[52:53]
	s_waitcnt lgkmcnt(8)
	s_barrier
	s_waitcnt lgkmcnt(0)
	s_setprio 1
	s_waitcnt lgkmcnt(0)
	v_mfma_f32_16x16x32_bf16 v[124:127], v[128:131], v[144:147], v[124:127]
	v_mfma_f32_16x16x32_bf16 v[120:123], v[136:139], v[144:147], v[120:123]
	v_mfma_f32_16x16x32_bf16 v[116:119], v[128:131], v[152:155], v[116:119]
	v_mfma_f32_16x16x32_bf16 v[108:111], v[136:139], v[152:155], v[108:111]
	v_mfma_f32_16x16x32_bf16 v[100:103], v[128:131], v[160:163], v[100:103]
	v_mfma_f32_16x16x32_bf16 v[92:95], v[136:139], v[160:163], v[92:95]
	v_mfma_f32_16x16x32_bf16 v[84:87], v[128:131], v[168:171], v[84:87]
	v_mfma_f32_16x16x32_bf16 v[76:79], v[136:139], v[168:171], v[76:79]
	v_mfma_f32_16x16x32_bf16 v[124:127], v[132:135], v[148:151], v[124:127]
	v_mfma_f32_16x16x32_bf16 v[120:123], v[140:143], v[148:151], v[120:123]
	v_mfma_f32_16x16x32_bf16 v[116:119], v[132:135], v[156:159], v[116:119]
	v_mfma_f32_16x16x32_bf16 v[108:111], v[140:143], v[156:159], v[108:111]
	v_mfma_f32_16x16x32_bf16 v[100:103], v[132:135], v[164:167], v[100:103]
	v_mfma_f32_16x16x32_bf16 v[92:95], v[140:143], v[164:167], v[92:95]
	v_mfma_f32_16x16x32_bf16 v[84:87], v[132:135], v[172:175], v[84:87]
	v_mfma_f32_16x16x32_bf16 v[76:79], v[140:143], v[172:175], v[76:79]
	s_setprio 0
	s_barrier
	s_add_i32 s33, s90, s64
	v_add_u32_e32 v188, s91, v215
	s_mov_b32 m0, s33
	ds_read_b128 v[176:179], v188
	ds_read_b128 v[180:183], v188 offset:1024
	ds_read_b128 v[184:187], v188 offset:2048
	ds_read_b128 v[188:191], v188 offset:3072
	global_load_lds_dwordx4 v228, s[98:99]
	s_add_i32 m0, s33, 0x2000
	s_nop 0
	global_load_lds_dwordx4 v224, s[98:99]
	s_barrier
	s_waitcnt lgkmcnt(0)
	s_setprio 1
	s_waitcnt lgkmcnt(0)
	v_mfma_f32_16x16x32_bf16 v[112:115], v[176:179], v[144:147], v[112:115]
	v_mfma_f32_16x16x32_bf16 v[104:107], v[184:187], v[144:147], v[104:107]
	v_mfma_f32_16x16x32_bf16 v[96:99], v[176:179], v[152:155], v[96:99]
	v_mfma_f32_16x16x32_bf16 v[88:91], v[184:187], v[152:155], v[88:91]
	v_mfma_f32_16x16x32_bf16 v[80:83], v[176:179], v[160:163], v[80:83]
	v_mfma_f32_16x16x32_bf16 v[72:75], v[184:187], v[160:163], v[72:75]
	v_mfma_f32_16x16x32_bf16 v[68:71], v[176:179], v[168:171], v[68:71]
	v_mfma_f32_16x16x32_bf16 v[64:67], v[184:187], v[168:171], v[64:67]
	v_mfma_f32_16x16x32_bf16 v[112:115], v[180:183], v[148:151], v[112:115]
	v_mfma_f32_16x16x32_bf16 v[104:107], v[188:191], v[148:151], v[104:107]
	v_mfma_f32_16x16x32_bf16 v[96:99], v[180:183], v[156:159], v[96:99]
	v_mfma_f32_16x16x32_bf16 v[88:91], v[188:191], v[156:159], v[88:91]
	v_mfma_f32_16x16x32_bf16 v[80:83], v[180:183], v[164:167], v[80:83]
	v_mfma_f32_16x16x32_bf16 v[72:75], v[188:191], v[164:167], v[72:75]
	v_mfma_f32_16x16x32_bf16 v[68:71], v[180:183], v[172:175], v[68:71]
	v_mfma_f32_16x16x32_bf16 v[64:67], v[188:191], v[172:175], v[64:67]
	s_setprio 0
	s_mov_b32 m0, s96
	s_barrier
	ds_read_b128 v[144:147], v246 offset:49152
	ds_read_b128 v[148:151], v246 offset:50176
	ds_read_b128 v[152:155], v246 offset:51200
	ds_read_b128 v[156:159], v246 offset:52224
	ds_read_b128 v[160:163], v246 offset:53248
	ds_read_b128 v[164:167], v246 offset:54272
	ds_read_b128 v[168:171], v246 offset:55296
	ds_read_b128 v[172:175], v246 offset:56320
	global_load_lds_dwordx4 v230, s[100:101]
	s_mov_b32 m0, s97
	s_nop 0
	global_load_lds_dwordx4 v226, s[100:101]
	s_barrier
; __device__ __forceinline__ unsigned pk2(float lo, float hi) { unsigned r; asm("v_cvt_pk_bf16_f32 %0, %1, %2" : "=v"(r) : "v"(lo), "v"(hi)); return r; }
; #define PG8_WAIT_V(n) asm volatile("s_waitcnt vmcnt(" #n ")" ::: "memory")
; #define PG8_BAR __builtin_amdgcn_s_barrier()
; template <class Epi, class S_t>
; __device__ __forceinline__ void gemm_phase(LAS unsigned char* lds, int lda, int ldb, const S_t& S, const Epi& E) {
;     ...
;             PG8_STAGE(PG8_SB(1, 1), b3 + hstepB, voffB);
;             PG8_WAIT_V(6); PG8_BAR; PG8_MMA(1, 1, At, B1); PG8_BAR;
;     __device__ __forceinline__ void operator()(const f32x4 (&acc)[2][2][4][2], const Unit& u, int wr, int wc, int fr, int fq) const {
;     ...
;         if (u.pm >= 32) {
; #pragma unroll
;             for (int ai = 0; ai < 2; ++ai)
; #pragma unroll
;                 for (int m = 0; m < 4; ++m) { bf16_t* rowp = UP + (size_t)(row0 + ai * HALF + m * 16) * (2 * DFF) + col0;
; #pragma unroll
;                     for (int bj = 0; bj < 2; ++bj) { const f32x4 v0 = acc[ai][bj][m][0], v1 = acc[ai][bj][m][1];
;                         u32x4 w; w.x = pk2(v0[0], v0[1]); w.y = pk2(v0[2], v0[3]); w.z = pk2(v1[0], v1[1]); w.w = pk2(v1[2], v1[3]);
;                         *(u32x4*)(rowp + bj * HALF) = w; } }
;             return;
;         }
;         const int j0 = u.pn * HALF + wc * 32 + 8 * fq;
;         u32x2 res0[8];
; #pragma unroll
;         for (int n = 0; n < 2; ++n) {
;             asm volatile("" ::: "memory");
;             const int jc = j0 + 4 * n;
;             const f32x4 wg0 = *(const f32x4*)(wconv + jc), wg1 = *(const f32x4*)(wconv + 2 * DFF + jc), wg2 = *(const f32x4*)(wconv + 4 * DFF + jc), bg = *(const f32x4*)(bconv + jc);
;             const f32x4 wv0 = *(const f32x4*)(wconv + DFF + jc), wv1 = *(const f32x4*)(wconv + 3 * DFF + jc), wv2 = *(const f32x4*)(wconv + 5 * DFF + jc), bv = *(const f32x4*)(bconv + DFF + jc);
; #pragma unroll
;             for (int ai = 0; ai < 2; ++ai)
; #pragma unroll
;                 for (int m = 0; m < 4; ++m) { const int row = row0 + ai * HALF + m * 16;
;                     const f32x4 g0 = acc[ai][0][m][n], v0 = acc[ai][1][m][n];
;                     f32x4 gp = (f32x4){0.f, 0.f, 0.f, 0.f}, vp = gp;
;                     if (m > 0) { gp = acc[ai][0][m > 0 ? m - 1 : 0][n]; vp = acc[ai][1][m > 0 ? m - 1 : 0][n]; }
	s_waitcnt lgkmcnt(0)
	s_setprio 1
	s_waitcnt lgkmcnt(0)
	v_mfma_f32_16x16x32_bf16 v[60:63], v[128:131], v[144:147], v[60:63]
	v_mfma_f32_16x16x32_bf16 v[56:59], v[136:139], v[144:147], v[56:59]
	v_mfma_f32_16x16x32_bf16 v[52:55], v[128:131], v[152:155], v[52:55]
	v_mfma_f32_16x16x32_bf16 v[44:47], v[136:139], v[152:155], v[44:47]
	v_mfma_f32_16x16x32_bf16 v[36:39], v[128:131], v[160:163], v[36:39]
	v_mfma_f32_16x16x32_bf16 v[28:31], v[136:139], v[160:163], v[28:31]
	v_mfma_f32_16x16x32_bf16 v[20:23], v[128:131], v[168:171], v[20:23]
	v_mfma_f32_16x16x32_bf16 v[12:15], v[136:139], v[168:171], v[12:15]
	v_mfma_f32_16x16x32_bf16 v[60:63], v[132:135], v[148:151], v[60:63]
	v_mfma_f32_16x16x32_bf16 v[56:59], v[140:143], v[148:151], v[56:59]
	v_mfma_f32_16x16x32_bf16 v[52:55], v[132:135], v[156:159], v[52:55]
	v_mfma_f32_16x16x32_bf16 v[44:47], v[140:143], v[156:159], v[44:47]
	v_mfma_f32_16x16x32_bf16 v[36:39], v[132:135], v[164:167], v[36:39]
	v_mfma_f32_16x16x32_bf16 v[28:31], v[140:143], v[164:167], v[28:31]
	v_mfma_f32_16x16x32_bf16 v[20:23], v[132:135], v[172:175], v[20:23]
	v_mfma_f32_16x16x32_bf16 v[12:15], v[140:143], v[172:175], v[12:15]
	s_setprio 0
	s_barrier
	s_add_u32 s52, s76, 0x80080
	s_addc_u32 s53, s77, 0
	s_add_i32 s33, s91, s64
	s_mov_b32 m0, s33
	s_nop 0
	global_load_lds_dwordx4 v228, s[52:53]
	s_add_i32 m0, s33, 0x2000
	s_nop 0
	global_load_lds_dwordx4 v224, s[52:53]
	s_waitcnt vmcnt(6)
	s_barrier
	s_setprio 1
	v_mfma_f32_16x16x32_bf16 v[48:51], v[176:179], v[144:147], v[48:51]
	v_mfma_f32_16x16x32_bf16 v[40:43], v[184:187], v[144:147], v[40:43]
	v_mfma_f32_16x16x32_bf16 v[32:35], v[176:179], v[152:155], v[32:35]
	v_mfma_f32_16x16x32_bf16 v[24:27], v[184:187], v[152:155], v[24:27]
	v_mfma_f32_16x16x32_bf16 v[16:19], v[176:179], v[160:163], v[16:19]
	v_mfma_f32_16x16x32_bf16 v[8:11], v[184:187], v[160:163], v[8:11]
	v_mfma_f32_16x16x32_bf16 v[4:7], v[176:179], v[168:171], v[4:7]
	v_mfma_f32_16x16x32_bf16 v[0:3], v[184:187], v[168:171], v[0:3]
	v_mfma_f32_16x16x32_bf16 v[48:51], v[180:183], v[148:151], v[48:51]
	v_mfma_f32_16x16x32_bf16 v[40:43], v[188:191], v[148:151], v[40:43]
	v_mfma_f32_16x16x32_bf16 v[32:35], v[180:183], v[156:159], v[32:35]
	v_mfma_f32_16x16x32_bf16 v[24:27], v[188:191], v[156:159], v[24:27]
	v_mfma_f32_16x16x32_bf16 v[16:19], v[180:183], v[164:167], v[16:19]
	v_mfma_f32_16x16x32_bf16 v[8:11], v[188:191], v[164:167], v[8:11]
	v_mfma_f32_16x16x32_bf16 v[4:7], v[180:183], v[172:175], v[4:7]
	v_mfma_f32_16x16x32_bf16 v[0:3], v[188:191], v[172:175], v[0:3]
	s_setprio 0
	s_add_i32 s5, s5, 2
	s_add_u32 s74, s74, 0x100
	s_addc_u32 s75, s75, 0
	s_add_u32 s0, s0, 0x100
	s_addc_u32 s1, s1, 0
	s_cmp_gt_u32 s5, 29
	s_barrier
	s_cbranch_scc0 .LBB0_1200
	s_lshl_b32 s5, s72, 8
	s_add_i32 s5, s5, s95
	v_or_b32_e32 v248, s5, v232
	s_cmp_lt_i32 s72, 32
	v_lshl_or_b32 v240, s42, 8, v219
	s_cbranch_scc0 .LBB0_1215
	v_lshl_or_b32 v130, s42, 7, v219
	v_ashrrev_i32_e32 v131, 31, v130
	v_readlane_b32 s16, v254, 33
	v_lshlrev_b64 v[128:129], 2, v[130:131]
	v_readlane_b32 s26, v254, 43
	v_readlane_b32 s27, v254, 44
	v_lshl_add_u64 v[132:133], s[46:47], 0, v[128:129]
	v_readlane_b32 s24, v254, 41
	v_readlane_b32 s25, v254, 42
	v_lshl_add_u64 v[176:177], s[26:27], 0, v[128:129]
	global_load_dwordx4 v[136:139], v[132:133], off
	global_load_dwordx4 v[146:149], v[176:177], off
	v_lshl_add_u64 v[132:133], s[56:57], 0, v[128:129]
	v_lshl_add_u64 v[182:183], s[24:25], 0, v[128:129]
	global_load_dwordx4 v[162:165], v[182:183], off
	global_load_dwordx4 v[150:153], v[132:133], off
	v_lshl_add_u64 v[132:133], s[54:55], 0, v[128:129]
	v_lshl_add_u64 v[134:135], s[60:61], 0, v[128:129]
	global_load_dwordx4 v[166:169], v[134:135], off
	global_load_dwordx4 v[154:157], v[132:133], off
	v_lshl_add_u64 v[132:133], s[58:59], 0, v[128:129]
	v_lshl_add_u64 v[128:129], s[48:49], 0, v[128:129]
	global_load_dwordx4 v[170:173], v[132:133], off
	global_load_dwordx4 v[158:161], v[128:129], off
	v_mov_b32_e32 v242, 0
	v_mov_b32_e32 v241, 0
	v_mov_b32_e32 v179, 0
	v_mov_b32_dpp v242, v242 row_ror:2 row_mask:0xf bank_mask:0xf
	v_mov_b32_dpp v241, v241 row_ror:1 row_mask:0xf bank_mask:0xf
	v_mov_b32_e32 v129, v242
	v_mov_b32_e32 v135, v242
	v_mov_b32_e32 v128, v241
	v_mov_b32_e32 v134, v241
	v_mov_b32_dpp v129, v124 row_shr:2 row_mask:0xf bank_mask:0xf
	v_mov_b32_dpp v135, v125 row_shr:2 row_mask:0xf bank_mask:0xf
	v_mov_b32_e32 v133, v242
	v_mov_b32_dpp v128, v124 row_shr:1 row_mask:0xf bank_mask:0xf
	v_mov_b32_dpp v134, v125 row_shr:1 row_mask:0xf bank_mask:0xf
	v_mov_b32_e32 v132, v241
	v_mov_b32_dpp v133, v112 row_shr:2 row_mask:0xf bank_mask:0xf
	v_mov_b32_e32 v143, v242
	v_mov_b32_dpp v132, v112 row_shr:1 row_mask:0xf bank_mask:0xf
	v_mov_b32_e32 v142, v241
	v_mov_b32_dpp v143, v126 row_shr:2 row_mask:0xf bank_mask:0xf
	v_mov_b32_e32 v141, v242
	v_mov_b32_dpp v142, v126 row_shr:1 row_mask:0xf bank_mask:0xf
	v_mov_b32_e32 v175, v242
	v_mov_b32_e32 v140, v241
	v_mov_b32_e32 v174, v241
	v_mov_b32_dpp v141, v113 row_shr:2 row_mask:0xf bank_mask:0xf
	v_mov_b32_dpp v175, v127 row_shr:2 row_mask:0xf bank_mask:0xf
	v_mov_b32_dpp v140, v113 row_shr:1 row_mask:0xf bank_mask:0xf
	v_mov_b32_dpp v174, v127 row_shr:1 row_mask:0xf bank_mask:0xf
	v_mov_b32_e32 v145, v242
	v_mov_b32_e32 v178, v241
	v_mov_b32_e32 v144, v241
	v_mov_b32_dpp v145, v114 row_shr:2 row_mask:0xf bank_mask:0xf
	v_mov_b32_dpp v178, v115 row_shr:1 row_mask:0xf bank_mask:0xf
	v_mov_b32_dpp v144, v114 row_shr:1 row_mask:0xf bank_mask:0xf
	v_mov_b32_dpp v179, v50 row_ror:2 row_mask:0xf bank_mask:0xf
	v_mov_b32_e32 v180, 0
	v_mov_b32_e32 v181, 0
	v_mov_b32_dpp v179, v34 row_shr:2 row_mask:0xf bank_mask:0xf
	v_mov_b32_dpp v180, v51 row_ror:2 row_mask:0xf bank_mask:0xf
	v_mov_b32_dpp v181, v34 row_ror:2 row_mask:0xf bank_mask:0xf
	v_mov_b32_e32 v184, 0
	v_mov_b32_dpp v180, v35 row_shr:2 row_mask:0xf bank_mask:0xf
	v_mov_b32_dpp v181, v18 row_shr:2 row_mask:0xf bank_mask:0xf
	v_mov_b32_dpp v184, v35 row_ror:2 row_mask:0xf bank_mask:0xf
	v_readlane_b32 s17, v254, 34
	v_readlane_b32 s18, v254, 35
	v_mov_b32_dpp v184, v19 row_shr:2 row_mask:0xf bank_mask:0xf
	v_readlane_b32 s19, v254, 36
	v_readlane_b32 s20, v254, 37
	v_readlane_b32 s21, v254, 38
	v_readlane_b32 s22, v254, 39
	v_readlane_b32 s23, v254, 40
	v_readlane_b32 s28, v254, 45
	v_readlane_b32 s29, v254, 46
	v_readlane_b32 s30, v254, 47
	v_readlane_b32 s31, v254, 48
	s_waitcnt vmcnt(0)
; __device__ __forceinline__ unsigned pk2(float lo, float hi) { unsigned r; asm("v_cvt_pk_bf16_f32 %0, %1, %2" : "=v"(r) : "v"(lo), "v"(hi)); return r; }
; __device__ __forceinline__ float gelu_tanh(float x) { const float y = 1.5957691216f * (x + 0.044715f * x * x * x); return x * __builtin_amdgcn_rcpf(1.0f + __expf(-y)); }
; __device__ __forceinline__ float dpp_shr1(float old, float src) { return __int_as_float(__builtin_amdgcn_update_dpp(__float_as_int(old), __float_as_int(src), 0x111, 0xf, 0xf, false)); }
; __device__ __forceinline__ float dpp_shr2(float old, float src) { return __int_as_float(__builtin_amdgcn_update_dpp(__float_as_int(old), __float_as_int(src), 0x112, 0xf, 0xf, false)); }
; __device__ __forceinline__ float dpp_ror1(float src) { return __int_as_float(__builtin_amdgcn_update_dpp(0, __float_as_int(src), 0x121, 0xf, 0xf, false)); }
; __device__ __forceinline__ float dpp_ror2(float src) { return __int_as_float(__builtin_amdgcn_update_dpp(0, __float_as_int(src), 0x122, 0xf, 0xf, false)); }
;     __device__ __forceinline__ void operator()(const f32x4 (&acc)[2][2][4][2], const Unit& u, int wr, int wc, int fr, int fq) const {
;     ...
;                     for (int j = 0; j < 4; ++j) {
;                         const float g1 = dpp_shr1(dpp_ror1(gp[j]), g0[j]), g2 = dpp_shr2(dpp_ror2(gp[j]), g0[j]);
;                         const float v1 = dpp_shr1(dpp_ror1(vp[j]), v0[j]), v2 = dpp_shr2(dpp_ror2(vp[j]), v0[j]);
;                         const float cg_ = bg[j] + g2 * wg0[j] + g1 * wg1[j] + g0[j] * wg2[j];
;                         const float cv_ = bv[j] + v2 * wv0[j] + v1 * wv1[j] + v0[j] * wv2[j];
;                         f[j] = gelu_tanh(cg_) * cv_; }
;                     u32x2 w; w.x = pk2(f[0], f[1]); w.y = pk2(f[2], f[3]);
;                     if (n == 0) res0[ai * 4 + m] = w;
	v_fma_f32 v129, v162, v129, v146
	v_fma_f32 v135, v163, v135, v147
	v_fma_f32 v133, v150, v133, v136
	v_fmac_f32_e32 v129, v166, v128
	v_fmac_f32_e32 v135, v167, v134
	v_fmac_f32_e32 v133, v154, v132
	v_fmac_f32_e32 v129, v124, v170
	v_fmac_f32_e32 v135, v125, v171
	v_mul_f32_e32 v128, 0x3d372713, v129
	v_mul_f32_e32 v132, 0x3d372713, v135
	v_mul_f32_e32 v128, v129, v128
	v_mul_f32_e32 v132, v135, v132
	v_fma_f32 v128, v129, v128, v129
	v_fma_f32 v132, v135, v132, v135
	v_mul_f32_e32 v128, 0xbfcc422a, v128
	v_mul_f32_e32 v132, 0xbfcc422a, v132
	v_mul_f32_e32 v128, 0x3fb8aa3b, v128
	v_mul_f32_e32 v132, 0x3fb8aa3b, v132
	v_exp_f32_e32 v128, v128
	v_exp_f32_e32 v132, v132
	v_fma_f32 v143, v164, v143, v148
	v_fmac_f32_e32 v143, v168, v142
	v_add_f32_e32 v128, 1.0, v128
	v_add_f32_e32 v132, 1.0, v132
	v_fmac_f32_e32 v143, v126, v172
	v_rcp_f32_e32 v128, v128
	v_rcp_f32_e32 v132, v132
	v_mul_f32_e32 v134, 0x3d372713, v143
	v_fma_f32 v141, v151, v141, v137
	v_fma_f32 v175, v165, v175, v149
	v_mul_f32_e32 v134, v143, v134
	v_fmac_f32_e32 v141, v155, v140
	v_fmac_f32_e32 v175, v169, v174
	v_fma_f32 v134, v143, v134, v143
	v_fmac_f32_e32 v133, v112, v158
	v_mul_f32_e32 v134, 0xbfcc422a, v134
	v_fmac_f32_e32 v141, v113, v159
	v_mul_f32_e32 v128, v129, v128
	v_mul_f32_e32 v129, v135, v132
	v_fmac_f32_e32 v175, v127, v173
	v_mul_f32_e32 v134, 0x3fb8aa3b, v134
	v_mul_f32_e32 v128, v133, v128
	v_mul_f32_e32 v129, v141, v129
	v_mul_f32_e32 v133, 0x3d372713, v175
	v_exp_f32_e32 v134, v134
	v_mul_f32_e32 v133, v175, v133
	v_cvt_pk_bf16_f32 v174, v128, v129
	v_mov_b32_e32 v129, 0
	v_fma_f32 v133, v175, v133, v175
	v_mov_b32_e32 v128, 0
	v_mov_b32_dpp v129, v124 row_ror:2 row_mask:0xf bank_mask:0xf
	v_mul_f32_e32 v133, 0xbfcc422a, v133
	v_mov_b32_dpp v128, v124 row_ror:1 row_mask:0xf bank_mask:0xf
	v_mov_b32_dpp v129, v116 row_shr:2 row_mask:0xf bank_mask:0xf
	v_mul_f32_e32 v133, 0x3fb8aa3b, v133
	v_mov_b32_dpp v128, v116 row_shr:1 row_mask:0xf bank_mask:0xf
	v_fma_f32 v129, v162, v129, v146
	v_add_f32_e32 v134, 1.0, v134
	v_exp_f32_e32 v133, v133
	v_fmac_f32_e32 v129, v166, v128
	v_rcp_f32_e32 v134, v134
	v_fmac_f32_e32 v129, v116, v170
	v_mul_f32_e32 v128, 0x3d372713, v129
	v_mul_f32_e32 v128, v129, v128
	v_add_f32_e32 v133, 1.0, v133
	v_fma_f32 v128, v129, v128, v129
	v_mul_f32_e32 v132, v143, v134
	v_mov_b32_e32 v134, v242
	v_rcp_f32_e32 v133, v133
	v_mul_f32_e32 v128, 0xbfcc422a, v128
	v_mov_b32_dpp v134, v115 row_shr:2 row_mask:0xf bank_mask:0xf
	v_mul_f32_e32 v128, 0x3fb8aa3b, v128
	v_fma_f32 v134, v153, v134, v139
	v_exp_f32_e32 v128, v128
	v_fma_f32 v145, v152, v145, v138
	v_fmac_f32_e32 v134, v157, v178
	v_fmac_f32_e32 v145, v156, v144
	v_fmac_f32_e32 v134, v115, v161
	v_mul_f32_e32 v133, v175, v133
	v_fmac_f32_e32 v145, v114, v160
	v_mul_f32_e32 v133, v134, v133
	v_mul_f32_e32 v132, v145, v132
	v_cvt_pk_bf16_f32 v175, v132, v133
	v_mov_b32_e32 v133, 0
	v_add_f32_e32 v128, 1.0, v128
	v_mov_b32_e32 v132, 0
	v_mov_b32_dpp v133, v112 row_ror:2 row_mask:0xf bank_mask:0xf
	v_rcp_f32_e32 v128, v128
	v_mov_b32_dpp v132, v112 row_ror:1 row_mask:0xf bank_mask:0xf
	v_mov_b32_dpp v133, v96 row_shr:2 row_mask:0xf bank_mask:0xf
	v_fma_f32 v133, v150, v133, v136
	v_mov_b32_dpp v132, v96 row_shr:1 row_mask:0xf bank_mask:0xf
	v_fmac_f32_e32 v133, v154, v132
	v_mov_b32_e32 v132, 0
	v_mul_f32_e32 v128, v129, v128
	v_mov_b32_e32 v129, 0
	v_mov_b32_dpp v132, v125 row_ror:2 row_mask:0xf bank_mask:0xf
	v_fmac_f32_e32 v133, v96, v158
	v_mov_b32_dpp v129, v125 row_ror:1 row_mask:0xf bank_mask:0xf
	v_mov_b32_dpp v132, v117 row_shr:2 row_mask:0xf bank_mask:0xf
	v_fma_f32 v132, v163, v132, v147
	v_mov_b32_dpp v129, v117 row_shr:1 row_mask:0xf bank_mask:0xf
	v_fmac_f32_e32 v132, v167, v129
	v_fmac_f32_e32 v132, v117, v171
	v_mul_f32_e32 v129, 0x3d372713, v132
	v_mul_f32_e32 v129, v132, v129
	v_fma_f32 v129, v132, v129, v132
	v_mul_f32_e32 v129, 0xbfcc422a, v129
	v_mul_f32_e32 v129, 0x3fb8aa3b, v129
	v_exp_f32_e32 v129, v129
	v_mov_b32_e32 v134, 0
	v_mul_f32_e32 v128, v133, v128
	v_mov_b32_e32 v133, 0
	v_add_f32_e32 v129, 1.0, v129
	v_mov_b32_dpp v134, v113 row_ror:2 row_mask:0xf bank_mask:0xf
	v_rcp_f32_e32 v129, v129
	v_mov_b32_dpp v133, v113 row_ror:1 row_mask:0xf bank_mask:0xf
	v_mov_b32_dpp v134, v97 row_shr:2 row_mask:0xf bank_mask:0xf
	v_fma_f32 v134, v151, v134, v137
	v_mov_b32_dpp v133, v97 row_shr:1 row_mask:0xf bank_mask:0xf
	v_fmac_f32_e32 v134, v155, v133
	v_mov_b32_e32 v133, 0
	v_mul_f32_e32 v129, v132, v129
	v_mov_b32_e32 v132, 0
	v_mov_b32_dpp v133, v126 row_ror:2 row_mask:0xf bank_mask:0xf
	v_fmac_f32_e32 v134, v97, v159
	v_mov_b32_dpp v132, v126 row_ror:1 row_mask:0xf bank_mask:0xf
	v_mov_b32_dpp v133, v118 row_shr:2 row_mask:0xf bank_mask:0xf
	v_fma_f32 v133, v164, v133, v148
	v_mov_b32_dpp v132, v118 row_shr:1 row_mask:0xf bank_mask:0xf
	v_fmac_f32_e32 v133, v168, v132
	v_fmac_f32_e32 v133, v118, v172
	v_mul_f32_e32 v132, 0x3d372713, v133
	v_mul_f32_e32 v132, v133, v132
	v_fma_f32 v132, v133, v132, v133
	v_mul_f32_e32 v132, 0xbfcc422a, v132
	v_mul_f32_e32 v132, 0x3fb8aa3b, v132
	v_exp_f32_e32 v132, v132
	v_mov_b32_e32 v135, 0
	v_mul_f32_e32 v129, v134, v129
	v_mov_b32_e32 v134, 0
	v_add_f32_e32 v132, 1.0, v132
	v_mov_b32_dpp v135, v114 row_ror:2 row_mask:0xf bank_mask:0xf
	v_rcp_f32_e32 v132, v132
	v_mov_b32_dpp v134, v114 row_ror:1 row_mask:0xf bank_mask:0xf
	v_mov_b32_dpp v135, v98 row_shr:2 row_mask:0xf bank_mask:0xf
	v_fma_f32 v135, v152, v135, v138
	v_mov_b32_dpp v134, v98 row_shr:1 row_mask:0xf bank_mask:0xf
	v_fmac_f32_e32 v135, v156, v134
	v_mov_b32_e32 v134, 0
	v_mul_f32_e32 v132, v133, v132
	v_mov_b32_e32 v133, 0
; __device__ __forceinline__ unsigned pk2(float lo, float hi) { unsigned r; asm("v_cvt_pk_bf16_f32 %0, %1, %2" : "=v"(r) : "v"(lo), "v"(hi)); return r; }
; __device__ __forceinline__ float gelu_tanh(float x) { const float y = 1.5957691216f * (x + 0.044715f * x * x * x); return x * __builtin_amdgcn_rcpf(1.0f + __expf(-y)); }
; __device__ __forceinline__ float dpp_shr1(float old, float src) { return __int_as_float(__builtin_amdgcn_update_dpp(__float_as_int(old), __float_as_int(src), 0x111, 0xf, 0xf, false)); }
; __device__ __forceinline__ float dpp_shr2(float old, float src) { return __int_as_float(__builtin_amdgcn_update_dpp(__float_as_int(old), __float_as_int(src), 0x112, 0xf, 0xf, false)); }
; __device__ __forceinline__ float dpp_ror1(float src) { return __int_as_float(__builtin_amdgcn_update_dpp(0, __float_as_int(src), 0x121, 0xf, 0xf, false)); }
; __device__ __forceinline__ float dpp_ror2(float src) { return __int_as_float(__builtin_amdgcn_update_dpp(0, __float_as_int(src), 0x122, 0xf, 0xf, false)); }
;     __device__ __forceinline__ void operator()(const f32x4 (&acc)[2][2][4][2], const Unit& u, int wr, int wc, int fr, int fq) const {
;     ...
;                     for (int j = 0; j < 4; ++j) {
;                         const float g1 = dpp_shr1(dpp_ror1(gp[j]), g0[j]), g2 = dpp_shr2(dpp_ror2(gp[j]), g0[j]);
;                         const float v1 = dpp_shr1(dpp_ror1(vp[j]), v0[j]), v2 = dpp_shr2(dpp_ror2(vp[j]), v0[j]);
;                         const float cg_ = bg[j] + g2 * wg0[j] + g1 * wg1[j] + g0[j] * wg2[j];
;                         const float cv_ = bv[j] + v2 * wv0[j] + v1 * wv1[j] + v0[j] * wv2[j];
;                         f[j] = gelu_tanh(cg_) * cv_; }
;                     u32x2 w; w.x = pk2(f[0], f[1]); w.y = pk2(f[2], f[3]);
;                     if (n == 0) res0[ai * 4 + m] = w;
	v_mov_b32_dpp v134, v127 row_ror:2 row_mask:0xf bank_mask:0xf
	v_cvt_pk_bf16_f32 v144, v128, v129
	v_mov_b32_e32 v129, 0
	v_mov_b32_dpp v133, v127 row_ror:1 row_mask:0xf bank_mask:0xf
	v_mov_b32_dpp v134, v119 row_shr:2 row_mask:0xf bank_mask:0xf
	v_fma_f32 v134, v165, v134, v149
	v_mov_b32_dpp v133, v119 row_shr:1 row_mask:0xf bank_mask:0xf
	v_fmac_f32_e32 v134, v169, v133
	v_fmac_f32_e32 v134, v119, v173
	v_mul_f32_e32 v133, 0x3d372713, v134
	v_mul_f32_e32 v133, v134, v133
	v_fma_f32 v133, v134, v133, v134
	v_mov_b32_e32 v128, 0
	v_mov_b32_dpp v129, v116 row_ror:2 row_mask:0xf bank_mask:0xf
	v_mul_f32_e32 v133, 0xbfcc422a, v133
	v_mov_b32_dpp v128, v116 row_ror:1 row_mask:0xf bank_mask:0xf
	v_mov_b32_dpp v129, v100 row_shr:2 row_mask:0xf bank_mask:0xf
	v_mul_f32_e32 v133, 0x3fb8aa3b, v133
	v_mov_b32_dpp v128, v100 row_shr:1 row_mask:0xf bank_mask:0xf
	v_fma_f32 v129, v162, v129, v146
	v_exp_f32_e32 v133, v133
	v_fmac_f32_e32 v129, v166, v128
	v_fmac_f32_e32 v129, v100, v170
	v_mul_f32_e32 v128, 0x3d372713, v129
	v_mul_f32_e32 v128, v129, v128
	v_fmac_f32_e32 v135, v98, v160
	v_mov_b32_e32 v140, 0
	v_add_f32_e32 v133, 1.0, v133
	v_fma_f32 v128, v129, v128, v129
	v_mul_f32_e32 v132, v135, v132
	v_mov_b32_e32 v135, 0
	v_mov_b32_dpp v140, v115 row_ror:2 row_mask:0xf bank_mask:0xf
	v_rcp_f32_e32 v133, v133
	v_mul_f32_e32 v128, 0xbfcc422a, v128
	v_mov_b32_dpp v135, v115 row_ror:1 row_mask:0xf bank_mask:0xf
	v_mov_b32_dpp v140, v99 row_shr:2 row_mask:0xf bank_mask:0xf
	v_mul_f32_e32 v128, 0x3fb8aa3b, v128
	v_mov_b32_dpp v135, v99 row_shr:1 row_mask:0xf bank_mask:0xf
	v_fma_f32 v140, v153, v140, v139
	v_exp_f32_e32 v128, v128
	v_fmac_f32_e32 v140, v157, v135
	v_fmac_f32_e32 v140, v99, v161
	v_mul_f32_e32 v133, v134, v133
	v_mul_f32_e32 v133, v140, v133
	v_cvt_pk_bf16_f32 v145, v132, v133
	v_mov_b32_e32 v133, 0
	v_add_f32_e32 v128, 1.0, v128
	v_mov_b32_e32 v132, 0
	v_mov_b32_dpp v133, v96 row_ror:2 row_mask:0xf bank_mask:0xf
	v_rcp_f32_e32 v128, v128
	v_mov_b32_dpp v132, v96 row_ror:1 row_mask:0xf bank_mask:0xf
	v_mov_b32_dpp v133, v80 row_shr:2 row_mask:0xf bank_mask:0xf
	v_fma_f32 v133, v150, v133, v136
	v_mov_b32_dpp v132, v80 row_shr:1 row_mask:0xf bank_mask:0xf
	v_fmac_f32_e32 v133, v154, v132
	v_mov_b32_e32 v132, 0
	v_mul_f32_e32 v128, v129, v128
	v_mov_b32_e32 v129, 0
	v_mov_b32_dpp v132, v117 row_ror:2 row_mask:0xf bank_mask:0xf
	v_fmac_f32_e32 v133, v80, v158
	v_mov_b32_dpp v129, v117 row_ror:1 row_mask:0xf bank_mask:0xf
	v_mov_b32_dpp v132, v101 row_shr:2 row_mask:0xf bank_mask:0xf
	v_fma_f32 v132, v163, v132, v147
	v_mov_b32_dpp v129, v101 row_shr:1 row_mask:0xf bank_mask:0xf
	v_fmac_f32_e32 v132, v167, v129
	v_fmac_f32_e32 v132, v101, v171
	v_mul_f32_e32 v129, 0x3d372713, v132
	v_mul_f32_e32 v129, v132, v129
	v_fma_f32 v129, v132, v129, v132
	v_mul_f32_e32 v129, 0xbfcc422a, v129
	v_mul_f32_e32 v129, 0x3fb8aa3b, v129
	v_exp_f32_e32 v129, v129
	v_mov_b32_e32 v134, 0
	v_mul_f32_e32 v128, v133, v128
	v_mov_b32_e32 v133, 0
	v_add_f32_e32 v129, 1.0, v129
	v_mov_b32_dpp v134, v97 row_ror:2 row_mask:0xf bank_mask:0xf
	v_rcp_f32_e32 v129, v129
	v_mov_b32_dpp v133, v97 row_ror:1 row_mask:0xf bank_mask:0xf
	v_mov_b32_dpp v134, v81 row_shr:2 row_mask:0xf bank_mask:0xf
	v_fma_f32 v134, v151, v134, v137
	v_mov_b32_dpp v133, v81 row_shr:1 row_mask:0xf bank_mask:0xf
	v_fmac_f32_e32 v134, v155, v133
	v_mov_b32_e32 v133, 0
	v_mul_f32_e32 v129, v132, v129
	v_mov_b32_e32 v132, 0
	v_mov_b32_dpp v133, v118 row_ror:2 row_mask:0xf bank_mask:0xf
	v_fmac_f32_e32 v134, v81, v159
	v_mov_b32_dpp v132, v118 row_ror:1 row_mask:0xf bank_mask:0xf
	v_mov_b32_dpp v133, v102 row_shr:2 row_mask:0xf bank_mask:0xf
	v_fma_f32 v133, v164, v133, v148
	v_mov_b32_dpp v132, v102 row_shr:1 row_mask:0xf bank_mask:0xf
	v_fmac_f32_e32 v133, v168, v132
	v_fmac_f32_e32 v133, v102, v172
	v_mul_f32_e32 v132, 0x3d372713, v133
	v_mul_f32_e32 v132, v133, v132
	v_fma_f32 v132, v133, v132, v133
	v_mul_f32_e32 v132, 0xbfcc422a, v132
	v_mul_f32_e32 v132, 0x3fb8aa3b, v132
	v_exp_f32_e32 v132, v132
	v_mov_b32_e32 v135, 0
	v_mul_f32_e32 v129, v134, v129
	v_mov_b32_e32 v134, 0
	v_add_f32_e32 v132, 1.0, v132
	v_mov_b32_dpp v135, v98 row_ror:2 row_mask:0xf bank_mask:0xf
	v_rcp_f32_e32 v132, v132
	v_mov_b32_dpp v134, v98 row_ror:1 row_mask:0xf bank_mask:0xf
	v_mov_b32_dpp v135, v82 row_shr:2 row_mask:0xf bank_mask:0xf
	v_fma_f32 v135, v152, v135, v138
	v_mov_b32_dpp v134, v82 row_shr:1 row_mask:0xf bank_mask:0xf
	v_fmac_f32_e32 v135, v156, v134
	v_mov_b32_e32 v134, 0
	v_mul_f32_e32 v132, v133, v132
	v_mov_b32_e32 v133, 0
	v_mov_b32_dpp v134, v119 row_ror:2 row_mask:0xf bank_mask:0xf
	v_cvt_pk_bf16_f32 v142, v128, v129
	v_mov_b32_e32 v129, 0
	v_mov_b32_dpp v133, v119 row_ror:1 row_mask:0xf bank_mask:0xf
	v_mov_b32_dpp v134, v103 row_shr:2 row_mask:0xf bank_mask:0xf
	v_fma_f32 v134, v165, v134, v149
	v_mov_b32_dpp v133, v103 row_shr:1 row_mask:0xf bank_mask:0xf
	v_fmac_f32_e32 v134, v169, v133
	v_fmac_f32_e32 v134, v103, v173
	v_mul_f32_e32 v133, 0x3d372713, v134
	v_mul_f32_e32 v133, v134, v133
	v_fma_f32 v133, v134, v133, v134
	v_mov_b32_e32 v128, 0
	v_mov_b32_dpp v129, v100 row_ror:2 row_mask:0xf bank_mask:0xf
	v_mul_f32_e32 v133, 0xbfcc422a, v133
	v_mov_b32_dpp v128, v100 row_ror:1 row_mask:0xf bank_mask:0xf
	v_mov_b32_dpp v129, v84 row_shr:2 row_mask:0xf bank_mask:0xf
	v_mul_f32_e32 v133, 0x3fb8aa3b, v133
	v_mov_b32_dpp v128, v84 row_shr:1 row_mask:0xf bank_mask:0xf
	v_fma_f32 v129, v162, v129, v146
	v_exp_f32_e32 v133, v133
	v_fmac_f32_e32 v129, v166, v128
	v_fmac_f32_e32 v129, v84, v170
	v_mul_f32_e32 v128, 0x3d372713, v129
	v_mul_f32_e32 v128, v129, v128
	v_fmac_f32_e32 v135, v82, v160
; __device__ __forceinline__ unsigned pk2(float lo, float hi) { unsigned r; asm("v_cvt_pk_bf16_f32 %0, %1, %2" : "=v"(r) : "v"(lo), "v"(hi)); return r; }
; __device__ __forceinline__ float gelu_tanh(float x) { const float y = 1.5957691216f * (x + 0.044715f * x * x * x); return x * __builtin_amdgcn_rcpf(1.0f + __expf(-y)); }
; __device__ __forceinline__ float dpp_shr1(float old, float src) { return __int_as_float(__builtin_amdgcn_update_dpp(__float_as_int(old), __float_as_int(src), 0x111, 0xf, 0xf, false)); }
; __device__ __forceinline__ float dpp_shr2(float old, float src) { return __int_as_float(__builtin_amdgcn_update_dpp(__float_as_int(old), __float_as_int(src), 0x112, 0xf, 0xf, false)); }
; __device__ __forceinline__ float dpp_ror1(float src) { return __int_as_float(__builtin_amdgcn_update_dpp(0, __float_as_int(src), 0x121, 0xf, 0xf, false)); }
; __device__ __forceinline__ float dpp_ror2(float src) { return __int_as_float(__builtin_amdgcn_update_dpp(0, __float_as_int(src), 0x122, 0xf, 0xf, false)); }
;     __device__ __forceinline__ void operator()(const f32x4 (&acc)[2][2][4][2], const Unit& u, int wr, int wc, int fr, int fq) const {
;     ...
;                     for (int j = 0; j < 4; ++j) {
;                         const float g1 = dpp_shr1(dpp_ror1(gp[j]), g0[j]), g2 = dpp_shr2(dpp_ror2(gp[j]), g0[j]);
;                         const float v1 = dpp_shr1(dpp_ror1(vp[j]), v0[j]), v2 = dpp_shr2(dpp_ror2(vp[j]), v0[j]);
;                         const float cg_ = bg[j] + g2 * wg0[j] + g1 * wg1[j] + g0[j] * wg2[j];
;                         const float cv_ = bv[j] + v2 * wv0[j] + v1 * wv1[j] + v0[j] * wv2[j];
;                         f[j] = gelu_tanh(cg_) * cv_; }
;                     u32x2 w; w.x = pk2(f[0], f[1]); w.y = pk2(f[2], f[3]);
;                     if (n == 0) res0[ai * 4 + m] = w;
	v_mov_b32_e32 v140, 0
	v_add_f32_e32 v133, 1.0, v133
	v_fma_f32 v128, v129, v128, v129
	v_mul_f32_e32 v132, v135, v132
	v_mov_b32_e32 v135, 0
	v_mov_b32_dpp v140, v99 row_ror:2 row_mask:0xf bank_mask:0xf
	v_rcp_f32_e32 v133, v133
	v_mul_f32_e32 v128, 0xbfcc422a, v128
	v_mov_b32_dpp v135, v99 row_ror:1 row_mask:0xf bank_mask:0xf
	v_mov_b32_dpp v140, v83 row_shr:2 row_mask:0xf bank_mask:0xf
	v_mul_f32_e32 v128, 0x3fb8aa3b, v128
	v_mov_b32_dpp v135, v83 row_shr:1 row_mask:0xf bank_mask:0xf
	v_fma_f32 v140, v153, v140, v139
	v_exp_f32_e32 v128, v128
	v_fmac_f32_e32 v140, v157, v135
	v_fmac_f32_e32 v140, v83, v161
	v_mul_f32_e32 v133, v134, v133
	v_mul_f32_e32 v133, v140, v133
	v_cvt_pk_bf16_f32 v143, v132, v133
	v_mov_b32_e32 v133, 0
	v_add_f32_e32 v128, 1.0, v128
	v_mov_b32_e32 v132, 0
	v_mov_b32_dpp v133, v80 row_ror:2 row_mask:0xf bank_mask:0xf
	v_rcp_f32_e32 v128, v128
	v_mov_b32_dpp v132, v80 row_ror:1 row_mask:0xf bank_mask:0xf
	v_mov_b32_dpp v133, v68 row_shr:2 row_mask:0xf bank_mask:0xf
	v_fma_f32 v133, v150, v133, v136
	v_mov_b32_dpp v132, v68 row_shr:1 row_mask:0xf bank_mask:0xf
	v_fmac_f32_e32 v133, v154, v132
	v_mov_b32_e32 v132, 0
	v_mul_f32_e32 v128, v129, v128
	v_mov_b32_e32 v129, 0
	v_mov_b32_dpp v132, v101 row_ror:2 row_mask:0xf bank_mask:0xf
	v_fmac_f32_e32 v133, v68, v158
	v_mov_b32_dpp v129, v101 row_ror:1 row_mask:0xf bank_mask:0xf
	v_mov_b32_dpp v132, v85 row_shr:2 row_mask:0xf bank_mask:0xf
	v_fma_f32 v132, v163, v132, v147
	v_mov_b32_dpp v129, v85 row_shr:1 row_mask:0xf bank_mask:0xf
	v_fmac_f32_e32 v132, v167, v129
	v_fmac_f32_e32 v132, v85, v171
	v_mul_f32_e32 v129, 0x3d372713, v132
	v_mul_f32_e32 v129, v132, v129
	v_fma_f32 v129, v132, v129, v132
	v_mul_f32_e32 v129, 0xbfcc422a, v129
	v_mul_f32_e32 v129, 0x3fb8aa3b, v129
	v_exp_f32_e32 v129, v129
	v_mov_b32_e32 v134, 0
	v_mul_f32_e32 v128, v133, v128
	v_mov_b32_e32 v133, 0
	v_add_f32_e32 v129, 1.0, v129
	v_mov_b32_dpp v134, v81 row_ror:2 row_mask:0xf bank_mask:0xf
	v_rcp_f32_e32 v129, v129
	v_mov_b32_dpp v133, v81 row_ror:1 row_mask:0xf bank_mask:0xf
	v_mov_b32_dpp v134, v69 row_shr:2 row_mask:0xf bank_mask:0xf
	v_fma_f32 v134, v151, v134, v137
	v_mov_b32_dpp v133, v69 row_shr:1 row_mask:0xf bank_mask:0xf
	v_fmac_f32_e32 v134, v155, v133
	v_mov_b32_e32 v133, 0
	v_mul_f32_e32 v129, v132, v129
	v_mov_b32_e32 v132, 0
	v_mov_b32_dpp v133, v102 row_ror:2 row_mask:0xf bank_mask:0xf
	v_fmac_f32_e32 v134, v69, v159
	v_mov_b32_dpp v132, v102 row_ror:1 row_mask:0xf bank_mask:0xf
	v_mov_b32_dpp v133, v86 row_shr:2 row_mask:0xf bank_mask:0xf
	v_fma_f32 v133, v164, v133, v148
	v_mov_b32_dpp v132, v86 row_shr:1 row_mask:0xf bank_mask:0xf
	v_fmac_f32_e32 v133, v168, v132
	v_fmac_f32_e32 v133, v86, v172
	v_mul_f32_e32 v132, 0x3d372713, v133
	v_mul_f32_e32 v132, v133, v132
	v_fma_f32 v132, v133, v132, v133
	v_mul_f32_e32 v132, 0xbfcc422a, v132
	v_mul_f32_e32 v132, 0x3fb8aa3b, v132
	v_exp_f32_e32 v132, v132
	v_mov_b32_e32 v135, 0
	v_mul_f32_e32 v129, v134, v129
	v_mov_b32_e32 v134, 0
	v_add_f32_e32 v132, 1.0, v132
	v_mov_b32_dpp v135, v82 row_ror:2 row_mask:0xf bank_mask:0xf
	v_rcp_f32_e32 v132, v132
	v_mov_b32_dpp v134, v82 row_ror:1 row_mask:0xf bank_mask:0xf
	v_mov_b32_dpp v135, v70 row_shr:2 row_mask:0xf bank_mask:0xf
	v_fma_f32 v135, v152, v135, v138
	v_mov_b32_dpp v134, v70 row_shr:1 row_mask:0xf bank_mask:0xf
	v_fmac_f32_e32 v135, v156, v134
	v_mov_b32_e32 v134, 0
	v_mul_f32_e32 v132, v133, v132
	v_mov_b32_e32 v133, 0
	v_mov_b32_dpp v134, v103 row_ror:2 row_mask:0xf bank_mask:0xf
	v_fmac_f32_e32 v135, v70, v160
	v_mov_b32_dpp v133, v103 row_ror:1 row_mask:0xf bank_mask:0xf
	v_mov_b32_dpp v134, v87 row_shr:2 row_mask:0xf bank_mask:0xf
	v_fma_f32 v134, v165, v134, v149
	v_mov_b32_dpp v133, v87 row_shr:1 row_mask:0xf bank_mask:0xf
	v_fmac_f32_e32 v134, v169, v133
	v_fmac_f32_e32 v134, v87, v173
	v_mul_f32_e32 v133, 0x3d372713, v134
	v_mul_f32_e32 v133, v134, v133
	v_fma_f32 v133, v134, v133, v134
	v_mul_f32_e32 v133, 0xbfcc422a, v133
	v_mul_f32_e32 v133, 0x3fb8aa3b, v133
	v_exp_f32_e32 v133, v133
	v_mov_b32_e32 v140, 0
	v_mul_f32_e32 v132, v135, v132
	v_mov_b32_e32 v135, 0
	v_add_f32_e32 v133, 1.0, v133
	v_mov_b32_dpp v140, v83 row_ror:2 row_mask:0xf bank_mask:0xf
	v_rcp_f32_e32 v133, v133
	v_mov_b32_dpp v135, v83 row_ror:1 row_mask:0xf bank_mask:0xf
	v_mov_b32_dpp v140, v71 row_shr:2 row_mask:0xf bank_mask:0xf
	v_fma_f32 v140, v153, v140, v139
	v_mov_b32_dpp v135, v71 row_shr:1 row_mask:0xf bank_mask:0xf
	v_fmac_f32_e32 v140, v157, v135
	v_fmac_f32_e32 v140, v71, v161
	v_mul_f32_e32 v133, v134, v133
	v_mul_f32_e32 v133, v140, v133
	v_cvt_pk_bf16_f32 v140, v128, v129
	v_mov_b32_e32 v129, v242
	v_mov_b32_e32 v128, v241
	v_cvt_pk_bf16_f32 v141, v132, v133
	v_mov_b32_e32 v133, v242
	v_mov_b32_dpp v129, v60 row_shr:2 row_mask:0xf bank_mask:0xf
	v_mov_b32_dpp v128, v60 row_shr:1 row_mask:0xf bank_mask:0xf
	v_fma_f32 v129, v162, v129, v146
	v_fmac_f32_e32 v129, v166, v128
	v_fmac_f32_e32 v129, v60, v170
	v_mul_f32_e32 v128, 0x3d372713, v129
	v_mul_f32_e32 v128, v129, v128
	v_fma_f32 v128, v129, v128, v129
	v_mul_f32_e32 v128, 0xbfcc422a, v128
	v_mul_f32_e32 v128, 0x3fb8aa3b, v128
	v_exp_f32_e32 v128, v128
	v_mov_b32_e32 v132, v241
	v_mov_b32_dpp v133, v48 row_shr:2 row_mask:0xf bank_mask:0xf
	v_fma_f32 v133, v150, v133, v136
	v_add_f32_e32 v128, 1.0, v128
	v_rcp_f32_e32 v128, v128
	v_mov_b32_dpp v132, v48 row_shr:1 row_mask:0xf bank_mask:0xf
	v_fmac_f32_e32 v133, v154, v132
	v_mov_b32_e32 v132, v242
	v_mul_f32_e32 v128, v129, v128
	v_mov_b32_e32 v129, v241
	v_mov_b32_dpp v132, v61 row_shr:2 row_mask:0xf bank_mask:0xf
	v_fma_f32 v132, v163, v132, v147
; __device__ __forceinline__ unsigned pk2(float lo, float hi) { unsigned r; asm("v_cvt_pk_bf16_f32 %0, %1, %2" : "=v"(r) : "v"(lo), "v"(hi)); return r; }
; __device__ __forceinline__ float gelu_tanh(float x) { const float y = 1.5957691216f * (x + 0.044715f * x * x * x); return x * __builtin_amdgcn_rcpf(1.0f + __expf(-y)); }
; __device__ __forceinline__ float dpp_shr1(float old, float src) { return __int_as_float(__builtin_amdgcn_update_dpp(__float_as_int(old), __float_as_int(src), 0x111, 0xf, 0xf, false)); }
; __device__ __forceinline__ float dpp_shr2(float old, float src) { return __int_as_float(__builtin_amdgcn_update_dpp(__float_as_int(old), __float_as_int(src), 0x112, 0xf, 0xf, false)); }
; __device__ __forceinline__ float dpp_ror1(float src) { return __int_as_float(__builtin_amdgcn_update_dpp(0, __float_as_int(src), 0x121, 0xf, 0xf, false)); }
; __device__ __forceinline__ float dpp_ror2(float src) { return __int_as_float(__builtin_amdgcn_update_dpp(0, __float_as_int(src), 0x122, 0xf, 0xf, false)); }
;     __device__ __forceinline__ void operator()(const f32x4 (&acc)[2][2][4][2], const Unit& u, int wr, int wc, int fr, int fq) const {
;     ...
;                     for (int j = 0; j < 4; ++j) {
;                         const float g1 = dpp_shr1(dpp_ror1(gp[j]), g0[j]), g2 = dpp_shr2(dpp_ror2(gp[j]), g0[j]);
;                         const float v1 = dpp_shr1(dpp_ror1(vp[j]), v0[j]), v2 = dpp_shr2(dpp_ror2(vp[j]), v0[j]);
;                         const float cg_ = bg[j] + g2 * wg0[j] + g1 * wg1[j] + g0[j] * wg2[j];
;                         const float cv_ = bv[j] + v2 * wv0[j] + v1 * wv1[j] + v0[j] * wv2[j];
;                         f[j] = gelu_tanh(cg_) * cv_; }
;                     u32x2 w; w.x = pk2(f[0], f[1]); w.y = pk2(f[2], f[3]);
;                     if (n == 0) res0[ai * 4 + m] = w;
	v_mov_b32_dpp v129, v61 row_shr:1 row_mask:0xf bank_mask:0xf
	v_fmac_f32_e32 v132, v167, v129
	v_fmac_f32_e32 v132, v61, v171
	v_mul_f32_e32 v129, 0x3d372713, v132
	v_mul_f32_e32 v129, v132, v129
	v_fma_f32 v129, v132, v129, v132
	v_mul_f32_e32 v129, 0xbfcc422a, v129
	v_mul_f32_e32 v129, 0x3fb8aa3b, v129
	v_exp_f32_e32 v129, v129
	v_fmac_f32_e32 v133, v48, v158
	v_mov_b32_e32 v134, v242
	v_mul_f32_e32 v128, v133, v128
	v_add_f32_e32 v129, 1.0, v129
	v_rcp_f32_e32 v129, v129
	v_mov_b32_e32 v133, v241
	v_mov_b32_dpp v134, v49 row_shr:2 row_mask:0xf bank_mask:0xf
	v_fma_f32 v134, v151, v134, v137
	v_mov_b32_dpp v133, v49 row_shr:1 row_mask:0xf bank_mask:0xf
	v_fmac_f32_e32 v134, v155, v133
	v_mov_b32_e32 v133, v242
	v_mul_f32_e32 v129, v132, v129
	v_mov_b32_e32 v132, v241
	v_mov_b32_dpp v133, v62 row_shr:2 row_mask:0xf bank_mask:0xf
	v_fma_f32 v133, v164, v133, v148
	v_mov_b32_dpp v132, v62 row_shr:1 row_mask:0xf bank_mask:0xf
	v_fmac_f32_e32 v133, v168, v132
	v_fmac_f32_e32 v133, v62, v172
	v_mul_f32_e32 v132, 0x3d372713, v133
	v_mul_f32_e32 v132, v133, v132
	v_fma_f32 v132, v133, v132, v133
	v_mul_f32_e32 v132, 0xbfcc422a, v132
	v_mul_f32_e32 v132, 0x3fb8aa3b, v132
	v_exp_f32_e32 v132, v132
	v_fmac_f32_e32 v134, v49, v159
	v_mov_b32_e32 v135, v242
	v_mul_f32_e32 v129, v134, v129
	v_add_f32_e32 v132, 1.0, v132
	v_rcp_f32_e32 v132, v132
	v_mov_b32_e32 v134, v241
	v_mov_b32_dpp v135, v50 row_shr:2 row_mask:0xf bank_mask:0xf
	v_fma_f32 v135, v152, v135, v138
	v_mov_b32_dpp v134, v50 row_shr:1 row_mask:0xf bank_mask:0xf
	v_fmac_f32_e32 v135, v156, v134
	v_mov_b32_e32 v134, v242
	v_mul_f32_e32 v132, v133, v132
	v_mov_b32_e32 v133, v241
	v_mov_b32_dpp v134, v63 row_shr:2 row_mask:0xf bank_mask:0xf
	v_fma_f32 v134, v165, v134, v149
	v_mov_b32_dpp v133, v63 row_shr:1 row_mask:0xf bank_mask:0xf
	v_fmac_f32_e32 v134, v169, v133
	v_fmac_f32_e32 v134, v63, v173
	v_mul_f32_e32 v133, 0x3d372713, v134
	v_mul_f32_e32 v133, v134, v133
	v_fma_f32 v133, v134, v133, v134
	v_mul_f32_e32 v133, 0xbfcc422a, v133
	v_mul_f32_e32 v133, 0x3fb8aa3b, v133
	v_exp_f32_e32 v133, v133
	v_fmac_f32_e32 v135, v50, v160
	v_mov_b32_e32 v178, v242
	v_mul_f32_e32 v132, v135, v132
	v_add_f32_e32 v133, 1.0, v133
	v_rcp_f32_e32 v133, v133
	v_mov_b32_e32 v135, v241
	v_mov_b32_dpp v178, v51 row_shr:2 row_mask:0xf bank_mask:0xf
	v_fma_f32 v178, v153, v178, v139
	v_mul_f32_e32 v133, v134, v133
	v_cvt_pk_bf16_f32 v134, v128, v129
	v_mov_b32_e32 v129, 0
	v_mov_b32_e32 v128, 0
	v_mov_b32_dpp v135, v51 row_shr:1 row_mask:0xf bank_mask:0xf
	v_mov_b32_dpp v129, v60 row_ror:2 row_mask:0xf bank_mask:0xf
	v_mov_b32_dpp v128, v60 row_ror:1 row_mask:0xf bank_mask:0xf
	v_fmac_f32_e32 v178, v157, v135
	v_mov_b32_dpp v129, v52 row_shr:2 row_mask:0xf bank_mask:0xf
	v_mov_b32_dpp v128, v52 row_shr:1 row_mask:0xf bank_mask:0xf
	v_fma_f32 v129, v162, v129, v146
	v_fmac_f32_e32 v129, v166, v128
	v_fmac_f32_e32 v129, v52, v170
	v_mul_f32_e32 v128, 0x3d372713, v129
	v_mul_f32_e32 v128, v129, v128
	v_fma_f32 v128, v129, v128, v129
	v_mul_f32_e32 v128, 0xbfcc422a, v128
	v_mul_f32_e32 v128, 0x3fb8aa3b, v128
	v_exp_f32_e32 v128, v128
	v_fmac_f32_e32 v178, v51, v161
	v_mul_f32_e32 v133, v178, v133
	v_cvt_pk_bf16_f32 v135, v132, v133
	v_mov_b32_e32 v133, 0
	v_add_f32_e32 v128, 1.0, v128
	v_mov_b32_e32 v132, 0
	v_mov_b32_dpp v133, v48 row_ror:2 row_mask:0xf bank_mask:0xf
	v_rcp_f32_e32 v128, v128
	v_mov_b32_dpp v132, v48 row_ror:1 row_mask:0xf bank_mask:0xf
	v_mov_b32_dpp v133, v32 row_shr:2 row_mask:0xf bank_mask:0xf
	v_fma_f32 v133, v150, v133, v136
	v_mov_b32_dpp v132, v32 row_shr:1 row_mask:0xf bank_mask:0xf
	v_fmac_f32_e32 v133, v154, v132
	v_mov_b32_e32 v132, 0
	v_mul_f32_e32 v128, v129, v128
	v_mov_b32_e32 v129, 0
	v_mov_b32_dpp v132, v61 row_ror:2 row_mask:0xf bank_mask:0xf
	v_fmac_f32_e32 v133, v32, v158
	v_mov_b32_dpp v129, v61 row_ror:1 row_mask:0xf bank_mask:0xf
	v_mov_b32_dpp v132, v53 row_shr:2 row_mask:0xf bank_mask:0xf
	v_fma_f32 v132, v163, v132, v147
	v_mov_b32_dpp v129, v53 row_shr:1 row_mask:0xf bank_mask:0xf
	v_fmac_f32_e32 v132, v167, v129
	v_fmac_f32_e32 v132, v53, v171
	v_mul_f32_e32 v129, 0x3d372713, v132
	v_mul_f32_e32 v129, v132, v129
	v_fma_f32 v129, v132, v129, v132
	v_mul_f32_e32 v129, 0xbfcc422a, v129
	v_mul_f32_e32 v129, 0x3fb8aa3b, v129
	v_exp_f32_e32 v129, v129
	v_mov_b32_e32 v178, 0
	v_mul_f32_e32 v128, v133, v128
	v_mov_b32_e32 v133, 0
	v_add_f32_e32 v129, 1.0, v129
	v_mov_b32_dpp v178, v49 row_ror:2 row_mask:0xf bank_mask:0xf
	v_rcp_f32_e32 v129, v129
	v_mov_b32_dpp v133, v49 row_ror:1 row_mask:0xf bank_mask:0xf
	v_mov_b32_dpp v178, v33 row_shr:2 row_mask:0xf bank_mask:0xf
	v_fma_f32 v178, v151, v178, v137
	v_mov_b32_dpp v133, v33 row_shr:1 row_mask:0xf bank_mask:0xf
	v_fmac_f32_e32 v178, v155, v133
	v_mov_b32_e32 v133, 0
	v_mul_f32_e32 v129, v132, v129
	v_mov_b32_e32 v132, 0
	v_mov_b32_dpp v133, v62 row_ror:2 row_mask:0xf bank_mask:0xf
	v_fmac_f32_e32 v178, v33, v159
	v_mov_b32_dpp v132, v62 row_ror:1 row_mask:0xf bank_mask:0xf
	v_mov_b32_dpp v133, v54 row_shr:2 row_mask:0xf bank_mask:0xf
	v_fma_f32 v133, v164, v133, v148
	v_mov_b32_dpp v132, v54 row_shr:1 row_mask:0xf bank_mask:0xf
	v_fmac_f32_e32 v133, v168, v132
	v_fmac_f32_e32 v133, v54, v172
	v_mul_f32_e32 v132, 0x3d372713, v133
	v_mul_f32_e32 v132, v133, v132
	v_fma_f32 v132, v133, v132, v133
	v_mul_f32_e32 v132, 0xbfcc422a, v132
	v_mul_f32_e32 v132, 0x3fb8aa3b, v132
	v_exp_f32_e32 v132, v132
	v_mul_f32_e32 v129, v178, v129
	v_mov_b32_e32 v178, 0
	v_fma_f32 v179, v152, v179, v138
	v_add_f32_e32 v132, 1.0, v132
	v_rcp_f32_e32 v132, v132
	v_mov_b32_dpp v178, v50 row_ror:1 row_mask:0xf bank_mask:0xf
	v_fma_f32 v180, v153, v180, v139
; __device__ __forceinline__ unsigned pk2(float lo, float hi) { unsigned r; asm("v_cvt_pk_bf16_f32 %0, %1, %2" : "=v"(r) : "v"(lo), "v"(hi)); return r; }
; __device__ __forceinline__ float gelu_tanh(float x) { const float y = 1.5957691216f * (x + 0.044715f * x * x * x); return x * __builtin_amdgcn_rcpf(1.0f + __expf(-y)); }
; __device__ __forceinline__ float dpp_shr1(float old, float src) { return __int_as_float(__builtin_amdgcn_update_dpp(__float_as_int(old), __float_as_int(src), 0x111, 0xf, 0xf, false)); }
; __device__ __forceinline__ float dpp_shr2(float old, float src) { return __int_as_float(__builtin_amdgcn_update_dpp(__float_as_int(old), __float_as_int(src), 0x112, 0xf, 0xf, false)); }
; __device__ __forceinline__ float dpp_ror1(float src) { return __int_as_float(__builtin_amdgcn_update_dpp(0, __float_as_int(src), 0x121, 0xf, 0xf, false)); }
; __device__ __forceinline__ float dpp_ror2(float src) { return __int_as_float(__builtin_amdgcn_update_dpp(0, __float_as_int(src), 0x122, 0xf, 0xf, false)); }
;     __device__ __forceinline__ void operator()(const f32x4 (&acc)[2][2][4][2], const Unit& u, int wr, int wc, int fr, int fq) const {
;     ...
;                     for (int j = 0; j < 4; ++j) {
;                         const float g1 = dpp_shr1(dpp_ror1(gp[j]), g0[j]), g2 = dpp_shr2(dpp_ror2(gp[j]), g0[j]);
;                         const float v1 = dpp_shr1(dpp_ror1(vp[j]), v0[j]), v2 = dpp_shr2(dpp_ror2(vp[j]), v0[j]);
;                         const float cg_ = bg[j] + g2 * wg0[j] + g1 * wg1[j] + g0[j] * wg2[j];
;                         const float cv_ = bv[j] + v2 * wv0[j] + v1 * wv1[j] + v0[j] * wv2[j];
;                         f[j] = gelu_tanh(cg_) * cv_; }
;                     u32x2 w; w.x = pk2(f[0], f[1]); w.y = pk2(f[2], f[3]);
;                     if (n == 0) res0[ai * 4 + m] = w;
	v_cvt_pk_bf16_f32 v128, v128, v129
	v_mul_f32_e32 v132, v133, v132
	v_mov_b32_dpp v178, v34 row_shr:1 row_mask:0xf bank_mask:0xf
	v_fmac_f32_e32 v179, v156, v178
	v_mov_b32_e32 v178, 0
	v_mov_b32_e32 v133, 0
	v_fmac_f32_e32 v179, v34, v160
	v_mov_b32_dpp v178, v63 row_ror:2 row_mask:0xf bank_mask:0xf
	v_mov_b32_dpp v133, v63 row_ror:1 row_mask:0xf bank_mask:0xf
	v_mul_f32_e32 v132, v179, v132
	v_mov_b32_dpp v178, v55 row_shr:2 row_mask:0xf bank_mask:0xf
	v_mov_b32_dpp v133, v55 row_shr:1 row_mask:0xf bank_mask:0xf
	v_fma_f32 v178, v165, v178, v149
	v_fmac_f32_e32 v178, v169, v133
	v_fmac_f32_e32 v178, v55, v173
	v_mul_f32_e32 v133, 0x3d372713, v178
	v_mul_f32_e32 v133, v178, v133
	v_fma_f32 v133, v178, v133, v178
	v_mul_f32_e32 v133, 0xbfcc422a, v133
	v_mul_f32_e32 v133, 0x3fb8aa3b, v133
	v_exp_f32_e32 v133, v133
	v_mov_b32_e32 v179, 0
	v_fma_f32 v181, v152, v181, v138
	v_fma_f32 v184, v153, v184, v139
	v_add_f32_e32 v133, 1.0, v133
	v_rcp_f32_e32 v133, v133
	v_mov_b32_dpp v179, v51 row_ror:1 row_mask:0xf bank_mask:0xf
	v_mul_f32_e32 v133, v178, v133
	s_nop 0
	v_mov_b32_dpp v179, v35 row_shr:1 row_mask:0xf bank_mask:0xf
	v_fmac_f32_e32 v180, v157, v179
	v_fmac_f32_e32 v180, v35, v161
	v_mul_f32_e32 v133, v180, v133
	v_cvt_pk_bf16_f32 v129, v132, v133
	v_mov_b32_e32 v133, 0
	v_mov_b32_e32 v132, 0
	v_mov_b32_e32 v179, 0
	v_mov_b32_dpp v133, v52 row_ror:2 row_mask:0xf bank_mask:0xf
	v_mov_b32_dpp v132, v52 row_ror:1 row_mask:0xf bank_mask:0xf
	v_mov_b32_e32 v178, 0
	v_mov_b32_dpp v133, v36 row_shr:2 row_mask:0xf bank_mask:0xf
	v_mov_b32_dpp v132, v36 row_shr:1 row_mask:0xf bank_mask:0xf
	v_fma_f32 v133, v162, v133, v146
	v_fmac_f32_e32 v133, v166, v132
	v_fmac_f32_e32 v133, v36, v170
	v_mul_f32_e32 v132, 0x3d372713, v133
	v_mul_f32_e32 v132, v133, v132
	v_fma_f32 v132, v133, v132, v133
	v_mul_f32_e32 v132, 0xbfcc422a, v132
	v_mul_f32_e32 v132, 0x3fb8aa3b, v132
	v_exp_f32_e32 v132, v132
	v_mov_b32_dpp v179, v32 row_ror:2 row_mask:0xf bank_mask:0xf
	v_mov_b32_dpp v178, v32 row_ror:1 row_mask:0xf bank_mask:0xf
	v_mov_b32_e32 v180, 0
	v_add_f32_e32 v132, 1.0, v132
	v_rcp_f32_e32 v132, v132
	v_mov_b32_dpp v179, v16 row_shr:2 row_mask:0xf bank_mask:0xf
	v_mov_b32_dpp v178, v16 row_shr:1 row_mask:0xf bank_mask:0xf
	v_fma_f32 v179, v150, v179, v136
	v_fmac_f32_e32 v179, v154, v178
	v_mov_b32_e32 v178, 0
	v_mul_f32_e32 v132, v133, v132
	v_mov_b32_e32 v133, 0
	v_mov_b32_dpp v178, v53 row_ror:2 row_mask:0xf bank_mask:0xf
	v_fmac_f32_e32 v179, v16, v158
	v_mov_b32_dpp v133, v53 row_ror:1 row_mask:0xf bank_mask:0xf
	v_mov_b32_dpp v178, v37 row_shr:2 row_mask:0xf bank_mask:0xf
	v_fma_f32 v178, v163, v178, v147
	v_mov_b32_dpp v133, v37 row_shr:1 row_mask:0xf bank_mask:0xf
	v_fmac_f32_e32 v178, v167, v133
	v_fmac_f32_e32 v178, v37, v171
	v_mul_f32_e32 v133, 0x3d372713, v178
	v_mul_f32_e32 v133, v178, v133
	v_fma_f32 v133, v178, v133, v178
	v_mul_f32_e32 v133, 0xbfcc422a, v133
	v_mul_f32_e32 v133, 0x3fb8aa3b, v133
	v_exp_f32_e32 v133, v133
	v_mul_f32_e32 v132, v179, v132
	v_mov_b32_e32 v179, 0
	v_mov_b32_dpp v180, v33 row_ror:2 row_mask:0xf bank_mask:0xf
	v_add_f32_e32 v133, 1.0, v133
	v_rcp_f32_e32 v133, v133
	v_mov_b32_dpp v179, v33 row_ror:1 row_mask:0xf bank_mask:0xf
	v_mov_b32_dpp v180, v17 row_shr:2 row_mask:0xf bank_mask:0xf
	v_fma_f32 v180, v151, v180, v137
	v_mov_b32_dpp v179, v17 row_shr:1 row_mask:0xf bank_mask:0xf
	v_fmac_f32_e32 v180, v155, v179
	v_mov_b32_e32 v179, 0
	v_mul_f32_e32 v133, v178, v133
	v_mov_b32_e32 v178, 0
	v_mov_b32_dpp v179, v54 row_ror:2 row_mask:0xf bank_mask:0xf
	v_fmac_f32_e32 v180, v17, v159
	v_mov_b32_dpp v178, v54 row_ror:1 row_mask:0xf bank_mask:0xf
	v_mov_b32_dpp v179, v38 row_shr:2 row_mask:0xf bank_mask:0xf
	v_fma_f32 v179, v164, v179, v148
	v_mov_b32_dpp v178, v38 row_shr:1 row_mask:0xf bank_mask:0xf
	v_fmac_f32_e32 v179, v168, v178
	v_fmac_f32_e32 v179, v38, v172
	v_mul_f32_e32 v178, 0x3d372713, v179
	v_mul_f32_e32 v178, v179, v178
	v_fma_f32 v178, v179, v178, v179
	v_mul_f32_e32 v178, 0xbfcc422a, v178
	v_mul_f32_e32 v178, 0x3fb8aa3b, v178
	v_exp_f32_e32 v178, v178
	v_mul_f32_e32 v133, v180, v133
	v_mov_b32_e32 v180, 0
	v_cvt_pk_bf16_f32 v132, v132, v133
	v_add_f32_e32 v178, 1.0, v178
	v_rcp_f32_e32 v178, v178
	v_mov_b32_dpp v180, v34 row_ror:1 row_mask:0xf bank_mask:0xf
	v_mul_f32_e32 v178, v179, v178
	s_nop 0
	v_mov_b32_dpp v180, v18 row_shr:1 row_mask:0xf bank_mask:0xf
	v_fmac_f32_e32 v181, v156, v180
	v_mov_b32_e32 v180, 0
	v_mov_b32_e32 v179, 0
	v_fmac_f32_e32 v181, v18, v160
	v_mov_b32_dpp v180, v55 row_ror:2 row_mask:0xf bank_mask:0xf
	v_mov_b32_dpp v179, v55 row_ror:1 row_mask:0xf bank_mask:0xf
	v_mul_f32_e32 v178, v181, v178
	v_mov_b32_dpp v180, v39 row_shr:2 row_mask:0xf bank_mask:0xf
	v_mov_b32_dpp v179, v39 row_shr:1 row_mask:0xf bank_mask:0xf
	v_fma_f32 v180, v165, v180, v149
	v_fmac_f32_e32 v180, v169, v179
	v_fmac_f32_e32 v180, v39, v173
	v_mul_f32_e32 v179, 0x3d372713, v180
	v_mul_f32_e32 v179, v180, v179
	v_fma_f32 v179, v180, v179, v180
	v_mul_f32_e32 v179, 0xbfcc422a, v179
	v_mul_f32_e32 v179, 0x3fb8aa3b, v179
	v_exp_f32_e32 v179, v179
	v_mov_b32_e32 v181, 0
	v_add_f32_e32 v179, 1.0, v179
	v_rcp_f32_e32 v179, v179
	v_mov_b32_dpp v181, v35 row_ror:1 row_mask:0xf bank_mask:0xf
	v_mul_f32_e32 v179, v180, v179
	s_nop 0
	v_mov_b32_dpp v181, v19 row_shr:1 row_mask:0xf bank_mask:0xf
	v_fmac_f32_e32 v184, v157, v181
	v_fmac_f32_e32 v184, v19, v161
	v_mul_f32_e32 v179, v184, v179
	v_cvt_pk_bf16_f32 v133, v178, v179
	v_mov_b32_e32 v179, 0
	v_mov_b32_e32 v178, 0
	v_mov_b32_e32 v180, 0
	v_mov_b32_dpp v179, v36 row_ror:2 row_mask:0xf bank_mask:0xf
	v_mov_b32_dpp v178, v36 row_ror:1 row_mask:0xf bank_mask:0xf
; __device__ __forceinline__ unsigned pk2(float lo, float hi) { unsigned r; asm("v_cvt_pk_bf16_f32 %0, %1, %2" : "=v"(r) : "v"(lo), "v"(hi)); return r; }
; __device__ __forceinline__ float gelu_tanh(float x) { const float y = 1.5957691216f * (x + 0.044715f * x * x * x); return x * __builtin_amdgcn_rcpf(1.0f + __expf(-y)); }
; __device__ __forceinline__ float dpp_shr1(float old, float src) { return __int_as_float(__builtin_amdgcn_update_dpp(__float_as_int(old), __float_as_int(src), 0x111, 0xf, 0xf, false)); }
; __device__ __forceinline__ float dpp_ror1(float src) { return __int_as_float(__builtin_amdgcn_update_dpp(0, __float_as_int(src), 0x121, 0xf, 0xf, false)); }
;     __device__ __forceinline__ void operator()(const f32x4 (&acc)[2][2][4][2], const Unit& u, int wr, int wc, int fr, int fq) const {
;     ...
;             const int jc = j0 + 4 * n;
;             const f32x4 wg0 = *(const f32x4*)(wconv + jc), wg1 = *(const f32x4*)(wconv + 2 * DFF + jc), wg2 = *(const f32x4*)(wconv + 4 * DFF + jc), bg = *(const f32x4*)(bconv + jc);
;             const f32x4 wv0 = *(const f32x4*)(wconv + DFF + jc), wv1 = *(const f32x4*)(wconv + 3 * DFF + jc), wv2 = *(const f32x4*)(wconv + 5 * DFF + jc), bv = *(const f32x4*)(bconv + DFF + jc);
; #pragma unroll
;             for (int ai = 0; ai < 2; ++ai)
; #pragma unroll
;                 for (int m = 0; m < 4; ++m) { const int row = row0 + ai * HALF + m * 16;
;                     const f32x4 g0 = acc[ai][0][m][n], v0 = acc[ai][1][m][n];
;                     f32x4 gp = (f32x4){0.f, 0.f, 0.f, 0.f}, vp = gp;
;                     if (m > 0) { gp = acc[ai][0][m > 0 ? m - 1 : 0][n]; vp = acc[ai][1][m > 0 ? m - 1 : 0][n]; }
;                     f32x4 f;
; #pragma unroll
;                     for (int j = 0; j < 4; ++j) {
;                         const float g1 = dpp_shr1(dpp_ror1(gp[j]), g0[j]), g2 = dpp_shr2(dpp_ror2(gp[j]), g0[j]);
;                         const float v1 = dpp_shr1(dpp_ror1(vp[j]), v0[j]), v2 = dpp_shr2(dpp_ror2(vp[j]), v0[j]);
;                         const float cg_ = bg[j] + g2 * wg0[j] + g1 * wg1[j] + g0[j] * wg2[j];
;                         const float cv_ = bv[j] + v2 * wv0[j] + v1 * wv1[j] + v0[j] * wv2[j];
;                         f[j] = gelu_tanh(cg_) * cv_; }
;                     u32x2 w; w.x = pk2(f[0], f[1]); w.y = pk2(f[2], f[3]);
;                     if (n == 0) res0[ai * 4 + m] = w;
	v_mov_b32_dpp v180, v16 row_ror:1 row_mask:0xf bank_mask:0xf
	v_mov_b32_dpp v179, v20 row_shr:2 row_mask:0xf bank_mask:0xf
	v_mov_b32_dpp v178, v20 row_shr:1 row_mask:0xf bank_mask:0xf
	v_fma_f32 v146, v162, v179, v146
	v_fmac_f32_e32 v146, v166, v178
	v_fmac_f32_e32 v146, v20, v170
	v_mul_f32_e32 v162, 0x3d372713, v146
	v_mul_f32_e32 v162, v146, v162
	v_fma_f32 v162, v146, v162, v146
	v_mul_f32_e32 v162, 0xbfcc422a, v162
	v_mul_f32_e32 v162, 0x3fb8aa3b, v162
	v_exp_f32_e32 v162, v162
	v_mov_b32_e32 v166, 0
	v_mov_b32_dpp v180, v4 row_shr:1 row_mask:0xf bank_mask:0xf
	v_add_f32_e32 v162, 1.0, v162
	v_mov_b32_dpp v166, v16 row_ror:2 row_mask:0xf bank_mask:0xf
	v_rcp_f32_e32 v162, v162
	s_nop 0
	v_mov_b32_dpp v166, v4 row_shr:2 row_mask:0xf bank_mask:0xf
	v_fma_f32 v136, v150, v166, v136
	v_fmac_f32_e32 v136, v154, v180
	v_fmac_f32_e32 v136, v4, v158
	v_mul_f32_e32 v146, v146, v162
	v_mul_f32_e32 v150, v136, v146
	v_mov_b32_e32 v146, 0
	v_mov_b32_e32 v136, 0
	global_load_dwordx4 v[178:181], v[176:177], off offset:16
	v_mov_b32_dpp v146, v37 row_ror:2 row_mask:0xf bank_mask:0xf
	v_mov_b32_dpp v136, v37 row_ror:1 row_mask:0xf bank_mask:0xf
	v_mov_b32_e32 v158, 0
	v_mov_b32_dpp v146, v21 row_shr:2 row_mask:0xf bank_mask:0xf
	v_mov_b32_dpp v136, v21 row_shr:1 row_mask:0xf bank_mask:0xf
	v_fma_f32 v186, v163, v146, v147
	v_fmac_f32_e32 v186, v167, v136
	v_or_b32_e32 v146, 4, v130
	v_fmac_f32_e32 v186, v21, v171
	v_ashrrev_i32_e32 v147, 31, v146
	v_mul_f32_e32 v136, 0x3d372713, v186
	v_lshlrev_b64 v[146:147], 2, v[146:147]
	v_mul_f32_e32 v136, v186, v136
	v_lshl_add_u64 v[170:171], s[60:61], 0, v[146:147]
	v_fma_f32 v136, v186, v136, v186
	v_lshl_add_u64 v[162:163], s[56:57], 0, v[146:147]
	v_lshl_add_u64 v[166:167], s[58:59], 0, v[146:147]
	global_load_dwordx4 v[198:201], v[170:171], off
	global_load_dwordx4 v[206:209], v[182:183], off offset:16
	s_nop 0
	global_load_dwordx4 v[182:185], v[162:163], off
	global_load_dwordx4 v[202:205], v[166:167], off
	v_mul_f32_e32 v136, 0xbfcc422a, v136
	v_mul_f32_e32 v136, 0x3fb8aa3b, v136
	v_exp_f32_e32 v136, v136
	v_mov_b32_e32 v154, 0
	v_mov_b32_dpp v158, v17 row_ror:2 row_mask:0xf bank_mask:0xf
	v_add_f32_e32 v136, 1.0, v136
	v_rcp_f32_e32 v136, v136
	v_mov_b32_dpp v154, v17 row_ror:1 row_mask:0xf bank_mask:0xf
	v_mov_b32_dpp v158, v5 row_shr:2 row_mask:0xf bank_mask:0xf
	v_fma_f32 v151, v151, v158, v137
	v_mov_b32_dpp v154, v5 row_shr:1 row_mask:0xf bank_mask:0xf
	v_fmac_f32_e32 v151, v155, v154
	v_mul_f32_e32 v154, v186, v136
	v_lshl_add_u64 v[136:137], s[46:47], 0, v[146:147]
	global_load_dwordx4 v[186:189], v[136:137], off
	v_lshl_add_u64 v[136:137], s[48:49], 0, v[146:147]
	v_lshl_add_u64 v[146:147], s[54:55], 0, v[146:147]
	global_load_dwordx4 v[190:193], v[136:137], off
	global_load_dwordx4 v[194:197], v[146:147], off
	v_mov_b32_e32 v146, 0
	v_mov_b32_e32 v137, 0
	v_mov_b32_e32 v147, 0
	v_mov_b32_dpp v146, v38 row_ror:2 row_mask:0xf bank_mask:0xf
	v_mov_b32_dpp v137, v38 row_ror:1 row_mask:0xf bank_mask:0xf
	v_mov_b32_dpp v147, v18 row_ror:1 row_mask:0xf bank_mask:0xf
	v_mov_b32_dpp v146, v22 row_shr:2 row_mask:0xf bank_mask:0xf
	v_mov_b32_dpp v137, v22 row_shr:1 row_mask:0xf bank_mask:0xf
	v_fma_f32 v146, v164, v146, v148
	v_fmac_f32_e32 v146, v168, v137
	v_fmac_f32_e32 v146, v22, v172
	v_mul_f32_e32 v137, 0x3d372713, v146
	v_mul_f32_e32 v137, v146, v137
	v_fma_f32 v137, v146, v137, v146
	v_mul_f32_e32 v137, 0xbfcc422a, v137
	v_mul_f32_e32 v137, 0x3fb8aa3b, v137
	v_exp_f32_e32 v137, v137
	v_mov_b32_e32 v148, 0
	v_mov_b32_dpp v147, v6 row_shr:1 row_mask:0xf bank_mask:0xf
	v_fmac_f32_e32 v151, v5, v159
	v_add_f32_e32 v137, 1.0, v137
	v_mov_b32_dpp v148, v18 row_ror:2 row_mask:0xf bank_mask:0xf
	v_rcp_f32_e32 v137, v137
	v_mul_f32_e32 v136, v151, v154
	v_mov_b32_dpp v148, v6 row_shr:2 row_mask:0xf bank_mask:0xf
	v_fma_f32 v138, v152, v148, v138
	v_fmac_f32_e32 v138, v156, v147
	v_fmac_f32_e32 v138, v6, v160
	v_mul_f32_e32 v137, v146, v137
	v_mov_b32_e32 v146, 0
	v_mul_f32_e32 v137, v138, v137
	v_mov_b32_e32 v138, 0
	v_mov_b32_dpp v146, v39 row_ror:2 row_mask:0xf bank_mask:0xf
	v_mov_b32_e32 v147, 0
	v_mov_b32_dpp v138, v39 row_ror:1 row_mask:0xf bank_mask:0xf
	v_mov_b32_dpp v146, v23 row_shr:2 row_mask:0xf bank_mask:0xf
	v_fmac_f32_e32 v149, v165, v146
	v_mov_b32_dpp v138, v23 row_shr:1 row_mask:0xf bank_mask:0xf
	v_fmac_f32_e32 v149, v169, v138
	v_fmac_f32_e32 v149, v23, v173
	v_mul_f32_e32 v138, 0x3d372713, v149
	v_mul_f32_e32 v138, v149, v138
	v_fma_f32 v138, v149, v138, v149
	v_mul_f32_e32 v138, 0xbfcc422a, v138
	v_mul_f32_e32 v138, 0x3fb8aa3b, v138
	v_exp_f32_e32 v138, v138
	v_mov_b32_e32 v146, 0
	v_mov_b32_dpp v147, v19 row_ror:1 row_mask:0xf bank_mask:0xf
	v_mov_b32_e32 v148, v242
	v_add_f32_e32 v138, 1.0, v138
	v_mov_b32_dpp v146, v19 row_ror:2 row_mask:0xf bank_mask:0xf
	v_rcp_f32_e32 v138, v138
	v_mov_b32_dpp v147, v7 row_shr:1 row_mask:0xf bank_mask:0xf
	v_mov_b32_dpp v146, v7 row_shr:2 row_mask:0xf bank_mask:0xf
	v_fmac_f32_e32 v139, v153, v146
	v_fmac_f32_e32 v139, v157, v147
	v_fmac_f32_e32 v139, v7, v161
	v_mul_f32_e32 v138, v149, v138
	v_mul_f32_e32 v139, v139, v138
	v_cvt_pk_bf16_f32 v139, v137, v139
	v_mov_b32_e32 v137, v242
	v_cvt_pk_bf16_f32 v138, v150, v136
	v_mov_b32_e32 v136, v241
	v_mov_b32_e32 v147, v242
	v_mov_b32_dpp v137, v120 row_shr:2 row_mask:0xf bank_mask:0xf
	v_mov_b32_dpp v136, v120 row_shr:1 row_mask:0xf bank_mask:0xf
	s_waitcnt vmcnt(0)
; __device__ __forceinline__ unsigned pk2(float lo, float hi) { unsigned r; asm("v_cvt_pk_bf16_f32 %0, %1, %2" : "=v"(r) : "v"(lo), "v"(hi)); return r; }
; __device__ __forceinline__ float gelu_tanh(float x) { const float y = 1.5957691216f * (x + 0.044715f * x * x * x); return x * __builtin_amdgcn_rcpf(1.0f + __expf(-y)); }
; __device__ __forceinline__ float dpp_shr1(float old, float src) { return __int_as_float(__builtin_amdgcn_update_dpp(__float_as_int(old), __float_as_int(src), 0x111, 0xf, 0xf, false)); }
; __device__ __forceinline__ float dpp_shr2(float old, float src) { return __int_as_float(__builtin_amdgcn_update_dpp(__float_as_int(old), __float_as_int(src), 0x112, 0xf, 0xf, false)); }
; __device__ __forceinline__ float dpp_ror1(float src) { return __int_as_float(__builtin_amdgcn_update_dpp(0, __float_as_int(src), 0x121, 0xf, 0xf, false)); }
; __device__ __forceinline__ float dpp_ror2(float src) { return __int_as_float(__builtin_amdgcn_update_dpp(0, __float_as_int(src), 0x122, 0xf, 0xf, false)); }
;     __device__ __forceinline__ void operator()(const f32x4 (&acc)[2][2][4][2], const Unit& u, int wr, int wc, int fr, int fq) const {
;     ...
;                     for (int j = 0; j < 4; ++j) {
;                         const float g1 = dpp_shr1(dpp_ror1(gp[j]), g0[j]), g2 = dpp_shr2(dpp_ror2(gp[j]), g0[j]);
;                         const float v1 = dpp_shr1(dpp_ror1(vp[j]), v0[j]), v2 = dpp_shr2(dpp_ror2(vp[j]), v0[j]);
;                         const float cg_ = bg[j] + g2 * wg0[j] + g1 * wg1[j] + g0[j] * wg2[j];
;                         const float cv_ = bv[j] + v2 * wv0[j] + v1 * wv1[j] + v0[j] * wv2[j];
;                         f[j] = gelu_tanh(cg_) * cv_; }
;                     u32x2 w; w.x = pk2(f[0], f[1]); w.y = pk2(f[2], f[3]);
;                     if (n == 0) res0[ai * 4 + m] = w;
;                     else if (m > 0 || fr >= 2) { u32x4 w4; w4.x = res0[ai * 4 + m].x; w4.y = res0[ai * 4 + m].y; w4.z = w.x; w4.w = w.y; *(u32x4*)(F + (size_t)row * DFF + j0) = w4; }
	v_fma_f32 v137, v206, v137, v178
	v_fmac_f32_e32 v137, v198, v136
	v_fmac_f32_e32 v137, v120, v202
	v_mul_f32_e32 v136, 0x3d372713, v137
	v_mul_f32_e32 v136, v137, v136
	v_fma_f32 v136, v137, v136, v137
	v_mul_f32_e32 v136, 0xbfcc422a, v136
	v_mul_f32_e32 v136, 0x3fb8aa3b, v136
	v_exp_f32_e32 v136, v136
	v_mov_b32_e32 v146, v241
	v_mov_b32_dpp v147, v104 row_shr:2 row_mask:0xf bank_mask:0xf
	v_fma_f32 v147, v182, v147, v186
	v_add_f32_e32 v136, 1.0, v136
	v_rcp_f32_e32 v136, v136
	v_mov_b32_dpp v146, v104 row_shr:1 row_mask:0xf bank_mask:0xf
	v_fmac_f32_e32 v147, v194, v146
	v_mov_b32_e32 v146, v242
	v_mul_f32_e32 v136, v137, v136
	v_mov_b32_e32 v137, v241
	v_mov_b32_dpp v146, v121 row_shr:2 row_mask:0xf bank_mask:0xf
	v_fma_f32 v146, v207, v146, v179
	v_mov_b32_dpp v137, v121 row_shr:1 row_mask:0xf bank_mask:0xf
	v_fmac_f32_e32 v146, v199, v137
	v_fmac_f32_e32 v146, v121, v203
	v_mul_f32_e32 v137, 0x3d372713, v146
	v_mul_f32_e32 v137, v146, v137
	v_fma_f32 v137, v146, v137, v146
	v_mul_f32_e32 v137, 0xbfcc422a, v137
	v_mul_f32_e32 v137, 0x3fb8aa3b, v137
	v_exp_f32_e32 v137, v137
	v_fmac_f32_e32 v147, v104, v190
	v_mul_f32_e32 v136, v147, v136
	v_mov_b32_e32 v147, v241
	v_add_f32_e32 v137, 1.0, v137
	v_rcp_f32_e32 v137, v137
	v_mov_b32_dpp v148, v105 row_shr:2 row_mask:0xf bank_mask:0xf
	v_mov_b32_dpp v147, v105 row_shr:1 row_mask:0xf bank_mask:0xf
	v_fma_f32 v148, v183, v148, v187
	v_fmac_f32_e32 v148, v195, v147
	v_mov_b32_e32 v147, v242
	v_mul_f32_e32 v137, v146, v137
	v_mov_b32_e32 v146, v241
	v_mov_b32_dpp v147, v122 row_shr:2 row_mask:0xf bank_mask:0xf
	v_fma_f32 v147, v208, v147, v180
	v_mov_b32_dpp v146, v122 row_shr:1 row_mask:0xf bank_mask:0xf
	v_fmac_f32_e32 v147, v200, v146
	v_fmac_f32_e32 v147, v122, v204
	v_mul_f32_e32 v146, 0x3d372713, v147
	v_mul_f32_e32 v146, v147, v146
	v_fma_f32 v146, v147, v146, v147
	v_mul_f32_e32 v146, 0xbfcc422a, v146
	v_mul_f32_e32 v146, 0x3fb8aa3b, v146
	v_exp_f32_e32 v146, v146
	v_fmac_f32_e32 v148, v105, v191
	v_mov_b32_e32 v149, v242
	v_mul_f32_e32 v137, v148, v137
	v_add_f32_e32 v146, 1.0, v146
	v_rcp_f32_e32 v146, v146
	v_mov_b32_e32 v148, v241
	v_mov_b32_dpp v149, v106 row_shr:2 row_mask:0xf bank_mask:0xf
	v_fma_f32 v149, v184, v149, v188
	v_mov_b32_dpp v148, v106 row_shr:1 row_mask:0xf bank_mask:0xf
	v_fmac_f32_e32 v149, v196, v148
	v_mov_b32_e32 v148, v242
	v_mul_f32_e32 v146, v147, v146
	v_mov_b32_e32 v147, v241
	v_mov_b32_dpp v148, v123 row_shr:2 row_mask:0xf bank_mask:0xf
	v_fma_f32 v148, v209, v148, v181
	v_mov_b32_dpp v147, v123 row_shr:1 row_mask:0xf bank_mask:0xf
	v_fmac_f32_e32 v148, v201, v147
	v_fmac_f32_e32 v148, v123, v205
	v_mul_f32_e32 v147, 0x3d372713, v148
	v_mul_f32_e32 v147, v148, v147
	v_fma_f32 v147, v148, v147, v148
	v_mul_f32_e32 v147, 0xbfcc422a, v147
	v_mul_f32_e32 v147, 0x3fb8aa3b, v147
	v_exp_f32_e32 v147, v147
	v_fmac_f32_e32 v149, v106, v192
	v_mov_b32_dpp v242, v107 row_shr:2 row_mask:0xf bank_mask:0xf
	v_mul_f32_e32 v146, v149, v146
	v_add_f32_e32 v147, 1.0, v147
	v_rcp_f32_e32 v147, v147
	v_mov_b32_dpp v241, v107 row_shr:1 row_mask:0xf bank_mask:0xf
	v_fma_f32 v149, v185, v242, v189
	v_fmac_f32_e32 v149, v197, v241
	v_fmac_f32_e32 v149, v107, v193
	v_mul_f32_e32 v147, v148, v147
	v_mul_f32_e32 v147, v149, v147
	v_cvt_pk_bf16_f32 v176, v136, v137
	v_cvt_pk_bf16_f32 v177, v146, v147
	s_and_saveexec_b64 s[0:1], s[8:9]
	s_cbranch_execz .LBB0_1204
	v_mov_b64_e32 v[136:137], s[40:41]
	v_mad_i64_i32 v[136:137], s[42:43], v248, s4, v[136:137]
	v_lshl_add_u64 v[136:137], v[130:131], 1, v[136:137]
	global_store_dwordx4 v[136:137], v[174:177], off

; #define PG8_STAGE(bufoff, gbase, voff) do { _Pragma("unroll") for (int _i = 0; _i < 2; ++_i) \
;         __builtin_amdgcn_global_load_lds((const unsigned*)((const char*)(gbase) + (voff)[_i]), (LAS unsigned*)(lds + (bufoff) + ldsw + _i * 8192), 16, 0, 0); } while (0)
; #define PG8_LDA(dst, b, h) do { _Pragma("unroll") for (int m = 0; m < 4; ++m) _Pragma("unroll") for (int k = 0; k < 2; ++k) dst[m][k] = *(const LAS bf16x8*)(lds + PG8_SA(b, h) + aoff + m * 2048 + k * 1024); } while (0)
; #define PG8_LDB(dst, b, h) do { _Pragma("unroll") for (int n = 0; n < 2; ++n) _Pragma("unroll") for (int k = 0; k < 2; ++k) dst[n][k] = *(const LAS bf16x8*)(lds + PG8_SB(b, h) + boff + n * 2048 + k * 1024); } while (0)
; #define PG8_MMA(ai, bj, At, Bt) do { __builtin_amdgcn_s_setprio(1); _Pragma("unroll") for (int m = 0; m < 4; ++m) _Pragma("unroll") for (int n = 0; n < 2; ++n) _Pragma("unroll") for (int k = 0; k < 2; ++k) \
;         acc[ai][bj][m][n] = __builtin_amdgcn_mfma_f32_16x16x32_bf16(Bt[n][k], At[m][k], acc[ai][bj][m][n], 0, 0, 0); __builtin_amdgcn_s_setprio(0); } while (0)
; #define PG8_WAIT_V(n) asm volatile("s_waitcnt vmcnt(" #n ")" ::: "memory")
; #define PG8_WAIT_L(n) asm volatile("s_waitcnt lgkmcnt(" #n ")" ::: "memory")
; #define PG8_BAR __builtin_amdgcn_s_barrier()
; #define PG8_SCHED __builtin_amdgcn_sched_barrier(0)
; template <class Epi, class S_t>
; __device__ __forceinline__ void gemm_phase(LAS unsigned char* lds, int lda, int ldb, const S_t& S, const Epi& E) {
;     ...
;             PG8_LDB(B0, 0, 0); PG8_SCHED; PG8_LDA(At, 0, 0); PG8_STAGE(PG8_SA(1, 1), a1 + hstepA, voffA);
;             PG8_WAIT_L(8); PG8_BAR; PG8_WAIT_L(0); PG8_MMA(0, 0, At, B0); PG8_BAR; PG8_SCHED;
;             PG8_LDB(B1, 0, 1); PG8_STAGE(PG8_SB(0, 0), b2, voffB);
;             PG8_BAR; PG8_WAIT_L(0); PG8_MMA(0, 1, At, B1); PG8_BAR;
;             PG8_LDA(At, 0, 1); PG8_STAGE(PG8_SA(0, 0), a2, voffA);
;             PG8_BAR; PG8_WAIT_L(0); PG8_MMA(1, 0, At, B0); PG8_BAR; PG8_SCHED;
;             PG8_STAGE(PG8_SB(0, 1), b2 + hstepB, voffB);
;             PG8_WAIT_V(6); PG8_BAR; PG8_MMA(1, 1, At, B1); PG8_BAR;
.LBB0_1383:
	ds_read_b128 v[150:153], v146
	ds_read_b128 v[154:157], v146 offset:1024
	ds_read_b128 v[158:161], v146 offset:2048
	ds_read_b128 v[162:165], v146 offset:3072
	s_add_i32 s71, s50, 2
	s_add_u32 s48, s46, 0x100
	s_addc_u32 s49, s47, 0
	s_cmp_eq_u32 s0, s50
	s_cselect_b32 s50, s40, s1
	s_cselect_b32 s53, s43, s49
	s_cselect_b32 s52, s42, s48
	s_cselect_b32 s51, s41, s70
	s_add_i32 m0, s20, 0xc000
	ds_read_b128 v[166:169], v147
	ds_read_b128 v[170:173], v147 offset:1024
	ds_read_b128 v[174:177], v147 offset:2048
	ds_read_b128 v[178:181], v147 offset:3072
	ds_read_b128 v[182:185], v147 offset:4096
	ds_read_b128 v[186:189], v147 offset:5120
	ds_read_b128 v[190:193], v147 offset:6144
	ds_read_b128 v[194:197], v147 offset:7168
	global_load_lds_dwordx4 v136, s[46:47]
	s_add_i32 m0, s20, 0xe000
	s_nop 0
	global_load_lds_dwordx4 v138, s[46:47]
	s_waitcnt lgkmcnt(8)
	s_barrier
	s_waitcnt lgkmcnt(0)
	s_setprio 1
	s_waitcnt lgkmcnt(0)
	v_mfma_f32_16x16x32_bf16 v[124:127], v[150:153], v[166:169], v[124:127]
	v_mfma_f32_16x16x32_bf16 v[120:123], v[158:161], v[166:169], v[120:123]
	v_mfma_f32_16x16x32_bf16 v[112:115], v[150:153], v[174:177], v[112:115]
	v_mfma_f32_16x16x32_bf16 v[104:107], v[158:161], v[174:177], v[104:107]
	v_mfma_f32_16x16x32_bf16 v[96:99], v[150:153], v[182:185], v[96:99]
	v_mfma_f32_16x16x32_bf16 v[88:91], v[158:161], v[182:185], v[88:91]
	v_mfma_f32_16x16x32_bf16 v[80:83], v[150:153], v[190:193], v[80:83]
	v_mfma_f32_16x16x32_bf16 v[72:75], v[158:161], v[190:193], v[72:75]
	v_mfma_f32_16x16x32_bf16 v[124:127], v[154:157], v[170:173], v[124:127]
	v_mfma_f32_16x16x32_bf16 v[120:123], v[162:165], v[170:173], v[120:123]
	v_mfma_f32_16x16x32_bf16 v[112:115], v[154:157], v[178:181], v[112:115]
	v_mfma_f32_16x16x32_bf16 v[104:107], v[162:165], v[178:181], v[104:107]
	v_mfma_f32_16x16x32_bf16 v[96:99], v[154:157], v[186:189], v[96:99]
	v_mfma_f32_16x16x32_bf16 v[88:91], v[162:165], v[186:189], v[88:91]
	v_mfma_f32_16x16x32_bf16 v[80:83], v[154:157], v[194:197], v[80:83]
	v_mfma_f32_16x16x32_bf16 v[72:75], v[162:165], v[194:197], v[72:75]
	s_setprio 0
	s_barrier
	s_add_i32 s33, s88, s17
	s_add_u32 s98, s50, s4
	s_addc_u32 s99, s51, s5
	s_mov_b32 m0, s33
	ds_read_b128 v[198:201], v148
	ds_read_b128 v[202:205], v148 offset:1024
	ds_read_b128 v[206:209], v148 offset:2048
	ds_read_b128 v[224:227], v148 offset:3072
	global_load_lds_dwordx4 v130, s[50:51]
	s_add_i32 m0, s33, 0x2000
	s_nop 0
	global_load_lds_dwordx4 v134, s[50:51]
	s_barrier
	s_waitcnt lgkmcnt(0)
	s_setprio 1
	s_waitcnt lgkmcnt(0)
	v_mfma_f32_16x16x32_bf16 v[116:119], v[198:201], v[166:169], v[116:119]
	v_mfma_f32_16x16x32_bf16 v[108:111], v[206:209], v[166:169], v[108:111]
	v_mfma_f32_16x16x32_bf16 v[100:103], v[198:201], v[174:177], v[100:103]
	v_mfma_f32_16x16x32_bf16 v[92:95], v[206:209], v[174:177], v[92:95]
	v_mfma_f32_16x16x32_bf16 v[84:87], v[198:201], v[182:185], v[84:87]
	v_mfma_f32_16x16x32_bf16 v[76:79], v[206:209], v[182:185], v[76:79]
	v_mfma_f32_16x16x32_bf16 v[68:71], v[198:201], v[190:193], v[68:71]
	v_mfma_f32_16x16x32_bf16 v[64:67], v[206:209], v[190:193], v[64:67]
	v_mfma_f32_16x16x32_bf16 v[116:119], v[202:205], v[170:173], v[116:119]
	v_mfma_f32_16x16x32_bf16 v[108:111], v[224:227], v[170:173], v[108:111]
	v_mfma_f32_16x16x32_bf16 v[100:103], v[202:205], v[178:181], v[100:103]
	v_mfma_f32_16x16x32_bf16 v[92:95], v[224:227], v[178:181], v[92:95]
	v_mfma_f32_16x16x32_bf16 v[84:87], v[202:205], v[186:189], v[84:87]
	v_mfma_f32_16x16x32_bf16 v[76:79], v[224:227], v[186:189], v[76:79]
	v_mfma_f32_16x16x32_bf16 v[68:71], v[202:205], v[194:197], v[68:71]
	v_mfma_f32_16x16x32_bf16 v[64:67], v[224:227], v[194:197], v[64:67]
	s_setprio 0
	s_mov_b32 m0, s20
	s_add_u32 s100, s52, s4
	s_addc_u32 s101, s53, s5
	s_barrier
	ds_read_b128 v[166:169], v147 offset:16384
	ds_read_b128 v[170:173], v147 offset:17408
	ds_read_b128 v[174:177], v147 offset:18432
	ds_read_b128 v[178:181], v147 offset:19456
	ds_read_b128 v[182:185], v147 offset:20480
	ds_read_b128 v[186:189], v147 offset:21504
	ds_read_b128 v[190:193], v147 offset:22528
	ds_read_b128 v[194:197], v147 offset:23552
	global_load_lds_dwordx4 v128, s[52:53]
	s_mov_b32 m0, s21
	s_nop 0
	global_load_lds_dwordx4 v132, s[52:53]
	s_barrier
	s_waitcnt lgkmcnt(0)
	s_setprio 1
	s_waitcnt lgkmcnt(0)
	v_mfma_f32_16x16x32_bf16 v[60:63], v[150:153], v[166:169], v[60:63]
	v_mfma_f32_16x16x32_bf16 v[56:59], v[158:161], v[166:169], v[56:59]
	v_mfma_f32_16x16x32_bf16 v[52:55], v[150:153], v[174:177], v[52:55]
	v_mfma_f32_16x16x32_bf16 v[44:47], v[158:161], v[174:177], v[44:47]
	v_mfma_f32_16x16x32_bf16 v[36:39], v[150:153], v[182:185], v[36:39]
	v_mfma_f32_16x16x32_bf16 v[28:31], v[158:161], v[182:185], v[28:31]
	v_mfma_f32_16x16x32_bf16 v[20:23], v[150:153], v[190:193], v[20:23]
	v_mfma_f32_16x16x32_bf16 v[12:15], v[158:161], v[190:193], v[12:15]
	v_mfma_f32_16x16x32_bf16 v[60:63], v[154:157], v[170:173], v[60:63]
	v_mfma_f32_16x16x32_bf16 v[56:59], v[162:165], v[170:173], v[56:59]
	v_mfma_f32_16x16x32_bf16 v[52:55], v[154:157], v[178:181], v[52:55]
	v_mfma_f32_16x16x32_bf16 v[44:47], v[162:165], v[178:181], v[44:47]
	v_mfma_f32_16x16x32_bf16 v[36:39], v[154:157], v[186:189], v[36:39]
	v_mfma_f32_16x16x32_bf16 v[28:31], v[162:165], v[186:189], v[28:31]
	v_mfma_f32_16x16x32_bf16 v[20:23], v[154:157], v[194:197], v[20:23]
	v_mfma_f32_16x16x32_bf16 v[12:15], v[162:165], v[194:197], v[12:15]
	s_setprio 0
	s_barrier
	s_add_u32 s46, s50, 0x180000
	s_addc_u32 s47, s51, 0
	s_add_i32 s33, s89, s17
	s_mov_b32 m0, s33
	s_nop 0
	global_load_lds_dwordx4 v130, s[46:47]
	s_add_i32 m0, s33, 0x2000
	s_nop 0
	global_load_lds_dwordx4 v134, s[46:47]
	s_waitcnt vmcnt(6)
	s_barrier
; #define PG8_STAGE(bufoff, gbase, voff) do { _Pragma("unroll") for (int _i = 0; _i < 2; ++_i) \
;         __builtin_amdgcn_global_load_lds((const unsigned*)((const char*)(gbase) + (voff)[_i]), (LAS unsigned*)(lds + (bufoff) + ldsw + _i * 8192), 16, 0, 0); } while (0)
; #define PG8_LDA(dst, b, h) do { _Pragma("unroll") for (int m = 0; m < 4; ++m) _Pragma("unroll") for (int k = 0; k < 2; ++k) dst[m][k] = *(const LAS bf16x8*)(lds + PG8_SA(b, h) + aoff + m * 2048 + k * 1024); } while (0)
; #define PG8_LDB(dst, b, h) do { _Pragma("unroll") for (int n = 0; n < 2; ++n) _Pragma("unroll") for (int k = 0; k < 2; ++k) dst[n][k] = *(const LAS bf16x8*)(lds + PG8_SB(b, h) + boff + n * 2048 + k * 1024); } while (0)
; #define PG8_MMA(ai, bj, At, Bt) do { __builtin_amdgcn_s_setprio(1); _Pragma("unroll") for (int m = 0; m < 4; ++m) _Pragma("unroll") for (int n = 0; n < 2; ++n) _Pragma("unroll") for (int k = 0; k < 2; ++k) \
;         acc[ai][bj][m][n] = __builtin_amdgcn_mfma_f32_16x16x32_bf16(Bt[n][k], At[m][k], acc[ai][bj][m][n], 0, 0, 0); __builtin_amdgcn_s_setprio(0); } while (0)
; #define PG8_WAIT_V(n) asm volatile("s_waitcnt vmcnt(" #n ")" ::: "memory")
; #define PG8_WAIT_L(n) asm volatile("s_waitcnt lgkmcnt(" #n ")" ::: "memory")
; #define PG8_BAR __builtin_amdgcn_s_barrier()
; #define PG8_SCHED __builtin_amdgcn_sched_barrier(0)
; template <class Epi, class S_t>
; __device__ __forceinline__ void gemm_phase(LAS unsigned char* lds, int lda, int ldb, const S_t& S, const Epi& E) {
;     ...
;             PG8_WAIT_V(6); PG8_BAR; PG8_MMA(1, 1, At, B1); PG8_BAR;
;             PG8_LDB(B0, 1, 0); PG8_SCHED; PG8_LDA(At, 1, 0); PG8_STAGE(PG8_SA(0, 1), a2 + hstepA, voffA);
;             PG8_WAIT_L(8); PG8_BAR; PG8_WAIT_L(0); PG8_MMA(0, 0, At, B0); PG8_BAR; PG8_SCHED;
;             PG8_LDB(B1, 1, 1); PG8_STAGE(PG8_SB(1, 0), b3, voffB);
;             PG8_BAR; PG8_WAIT_L(0); PG8_MMA(0, 1, At, B1); PG8_BAR;
;             PG8_LDA(At, 1, 1); PG8_STAGE(PG8_SA(1, 0), a3, voffA);
;             PG8_BAR; PG8_WAIT_L(0); PG8_MMA(1, 0, At, B0); PG8_BAR; PG8_SCHED;
	s_setprio 1
	v_mfma_f32_16x16x32_bf16 v[48:51], v[198:201], v[166:169], v[48:51]
	v_mfma_f32_16x16x32_bf16 v[40:43], v[206:209], v[166:169], v[40:43]
	v_mfma_f32_16x16x32_bf16 v[32:35], v[198:201], v[174:177], v[32:35]
	v_mfma_f32_16x16x32_bf16 v[24:27], v[206:209], v[174:177], v[24:27]
	v_mfma_f32_16x16x32_bf16 v[16:19], v[198:201], v[182:185], v[16:19]
	v_mfma_f32_16x16x32_bf16 v[8:11], v[206:209], v[182:185], v[8:11]
	v_mfma_f32_16x16x32_bf16 v[4:7], v[198:201], v[190:193], v[4:7]
	v_mfma_f32_16x16x32_bf16 v[0:3], v[206:209], v[190:193], v[0:3]
	v_mfma_f32_16x16x32_bf16 v[48:51], v[202:205], v[170:173], v[48:51]
	v_mfma_f32_16x16x32_bf16 v[40:43], v[224:227], v[170:173], v[40:43]
	v_mfma_f32_16x16x32_bf16 v[32:35], v[202:205], v[178:181], v[32:35]
	v_mfma_f32_16x16x32_bf16 v[24:27], v[224:227], v[178:181], v[24:27]
	v_mfma_f32_16x16x32_bf16 v[16:19], v[202:205], v[186:189], v[16:19]
	v_mfma_f32_16x16x32_bf16 v[8:11], v[224:227], v[186:189], v[8:11]
	v_mfma_f32_16x16x32_bf16 v[4:7], v[202:205], v[194:197], v[4:7]
	v_mfma_f32_16x16x32_bf16 v[0:3], v[224:227], v[194:197], v[0:3]
	s_setprio 0
	v_add_u32_e32 v149, s90, v143
	s_barrier
	ds_read_b128 v[150:153], v149
	ds_read_b128 v[154:157], v149 offset:1024
	ds_read_b128 v[158:161], v149 offset:2048
	ds_read_b128 v[162:165], v149 offset:3072
	s_add_u32 s46, s52, 0x180000
	s_addc_u32 s47, s53, 0
	s_mov_b32 m0, s35
	ds_read_b128 v[166:169], v147 offset:32768
	ds_read_b128 v[170:173], v147 offset:33792
	ds_read_b128 v[174:177], v147 offset:34816
	ds_read_b128 v[178:181], v147 offset:35840
	ds_read_b128 v[182:185], v147 offset:36864
	ds_read_b128 v[186:189], v147 offset:37888
	ds_read_b128 v[190:193], v147 offset:38912
	ds_read_b128 v[194:197], v147 offset:39936
	global_load_lds_dwordx4 v128, s[46:47]
	s_mov_b32 m0, s54
	s_nop 0
	global_load_lds_dwordx4 v132, s[46:47]
	s_waitcnt lgkmcnt(8)
	s_barrier
	s_waitcnt lgkmcnt(0)
	s_setprio 1
	s_waitcnt lgkmcnt(0)
	v_mfma_f32_16x16x32_bf16 v[124:127], v[150:153], v[166:169], v[124:127]
	v_mfma_f32_16x16x32_bf16 v[120:123], v[158:161], v[166:169], v[120:123]
	v_mfma_f32_16x16x32_bf16 v[112:115], v[150:153], v[174:177], v[112:115]
	v_mfma_f32_16x16x32_bf16 v[104:107], v[158:161], v[174:177], v[104:107]
	v_mfma_f32_16x16x32_bf16 v[96:99], v[150:153], v[182:185], v[96:99]
	v_mfma_f32_16x16x32_bf16 v[88:91], v[158:161], v[182:185], v[88:91]
	v_mfma_f32_16x16x32_bf16 v[80:83], v[150:153], v[190:193], v[80:83]
	v_mfma_f32_16x16x32_bf16 v[72:75], v[158:161], v[190:193], v[72:75]
	v_mfma_f32_16x16x32_bf16 v[124:127], v[154:157], v[170:173], v[124:127]
	v_mfma_f32_16x16x32_bf16 v[120:123], v[162:165], v[170:173], v[120:123]
	v_mfma_f32_16x16x32_bf16 v[112:115], v[154:157], v[178:181], v[112:115]
	v_mfma_f32_16x16x32_bf16 v[104:107], v[162:165], v[178:181], v[104:107]
	v_mfma_f32_16x16x32_bf16 v[96:99], v[154:157], v[186:189], v[96:99]
	v_mfma_f32_16x16x32_bf16 v[88:91], v[162:165], v[186:189], v[88:91]
	v_mfma_f32_16x16x32_bf16 v[80:83], v[154:157], v[194:197], v[80:83]
	v_mfma_f32_16x16x32_bf16 v[72:75], v[162:165], v[194:197], v[72:75]
	s_setprio 0
	s_barrier
	s_add_i32 s33, s90, s17
	v_add_u32_e32 v149, s91, v143
	s_mov_b32 m0, s33
	ds_read_b128 v[198:201], v149
	ds_read_b128 v[202:205], v149 offset:1024
	ds_read_b128 v[206:209], v149 offset:2048
	ds_read_b128 v[224:227], v149 offset:3072
	global_load_lds_dwordx4 v130, s[98:99]
	s_add_i32 m0, s33, 0x2000
	s_nop 0
	global_load_lds_dwordx4 v134, s[98:99]
	s_barrier
	s_waitcnt lgkmcnt(0)
	s_setprio 1
	s_waitcnt lgkmcnt(0)
	v_mfma_f32_16x16x32_bf16 v[116:119], v[198:201], v[166:169], v[116:119]
	v_mfma_f32_16x16x32_bf16 v[108:111], v[206:209], v[166:169], v[108:111]
	v_mfma_f32_16x16x32_bf16 v[100:103], v[198:201], v[174:177], v[100:103]
	v_mfma_f32_16x16x32_bf16 v[92:95], v[206:209], v[174:177], v[92:95]
	v_mfma_f32_16x16x32_bf16 v[84:87], v[198:201], v[182:185], v[84:87]
	v_mfma_f32_16x16x32_bf16 v[76:79], v[206:209], v[182:185], v[76:79]
	v_mfma_f32_16x16x32_bf16 v[68:71], v[198:201], v[190:193], v[68:71]
	v_mfma_f32_16x16x32_bf16 v[64:67], v[206:209], v[190:193], v[64:67]
	v_mfma_f32_16x16x32_bf16 v[116:119], v[202:205], v[170:173], v[116:119]
	v_mfma_f32_16x16x32_bf16 v[108:111], v[224:227], v[170:173], v[108:111]
	v_mfma_f32_16x16x32_bf16 v[100:103], v[202:205], v[178:181], v[100:103]
	v_mfma_f32_16x16x32_bf16 v[92:95], v[224:227], v[178:181], v[92:95]
	v_mfma_f32_16x16x32_bf16 v[84:87], v[202:205], v[186:189], v[84:87]
	v_mfma_f32_16x16x32_bf16 v[76:79], v[224:227], v[186:189], v[76:79]
	v_mfma_f32_16x16x32_bf16 v[68:71], v[202:205], v[194:197], v[68:71]
	v_mfma_f32_16x16x32_bf16 v[64:67], v[224:227], v[194:197], v[64:67]
	s_setprio 0
	s_mov_b32 m0, s55
	s_barrier
	ds_read_b128 v[166:169], v147 offset:49152
	ds_read_b128 v[170:173], v147 offset:50176
	ds_read_b128 v[174:177], v147 offset:51200
	ds_read_b128 v[178:181], v147 offset:52224
	ds_read_b128 v[182:185], v147 offset:53248
	ds_read_b128 v[186:189], v147 offset:54272
	ds_read_b128 v[190:193], v147 offset:55296
	ds_read_b128 v[194:197], v147 offset:56320
	global_load_lds_dwordx4 v128, s[100:101]
	s_mov_b32 m0, s56
	s_nop 0
	global_load_lds_dwordx4 v132, s[100:101]
	s_barrier
; #define PG8_STAGE(bufoff, gbase, voff) do { _Pragma("unroll") for (int _i = 0; _i < 2; ++_i) \
;         __builtin_amdgcn_global_load_lds((const unsigned*)((const char*)(gbase) + (voff)[_i]), (LAS unsigned*)(lds + (bufoff) + ldsw + _i * 8192), 16, 0, 0); } while (0)
; #define PG8_MMA(ai, bj, At, Bt) do { __builtin_amdgcn_s_setprio(1); _Pragma("unroll") for (int m = 0; m < 4; ++m) _Pragma("unroll") for (int n = 0; n < 2; ++n) _Pragma("unroll") for (int k = 0; k < 2; ++k) \
;         acc[ai][bj][m][n] = __builtin_amdgcn_mfma_f32_16x16x32_bf16(Bt[n][k], At[m][k], acc[ai][bj][m][n], 0, 0, 0); __builtin_amdgcn_s_setprio(0); } while (0)
; #define PG8_WAIT_V(n) asm volatile("s_waitcnt vmcnt(" #n ")" ::: "memory")
; #define PG8_BAR __builtin_amdgcn_s_barrier()
; template <class Epi, class S_t>
; __device__ __forceinline__ void gemm_phase(LAS unsigned char* lds, int lda, int ldb, const S_t& S, const Epi& E) {
;     ...
;             PG8_STAGE(PG8_SB(1, 1), b3 + hstepB, voffB);
;             PG8_WAIT_V(6); PG8_BAR; PG8_MMA(1, 1, At, B1); PG8_BAR;
;     __device__ __forceinline__ void operator()(const f32x4 (&acc)[2][2][4][2], const Unit& u, int wr, int wc, int fr, int fq) const {
;     ...
;             const int row0 = (u.pm - 32) * BM + wr * 64 + fr;
;             float* Op = Os + (size_t)(u.tag - 1) * (1024ull * DM);
; #pragma unroll
;             for (int ai = 0; ai < 2; ++ai)
; #pragma unroll
;                 for (int m = 0; m < 4; ++m) { float* rowp = Op + (size_t)(row0 + ai * HALF + m * 16) * DM + col0;
; #pragma unroll
;                     for (int bj = 0; bj < 2; ++bj)
; #pragma unroll
;                         for (int n = 0; n < 2; ++n) *(f32x4*)(rowp + bj * HALF + 4 * n) = acc[ai][bj][m][n]; }
	s_waitcnt lgkmcnt(0)
	s_setprio 1
	s_waitcnt lgkmcnt(0)
	v_mfma_f32_16x16x32_bf16 v[60:63], v[150:153], v[166:169], v[60:63]
	v_mfma_f32_16x16x32_bf16 v[56:59], v[158:161], v[166:169], v[56:59]
	v_mfma_f32_16x16x32_bf16 v[52:55], v[150:153], v[174:177], v[52:55]
	v_mfma_f32_16x16x32_bf16 v[44:47], v[158:161], v[174:177], v[44:47]
	v_mfma_f32_16x16x32_bf16 v[36:39], v[150:153], v[182:185], v[36:39]
	v_mfma_f32_16x16x32_bf16 v[28:31], v[158:161], v[182:185], v[28:31]
	v_mfma_f32_16x16x32_bf16 v[20:23], v[150:153], v[190:193], v[20:23]
	v_mfma_f32_16x16x32_bf16 v[12:15], v[158:161], v[190:193], v[12:15]
	v_mfma_f32_16x16x32_bf16 v[60:63], v[154:157], v[170:173], v[60:63]
	v_mfma_f32_16x16x32_bf16 v[56:59], v[162:165], v[170:173], v[56:59]
	v_mfma_f32_16x16x32_bf16 v[52:55], v[154:157], v[178:181], v[52:55]
	v_mfma_f32_16x16x32_bf16 v[44:47], v[162:165], v[178:181], v[44:47]
	v_mfma_f32_16x16x32_bf16 v[36:39], v[154:157], v[186:189], v[36:39]
	v_mfma_f32_16x16x32_bf16 v[28:31], v[162:165], v[186:189], v[28:31]
	v_mfma_f32_16x16x32_bf16 v[20:23], v[154:157], v[194:197], v[20:23]
	v_mfma_f32_16x16x32_bf16 v[12:15], v[162:165], v[194:197], v[12:15]
	s_setprio 0
	s_barrier
	s_add_u32 s46, s50, 0x180080
	s_addc_u32 s47, s51, 0
	s_add_i32 s33, s91, s17
	s_mov_b32 m0, s33
	s_nop 0
	global_load_lds_dwordx4 v130, s[46:47]
	s_add_i32 m0, s33, 0x2000
	s_nop 0
	global_load_lds_dwordx4 v134, s[46:47]
	s_waitcnt vmcnt(6)
	s_barrier
	s_setprio 1
	v_mfma_f32_16x16x32_bf16 v[48:51], v[198:201], v[166:169], v[48:51]
	v_mfma_f32_16x16x32_bf16 v[40:43], v[206:209], v[166:169], v[40:43]
	v_mfma_f32_16x16x32_bf16 v[32:35], v[198:201], v[174:177], v[32:35]
	v_mfma_f32_16x16x32_bf16 v[24:27], v[206:209], v[174:177], v[24:27]
	v_mfma_f32_16x16x32_bf16 v[16:19], v[198:201], v[182:185], v[16:19]
	v_mfma_f32_16x16x32_bf16 v[8:11], v[206:209], v[182:185], v[8:11]
	v_mfma_f32_16x16x32_bf16 v[4:7], v[198:201], v[190:193], v[4:7]
	v_mfma_f32_16x16x32_bf16 v[0:3], v[206:209], v[190:193], v[0:3]
	v_mfma_f32_16x16x32_bf16 v[48:51], v[202:205], v[170:173], v[48:51]
	v_mfma_f32_16x16x32_bf16 v[40:43], v[224:227], v[170:173], v[40:43]
	v_mfma_f32_16x16x32_bf16 v[32:35], v[202:205], v[178:181], v[32:35]
	v_mfma_f32_16x16x32_bf16 v[24:27], v[224:227], v[178:181], v[24:27]
	v_mfma_f32_16x16x32_bf16 v[16:19], v[202:205], v[186:189], v[16:19]
	v_mfma_f32_16x16x32_bf16 v[8:11], v[224:227], v[186:189], v[8:11]
	v_mfma_f32_16x16x32_bf16 v[4:7], v[202:205], v[194:197], v[4:7]
	v_mfma_f32_16x16x32_bf16 v[0:3], v[224:227], v[194:197], v[0:3]
	s_setprio 0
	s_add_u32 s1, s1, 0x100
	s_addc_u32 s70, s70, 0
	s_cmp_ge_u32 s71, s69
	s_mov_b64 s[46:47], s[48:49]
	s_mov_b32 s50, s71
	s_barrier
	s_cbranch_scc0 .LBB0_1383
	v_lshl_or_b32 v140, s68, 8, v145
	s_lshl_b32 s33, s67, 8
	s_cmp_lg_u32 s2, 0
	v_ashrrev_i32_e32 v141, 31, v140
	s_cbranch_scc0 .LBB0_1386
	s_add_i32 s2, s2, -1
	s_lshl_b64 s[0:1], s[2:3], 23
	v_add_u32_e32 v150, s33, v144
	s_add_u32 s0, s6, s0
	v_or_b32_e32 v156, 16, v150
	s_addc_u32 s1, s7, s1
	v_ashrrev_i32_e32 v151, 31, v150
	v_ashrrev_i32_e32 v157, 31, v156
	v_lshl_add_u64 v[152:153], v[140:141], 2, s[0:1]
	v_lshlrev_b64 v[154:155], 13, v[150:151]
	v_lshlrev_b64 v[156:157], 13, v[156:157]
	v_lshl_add_u64 v[154:155], v[152:153], 0, v[154:155]
	v_lshl_add_u64 v[156:157], v[152:153], 0, v[156:157]
	global_store_dwordx4 v[154:155], v[124:127], off
	global_store_dwordx4 v[154:155], v[120:123], off offset:16
	global_store_dwordx4 v[154:155], v[116:119], off offset:512
	global_store_dwordx4 v[154:155], v[108:111], off offset:528
	global_store_dwordx4 v[156:157], v[112:115], off
	global_store_dwordx4 v[156:157], v[104:107], off offset:16
	global_store_dwordx4 v[156:157], v[100:103], off offset:512
	global_store_dwordx4 v[156:157], v[92:95], off offset:528
	v_or_b32_e32 v156, 32, v150
	v_or_b32_e32 v150, 48, v150
	v_ashrrev_i32_e32 v157, 31, v156
	v_ashrrev_i32_e32 v151, 31, v150
	v_lshlrev_b64 v[156:157], 13, v[156:157]
	v_lshlrev_b64 v[150:151], 13, v[150:151]
	v_lshl_add_u64 v[156:157], v[152:153], 0, v[156:157]
	v_lshl_add_u64 v[150:151], v[152:153], 0, v[150:151]
	v_add_co_u32_e32 v152, vcc, s60, v154
	global_store_dwordx4 v[156:157], v[96:99], off
	global_store_dwordx4 v[156:157], v[88:91], off offset:16
	global_store_dwordx4 v[156:157], v[84:87], off offset:512
	global_store_dwordx4 v[156:157], v[76:79], off offset:528
	v_addc_co_u32_e32 v153, vcc, 0, v155, vcc
	global_store_dwordx4 v[150:151], v[80:83], off
	global_store_dwordx4 v[150:151], v[72:75], off offset:16
	global_store_dwordx4 v[150:151], v[68:71], off offset:512
	global_store_dwordx4 v[150:151], v[64:67], off offset:528
	v_lshl_add_u64 v[150:151], v[154:155], 0, s[12:13]
	global_store_dwordx4 v[152:153], v[60:63], off
	global_store_dwordx4 v[150:151], v[56:59], off offset:16
	global_store_dwordx4 v[150:151], v[48:51], off offset:512
	global_store_dwordx4 v[150:151], v[40:43], off offset:528
	v_add_co_u32_e32 v152, vcc, s61, v154
	v_lshl_add_u64 v[150:151], v[154:155], 0, s[14:15]
	s_nop 0
	v_addc_co_u32_e32 v153, vcc, 0, v155, vcc
	global_store_dwordx4 v[152:153], v[52:55], off
	global_store_dwordx4 v[150:151], v[44:47], off offset:16
	global_store_dwordx4 v[150:151], v[32:35], off offset:512
	global_store_dwordx4 v[150:151], v[24:27], off offset:528
	v_add_co_u32_e32 v152, vcc, s62, v154
	v_lshl_add_u64 v[150:151], v[154:155], 0, s[18:19]
	s_nop 0
	v_addc_co_u32_e32 v153, vcc, 0, v155, vcc
	global_store_dwordx4 v[152:153], v[36:39], off
	global_store_dwordx4 v[150:151], v[28:31], off offset:16
	global_store_dwordx4 v[150:151], v[16:19], off offset:512
	global_store_dwordx4 v[150:151], v[8:11], off offset:528
	v_add_co_u32_e32 v152, vcc, 0x160000, v154
	v_lshl_add_u64 v[150:151], v[154:155], 0, s[22:23]
	s_nop 0
	v_addc_co_u32_e32 v153, vcc, 0, v155, vcc
	global_store_dwordx4 v[152:153], v[20:23], off
	global_store_dwordx4 v[150:151], v[12:15], off offset:16
	global_store_dwordx4 v[150:151], v[4:7], off offset:512
	global_store_dwordx4 v[150:151], v[0:3], off offset:528
	s_cbranch_execnz .LBB0_1379
	s_branch .LBB0_1378

; __global__ void __launch_bounds__(NTHREADS, 2) fwd_megakernel(Params p) {
;     extern __shared__ __attribute__((aligned(16))) unsigned char lds_raw[];
	.amdhsa_kernel _Z14fwd_megakernel6Params
		.amdhsa_group_segment_fixed_size 0
		.amdhsa_private_segment_fixed_size 0
		.amdhsa_kernarg_size 520
		.amdhsa_user_sgpr_count 2
		.amdhsa_user_sgpr_dispatch_ptr 0
		.amdhsa_user_sgpr_queue_ptr 0
		.amdhsa_user_sgpr_kernarg_segment_ptr 1
		.amdhsa_user_sgpr_dispatch_id 0
		.amdhsa_user_sgpr_kernarg_preload_length 0
		.amdhsa_user_sgpr_kernarg_preload_offset 0
		.amdhsa_user_sgpr_private_segment_size 0
		.amdhsa_uses_dynamic_stack 0
		.amdhsa_enable_private_segment 0
		.amdhsa_system_sgpr_workgroup_id_x 1
		.amdhsa_system_sgpr_workgroup_id_y 0
		.amdhsa_system_sgpr_workgroup_id_z 0
		.amdhsa_system_sgpr_workgroup_info 0
		.amdhsa_system_vgpr_workitem_id 2
		.amdhsa_next_free_vgpr 256
		.amdhsa_next_free_sgpr 102
		.amdhsa_accum_offset 256
		.amdhsa_reserve_vcc 1
		.amdhsa_float_round_mode_32 0
		.amdhsa_float_round_mode_16_64 0
		.amdhsa_float_denorm_mode_32 3
		.amdhsa_float_denorm_mode_16_64 3
		.amdhsa_dx10_clamp 1
		.amdhsa_ieee_mode 1
		.amdhsa_fp16_overflow 0
		.amdhsa_tg_split 0
		.amdhsa_exception_fp_ieee_invalid_op 0
		.amdhsa_exception_fp_denorm_src 0
		.amdhsa_exception_fp_ieee_div_zero 0
		.amdhsa_exception_fp_ieee_overflow 0
		.amdhsa_exception_fp_ieee_underflow 0
		.amdhsa_exception_fp_ieee_inexact 0
		.amdhsa_exception_int_div_zero 0
	.end_amdhsa_kernel

; __global__ void __launch_bounds__(NTHREADS, 2) fwd_megakernel(Params p) {
;     extern __shared__ __attribute__((aligned(16))) unsigned char lds_raw[];
amdhsa.kernels:
  - .agpr_count:     0
    .args:
      - .offset:         0
        .size:           264
        .value_kind:     by_value
      - .offset:         264
        .size:           4
        .value_kind:     hidden_block_count_x
      - .offset:         268
        .size:           4
        .value_kind:     hidden_block_count_y
      - .offset:         272
        .size:           4
        .value_kind:     hidden_block_count_z
      - .offset:         276
        .size:           2
        .value_kind:     hidden_group_size_x
      - .offset:         278
        .size:           2
        .value_kind:     hidden_group_size_y
      - .offset:         280
        .size:           2
        .value_kind:     hidden_group_size_z
      - .offset:         282
        .size:           2
        .value_kind:     hidden_remainder_x
      - .offset:         284
        .size:           2
        .value_kind:     hidden_remainder_y
      - .offset:         286
        .size:           2
        .value_kind:     hidden_remainder_z
      - .offset:         304
        .size:           8
        .value_kind:     hidden_global_offset_x
      - .offset:         312
        .size:           8
        .value_kind:     hidden_global_offset_y
      - .offset:         320
        .size:           8
        .value_kind:     hidden_global_offset_z
      - .offset:         328
        .size:           2
        .value_kind:     hidden_grid_dims
      - .offset:         352
        .size:           8
        .value_kind:     hidden_multigrid_sync_arg
      - .offset:         384
        .size:           4
        .value_kind:     hidden_dynamic_lds_size
    .group_segment_fixed_size: 0
    .kernarg_segment_align: 8
    .kernarg_segment_size: 520
    .language:       OpenCL C
    .language_version:
      - 2
      - 0
    .max_flat_workgroup_size: 512
    .name:           _Z14fwd_megakernel6Params
    .private_segment_fixed_size: 0
    .sgpr_count:     108
    .sgpr_spill_count: 87
    .symbol:         _Z14fwd_megakernel6Params.kd
    .uniform_work_group_size: 1
    .uses_dynamic_stack: false
    .vgpr_count:     256
    .vgpr_spill_count: 0
    .wavefront_size: 64
